# GC next-unit prefetch + 152 ds_bpermute xor-1/2/4/8 shuffles replaced by DPP moves (attention epilogue pairs, wave max/sum butterflies)
# speedup vs baseline: 1.0110x; 1.0106x over previous
; __device__ __forceinline__ float bflo(unsigned w) { return __uint_as_float(w << 16); }
; __device__ __forceinline__ float bfhi(unsigned w) { return __uint_as_float(w & 0xffff0000u); }
; #pragma unroll
;     for (int j = 0; j < 8; ++j) mx = fmaxf(mx, fmaxf(fmaxf(fmaxf(fabsf(bflo(w[j].x)), fabsf(bfhi(w[j].x))), fmaxf(fabsf(bflo(w[j].y)), fabsf(bfhi(w[j].y)))), fmaxf(fmaxf(fabsf(bflo(w[j].z)), fabsf(bfhi(w[j].z))), fmaxf(fabsf(bflo(w[j].w)), fabsf(bfhi(w[j].w))))));
; #pragma unroll
;     for (int o = 1; o < 64; o <<= 1) mx = fmaxf(mx, __shfl_xor(mx, o));
;     return mx; }
; __device__ __forceinline__ void quant_rows2(const bf16_t* s0, const bf16_t* s1, signed char* d0, signed char* d1, int lane, float& step0, float& step1) {
;     const u32x4* p0 = (const u32x4*)s0 + lane; const u32x4* p1 = (const u32x4*)s1 + lane; u32x4 w0[8], w1[8];
; #pragma unroll
;     for (int j = 0; j < 8; ++j) { w0[j] = p0[64 * j]; w1[j] = p1[64 * j]; }
; __global__ void __launch_bounds__(NWAVES * 64, 2) fwd(Args args) {
;     ...
;             for (int p = 0; p < 4; ++p) { const int n = 64 * bx + 8 * F.wave + 2 * p; float s0, s1;
;                 quant_rows2(W_inT + (size_t)(IN_Q0 + n) * DM, W_inT + (size_t)(IN_Q0 + n + 1) * DM, W_inq + (size_t)n * DM, W_inq + (size_t)(n + 1) * DM, F.lane, s0, s1);
;                 if (F.lane == 0) { colq[n] = s0; colq[n + 1] = s1; } }
.LBB0_64:
	v_lshl_add_u64 v[2:3], s[78:79], 0, v[30:31]
	v_add_co_u32_e32 v4, vcc, 0x800000, v2
	s_nop 1
	v_addc_co_u32_e32 v5, vcc, 0, v3, vcc
	global_load_dwordx4 v[42:45], v[4:5], off
	global_load_dwordx4 v[46:49], v[4:5], off offset:1024
	global_load_dwordx4 v[50:53], v[4:5], off offset:2048
	global_load_dwordx4 v[54:57], v[4:5], off offset:3072
	v_add_co_u32_e32 v6, vcc, 0x802000, v2
	s_waitcnt vmcnt(3)
	v_lshlrev_b32_e32 v83, 16, v42
	v_addc_co_u32_e32 v7, vcc, 0, v3, vcc
	v_add_co_u32_e32 v78, vcc, s17, v2
	global_load_dwordx4 v[58:61], v[6:7], off
	global_load_dwordx4 v[26:29], v[6:7], off offset:1024
	global_load_dwordx4 v[22:25], v[6:7], off offset:2048
	global_load_dwordx4 v[18:21], v[6:7], off offset:3072
	v_addc_co_u32_e32 v79, vcc, 0, v3, vcc
	v_add_co_u32_e32 v80, vcc, s18, v2
	v_and_b32_e32 v84, 0xffff0000, v42
	s_nop 0
	v_addc_co_u32_e32 v81, vcc, 0, v3, vcc
	global_load_dwordx4 v[62:65], v[78:79], off
	global_load_dwordx4 v[66:69], v[78:79], off offset:1024
	global_load_dwordx4 v[70:73], v[78:79], off offset:2048
	global_load_dwordx4 v[74:77], v[78:79], off offset:3072
	global_load_dwordx4 v[14:17], v[80:81], off
	global_load_dwordx4 v[10:13], v[80:81], off offset:1024
	global_load_dwordx4 v[6:9], v[80:81], off offset:2048
	global_load_dwordx4 v[2:5], v[80:81], off offset:3072
	v_lshlrev_b32_e32 v85, 16, v43
	v_and_b32_e32 v86, 0xffff0000, v43
	v_lshlrev_b32_e32 v89, 16, v45
	v_and_b32_e32 v90, 0xffff0000, v45
	s_waitcnt vmcnt(14)
	v_lshlrev_b32_e32 v97, 16, v49
	v_and_b32_e32 v98, 0xffff0000, v49
	v_lshlrev_b32_e32 v87, 16, v44
	v_and_b32_e32 v88, 0xffff0000, v44
	v_lshlrev_b32_e32 v91, 16, v46
	v_and_b32_e32 v92, 0xffff0000, v46
	v_lshlrev_b32_e32 v93, 16, v47
	v_and_b32_e32 v94, 0xffff0000, v47
	s_waitcnt vmcnt(13)
	v_lshlrev_b32_e32 v101, 16, v51
	v_and_b32_e32 v102, 0xffff0000, v51
	v_lshlrev_b32_e32 v103, 16, v52
	v_and_b32_e32 v104, 0xffff0000, v52
	v_max_f32_e64 v41, |v84|, |v84|
	v_max_f32_e64 v42, |v83|, |v83|
	v_max_f32_e64 v43, |v86|, |v86|
	v_max_f32_e64 v44, |v85|, |v85|
	v_max_f32_e64 v45, |v90|, |v90|
	v_max_f32_e64 v46, |v89|, |v89|
	v_max_f32_e64 v51, |v98|, |v98|
	v_max_f32_e64 v52, |v97|, |v97|
	v_lshlrev_b32_e32 v95, 16, v48
	v_and_b32_e32 v96, 0xffff0000, v48
	v_lshlrev_b32_e32 v99, 16, v50
	v_and_b32_e32 v100, 0xffff0000, v50
	v_max_f32_e64 v47, |v92|, |v92|
	v_max_f32_e64 v48, |v91|, |v91|
	v_max_f32_e64 v49, |v94|, |v94|
	v_max_f32_e64 v50, |v93|, |v93|
	v_max_f32_e32 v41, v42, v41
	v_max_f32_e32 v42, v44, v43
	v_max_f32_e32 v43, v46, v45
	v_max_f32_e32 v46, v52, v51
	v_max_f32_e32 v44, v48, v47
	v_max_f32_e32 v45, v50, v49
	v_max3_f32 v43, |v87|, |v88|, v43
	v_max3_f32 v46, |v95|, |v96|, v46
	v_lshlrev_b32_e32 v105, 16, v53
	v_max3_f32 v41, v41, v42, v43
	v_max3_f32 v42, v44, v45, v46
	v_and_b32_e32 v106, 0xffff0000, v53
	v_max3_f32 v41, v41, 0, v42
	v_max_f32_e64 v42, |v106|, |v106|
	v_max_f32_e64 v43, |v105|, |v105|
	s_waitcnt vmcnt(12)
	v_lshlrev_b32_e32 v107, 16, v54
	v_and_b32_e32 v108, 0xffff0000, v54
	v_max_f32_e32 v42, v43, v42
	v_max_f32_e64 v43, |v108|, |v108|
	v_max_f32_e64 v44, |v107|, |v107|
	v_lshlrev_b32_e32 v109, 16, v55
	v_and_b32_e32 v110, 0xffff0000, v55
	v_max_f32_e32 v43, v44, v43
	v_max_f32_e64 v44, |v110|, |v110|
	v_max_f32_e64 v45, |v109|, |v109|
	v_lshlrev_b32_e32 v113, 16, v57
	v_and_b32_e32 v114, 0xffff0000, v57
	v_max_f32_e32 v44, v45, v44
	v_max_f32_e64 v45, |v114|, |v114|
	v_max_f32_e64 v46, |v113|, |v113|
	v_max_f32_e64 v78, |v100|, |v100|
	v_max_f32_e64 v79, |v99|, |v99|
	v_max_f32_e64 v80, |v102|, |v102|
	v_max_f32_e64 v81, |v101|, |v101|
	v_lshlrev_b32_e32 v111, 16, v56
	v_and_b32_e32 v112, 0xffff0000, v56
	v_max_f32_e32 v45, v46, v45
	v_max_f32_e32 v47, v79, v78
	v_max_f32_e32 v48, v81, v80
	v_max3_f32 v42, |v103|, |v104|, v42
	v_max3_f32 v45, |v111|, |v112|, v45
	v_max3_f32 v42, v47, v48, v42
	v_max3_f32 v43, v43, v44, v45
	s_waitcnt vmcnt(7)
	v_lshlrev_b32_e32 v115, 16, v62
	v_and_b32_e32 v116, 0xffff0000, v62
	v_max3_f32 v41, v41, v42, v43
	v_max_f32_e64 v42, |v116|, |v116|
	v_max_f32_e64 v43, |v115|, |v115|
	v_lshlrev_b32_e32 v117, 16, v63
	v_and_b32_e32 v118, 0xffff0000, v63
	v_max_f32_e32 v42, v43, v42
	v_max_f32_e64 v43, |v118|, |v118|
	v_max_f32_e64 v44, |v117|, |v117|
	v_lshlrev_b32_e32 v121, 16, v65
	v_and_b32_e32 v122, 0xffff0000, v65
	v_max_f32_e32 v43, v44, v43
	v_max_f32_e64 v44, |v122|, |v122|
	v_max_f32_e64 v45, |v121|, |v121|
	v_lshlrev_b32_e32 v119, 16, v64
	v_and_b32_e32 v120, 0xffff0000, v64
	v_max_f32_e32 v44, v45, v44
	v_max3_f32 v44, |v119|, |v120|, v44
	s_waitcnt vmcnt(6)
	v_lshlrev_b32_e32 v123, 16, v66
	v_and_b32_e32 v124, 0xffff0000, v66
	v_max3_f32 v42, v42, v43, v44
	v_max_f32_e64 v43, |v124|, |v124|
	v_max_f32_e64 v44, |v123|, |v123|
	v_lshlrev_b32_e32 v125, 16, v67
	v_and_b32_e32 v126, 0xffff0000, v67
	v_max_f32_e32 v43, v44, v43
	v_max_f32_e64 v44, |v126|, |v126|
	v_max_f32_e64 v45, |v125|, |v125|
	v_lshlrev_b32_e32 v129, 16, v69
	v_and_b32_e32 v130, 0xffff0000, v69
	v_max_f32_e32 v44, v45, v44
	v_max_f32_e64 v45, |v130|, |v130|
	v_max_f32_e64 v46, |v129|, |v129|
	v_lshlrev_b32_e32 v127, 16, v68
	v_and_b32_e32 v128, 0xffff0000, v68
	v_max_f32_e32 v45, v46, v45
	v_max3_f32 v45, |v127|, |v128|, v45
	v_max3_f32 v43, v43, v44, v45
	s_waitcnt vmcnt(5)
	v_lshlrev_b32_e32 v131, 16, v70
	v_and_b32_e32 v132, 0xffff0000, v70
	v_max3_f32 v41, v41, v42, v43
	v_max_f32_e64 v42, |v132|, |v132|
	v_max_f32_e64 v43, |v131|, |v131|
	v_lshlrev_b32_e32 v133, 16, v71
	v_and_b32_e32 v134, 0xffff0000, v71
	v_max_f32_e32 v42, v43, v42
	v_max_f32_e64 v43, |v134|, |v134|
	v_max_f32_e64 v44, |v133|, |v133|
	v_lshlrev_b32_e32 v137, 16, v73
	v_and_b32_e32 v138, 0xffff0000, v73
	v_max_f32_e32 v43, v44, v43
	v_max_f32_e64 v44, |v138|, |v138|
	v_max_f32_e64 v45, |v137|, |v137|
	v_lshlrev_b32_e32 v135, 16, v72
	v_and_b32_e32 v136, 0xffff0000, v72
	v_max_f32_e32 v44, v45, v44
	v_max3_f32 v44, |v135|, |v136|, v44
	s_waitcnt vmcnt(4)
; __device__ __forceinline__ float bflo(unsigned w) { return __uint_as_float(w << 16); }
; __device__ __forceinline__ float bfhi(unsigned w) { return __uint_as_float(w & 0xffff0000u); }
; #pragma unroll
;     for (int j = 0; j < 8; ++j) mx = fmaxf(mx, fmaxf(fmaxf(fmaxf(fabsf(bflo(w[j].x)), fabsf(bfhi(w[j].x))), fmaxf(fabsf(bflo(w[j].y)), fabsf(bfhi(w[j].y)))), fmaxf(fmaxf(fabsf(bflo(w[j].z)), fabsf(bfhi(w[j].z))), fmaxf(fabsf(bflo(w[j].w)), fabsf(bfhi(w[j].w))))));
; #pragma unroll
;     for (int o = 1; o < 64; o <<= 1) mx = fmaxf(mx, __shfl_xor(mx, o));
;     return mx; }
	v_lshlrev_b32_e32 v139, 16, v74
	v_and_b32_e32 v140, 0xffff0000, v74
	v_max3_f32 v42, v42, v43, v44
	v_max_f32_e64 v43, |v140|, |v140|
	v_max_f32_e64 v44, |v139|, |v139|
	v_lshlrev_b32_e32 v141, 16, v75
	v_and_b32_e32 v142, 0xffff0000, v75
	v_max_f32_e32 v43, v44, v43
	v_max_f32_e64 v44, |v142|, |v142|
	v_max_f32_e64 v45, |v141|, |v141|
	v_lshlrev_b32_e32 v145, 16, v77
	v_and_b32_e32 v146, 0xffff0000, v77
	v_max_f32_e32 v44, v45, v44
	v_max_f32_e64 v45, |v146|, |v146|
	v_max_f32_e64 v46, |v145|, |v145|
	v_lshlrev_b32_e32 v143, 16, v76
	v_and_b32_e32 v144, 0xffff0000, v76
	v_max_f32_e32 v45, v46, v45
	v_max3_f32 v45, |v143|, |v144|, v45
	v_max3_f32 v43, v43, v44, v45
	v_lshlrev_b32_e32 v82, 16, v58
	v_and_b32_e32 v80, 0xffff0000, v58
	v_max3_f32 v147, v41, v42, v43
	v_max_f32_e64 v41, |v80|, |v80|
	v_max_f32_e64 v42, |v82|, |v82|
	v_lshlrev_b32_e32 v81, 16, v59
	v_and_b32_e32 v79, 0xffff0000, v59
	v_max_f32_e32 v41, v42, v41
	v_max_f32_e64 v42, |v79|, |v79|
	v_max_f32_e64 v43, |v81|, |v81|
	v_lshlrev_b32_e32 v76, 16, v61
	v_and_b32_e32 v75, 0xffff0000, v61
	v_max_f32_e32 v42, v43, v42
	v_max_f32_e64 v43, |v75|, |v75|
	v_max_f32_e64 v44, |v76|, |v76|
	v_lshlrev_b32_e32 v78, 16, v60
	v_and_b32_e32 v77, 0xffff0000, v60
	v_max_f32_e32 v43, v44, v43
	v_max3_f32 v43, |v78|, |v77|, v43
	v_lshlrev_b32_e32 v74, 16, v26
	v_and_b32_e32 v72, 0xffff0000, v26
	v_lshlrev_b32_e32 v68, 16, v29
	v_and_b32_e32 v67, 0xffff0000, v29
	v_max3_f32 v41, v41, v42, v43
	v_max_f32_e64 v26, |v72|, |v72|
	v_max_f32_e64 v42, |v74|, |v74|
	v_lshlrev_b32_e32 v73, 16, v27
	v_and_b32_e32 v71, 0xffff0000, v27
	v_lshlrev_b32_e32 v70, 16, v28
	v_and_b32_e32 v69, 0xffff0000, v28
	v_max_f32_e64 v28, |v67|, |v67|
	v_max_f32_e64 v29, |v68|, |v68|
	v_max_f32_e32 v26, v42, v26
	v_max_f32_e64 v27, |v71|, |v71|
	v_max_f32_e64 v42, |v73|, |v73|
	v_max_f32_e32 v28, v29, v28
	v_max_f32_e32 v27, v42, v27
	v_max3_f32 v28, |v70|, |v69|, v28
	v_lshlrev_b32_e32 v66, 16, v22
	v_and_b32_e32 v64, 0xffff0000, v22
	v_lshlrev_b32_e32 v60, 16, v25
	v_and_b32_e32 v59, 0xffff0000, v25
	v_max3_f32 v26, v26, v27, v28
	v_max_f32_e64 v22, |v64|, |v64|
	v_max_f32_e64 v27, |v66|, |v66|
	v_lshlrev_b32_e32 v65, 16, v23
	v_and_b32_e32 v63, 0xffff0000, v23
	v_lshlrev_b32_e32 v62, 16, v24
	v_and_b32_e32 v61, 0xffff0000, v24
	v_max_f32_e64 v24, |v59|, |v59|
	v_max_f32_e64 v25, |v60|, |v60|
	v_max_f32_e32 v22, v27, v22
	v_max_f32_e64 v23, |v63|, |v63|
	v_max_f32_e64 v27, |v65|, |v65|
	v_max_f32_e32 v24, v25, v24
	v_max_f32_e32 v23, v27, v23
	v_max3_f32 v24, |v62|, |v61|, v24
	v_lshlrev_b32_e32 v58, 16, v18
	v_and_b32_e32 v56, 0xffff0000, v18
	v_lshlrev_b32_e32 v52, 16, v21
	v_and_b32_e32 v51, 0xffff0000, v21
	v_max3_f32 v22, v22, v23, v24
	v_max_f32_e64 v18, |v56|, |v56|
	v_max_f32_e64 v23, |v58|, |v58|
	v_lshlrev_b32_e32 v57, 16, v19
	v_and_b32_e32 v55, 0xffff0000, v19
	v_lshlrev_b32_e32 v54, 16, v20
	v_and_b32_e32 v53, 0xffff0000, v20
	v_max_f32_e64 v20, |v51|, |v51|
	v_max_f32_e64 v21, |v52|, |v52|
	v_max_f32_e32 v18, v23, v18
	v_max_f32_e64 v19, |v55|, |v55|
	v_max_f32_e64 v23, |v57|, |v57|
	v_max_f32_e32 v20, v21, v20
	v_max_f32_e32 v19, v23, v19
	v_max3_f32 v20, |v54|, |v53|, v20
	s_waitcnt vmcnt(3)
	v_lshlrev_b32_e32 v50, 16, v14
	v_and_b32_e32 v48, 0xffff0000, v14
	v_lshlrev_b32_e32 v44, 16, v17
	v_and_b32_e32 v43, 0xffff0000, v17
	v_max3_f32 v18, v18, v19, v20
	v_max_f32_e64 v14, |v48|, |v48|
	v_max_f32_e64 v19, |v50|, |v50|
	v_lshlrev_b32_e32 v49, 16, v15
	v_and_b32_e32 v47, 0xffff0000, v15
	v_lshlrev_b32_e32 v46, 16, v16
	v_and_b32_e32 v45, 0xffff0000, v16
	v_max_f32_e64 v16, |v43|, |v43|
	v_max_f32_e64 v17, |v44|, |v44|
	v_max_f32_e32 v14, v19, v14
	v_max_f32_e64 v15, |v47|, |v47|
	v_max_f32_e64 v19, |v49|, |v49|
	v_max_f32_e32 v16, v17, v16
	v_max3_f32 v26, v41, 0, v26
	v_max_f32_e32 v15, v19, v15
	v_max3_f32 v16, |v46|, |v45|, v16
	s_waitcnt vmcnt(2)
	v_lshlrev_b32_e32 v42, 16, v10
	v_and_b32_e32 v29, 0xffff0000, v10
	v_lshlrev_b32_e32 v25, 16, v13
	v_and_b32_e32 v24, 0xffff0000, v13
	v_max3_f32 v18, v26, v22, v18
	v_max3_f32 v14, v14, v15, v16
	v_max_f32_e64 v10, |v29|, |v29|
	v_max_f32_e64 v15, |v42|, |v42|
	v_lshlrev_b32_e32 v41, 16, v11
	v_and_b32_e32 v28, 0xffff0000, v11
	v_lshlrev_b32_e32 v27, 16, v12
	v_and_b32_e32 v26, 0xffff0000, v12
	v_max_f32_e64 v12, |v24|, |v24|
	v_max_f32_e64 v13, |v25|, |v25|
	v_max_f32_e32 v10, v15, v10
	v_max_f32_e64 v11, |v28|, |v28|
	v_max_f32_e64 v15, |v41|, |v41|
	v_max_f32_e32 v12, v13, v12
	v_max_f32_e32 v11, v15, v11
	v_max3_f32 v12, |v27|, |v26|, v12
	v_max3_f32 v10, v10, v11, v12
	s_waitcnt vmcnt(1)
	v_lshlrev_b32_e32 v23, 16, v6
	v_and_b32_e32 v21, 0xffff0000, v6
	v_lshlrev_b32_e32 v17, 16, v9
	v_and_b32_e32 v16, 0xffff0000, v9
	v_max3_f32 v149, v18, v14, v10
	v_max_f32_e64 v6, |v21|, |v21|
	v_max_f32_e64 v10, |v23|, |v23|
	v_lshlrev_b32_e32 v22, 16, v7
	v_and_b32_e32 v20, 0xffff0000, v7
	v_lshlrev_b32_e32 v19, 16, v8
	v_and_b32_e32 v18, 0xffff0000, v8
	v_max_f32_e64 v8, |v16|, |v16|
	v_max_f32_e64 v9, |v17|, |v17|
	v_max_f32_e32 v6, v10, v6
	v_max_f32_e64 v7, |v20|, |v20|
	v_max_f32_e64 v10, |v22|, |v22|
	v_max_f32_e32 v8, v9, v8
	v_max_f32_e32 v7, v10, v7
	v_max3_f32 v8, |v19|, |v18|, v8
	v_max3_f32 v6, v6, v7, v8
	s_waitcnt vmcnt(0)
	v_lshlrev_b32_e32 v15, 16, v2
	v_and_b32_e32 v13, 0xffff0000, v2
	v_lshlrev_b32_e32 v9, 16, v5
	v_and_b32_e32 v8, 0xffff0000, v5
	v_max_f32_e64 v2, |v13|, |v13|
	v_max_f32_e64 v7, |v15|, |v15|
	v_lshlrev_b32_e32 v14, 16, v3
	v_and_b32_e32 v12, 0xffff0000, v3
	v_lshlrev_b32_e32 v11, 16, v4
	v_and_b32_e32 v10, 0xffff0000, v4
	v_max_f32_e64 v4, |v8|, |v8|
	v_max_f32_e64 v5, |v9|, |v9|
	v_max_f32_e32 v2, v7, v2
	v_max_f32_e64 v3, |v12|, |v12|
	v_max_f32_e64 v7, |v14|, |v14|
	v_max_f32_e32 v4, v5, v4
	v_max_f32_e32 v3, v7, v3
	v_max3_f32 v4, |v11|, |v10|, v4
	v_max3_f32 v2, v2, v3, v4
	v_max3_f32 v2, v149, v6, v2
	s_nop 1
	v_mov_b32_dpp v148, v147 quad_perm:[1,0,3,2] row_mask:0xf bank_mask:0xf
	s_nop 1
	v_mov_b32_dpp v3, v2 quad_perm:[1,0,3,2] row_mask:0xf bank_mask:0xf
	s_waitcnt lgkmcnt(0)
; __device__ __forceinline__ float bflo(unsigned w) { return __uint_as_float(w << 16); }
; __device__ __forceinline__ float bfhi(unsigned w) { return __uint_as_float(w & 0xffff0000u); }
;     ...
; #pragma unroll
;     for (int o = 1; o < 64; o <<= 1) mx = fmaxf(mx, __shfl_xor(mx, o));
;     return mx; }
; __device__ __forceinline__ void quant_store8(const u32x4 (&w)[8], float inv, signed char* dst, int lane) { u32x2* qp = (u32x2*)dst + lane;
; #pragma unroll
;     for (int j = 0; j < 8; ++j) { const unsigned ww[4] = {w[j].x, w[j].y, w[j].z, w[j].w}; unsigned o2[2];
; #pragma unroll
;         for (int h2 = 0; h2 < 2; ++h2) { const int q0 = (int)rintf(bflo(ww[2 * h2]) * inv), q1 = (int)rintf(bfhi(ww[2 * h2]) * inv), q2 = (int)rintf(bflo(ww[2 * h2 + 1]) * inv), q3 = (int)rintf(bfhi(ww[2 * h2 + 1]) * inv);
;             o2[h2] = (unsigned)(q0 & 255) | ((unsigned)(q1 & 255) << 8) | ((unsigned)(q2 & 255) << 16) | ((unsigned)(q3 & 255) << 24); }
;         u32x2 o; o.x = o2[0]; o.y = o2[1]; qp[64 * j] = o; } }
; __device__ __forceinline__ void quant_rows2(const bf16_t* s0, const bf16_t* s1, signed char* d0, signed char* d1, int lane, float& step0, float& step1) {
;     ...
;     step0 = fmaxf(absmax8(w0), 1e-30f) * (1.0f / 127.0f); step1 = fmaxf(absmax8(w1), 1e-30f) * (1.0f / 127.0f);
;     quant_store8(w0, 1.0f / step0, d0, lane); quant_store8(w1, 1.0f / step1, d1, lane);
	v_max_f32_e32 v4, v148, v148
	s_waitcnt lgkmcnt(0)
	v_max_f32_e32 v3, v3, v3
	v_max_f32_e32 v4, v147, v4
	v_max_f32_e32 v2, v2, v3
	s_nop 1
	v_mov_b32_dpp v5, v4 quad_perm:[2,3,0,1] row_mask:0xf bank_mask:0xf
	s_nop 1
	v_mov_b32_dpp v3, v2 quad_perm:[2,3,0,1] row_mask:0xf bank_mask:0xf
	s_waitcnt lgkmcnt(0)
	v_max_f32_e32 v5, v5, v5
	s_waitcnt lgkmcnt(0)
	v_max_f32_e32 v3, v3, v3
	v_max_f32_e32 v4, v4, v5
	v_max_f32_e32 v2, v2, v3
	s_nop 1
	v_mov_b32_dpp v5, v4 row_half_mirror row_mask:0xf bank_mask:0xf
	s_nop 1
	v_mov_b32_dpp v3, v2 row_half_mirror row_mask:0xf bank_mask:0xf
	s_waitcnt lgkmcnt(0)
	v_max_f32_e32 v5, v5, v5
	s_waitcnt lgkmcnt(0)
	v_max_f32_e32 v3, v3, v3
	v_max_f32_e32 v4, v4, v5
	v_max_f32_e32 v2, v2, v3
	s_nop 1
	v_mov_b32_dpp v5, v4 row_mirror row_mask:0xf bank_mask:0xf
	s_nop 1
	v_mov_b32_dpp v3, v2 row_mirror row_mask:0xf bank_mask:0xf
	s_waitcnt lgkmcnt(0)
	v_max_f32_e32 v5, v5, v5
	s_waitcnt lgkmcnt(0)
	v_max_f32_e32 v3, v3, v3
	v_max_f32_e32 v4, v4, v5
	v_max_f32_e32 v2, v2, v3
	ds_bpermute_b32 v5, v38, v4
	ds_bpermute_b32 v3, v38, v2
	s_waitcnt lgkmcnt(1)
	v_max_f32_e32 v5, v5, v5
	s_waitcnt lgkmcnt(0)
	v_max_f32_e32 v3, v3, v3
	v_max_f32_e32 v4, v4, v5
	v_max_f32_e32 v3, v2, v3
	ds_bpermute_b32 v5, v39, v4
	ds_bpermute_b32 v6, v39, v3
	s_waitcnt lgkmcnt(1)
	v_max3_f32 v2, v4, v5, s19
	s_waitcnt lgkmcnt(0)
	v_max3_f32 v3, v3, v6, s19
	v_pk_mul_f32 v[2:3], v[2:3], s[6:7] op_sel_hi:[1,0]
	s_nop 0
	v_div_scale_f32 v4, s[14:15], v2, v2, 1.0
	v_rcp_f32_e32 v5, v4
	s_nop 0
	v_fma_f32 v6, -v4, v5, 1.0
	v_fmac_f32_e32 v5, v6, v5
	v_div_scale_f32 v6, vcc, 1.0, v2, 1.0
	v_mul_f32_e32 v7, v6, v5
	v_fma_f32 v147, -v4, v7, v6
	v_fmac_f32_e32 v7, v147, v5
	v_fma_f32 v4, -v4, v7, v6
	v_div_fmas_f32 v4, v4, v5, v7
	v_div_fixup_f32 v147, v4, v2, 1.0
	v_mul_f32_e32 v7, v147, v84
	v_mul_f32_e32 v6, v147, v83
	v_rndne_f32_e32 v7, v7
	v_mul_f32_e32 v83, v147, v85
	v_rndne_f32_e32 v6, v6
	v_cvt_i32_f32_e32 v7, v7
	v_rndne_f32_e32 v83, v83
	v_mul_f32_e32 v84, v147, v86
	v_cvt_i32_f32_e32 v6, v6
	v_cvt_i32_f32_sdwa v83, v83 dst_sel:WORD_1 dst_unused:UNUSED_PAD src0_sel:DWORD
	v_rndne_f32_e32 v84, v84
	v_cvt_i32_f32_sdwa v84, v84 dst_sel:BYTE_3 dst_unused:UNUSED_PAD src0_sel:DWORD
	v_lshlrev_b32_e32 v7, 8, v7
	v_and_b32_e32 v83, 0xff0000, v83
	v_perm_b32 v6, v7, v6, s20
	v_mul_f32_e32 v7, v147, v88
	v_or3_b32 v84, v6, v84, v83
	v_mul_f32_e32 v6, v147, v87
	v_rndne_f32_e32 v7, v7
	v_mul_f32_e32 v83, v147, v89
	v_rndne_f32_e32 v6, v6
	v_cvt_i32_f32_e32 v7, v7
	v_rndne_f32_e32 v83, v83
	v_mul_f32_e32 v85, v147, v90
	v_cvt_i32_f32_e32 v6, v6
	v_cvt_i32_f32_sdwa v83, v83 dst_sel:WORD_1 dst_unused:UNUSED_PAD src0_sel:DWORD
	v_rndne_f32_e32 v85, v85
	v_cvt_i32_f32_sdwa v85, v85 dst_sel:BYTE_3 dst_unused:UNUSED_PAD src0_sel:DWORD
	v_lshlrev_b32_e32 v7, 8, v7
	v_lshl_add_u64 v[4:5], s[78:79], 0, v[32:33]
	v_and_b32_e32 v83, 0xff0000, v83
	v_perm_b32 v6, v7, v6, s20
	v_or3_b32 v85, v6, v85, v83
	v_add_co_u32_e32 v6, vcc, s21, v4
	v_mul_f32_e32 v83, v147, v91
	s_nop 0
	v_addc_co_u32_e32 v7, vcc, 0, v5, vcc
	v_add_co_u32_e32 v4, vcc, s22, v4
	v_rndne_f32_e32 v83, v83
	s_nop 0
	v_addc_co_u32_e32 v5, vcc, 0, v5, vcc
	global_store_dwordx2 v[4:5], v[84:85], off offset:-4096
	v_mul_f32_e32 v84, v147, v92
	v_rndne_f32_e32 v84, v84
	v_mul_f32_e32 v85, v147, v93
	v_cvt_i32_f32_e32 v84, v84
	v_rndne_f32_e32 v85, v85
	v_mul_f32_e32 v86, v147, v94
	v_cvt_i32_f32_e32 v83, v83
	v_cvt_i32_f32_sdwa v85, v85 dst_sel:WORD_1 dst_unused:UNUSED_PAD src0_sel:DWORD
	v_rndne_f32_e32 v86, v86
	v_cvt_i32_f32_sdwa v86, v86 dst_sel:BYTE_3 dst_unused:UNUSED_PAD src0_sel:DWORD
	v_lshlrev_b32_e32 v84, 8, v84
	v_and_b32_e32 v85, 0xff0000, v85
	v_perm_b32 v83, v84, v83, s20
	v_or3_b32 v84, v83, v86, v85
	v_mul_f32_e32 v85, v147, v96
	v_mul_f32_e32 v83, v147, v95
	v_rndne_f32_e32 v85, v85
	v_mul_f32_e32 v86, v147, v97
	v_rndne_f32_e32 v83, v83
	v_cvt_i32_f32_e32 v85, v85
	v_rndne_f32_e32 v86, v86
	v_mul_f32_e32 v87, v147, v98
	v_cvt_i32_f32_e32 v83, v83
	v_cvt_i32_f32_sdwa v86, v86 dst_sel:WORD_1 dst_unused:UNUSED_PAD src0_sel:DWORD
	v_rndne_f32_e32 v87, v87
	v_cvt_i32_f32_sdwa v87, v87 dst_sel:BYTE_3 dst_unused:UNUSED_PAD src0_sel:DWORD
	v_lshlrev_b32_e32 v85, 8, v85
	v_and_b32_e32 v86, 0xff0000, v86
	v_perm_b32 v83, v85, v83, s20
	v_or3_b32 v85, v83, v87, v86
	global_store_dwordx2 v[6:7], v[84:85], off offset:512
	v_mul_f32_e32 v84, v147, v100
	v_mul_f32_e32 v83, v147, v99
	v_rndne_f32_e32 v84, v84
	v_mul_f32_e32 v85, v147, v101
	v_rndne_f32_e32 v83, v83
	v_cvt_i32_f32_e32 v84, v84
	v_rndne_f32_e32 v85, v85
	v_mul_f32_e32 v86, v147, v102
	v_cvt_i32_f32_e32 v83, v83
	v_cvt_i32_f32_sdwa v85, v85 dst_sel:WORD_1 dst_unused:UNUSED_PAD src0_sel:DWORD
	v_rndne_f32_e32 v86, v86
	v_cvt_i32_f32_sdwa v86, v86 dst_sel:BYTE_3 dst_unused:UNUSED_PAD src0_sel:DWORD
	v_lshlrev_b32_e32 v84, 8, v84
	v_and_b32_e32 v85, 0xff0000, v85
	v_perm_b32 v83, v84, v83, s20
	v_or3_b32 v84, v83, v86, v85
	v_mul_f32_e32 v85, v147, v104
	v_mul_f32_e32 v83, v147, v103
	v_rndne_f32_e32 v85, v85
	v_mul_f32_e32 v86, v147, v105
	v_rndne_f32_e32 v83, v83
	v_cvt_i32_f32_e32 v85, v85
	v_rndne_f32_e32 v86, v86
	v_mul_f32_e32 v87, v147, v106
	v_cvt_i32_f32_e32 v83, v83
	v_cvt_i32_f32_sdwa v86, v86 dst_sel:WORD_1 dst_unused:UNUSED_PAD src0_sel:DWORD
	v_rndne_f32_e32 v87, v87
	v_cvt_i32_f32_sdwa v87, v87 dst_sel:BYTE_3 dst_unused:UNUSED_PAD src0_sel:DWORD
	v_lshlrev_b32_e32 v85, 8, v85
	v_and_b32_e32 v86, 0xff0000, v86
	v_perm_b32 v83, v85, v83, s20
	v_or3_b32 v85, v83, v87, v86
	global_store_dwordx2 v[6:7], v[84:85], off offset:1024
	v_mul_f32_e32 v84, v147, v108
	v_mul_f32_e32 v83, v147, v107
	v_rndne_f32_e32 v84, v84
; __device__ __forceinline__ float bflo(unsigned w) { return __uint_as_float(w << 16); }
; __device__ __forceinline__ float bfhi(unsigned w) { return __uint_as_float(w & 0xffff0000u); }
; __device__ __forceinline__ void quant_store8(const u32x4 (&w)[8], float inv, signed char* dst, int lane) { u32x2* qp = (u32x2*)dst + lane;
; #pragma unroll
;     for (int j = 0; j < 8; ++j) { const unsigned ww[4] = {w[j].x, w[j].y, w[j].z, w[j].w}; unsigned o2[2];
; #pragma unroll
;         for (int h2 = 0; h2 < 2; ++h2) { const int q0 = (int)rintf(bflo(ww[2 * h2]) * inv), q1 = (int)rintf(bfhi(ww[2 * h2]) * inv), q2 = (int)rintf(bflo(ww[2 * h2 + 1]) * inv), q3 = (int)rintf(bfhi(ww[2 * h2 + 1]) * inv);
;             o2[h2] = (unsigned)(q0 & 255) | ((unsigned)(q1 & 255) << 8) | ((unsigned)(q2 & 255) << 16) | ((unsigned)(q3 & 255) << 24); }
;         u32x2 o; o.x = o2[0]; o.y = o2[1]; qp[64 * j] = o; } }
	v_mul_f32_e32 v85, v147, v109
	v_rndne_f32_e32 v83, v83
	v_cvt_i32_f32_e32 v84, v84
	v_rndne_f32_e32 v85, v85
	v_mul_f32_e32 v86, v147, v110
	v_cvt_i32_f32_e32 v83, v83
	v_cvt_i32_f32_sdwa v85, v85 dst_sel:WORD_1 dst_unused:UNUSED_PAD src0_sel:DWORD
	v_rndne_f32_e32 v86, v86
	v_cvt_i32_f32_sdwa v86, v86 dst_sel:BYTE_3 dst_unused:UNUSED_PAD src0_sel:DWORD
	v_lshlrev_b32_e32 v84, 8, v84
	v_and_b32_e32 v85, 0xff0000, v85
	v_perm_b32 v83, v84, v83, s20
	v_or3_b32 v84, v83, v86, v85
	v_mul_f32_e32 v85, v147, v112
	v_mul_f32_e32 v83, v147, v111
	v_rndne_f32_e32 v85, v85
	v_mul_f32_e32 v86, v147, v113
	v_rndne_f32_e32 v83, v83
	v_cvt_i32_f32_e32 v85, v85
	v_rndne_f32_e32 v86, v86
	v_mul_f32_e32 v87, v147, v114
	v_cvt_i32_f32_e32 v83, v83
	v_cvt_i32_f32_sdwa v86, v86 dst_sel:WORD_1 dst_unused:UNUSED_PAD src0_sel:DWORD
	v_rndne_f32_e32 v87, v87
	v_cvt_i32_f32_sdwa v87, v87 dst_sel:BYTE_3 dst_unused:UNUSED_PAD src0_sel:DWORD
	v_lshlrev_b32_e32 v85, 8, v85
	v_and_b32_e32 v86, 0xff0000, v86
	v_perm_b32 v83, v85, v83, s20
	v_or3_b32 v85, v83, v87, v86
	global_store_dwordx2 v[6:7], v[84:85], off offset:1536
	v_mul_f32_e32 v84, v147, v116
	v_mul_f32_e32 v83, v147, v115
	v_rndne_f32_e32 v84, v84
	v_mul_f32_e32 v85, v147, v117
	v_rndne_f32_e32 v83, v83
	v_cvt_i32_f32_e32 v84, v84
	v_rndne_f32_e32 v85, v85
	v_mul_f32_e32 v86, v147, v118
	v_cvt_i32_f32_e32 v83, v83
	v_cvt_i32_f32_sdwa v85, v85 dst_sel:WORD_1 dst_unused:UNUSED_PAD src0_sel:DWORD
	v_rndne_f32_e32 v86, v86
	v_cvt_i32_f32_sdwa v86, v86 dst_sel:BYTE_3 dst_unused:UNUSED_PAD src0_sel:DWORD
	v_lshlrev_b32_e32 v84, 8, v84
	v_and_b32_e32 v85, 0xff0000, v85
	v_perm_b32 v83, v84, v83, s20
	v_or3_b32 v84, v83, v86, v85
	v_mul_f32_e32 v85, v147, v120
	v_mul_f32_e32 v83, v147, v119
	v_rndne_f32_e32 v85, v85
	v_mul_f32_e32 v86, v147, v121
	v_rndne_f32_e32 v83, v83
	v_cvt_i32_f32_e32 v85, v85
	v_rndne_f32_e32 v86, v86
	v_mul_f32_e32 v87, v147, v122
	v_cvt_i32_f32_e32 v83, v83
	v_cvt_i32_f32_sdwa v86, v86 dst_sel:WORD_1 dst_unused:UNUSED_PAD src0_sel:DWORD
	v_rndne_f32_e32 v87, v87
	v_cvt_i32_f32_sdwa v87, v87 dst_sel:BYTE_3 dst_unused:UNUSED_PAD src0_sel:DWORD
	v_lshlrev_b32_e32 v85, 8, v85
	v_and_b32_e32 v86, 0xff0000, v86
	v_perm_b32 v83, v85, v83, s20
	v_or3_b32 v85, v83, v87, v86
	global_store_dwordx2 v[6:7], v[84:85], off offset:2048
	v_mul_f32_e32 v84, v147, v124
	v_mul_f32_e32 v83, v147, v123
	v_rndne_f32_e32 v84, v84
	v_mul_f32_e32 v85, v147, v125
	v_rndne_f32_e32 v83, v83
	v_cvt_i32_f32_e32 v84, v84
	v_rndne_f32_e32 v85, v85
	v_mul_f32_e32 v86, v147, v126
	v_cvt_i32_f32_e32 v83, v83
	v_cvt_i32_f32_sdwa v85, v85 dst_sel:WORD_1 dst_unused:UNUSED_PAD src0_sel:DWORD
	v_rndne_f32_e32 v86, v86
	v_cvt_i32_f32_sdwa v86, v86 dst_sel:BYTE_3 dst_unused:UNUSED_PAD src0_sel:DWORD
	v_lshlrev_b32_e32 v84, 8, v84
	v_and_b32_e32 v85, 0xff0000, v85
	v_perm_b32 v83, v84, v83, s20
	v_or3_b32 v84, v83, v86, v85
	v_mul_f32_e32 v85, v147, v128
	v_mul_f32_e32 v83, v147, v127
	v_rndne_f32_e32 v85, v85
	v_mul_f32_e32 v86, v147, v129
	v_rndne_f32_e32 v83, v83
	v_cvt_i32_f32_e32 v85, v85
	v_rndne_f32_e32 v86, v86
	v_mul_f32_e32 v87, v147, v130
	v_cvt_i32_f32_e32 v83, v83
	v_cvt_i32_f32_sdwa v86, v86 dst_sel:WORD_1 dst_unused:UNUSED_PAD src0_sel:DWORD
	v_rndne_f32_e32 v87, v87
	v_cvt_i32_f32_sdwa v87, v87 dst_sel:BYTE_3 dst_unused:UNUSED_PAD src0_sel:DWORD
	v_lshlrev_b32_e32 v85, 8, v85
	v_and_b32_e32 v86, 0xff0000, v86
	v_perm_b32 v83, v85, v83, s20
	v_or3_b32 v85, v83, v87, v86
	global_store_dwordx2 v[6:7], v[84:85], off offset:2560
	v_mul_f32_e32 v84, v147, v132
	v_mul_f32_e32 v83, v147, v131
	v_rndne_f32_e32 v84, v84
	v_mul_f32_e32 v85, v147, v133
	v_rndne_f32_e32 v83, v83
	v_cvt_i32_f32_e32 v84, v84
	v_rndne_f32_e32 v85, v85
	v_mul_f32_e32 v86, v147, v134
	v_cvt_i32_f32_e32 v83, v83
	v_cvt_i32_f32_sdwa v85, v85 dst_sel:WORD_1 dst_unused:UNUSED_PAD src0_sel:DWORD
	v_rndne_f32_e32 v86, v86
	v_cvt_i32_f32_sdwa v86, v86 dst_sel:BYTE_3 dst_unused:UNUSED_PAD src0_sel:DWORD
	v_lshlrev_b32_e32 v84, 8, v84
	v_and_b32_e32 v85, 0xff0000, v85
	v_perm_b32 v83, v84, v83, s20
	v_or3_b32 v84, v83, v86, v85
	v_mul_f32_e32 v85, v147, v136
	v_mul_f32_e32 v83, v147, v135
	v_rndne_f32_e32 v85, v85
	v_mul_f32_e32 v86, v147, v137
	v_rndne_f32_e32 v83, v83
	v_cvt_i32_f32_e32 v85, v85
	v_rndne_f32_e32 v86, v86
	v_mul_f32_e32 v87, v147, v138
	v_cvt_i32_f32_e32 v83, v83
	v_cvt_i32_f32_sdwa v86, v86 dst_sel:WORD_1 dst_unused:UNUSED_PAD src0_sel:DWORD
	v_rndne_f32_e32 v87, v87
	v_cvt_i32_f32_sdwa v87, v87 dst_sel:BYTE_3 dst_unused:UNUSED_PAD src0_sel:DWORD
	v_lshlrev_b32_e32 v85, 8, v85
	v_and_b32_e32 v86, 0xff0000, v86
	v_perm_b32 v83, v85, v83, s20
	v_or3_b32 v85, v83, v87, v86
	global_store_dwordx2 v[6:7], v[84:85], off offset:3072
	v_mul_f32_e32 v84, v147, v140
	v_mul_f32_e32 v83, v147, v139
	v_rndne_f32_e32 v84, v84
	v_mul_f32_e32 v85, v147, v141
	v_rndne_f32_e32 v83, v83
	v_cvt_i32_f32_e32 v84, v84
	v_rndne_f32_e32 v85, v85
	v_mul_f32_e32 v86, v147, v142
	v_cvt_i32_f32_e32 v83, v83
	v_cvt_i32_f32_sdwa v85, v85 dst_sel:WORD_1 dst_unused:UNUSED_PAD src0_sel:DWORD
	v_rndne_f32_e32 v86, v86
	v_cvt_i32_f32_sdwa v86, v86 dst_sel:BYTE_3 dst_unused:UNUSED_PAD src0_sel:DWORD
	v_lshlrev_b32_e32 v84, 8, v84
	v_and_b32_e32 v85, 0xff0000, v85
	v_perm_b32 v83, v84, v83, s20
	v_or3_b32 v84, v83, v86, v85
	v_mul_f32_e32 v85, v147, v144
	v_mul_f32_e32 v83, v147, v143
	v_rndne_f32_e32 v85, v85
	v_mul_f32_e32 v86, v147, v145
	v_rndne_f32_e32 v83, v83
	v_cvt_i32_f32_e32 v85, v85
	v_rndne_f32_e32 v86, v86
	v_mul_f32_e32 v87, v147, v146
	v_cvt_i32_f32_e32 v83, v83
	v_cvt_i32_f32_sdwa v86, v86 dst_sel:WORD_1 dst_unused:UNUSED_PAD src0_sel:DWORD
	v_rndne_f32_e32 v87, v87
; __device__ __forceinline__ float bflo(unsigned w) { return __uint_as_float(w << 16); }
; __device__ __forceinline__ float bfhi(unsigned w) { return __uint_as_float(w & 0xffff0000u); }
; __device__ __forceinline__ void quant_store8(const u32x4 (&w)[8], float inv, signed char* dst, int lane) { u32x2* qp = (u32x2*)dst + lane;
; #pragma unroll
;     for (int j = 0; j < 8; ++j) { const unsigned ww[4] = {w[j].x, w[j].y, w[j].z, w[j].w}; unsigned o2[2];
; #pragma unroll
;         for (int h2 = 0; h2 < 2; ++h2) { const int q0 = (int)rintf(bflo(ww[2 * h2]) * inv), q1 = (int)rintf(bfhi(ww[2 * h2]) * inv), q2 = (int)rintf(bflo(ww[2 * h2 + 1]) * inv), q3 = (int)rintf(bfhi(ww[2 * h2 + 1]) * inv);
;             o2[h2] = (unsigned)(q0 & 255) | ((unsigned)(q1 & 255) << 8) | ((unsigned)(q2 & 255) << 16) | ((unsigned)(q3 & 255) << 24); }
;         u32x2 o; o.x = o2[0]; o.y = o2[1]; qp[64 * j] = o; } }
; __device__ __forceinline__ void quant_rows2(const bf16_t* s0, const bf16_t* s1, signed char* d0, signed char* d1, int lane, float& step0, float& step1) {
;     ...
;     step0 = fmaxf(absmax8(w0), 1e-30f) * (1.0f / 127.0f); step1 = fmaxf(absmax8(w1), 1e-30f) * (1.0f / 127.0f);
;     quant_store8(w0, 1.0f / step0, d0, lane); quant_store8(w1, 1.0f / step1, d1, lane);
	v_cvt_i32_f32_sdwa v87, v87 dst_sel:BYTE_3 dst_unused:UNUSED_PAD src0_sel:DWORD
	v_div_scale_f32 v88, s[14:15], v3, v3, 1.0
	v_rcp_f32_e32 v89, v88
	v_lshlrev_b32_e32 v85, 8, v85
	v_and_b32_e32 v86, 0xff0000, v86
	v_perm_b32 v83, v85, v83, s20
	v_or3_b32 v85, v83, v87, v86
	global_store_dwordx2 v[6:7], v[84:85], off offset:3584
	v_fma_f32 v6, -v88, v89, 1.0
	v_fmac_f32_e32 v89, v6, v89
	v_div_scale_f32 v6, vcc, 1.0, v3, 1.0
	v_mul_f32_e32 v7, v6, v89
	v_fma_f32 v83, -v88, v7, v6
	v_fmac_f32_e32 v7, v83, v89
	v_fma_f32 v6, -v88, v7, v6
	v_div_fmas_f32 v6, v6, v89, v7
	v_div_fixup_f32 v83, v6, v3, 1.0
	v_mul_f32_e32 v7, v83, v80
	v_mul_f32_e32 v6, v83, v82
	v_rndne_f32_e32 v7, v7
	v_rndne_f32_e32 v6, v6
	v_cvt_i32_f32_e32 v7, v7
	v_cvt_i32_f32_e32 v6, v6
	v_mul_f32_e32 v77, v83, v77
	v_mul_f32_e32 v80, v83, v81
	v_lshlrev_b32_e32 v7, 8, v7
	v_perm_b32 v6, v7, v6, s20
	v_mul_f32_e32 v7, v83, v78
	v_rndne_f32_e32 v77, v77
	v_mul_f32_e32 v76, v83, v76
	v_rndne_f32_e32 v80, v80
	v_mul_f32_e32 v79, v83, v79
	v_rndne_f32_e32 v7, v7
	v_cvt_i32_f32_e32 v77, v77
	v_rndne_f32_e32 v76, v76
	v_mul_f32_e32 v75, v83, v75
	v_cvt_i32_f32_sdwa v80, v80 dst_sel:WORD_1 dst_unused:UNUSED_PAD src0_sel:DWORD
	v_rndne_f32_e32 v79, v79
	v_cvt_i32_f32_e32 v7, v7
	v_cvt_i32_f32_sdwa v76, v76 dst_sel:WORD_1 dst_unused:UNUSED_PAD src0_sel:DWORD
	v_rndne_f32_e32 v75, v75
	v_cvt_i32_f32_sdwa v79, v79 dst_sel:BYTE_3 dst_unused:UNUSED_PAD src0_sel:DWORD
	v_cvt_i32_f32_sdwa v75, v75 dst_sel:BYTE_3 dst_unused:UNUSED_PAD src0_sel:DWORD
	v_lshlrev_b32_e32 v77, 8, v77
	v_and_b32_e32 v80, 0xff0000, v80
	v_and_b32_e32 v76, 0xff0000, v76
	v_perm_b32 v7, v77, v7, s20
	v_or3_b32 v6, v6, v79, v80
	v_or3_b32 v7, v7, v75, v76
	global_store_dwordx2 v[4:5], v[6:7], off
	v_mul_f32_e32 v7, v83, v72
	v_mul_f32_e32 v6, v83, v74
	v_rndne_f32_e32 v7, v7
	v_rndne_f32_e32 v6, v6
	v_cvt_i32_f32_e32 v7, v7
	v_cvt_i32_f32_e32 v6, v6
	v_mul_f32_e32 v69, v83, v69
	v_mul_f32_e32 v72, v83, v73
	v_lshlrev_b32_e32 v7, 8, v7
	v_perm_b32 v6, v7, v6, s20
	v_mul_f32_e32 v7, v83, v70
	v_rndne_f32_e32 v69, v69
	v_mul_f32_e32 v68, v83, v68
	v_rndne_f32_e32 v72, v72
	v_mul_f32_e32 v71, v83, v71
	v_rndne_f32_e32 v7, v7
	v_cvt_i32_f32_e32 v69, v69
	v_rndne_f32_e32 v68, v68
	v_mul_f32_e32 v67, v83, v67
	v_cvt_i32_f32_sdwa v72, v72 dst_sel:WORD_1 dst_unused:UNUSED_PAD src0_sel:DWORD
	v_rndne_f32_e32 v71, v71
	v_cvt_i32_f32_e32 v7, v7
	v_cvt_i32_f32_sdwa v68, v68 dst_sel:WORD_1 dst_unused:UNUSED_PAD src0_sel:DWORD
	v_rndne_f32_e32 v67, v67
	v_cvt_i32_f32_sdwa v71, v71 dst_sel:BYTE_3 dst_unused:UNUSED_PAD src0_sel:DWORD
	v_cvt_i32_f32_sdwa v67, v67 dst_sel:BYTE_3 dst_unused:UNUSED_PAD src0_sel:DWORD
	v_lshlrev_b32_e32 v69, 8, v69
	v_and_b32_e32 v72, 0xff0000, v72
	v_and_b32_e32 v68, 0xff0000, v68
	v_perm_b32 v7, v69, v7, s20
	v_or3_b32 v6, v6, v71, v72
	v_or3_b32 v7, v7, v67, v68
	global_store_dwordx2 v[4:5], v[6:7], off offset:512
	v_mul_f32_e32 v7, v83, v64
	v_mul_f32_e32 v6, v83, v66
	v_rndne_f32_e32 v7, v7
	v_rndne_f32_e32 v6, v6
	v_cvt_i32_f32_e32 v7, v7
	v_cvt_i32_f32_e32 v6, v6
	v_mul_f32_e32 v61, v83, v61
	v_mul_f32_e32 v64, v83, v65
	v_lshlrev_b32_e32 v7, 8, v7
	v_perm_b32 v6, v7, v6, s20
	v_mul_f32_e32 v7, v83, v62
	v_rndne_f32_e32 v61, v61
	v_mul_f32_e32 v60, v83, v60
	v_rndne_f32_e32 v64, v64
	v_mul_f32_e32 v63, v83, v63
	v_rndne_f32_e32 v7, v7
	v_cvt_i32_f32_e32 v61, v61
	v_rndne_f32_e32 v60, v60
	v_mul_f32_e32 v59, v83, v59
	v_cvt_i32_f32_sdwa v64, v64 dst_sel:WORD_1 dst_unused:UNUSED_PAD src0_sel:DWORD
	v_rndne_f32_e32 v63, v63
	v_cvt_i32_f32_e32 v7, v7
	v_cvt_i32_f32_sdwa v60, v60 dst_sel:WORD_1 dst_unused:UNUSED_PAD src0_sel:DWORD
	v_rndne_f32_e32 v59, v59
	v_cvt_i32_f32_sdwa v63, v63 dst_sel:BYTE_3 dst_unused:UNUSED_PAD src0_sel:DWORD
	v_cvt_i32_f32_sdwa v59, v59 dst_sel:BYTE_3 dst_unused:UNUSED_PAD src0_sel:DWORD
	v_lshlrev_b32_e32 v61, 8, v61
	v_and_b32_e32 v64, 0xff0000, v64
	v_and_b32_e32 v60, 0xff0000, v60
	v_perm_b32 v7, v61, v7, s20
	v_or3_b32 v6, v6, v63, v64
	v_or3_b32 v7, v7, v59, v60
	global_store_dwordx2 v[4:5], v[6:7], off offset:1024
	v_mul_f32_e32 v7, v83, v56
	v_mul_f32_e32 v6, v83, v58
	v_rndne_f32_e32 v7, v7
	v_rndne_f32_e32 v6, v6
	v_cvt_i32_f32_e32 v7, v7
	v_cvt_i32_f32_e32 v6, v6
	v_mul_f32_e32 v53, v83, v53
	v_mul_f32_e32 v56, v83, v57
	v_lshlrev_b32_e32 v7, 8, v7
	v_perm_b32 v6, v7, v6, s20
	v_mul_f32_e32 v7, v83, v54
	v_rndne_f32_e32 v53, v53
	v_mul_f32_e32 v52, v83, v52
	v_rndne_f32_e32 v56, v56
	v_mul_f32_e32 v55, v83, v55
	v_rndne_f32_e32 v7, v7
	v_cvt_i32_f32_e32 v53, v53
	v_rndne_f32_e32 v52, v52
	v_mul_f32_e32 v51, v83, v51
	v_cvt_i32_f32_sdwa v56, v56 dst_sel:WORD_1 dst_unused:UNUSED_PAD src0_sel:DWORD
	v_rndne_f32_e32 v55, v55
	v_cvt_i32_f32_e32 v7, v7
	v_cvt_i32_f32_sdwa v52, v52 dst_sel:WORD_1 dst_unused:UNUSED_PAD src0_sel:DWORD
	v_rndne_f32_e32 v51, v51
	v_cvt_i32_f32_sdwa v55, v55 dst_sel:BYTE_3 dst_unused:UNUSED_PAD src0_sel:DWORD
	v_cvt_i32_f32_sdwa v51, v51 dst_sel:BYTE_3 dst_unused:UNUSED_PAD src0_sel:DWORD
	v_lshlrev_b32_e32 v53, 8, v53
; __device__ __forceinline__ float bflo(unsigned w) { return __uint_as_float(w << 16); }
; __device__ __forceinline__ float bfhi(unsigned w) { return __uint_as_float(w & 0xffff0000u); }
; __device__ __forceinline__ void quant_store8(const u32x4 (&w)[8], float inv, signed char* dst, int lane) { u32x2* qp = (u32x2*)dst + lane;
; #pragma unroll
;     for (int j = 0; j < 8; ++j) { const unsigned ww[4] = {w[j].x, w[j].y, w[j].z, w[j].w}; unsigned o2[2];
; #pragma unroll
;         for (int h2 = 0; h2 < 2; ++h2) { const int q0 = (int)rintf(bflo(ww[2 * h2]) * inv), q1 = (int)rintf(bfhi(ww[2 * h2]) * inv), q2 = (int)rintf(bflo(ww[2 * h2 + 1]) * inv), q3 = (int)rintf(bfhi(ww[2 * h2 + 1]) * inv);
;             o2[h2] = (unsigned)(q0 & 255) | ((unsigned)(q1 & 255) << 8) | ((unsigned)(q2 & 255) << 16) | ((unsigned)(q3 & 255) << 24); }
;         u32x2 o; o.x = o2[0]; o.y = o2[1]; qp[64 * j] = o; } }
; __global__ void __launch_bounds__(NWAVES * 64, 2) fwd(Args args) {
;     ...
;                 if (F.lane == 0) { colq[n] = s0; colq[n + 1] = s1; } }
	v_and_b32_e32 v56, 0xff0000, v56
	v_and_b32_e32 v52, 0xff0000, v52
	v_perm_b32 v7, v53, v7, s20
	v_or3_b32 v6, v6, v55, v56
	v_or3_b32 v7, v7, v51, v52
	global_store_dwordx2 v[4:5], v[6:7], off offset:1536
	v_mul_f32_e32 v7, v83, v48
	v_mul_f32_e32 v6, v83, v50
	v_rndne_f32_e32 v7, v7
	v_rndne_f32_e32 v6, v6
	v_cvt_i32_f32_e32 v7, v7
	v_cvt_i32_f32_e32 v6, v6
	v_mul_f32_e32 v45, v83, v45
	v_mul_f32_e32 v48, v83, v49
	v_lshlrev_b32_e32 v7, 8, v7
	v_perm_b32 v6, v7, v6, s20
	v_mul_f32_e32 v7, v83, v46
	v_rndne_f32_e32 v45, v45
	v_mul_f32_e32 v44, v83, v44
	v_rndne_f32_e32 v48, v48
	v_mul_f32_e32 v47, v83, v47
	v_rndne_f32_e32 v7, v7
	v_cvt_i32_f32_e32 v45, v45
	v_rndne_f32_e32 v44, v44
	v_mul_f32_e32 v43, v83, v43
	v_cvt_i32_f32_sdwa v48, v48 dst_sel:WORD_1 dst_unused:UNUSED_PAD src0_sel:DWORD
	v_rndne_f32_e32 v47, v47
	v_cvt_i32_f32_e32 v7, v7
	v_cvt_i32_f32_sdwa v44, v44 dst_sel:WORD_1 dst_unused:UNUSED_PAD src0_sel:DWORD
	v_rndne_f32_e32 v43, v43
	v_cvt_i32_f32_sdwa v47, v47 dst_sel:BYTE_3 dst_unused:UNUSED_PAD src0_sel:DWORD
	v_cvt_i32_f32_sdwa v43, v43 dst_sel:BYTE_3 dst_unused:UNUSED_PAD src0_sel:DWORD
	v_lshlrev_b32_e32 v45, 8, v45
	v_and_b32_e32 v48, 0xff0000, v48
	v_and_b32_e32 v44, 0xff0000, v44
	v_perm_b32 v7, v45, v7, s20
	v_or3_b32 v6, v6, v47, v48
	v_or3_b32 v7, v7, v43, v44
	global_store_dwordx2 v[4:5], v[6:7], off offset:2048
	v_mul_f32_e32 v7, v83, v29
	v_mul_f32_e32 v6, v83, v42
	v_rndne_f32_e32 v7, v7
	v_rndne_f32_e32 v6, v6
	v_cvt_i32_f32_e32 v7, v7
	v_cvt_i32_f32_e32 v6, v6
	v_mul_f32_e32 v26, v83, v26
	v_mul_f32_e32 v29, v83, v41
	v_lshlrev_b32_e32 v7, 8, v7
	v_perm_b32 v6, v7, v6, s20
	v_mul_f32_e32 v7, v83, v27
	v_rndne_f32_e32 v26, v26
	v_mul_f32_e32 v25, v83, v25
	v_rndne_f32_e32 v29, v29
	v_mul_f32_e32 v28, v83, v28
	v_rndne_f32_e32 v7, v7
	v_cvt_i32_f32_e32 v26, v26
	v_rndne_f32_e32 v25, v25
	v_mul_f32_e32 v24, v83, v24
	v_cvt_i32_f32_sdwa v29, v29 dst_sel:WORD_1 dst_unused:UNUSED_PAD src0_sel:DWORD
	v_rndne_f32_e32 v28, v28
	v_cvt_i32_f32_e32 v7, v7
	v_cvt_i32_f32_sdwa v25, v25 dst_sel:WORD_1 dst_unused:UNUSED_PAD src0_sel:DWORD
	v_rndne_f32_e32 v24, v24
	v_cvt_i32_f32_sdwa v28, v28 dst_sel:BYTE_3 dst_unused:UNUSED_PAD src0_sel:DWORD
	v_cvt_i32_f32_sdwa v24, v24 dst_sel:BYTE_3 dst_unused:UNUSED_PAD src0_sel:DWORD
	v_lshlrev_b32_e32 v26, 8, v26
	v_and_b32_e32 v29, 0xff0000, v29
	v_and_b32_e32 v25, 0xff0000, v25
	v_perm_b32 v7, v26, v7, s20
	v_or3_b32 v6, v6, v28, v29
	v_or3_b32 v7, v7, v24, v25
	global_store_dwordx2 v[4:5], v[6:7], off offset:2560
	v_mul_f32_e32 v7, v83, v21
	v_mul_f32_e32 v6, v83, v23
	v_rndne_f32_e32 v7, v7
	v_rndne_f32_e32 v6, v6
	v_cvt_i32_f32_e32 v7, v7
	v_cvt_i32_f32_e32 v6, v6
	v_mul_f32_e32 v18, v83, v18
	v_mul_f32_e32 v21, v83, v22
	v_lshlrev_b32_e32 v7, 8, v7
	v_perm_b32 v6, v7, v6, s20
	v_mul_f32_e32 v7, v83, v19
	v_rndne_f32_e32 v18, v18
	v_mul_f32_e32 v17, v83, v17
	v_rndne_f32_e32 v21, v21
	v_mul_f32_e32 v20, v83, v20
	v_rndne_f32_e32 v7, v7
	v_cvt_i32_f32_e32 v18, v18
	v_rndne_f32_e32 v17, v17
	v_mul_f32_e32 v16, v83, v16
	v_cvt_i32_f32_sdwa v21, v21 dst_sel:WORD_1 dst_unused:UNUSED_PAD src0_sel:DWORD
	v_rndne_f32_e32 v20, v20
	v_cvt_i32_f32_e32 v7, v7
	v_cvt_i32_f32_sdwa v17, v17 dst_sel:WORD_1 dst_unused:UNUSED_PAD src0_sel:DWORD
	v_rndne_f32_e32 v16, v16
	v_cvt_i32_f32_sdwa v20, v20 dst_sel:BYTE_3 dst_unused:UNUSED_PAD src0_sel:DWORD
	v_cvt_i32_f32_sdwa v16, v16 dst_sel:BYTE_3 dst_unused:UNUSED_PAD src0_sel:DWORD
	v_lshlrev_b32_e32 v18, 8, v18
	v_and_b32_e32 v21, 0xff0000, v21
	v_and_b32_e32 v17, 0xff0000, v17
	v_perm_b32 v7, v18, v7, s20
	v_or3_b32 v6, v6, v20, v21
	v_or3_b32 v7, v7, v16, v17
	global_store_dwordx2 v[4:5], v[6:7], off offset:3072
	v_mul_f32_e32 v7, v83, v13
	v_mul_f32_e32 v6, v83, v15
	v_rndne_f32_e32 v7, v7
	v_rndne_f32_e32 v6, v6
	v_cvt_i32_f32_e32 v7, v7
	v_cvt_i32_f32_e32 v6, v6
	v_mul_f32_e32 v10, v83, v10
	v_mul_f32_e32 v13, v83, v14
	v_lshlrev_b32_e32 v7, 8, v7
	v_perm_b32 v6, v7, v6, s20
	v_mul_f32_e32 v7, v83, v11
	v_rndne_f32_e32 v10, v10
	v_mul_f32_e32 v9, v83, v9
	v_rndne_f32_e32 v13, v13
	v_mul_f32_e32 v12, v83, v12
	v_rndne_f32_e32 v7, v7
	v_cvt_i32_f32_e32 v10, v10
	v_rndne_f32_e32 v9, v9
	v_mul_f32_e32 v8, v83, v8
	v_cvt_i32_f32_sdwa v13, v13 dst_sel:WORD_1 dst_unused:UNUSED_PAD src0_sel:DWORD
	v_rndne_f32_e32 v12, v12
	v_cvt_i32_f32_e32 v7, v7
	v_cvt_i32_f32_sdwa v9, v9 dst_sel:WORD_1 dst_unused:UNUSED_PAD src0_sel:DWORD
	v_rndne_f32_e32 v8, v8
	v_cvt_i32_f32_sdwa v12, v12 dst_sel:BYTE_3 dst_unused:UNUSED_PAD src0_sel:DWORD
	v_cvt_i32_f32_sdwa v8, v8 dst_sel:BYTE_3 dst_unused:UNUSED_PAD src0_sel:DWORD
	v_lshlrev_b32_e32 v10, 8, v10
	v_and_b32_e32 v13, 0xff0000, v13
	v_and_b32_e32 v9, 0xff0000, v9
	v_perm_b32 v7, v10, v7, s20
	v_or3_b32 v6, v6, v12, v13
	v_or3_b32 v7, v7, v8, v9
	global_store_dwordx2 v[4:5], v[6:7], off offset:3584
	s_and_saveexec_b64 s[14:15], s[4:5]
	s_cbranch_execz .LBB0_63
	s_add_u32 s24, s78, s7
	s_addc_u32 s25, s79, s16
	global_store_dwordx2 v40, v[2:3], s[24:25]
	s_branch .LBB0_63

; #define in_x ARGP(0)
; __global__ void __launch_bounds__(NWAVES * 64, 2) fwd(Args args) {
;     ...
;           for (int j = 0; j < mcnt && m < T; ++j, m += mstep) {
;             const f32x4* xr = (const f32x4*)(in_x + (size_t)m * DM) + F.lane; f32x4 v[16]; float s2 = 0.f;
; #pragma unroll
;             for (int j2 = 0; j2 < 16; ++j2) { v[j2] = __builtin_nontemporal_load(xr + 64 * j2); s2 += (v[j2][0] * v[j2][0] + v[j2][1] * v[j2][1]) + (v[j2][2] * v[j2][2] + v[j2][3] * v[j2][3]); }
;             const float rs = 1.0f / sqrtf(wave_sum(s2) * (1.0f / DM) + EPS);
;             float mx = 0.f;
; #pragma unroll
;             for (int j2 = 0; j2 < 16; ++j2) mx = fmaxf(fmaxf(mx, fmaxf(fabsf(v[j2][0]), fabsf(v[j2][1]))), fmaxf(fabsf(v[j2][2]), fabsf(v[j2][3])));
.LBB0_73:
	flat_load_dwordx2 v[2:3], v[72:73] sc0 sc1
	s_waitcnt vmcnt(0) lgkmcnt(0)
	v_lshl_add_u64 v[6:7], v[2:3], 0, v[70:71]
	v_add_co_u32_e32 v2, vcc, 0xffffc400, v6
	s_nop 1
	v_addc_co_u32_e32 v3, vcc, -1, v7, vcc
	v_add_co_u32_e32 v8, vcc, 0xffffc800, v6
	flat_load_dwordx4 v[30:33], v[2:3] nt
	s_nop 0
	v_addc_co_u32_e32 v9, vcc, -1, v7, vcc
	v_add_co_u32_e32 v10, vcc, 0xffffcc00, v6
	flat_load_dwordx4 v[2:5], v[6:7] nt
	flat_load_dwordx4 v[62:65], v[8:9] nt
	v_addc_co_u32_e32 v11, vcc, -1, v7, vcc
	v_add_co_u32_e32 v8, vcc, 0xffffd000, v6
	flat_load_dwordx4 v[58:61], v[10:11] nt
	s_nop 0
	v_addc_co_u32_e32 v9, vcc, -1, v7, vcc
	flat_load_dwordx4 v[54:57], v[8:9] nt
	v_add_co_u32_e32 v8, vcc, 0xffffd400, v6
	s_waitcnt vmcnt(0) lgkmcnt(0)
	v_mul_f32_e32 v74, v31, v31
	v_addc_co_u32_e32 v9, vcc, -1, v7, vcc
	flat_load_dwordx4 v[50:53], v[8:9] nt
	v_add_co_u32_e32 v8, vcc, 0xffffd800, v6
	v_mul_f32_e32 v75, v33, v33
	s_nop 0
	v_addc_co_u32_e32 v9, vcc, -1, v7, vcc
	flat_load_dwordx4 v[46:49], v[8:9] nt
	v_add_co_u32_e32 v8, vcc, 0xffffdc00, v6
	v_fmac_f32_e32 v74, v30, v30
	s_nop 0
	v_addc_co_u32_e32 v9, vcc, -1, v7, vcc
	flat_load_dwordx4 v[42:45], v[8:9] nt
	v_add_co_u32_e32 v8, vcc, 0xffffe000, v6
	v_fmac_f32_e32 v75, v32, v32
	s_nop 0
	v_addc_co_u32_e32 v9, vcc, -1, v7, vcc
	flat_load_dwordx4 v[38:41], v[8:9] nt
	v_add_co_u32_e32 v8, vcc, 0xffffe400, v6
	v_mul_f32_e32 v86, v63, v63
	s_nop 0
	v_addc_co_u32_e32 v9, vcc, -1, v7, vcc
	flat_load_dwordx4 v[34:37], v[8:9] nt
	v_add_co_u32_e32 v8, vcc, 0xffffe800, v6
	v_mul_f32_e32 v87, v65, v65
	s_nop 0
	v_addc_co_u32_e32 v9, vcc, -1, v7, vcc
	flat_load_dwordx4 v[26:29], v[8:9] nt
	v_add_co_u32_e32 v8, vcc, 0xffffec00, v6
	v_add_f32_e32 v74, v74, v75
	s_nop 0
	v_addc_co_u32_e32 v9, vcc, -1, v7, vcc
	flat_load_dwordx4 v[22:25], v[8:9] nt
	v_add_co_u32_e32 v8, vcc, 0xfffff000, v6
	v_fmac_f32_e32 v86, v62, v62
	s_nop 0
	v_addc_co_u32_e32 v9, vcc, -1, v7, vcc
	flat_load_dwordx4 v[18:21], v[8:9] nt
	v_add_co_u32_e32 v8, vcc, 0xfffff400, v6
	v_fmac_f32_e32 v87, v64, v64
	s_nop 0
	v_addc_co_u32_e32 v9, vcc, -1, v7, vcc
	flat_load_dwordx4 v[14:17], v[8:9] nt
	v_add_co_u32_e32 v8, vcc, 0xfffff800, v6
	v_mul_f32_e32 v75, v59, v59
	s_nop 0
	v_addc_co_u32_e32 v9, vcc, -1, v7, vcc
	v_add_co_u32_e32 v6, vcc, 0xfffffc00, v6
	flat_load_dwordx4 v[10:13], v[8:9] nt
	s_nop 0
	v_addc_co_u32_e32 v7, vcc, -1, v7, vcc
	flat_load_dwordx4 v[6:9], v[6:7] nt
	v_mul_f32_e32 v88, v61, v61
	v_add_f32_e32 v86, v86, v87
	v_fmac_f32_e32 v75, v58, v58
	v_fmac_f32_e32 v88, v60, v60
	v_mul_f32_e32 v87, v55, v55
	v_mul_f32_e32 v89, v57, v57
	v_add_f32_e32 v74, v74, v86
	v_add_f32_e32 v75, v75, v88
	v_fmac_f32_e32 v87, v54, v54
	v_fmac_f32_e32 v89, v56, v56
	v_add_f32_e32 v74, v74, v75
	v_add_f32_e32 v75, v87, v89
	v_add_f32_e32 v74, v74, v75
	v_max_f32_e64 v90, |v64|, |v64|
	s_waitcnt vmcnt(0) lgkmcnt(0)
	v_mul_f32_e32 v86, v51, v51
	v_mul_f32_e32 v88, v53, v53
	v_fmac_f32_e32 v86, v50, v50
	v_fmac_f32_e32 v88, v52, v52
	v_add_f32_e32 v75, v86, v88
	v_add_f32_e32 v74, v74, v75
	v_mul_f32_e32 v87, v47, v47
	v_mul_f32_e32 v89, v49, v49
	v_fmac_f32_e32 v87, v46, v46
	v_fmac_f32_e32 v89, v48, v48
	v_add_f32_e32 v75, v87, v89
	v_add_f32_e32 v74, v74, v75
	v_mul_f32_e32 v86, v43, v43
	v_mul_f32_e32 v88, v45, v45
	v_fmac_f32_e32 v86, v42, v42
	v_fmac_f32_e32 v88, v44, v44
	v_add_f32_e32 v75, v86, v88
	v_add_f32_e32 v74, v74, v75
	v_mul_f32_e32 v87, v39, v39
	v_mul_f32_e32 v89, v41, v41
	v_fmac_f32_e32 v87, v38, v38
	v_fmac_f32_e32 v89, v40, v40
	v_add_f32_e32 v75, v87, v89
	v_add_f32_e32 v74, v74, v75
	v_mul_f32_e32 v86, v35, v35
	v_mul_f32_e32 v88, v37, v37
	v_fmac_f32_e32 v86, v34, v34
	v_fmac_f32_e32 v88, v36, v36
	v_add_f32_e32 v75, v86, v88
	v_add_f32_e32 v74, v74, v75
	v_mul_f32_e32 v87, v27, v27
	v_mul_f32_e32 v89, v29, v29
	v_fmac_f32_e32 v87, v26, v26
	v_fmac_f32_e32 v89, v28, v28
	v_add_f32_e32 v75, v87, v89
	v_add_f32_e32 v74, v74, v75
	v_mul_f32_e32 v86, v23, v23
	v_mul_f32_e32 v88, v25, v25
	v_fmac_f32_e32 v86, v22, v22
	v_fmac_f32_e32 v88, v24, v24
	v_add_f32_e32 v75, v86, v88
	v_add_f32_e32 v74, v74, v75
	v_mul_f32_e32 v87, v19, v19
	v_mul_f32_e32 v89, v21, v21
	v_fmac_f32_e32 v87, v18, v18
	v_fmac_f32_e32 v89, v20, v20
	v_add_f32_e32 v75, v87, v89
	v_add_f32_e32 v74, v74, v75
	v_mul_f32_e32 v86, v15, v15
	v_mul_f32_e32 v88, v17, v17
	v_fmac_f32_e32 v86, v14, v14
	v_fmac_f32_e32 v88, v16, v16
	v_add_f32_e32 v75, v86, v88
	v_add_f32_e32 v74, v74, v75
	v_mul_f32_e32 v87, v11, v11
	v_mul_f32_e32 v89, v13, v13
	v_fmac_f32_e32 v87, v10, v10
	v_fmac_f32_e32 v89, v12, v12
	v_mul_f32_e32 v86, v7, v7
	v_mul_f32_e32 v88, v9, v9
	v_add_f32_e32 v75, v87, v89
	v_fmac_f32_e32 v86, v6, v6
	v_fmac_f32_e32 v88, v8, v8
	v_add_f32_e32 v74, v74, v75
	v_add_f32_e32 v75, v86, v88
	v_max_f32_e64 v87, |v31|, |v31|
	v_max_f32_e64 v88, |v30|, |v30|
	v_max_f32_e32 v87, v88, v87
	v_max_f32_e64 v88, |v33|, |v33|
	v_max_f32_e64 v89, |v32|, |v32|
	v_max_f32_e32 v88, v89, v88
	v_max3_f32 v87, v87, 0, v88
	v_max_f32_e64 v88, |v63|, |v63|
	v_max_f32_e64 v89, |v62|, |v62|
	v_max_f32_e32 v88, v89, v88
	v_max_f32_e64 v89, |v65|, |v65|
	v_max_f32_e32 v89, v90, v89
	v_max3_f32 v87, v87, v88, v89
	v_max_f32_e64 v88, |v59|, |v59|
	v_max_f32_e64 v89, |v58|, |v58|
	v_max_f32_e32 v88, v89, v88
	v_max_f32_e64 v89, |v61|, |v61|
	v_max_f32_e64 v90, |v60|, |v60|
	v_max_f32_e32 v89, v90, v89
	v_max3_f32 v87, v87, v88, v89
	v_max_f32_e64 v88, |v55|, |v55|
	v_max_f32_e64 v89, |v54|, |v54|
	v_max_f32_e32 v88, v89, v88
	v_max_f32_e64 v89, |v57|, |v57|
	v_max_f32_e64 v90, |v56|, |v56|
	v_max_f32_e32 v89, v90, v89
	v_max3_f32 v87, v87, v88, v89
; __global__ void __launch_bounds__(NWAVES * 64, 2) fwd(Args args) {
;     ...
;             for (int j2 = 0; j2 < 16; ++j2) { v[j2] = __builtin_nontemporal_load(xr + 64 * j2); s2 += (v[j2][0] * v[j2][0] + v[j2][1] * v[j2][1]) + (v[j2][2] * v[j2][2] + v[j2][3] * v[j2][3]); }
;             const float rs = 1.0f / sqrtf(wave_sum(s2) * (1.0f / DM) + EPS);
;             float mx = 0.f;
; #pragma unroll
;             for (int j2 = 0; j2 < 16; ++j2) mx = fmaxf(fmaxf(mx, fmaxf(fabsf(v[j2][0]), fabsf(v[j2][1]))), fmaxf(fabsf(v[j2][2]), fabsf(v[j2][3])));
; #pragma unroll
;             for (int o = 1; o < 64; o <<= 1) mx = fmaxf(mx, __shfl_xor(mx, o));
;             const float step = fmaxf(mx, 1e-30f) * (1.0f / 127.0f), inv = 1.0f / step;
;             if (F.lane == 0) { rstd_x[m] = rs; rowq[m] = rs * step; }
	v_max_f32_e64 v88, |v51|, |v51|
	v_max_f32_e64 v89, |v50|, |v50|
	v_max_f32_e32 v88, v89, v88
	v_max_f32_e64 v89, |v53|, |v53|
	v_max_f32_e64 v90, |v52|, |v52|
	v_max_f32_e32 v89, v90, v89
	v_max3_f32 v87, v87, v88, v89
	v_max_f32_e64 v88, |v47|, |v47|
	v_max_f32_e64 v89, |v46|, |v46|
	v_max_f32_e32 v88, v89, v88
	v_max_f32_e64 v89, |v49|, |v49|
	v_max_f32_e64 v90, |v48|, |v48|
	v_max_f32_e32 v89, v90, v89
	v_max3_f32 v87, v87, v88, v89
	v_max_f32_e64 v88, |v43|, |v43|
	v_max_f32_e64 v89, |v42|, |v42|
	v_max_f32_e32 v88, v89, v88
	v_max_f32_e64 v89, |v45|, |v45|
	v_max_f32_e64 v90, |v44|, |v44|
	v_max_f32_e32 v89, v90, v89
	v_max3_f32 v87, v87, v88, v89
	v_max_f32_e64 v88, |v39|, |v39|
	v_max_f32_e64 v89, |v38|, |v38|
	v_max_f32_e32 v88, v89, v88
	v_max_f32_e64 v89, |v41|, |v41|
	v_max_f32_e64 v90, |v40|, |v40|
	v_max_f32_e32 v89, v90, v89
	v_max3_f32 v87, v87, v88, v89
	v_max_f32_e64 v88, |v35|, |v35|
	v_max_f32_e64 v89, |v34|, |v34|
	v_max_f32_e32 v88, v89, v88
	v_max_f32_e64 v89, |v37|, |v37|
	v_max_f32_e64 v90, |v36|, |v36|
	v_max_f32_e32 v89, v90, v89
	v_max3_f32 v87, v87, v88, v89
	v_max_f32_e64 v88, |v27|, |v27|
	v_max_f32_e64 v89, |v26|, |v26|
	v_max_f32_e32 v88, v89, v88
	v_max_f32_e64 v89, |v29|, |v29|
	v_max_f32_e64 v90, |v28|, |v28|
	v_max_f32_e32 v89, v90, v89
	v_max3_f32 v87, v87, v88, v89
	v_max_f32_e64 v88, |v23|, |v23|
	v_max_f32_e64 v89, |v22|, |v22|
	v_max_f32_e32 v88, v89, v88
	v_max_f32_e64 v89, |v25|, |v25|
	v_max_f32_e64 v90, |v24|, |v24|
	v_max_f32_e32 v89, v90, v89
	v_max3_f32 v87, v87, v88, v89
	v_max_f32_e64 v88, |v19|, |v19|
	v_max_f32_e64 v89, |v18|, |v18|
	v_max_f32_e32 v88, v89, v88
	v_max_f32_e64 v89, |v21|, |v21|
	v_max_f32_e64 v90, |v20|, |v20|
	v_max_f32_e32 v89, v90, v89
	v_max3_f32 v87, v87, v88, v89
	v_max_f32_e64 v88, |v15|, |v15|
	v_max_f32_e64 v89, |v14|, |v14|
	v_max_f32_e32 v88, v89, v88
	v_max_f32_e64 v89, |v17|, |v17|
	v_max_f32_e64 v90, |v16|, |v16|
	v_max_f32_e32 v89, v90, v89
	v_max3_f32 v87, v87, v88, v89
	v_max_f32_e64 v88, |v11|, |v11|
	v_max_f32_e64 v89, |v10|, |v10|
	v_max_f32_e32 v88, v89, v88
	v_max_f32_e64 v89, |v13|, |v13|
	v_max_f32_e64 v90, |v12|, |v12|
	v_max_f32_e32 v89, v90, v89
	v_max3_f32 v87, v87, v88, v89
	v_max_f32_e64 v88, |v7|, |v7|
	v_max_f32_e64 v89, |v6|, |v6|
	v_max_f32_e32 v88, v89, v88
	v_max_f32_e64 v89, |v9|, |v9|
	v_max_f32_e64 v90, |v8|, |v8|
	v_max_f32_e32 v89, v90, v89
	v_max3_f32 v87, v87, v88, v89
	v_max_f32_e64 v88, |v3|, |v3|
	v_max_f32_e64 v89, |v2|, |v2|
	v_max_f32_e32 v88, v89, v88
	v_max_f32_e64 v89, |v5|, |v5|
	v_max_f32_e64 v90, |v4|, |v4|
	v_max_f32_e32 v89, v90, v89
	v_max3_f32 v87, v87, v88, v89
	s_nop 1
	v_mov_b32_dpp v88, v87 quad_perm:[1,0,3,2] row_mask:0xf bank_mask:0xf
	v_add_f32_e32 v74, v74, v75
	v_mul_f32_e32 v75, v3, v3
	v_mul_f32_e32 v86, v5, v5
	v_fmac_f32_e32 v75, v2, v2
	v_fmac_f32_e32 v86, v4, v4
	v_add_f32_e32 v75, v75, v86
	s_waitcnt lgkmcnt(0)
	v_max_f32_e32 v86, v88, v88
	v_add_f32_e32 v74, v74, v75
	v_max_f32_e32 v86, v87, v86
	s_nop 1
	v_mov_b32_dpp v75, v74 quad_perm:[1,0,3,2] row_mask:0xf bank_mask:0xf
	s_nop 1
	v_mov_b32_dpp v87, v86 quad_perm:[2,3,0,1] row_mask:0xf bank_mask:0xf
	s_waitcnt lgkmcnt(0)
	v_add_f32_e32 v74, v74, v75
	s_waitcnt lgkmcnt(0)
	v_max_f32_e32 v87, v87, v87
	s_nop 1
	v_mov_b32_dpp v75, v74 quad_perm:[2,3,0,1] row_mask:0xf bank_mask:0xf
	v_max_f32_e32 v86, v86, v87
	s_nop 1
	v_mov_b32_dpp v87, v86 row_half_mirror row_mask:0xf bank_mask:0xf
	s_waitcnt lgkmcnt(0)
	v_add_f32_e32 v74, v74, v75
	s_nop 1
	v_mov_b32_dpp v75, v74 row_half_mirror row_mask:0xf bank_mask:0xf
	s_waitcnt lgkmcnt(0)
	v_max_f32_e32 v87, v87, v87
	v_max_f32_e32 v86, v86, v87
	s_nop 1
	v_mov_b32_dpp v87, v86 row_mirror row_mask:0xf bank_mask:0xf
	s_waitcnt lgkmcnt(0)
	v_add_f32_e32 v74, v74, v75
	s_nop 1
	v_mov_b32_dpp v75, v74 row_mirror row_mask:0xf bank_mask:0xf
	s_waitcnt lgkmcnt(0)
	v_max_f32_e32 v87, v87, v87
	v_max_f32_e32 v86, v86, v87
	ds_bpermute_b32 v87, v80, v86
	s_waitcnt lgkmcnt(1)
	v_add_f32_e32 v74, v74, v75
	ds_bpermute_b32 v75, v80, v74
	s_waitcnt lgkmcnt(1)
	v_max_f32_e32 v87, v87, v87
	v_max_f32_e32 v87, v86, v87
	ds_bpermute_b32 v88, v81, v87
	s_waitcnt lgkmcnt(1)
	v_add_f32_e32 v75, v74, v75
	ds_bpermute_b32 v86, v81, v75
	s_waitcnt lgkmcnt(1)
	v_max3_f32 v74, v87, v88, s22
	v_mul_f32_e32 v74, 0x3c010204, v74
	s_and_saveexec_b64 s[16:17], s[4:5]
	s_cbranch_execz .LBB0_72
	s_waitcnt lgkmcnt(0)
	v_add_f32_e32 v75, v75, v86
	v_fmamk_f32 v75, v75, 0x39800000, v82
	v_mul_f32_e32 v86, 0x4f800000, v75
	v_cmp_gt_f32_e32 vcc, s23, v75
	s_nop 1
	v_cndmask_b32_e32 v75, v75, v86, vcc
	v_sqrt_f32_e32 v86, v75
	s_nop 0
	v_add_u32_e32 v87, -1, v86
	v_fma_f32 v89, -v87, v86, v75
	v_add_u32_e32 v88, 1, v86
	v_cmp_ge_f32_e64 s[6:7], 0, v89
	s_nop 1
	v_cndmask_b32_e64 v87, v86, v87, s[6:7]
	v_fma_f32 v86, -v88, v86, v75
	v_cmp_lt_f32_e64 s[6:7], 0, v86
	s_nop 1
	v_cndmask_b32_e64 v86, v87, v88, s[6:7]
	v_mul_f32_e32 v87, 0x37800000, v86
	v_cndmask_b32_e32 v86, v86, v87, vcc
	v_cmp_class_f32_e32 vcc, v75, v83
	s_nop 1
	v_cndmask_b32_e32 v75, v86, v75, vcc
	v_div_scale_f32 v86, s[6:7], v75, v75, 1.0
	v_rcp_f32_e32 v87, v86
	s_add_u32 s6, s78, s10
	s_addc_u32 s7, s79, s11
	v_fma_f32 v88, -v86, v87, 1.0
	v_fmac_f32_e32 v87, v88, v87
	v_div_scale_f32 v88, vcc, 1.0, v75, 1.0
	v_mul_f32_e32 v89, v88, v87
	v_fma_f32 v90, -v86, v89, v88
	v_fmac_f32_e32 v89, v90, v87
	v_fma_f32 v86, -v86, v89, v88
	v_div_fmas_f32 v86, v86, v87, v89
	v_div_fixup_f32 v75, v86, v75, 1.0
	v_mul_f32_e32 v86, v75, v74
	global_store_dword v84, v75, s[6:7]
	global_store_dword v85, v86, s[6:7]
	s_branch .LBB0_72

; #define in_mem ARGP(1)
; __global__ void __launch_bounds__(NWAVES * 64, 2) fwd(Args args) {
;     ...
;         for (int m = gw; m < TM; m += NGW) {
;             const f32x4* xr = (const f32x4*)(in_mem + (size_t)m * DM) + F.lane; f32x4 v[16]; float s2 = 0.f;
; #pragma unroll
;             for (int j = 0; j < 16; ++j) { v[j] = xr[64 * j]; s2 += (v[j][0] * v[j][0] + v[j][1] * v[j][1]) + (v[j][2] * v[j][2] + v[j][3] * v[j][3]); }
;             const float rs = 1.0f / sqrtf(wave_sum(s2) * (1.0f / DM) + EPS);
.LBB0_77:
	flat_load_dwordx2 v[2:3], v[56:57] offset:8 sc0 sc1
	s_waitcnt vmcnt(0)
	v_add_co_u32_e32 v58, vcc, s3, v52
	s_add_i32 s14, s14, s68
	s_nop 0
	v_addc_co_u32_e32 v59, vcc, -1, v53, vcc
	s_cmpk_gt_i32 s14, 0x3ff
	s_waitcnt lgkmcnt(0)
	v_lshl_add_u64 v[6:7], v[2:3], 0, v[54:55]
	v_add_co_u32_e32 v8, vcc, 0xffffc400, v6
	v_lshl_add_u64 v[54:55], v[54:55], 0, s[8:9]
	s_nop 0
	v_addc_co_u32_e32 v9, vcc, -1, v7, vcc
	v_add_co_u32_e32 v10, vcc, 0xffffc800, v6
	s_nop 1
	v_addc_co_u32_e32 v11, vcc, -1, v7, vcc
	v_add_co_u32_e32 v12, vcc, 0xffffcc00, v6
	flat_load_dwordx4 v[68:71], v[8:9]
	flat_load_dwordx4 v[2:5], v[6:7]
	flat_load_dwordx4 v[72:75], v[10:11]
	v_addc_co_u32_e32 v13, vcc, -1, v7, vcc
	v_add_co_u32_e32 v8, vcc, 0xffffd000, v6
	flat_load_dwordx4 v[76:79], v[12:13]
	s_nop 0
	v_addc_co_u32_e32 v9, vcc, -1, v7, vcc
	v_add_co_u32_e32 v10, vcc, 0xffffd400, v6
	s_waitcnt vmcnt(0) lgkmcnt(0)
	v_mul_f32_e32 v90, v73, v73
	v_addc_co_u32_e32 v11, vcc, -1, v7, vcc
	v_add_co_u32_e32 v12, vcc, 0xffffd800, v6
	flat_load_dwordx4 v[80:83], v[8:9]
	flat_load_dwordx4 v[46:49], v[10:11]
	v_addc_co_u32_e32 v13, vcc, -1, v7, vcc
	v_add_co_u32_e32 v8, vcc, 0xffffdc00, v6
	v_mul_f32_e32 v91, v75, v75
	s_nop 0
	v_addc_co_u32_e32 v9, vcc, -1, v7, vcc
	v_add_co_u32_e32 v10, vcc, 0xffffe000, v6
	flat_load_dwordx4 v[42:45], v[12:13]
	flat_load_dwordx4 v[38:41], v[8:9]
	v_addc_co_u32_e32 v11, vcc, -1, v7, vcc
	v_add_co_u32_e32 v8, vcc, 0xffffe400, v6
	v_fmac_f32_e32 v90, v72, v72
	s_nop 0
	v_addc_co_u32_e32 v9, vcc, -1, v7, vcc
	v_add_co_u32_e32 v12, vcc, 0xffffe800, v6
	flat_load_dwordx4 v[34:37], v[10:11]
	flat_load_dwordx4 v[30:33], v[8:9]
	v_addc_co_u32_e32 v13, vcc, -1, v7, vcc
	v_add_co_u32_e32 v8, vcc, 0xffffec00, v6
	v_fmac_f32_e32 v91, v74, v74
	s_nop 0
	v_addc_co_u32_e32 v9, vcc, -1, v7, vcc
	v_add_co_u32_e32 v10, vcc, 0xfffff000, v6
	flat_load_dwordx4 v[26:29], v[12:13]
	flat_load_dwordx4 v[22:25], v[8:9]
	v_addc_co_u32_e32 v11, vcc, -1, v7, vcc
	v_add_co_u32_e32 v8, vcc, 0xfffff400, v6
	v_mul_f32_e32 v92, v79, v79
	s_nop 0
	v_addc_co_u32_e32 v9, vcc, -1, v7, vcc
	v_add_co_u32_e32 v84, vcc, 0xfffff800, v6
	flat_load_dwordx4 v[18:21], v[10:11]
	flat_load_dwordx4 v[14:17], v[8:9]
	v_addc_co_u32_e32 v85, vcc, -1, v7, vcc
	v_add_co_u32_e32 v86, vcc, 0xfffffc00, v6
	v_fmac_f32_e32 v92, v78, v78
	s_nop 0
	v_addc_co_u32_e32 v87, vcc, -1, v7, vcc
	flat_load_dwordx4 v[10:13], v[84:85]
	flat_load_dwordx4 v[6:9], v[86:87]
	flat_load_dwordx2 v[88:89], v[56:57] offset:72 sc0 sc1
	s_waitcnt vmcnt(0)
	v_mul_f32_e32 v84, v69, v69
	v_mul_f32_e32 v85, v71, v71
	v_mul_f32_e32 v86, v3, v3
	v_mul_f32_e32 v87, v5, v5
	v_fmac_f32_e32 v84, v68, v68
	v_fmac_f32_e32 v85, v70, v70
	v_fmac_f32_e32 v86, v2, v2
	v_fmac_f32_e32 v87, v4, v4
	v_add_f32_e32 v84, v84, v85
	v_mul_f32_e32 v85, v77, v77
	v_add_f32_e32 v93, v86, v87
	v_add_f32_e32 v86, v90, v91
	v_fmac_f32_e32 v85, v76, v76
	v_add_f32_e32 v84, v84, v86
	v_add_f32_e32 v85, v85, v92
	v_add_f32_e32 v84, v84, v85
	s_waitcnt lgkmcnt(0)
	v_mul_f32_e32 v87, v81, v81
	v_mul_f32_e32 v90, v83, v83
	v_fmac_f32_e32 v87, v80, v80
	v_fmac_f32_e32 v90, v82, v82
	v_mul_f32_e32 v86, v47, v47
	v_mul_f32_e32 v91, v49, v49
	v_add_f32_e32 v85, v87, v90
	v_fmac_f32_e32 v86, v46, v46
	v_fmac_f32_e32 v91, v48, v48
	v_add_f32_e32 v84, v84, v85
	v_mul_f32_e32 v87, v43, v43
	v_mul_f32_e32 v90, v45, v45
	v_add_f32_e32 v85, v86, v91
	v_fmac_f32_e32 v87, v42, v42
	v_fmac_f32_e32 v90, v44, v44
	v_mul_f32_e32 v86, v39, v39
	v_mul_f32_e32 v91, v41, v41
	v_add_f32_e32 v84, v84, v85
	v_add_f32_e32 v85, v87, v90
	v_fmac_f32_e32 v86, v38, v38
	v_fmac_f32_e32 v91, v40, v40
	v_mul_f32_e32 v87, v35, v35
	v_mul_f32_e32 v90, v37, v37
	v_add_f32_e32 v84, v84, v85
	v_add_f32_e32 v85, v86, v91
	v_fmac_f32_e32 v87, v34, v34
	v_fmac_f32_e32 v90, v36, v36
	v_mul_f32_e32 v86, v31, v31
	v_mul_f32_e32 v91, v33, v33
	v_add_f32_e32 v84, v84, v85
	v_add_f32_e32 v85, v87, v90
	v_fmac_f32_e32 v86, v30, v30
	v_fmac_f32_e32 v91, v32, v32
	v_mul_f32_e32 v87, v27, v27
	v_mul_f32_e32 v90, v29, v29
	v_add_f32_e32 v84, v84, v85
	v_add_f32_e32 v85, v86, v91
	v_fmac_f32_e32 v87, v26, v26
	v_fmac_f32_e32 v90, v28, v28
	v_mul_f32_e32 v86, v23, v23
	v_mul_f32_e32 v91, v25, v25
	v_add_f32_e32 v84, v84, v85
	v_add_f32_e32 v85, v87, v90
	v_fmac_f32_e32 v86, v22, v22
	v_fmac_f32_e32 v91, v24, v24
	v_mul_f32_e32 v87, v19, v19
	v_mul_f32_e32 v90, v21, v21
	v_add_f32_e32 v84, v84, v85
	v_add_f32_e32 v85, v86, v91
	v_fmac_f32_e32 v87, v18, v18
	v_fmac_f32_e32 v90, v20, v20
	v_mul_f32_e32 v86, v15, v15
	v_mul_f32_e32 v91, v17, v17
	v_add_f32_e32 v84, v84, v85
	v_add_f32_e32 v85, v87, v90
	v_fmac_f32_e32 v86, v14, v14
	v_fmac_f32_e32 v91, v16, v16
	v_mul_f32_e32 v87, v11, v11
	v_mul_f32_e32 v90, v13, v13
	v_add_f32_e32 v92, v84, v85
	v_add_f32_e32 v86, v86, v91
	v_fmac_f32_e32 v87, v10, v10
	v_fmac_f32_e32 v90, v12, v12
	v_lshl_add_u64 v[84:85], v[88:89], 0, v[50:51]
	v_add_f32_e32 v88, v92, v86
	v_add_f32_e32 v89, v87, v90
	flat_load_dwordx4 v[84:87], v[84:85]
	v_mul_f32_e32 v91, v7, v7
	v_mul_f32_e32 v94, v9, v9
	v_fmac_f32_e32 v91, v6, v6
	v_fmac_f32_e32 v94, v8, v8
	v_add_f32_e32 v88, v88, v89
	v_add_f32_e32 v89, v91, v94
	v_add_f32_e32 v88, v88, v89
	v_add_f32_e32 v88, v88, v93
	s_nop 1
	v_mov_b32_dpp v89, v88 quad_perm:[1,0,3,2] row_mask:0xf bank_mask:0xf
	s_waitcnt lgkmcnt(0)
	v_add_f32_e32 v88, v88, v89
	s_nop 1
	v_mov_b32_dpp v89, v88 quad_perm:[2,3,0,1] row_mask:0xf bank_mask:0xf
	s_waitcnt lgkmcnt(0)
	v_add_f32_e32 v88, v88, v89
	s_nop 1
	v_mov_b32_dpp v89, v88 row_half_mirror row_mask:0xf bank_mask:0xf
	s_waitcnt lgkmcnt(0)
; __device__ __forceinline__ unsigned cvt_pk_bf16(float lo, float hi) { unsigned r; asm volatile("v_cvt_pk_bf16_f32 %0, %1, %2" : "=v"(r) : "v"(lo), "v"(hi)); return r; }
; #define g_mem ARGP(9)
; __global__ void __launch_bounds__(NWAVES * 64, 2) fwd(Args args) {
;     ...
;             const float rs = 1.0f / sqrtf(wave_sum(s2) * (1.0f / DM) + EPS);
;             u32x2* o8 = (u32x2*)(memn + (size_t)m * DM) + F.lane;
; #pragma unroll
;             for (int j = 0; j < 16; ++j) { const f32x4 g = *((const f32x4*)g_mem + F.lane + 64 * j); u32x2 w; w.x = cvt_pk_bf16(v[j][0] * rs * g[0], v[j][1] * rs * g[1]); w.y = cvt_pk_bf16(v[j][2] * rs * g[2], v[j][3] * rs * g[3]); o8[64 * j] = w; }
	v_add_f32_e32 v88, v88, v89
	s_nop 1
	v_mov_b32_dpp v89, v88 row_mirror row_mask:0xf bank_mask:0xf
	s_waitcnt lgkmcnt(0)
	v_add_f32_e32 v88, v88, v89
	ds_bpermute_b32 v89, v64, v88
	s_waitcnt lgkmcnt(0)
	v_add_f32_e32 v88, v88, v89
	ds_bpermute_b32 v89, v65, v88
	s_waitcnt lgkmcnt(0)
	v_add_f32_e32 v88, v88, v89
	v_fmamk_f32 v88, v88, 0x39800000, v66
	v_mul_f32_e32 v89, 0x4f800000, v88
	v_cmp_gt_f32_e32 vcc, s10, v88
	s_nop 1
	v_cndmask_b32_e32 v88, v88, v89, vcc
	v_sqrt_f32_e32 v89, v88
	s_nop 0
	v_add_u32_e32 v90, -1, v89
	v_add_u32_e32 v91, 1, v89
	v_fma_f32 v92, -v90, v89, v88
	v_fma_f32 v93, -v91, v89, v88
	v_cmp_ge_f32_e64 s[4:5], 0, v92
	s_nop 1
	v_cndmask_b32_e64 v89, v89, v90, s[4:5]
	v_cmp_lt_f32_e64 s[4:5], 0, v93
	s_nop 1
	v_cndmask_b32_e64 v89, v89, v91, s[4:5]
	v_mul_f32_e32 v90, 0x37800000, v89
	v_cndmask_b32_e32 v89, v89, v90, vcc
	v_cmp_class_f32_e32 vcc, v88, v67
	s_nop 1
	v_cndmask_b32_e32 v88, v89, v88, vcc
	v_div_scale_f32 v89, s[4:5], v88, v88, 1.0
	v_rcp_f32_e32 v91, v89
	v_div_scale_f32 v90, vcc, 1.0, v88, 1.0
	v_fma_f32 v92, -v89, v91, 1.0
	v_fmac_f32_e32 v91, v92, v91
	v_mul_f32_e32 v92, v90, v91
	v_fma_f32 v93, -v89, v92, v90
	v_fmac_f32_e32 v92, v93, v91
	v_fma_f32 v89, -v89, v92, v90
	v_div_fmas_f32 v89, v89, v91, v92
	v_div_fixup_f32 v88, v89, v88, 1.0
	v_mul_f32_e32 v68, v88, v68
	v_mul_f32_e32 v69, v88, v69
	v_mul_f32_e32 v70, v88, v70
	v_mul_f32_e32 v71, v88, v71
	v_mul_f32_e32 v89, v88, v46
	v_mul_f32_e32 v90, v88, v47
	s_waitcnt vmcnt(0)
	v_mul_f32_e32 v46, v84, v68
	v_mul_f32_e32 v47, v85, v69
	v_mul_f32_e32 v91, v88, v48
	v_mul_f32_e32 v92, v88, v49
	v_mul_f32_e32 v48, v86, v70
	v_mul_f32_e32 v49, v87, v71
	v_cvt_pk_bf16_f32 v46, v46, v47
	v_cvt_pk_bf16_f32 v47, v48, v49
	global_store_dwordx2 v[58:59], v[46:47], off offset:-3584
	flat_load_dwordx2 v[46:47], v[56:57] offset:72 sc0 sc1
	s_waitcnt vmcnt(0)
	v_mul_f32_e32 v72, v88, v72
	v_mul_f32_e32 v73, v88, v73
	v_mul_f32_e32 v74, v88, v74
	v_mul_f32_e32 v75, v88, v75
	v_mul_f32_e32 v76, v88, v76
	v_mul_f32_e32 v77, v88, v77
	v_mul_f32_e32 v78, v88, v78
	v_mul_f32_e32 v79, v88, v79
	v_mul_f32_e32 v80, v88, v80
	v_mul_f32_e32 v81, v88, v81
	v_mul_f32_e32 v82, v88, v82
	v_mul_f32_e32 v83, v88, v83
	v_mul_f32_e32 v42, v88, v42
	v_mul_f32_e32 v43, v88, v43
	v_mul_f32_e32 v44, v88, v44
	v_mul_f32_e32 v45, v88, v45
	v_mul_f32_e32 v38, v88, v38
	v_mul_f32_e32 v39, v88, v39
	v_mul_f32_e32 v40, v88, v40
	v_mul_f32_e32 v41, v88, v41
	v_mul_f32_e32 v34, v88, v34
	v_mul_f32_e32 v35, v88, v35
	v_mul_f32_e32 v36, v88, v36
	v_mul_f32_e32 v37, v88, v37
	v_mul_f32_e32 v30, v88, v30
	v_mul_f32_e32 v31, v88, v31
	v_mul_f32_e32 v32, v88, v32
	v_mul_f32_e32 v33, v88, v33
	v_mul_f32_e32 v26, v88, v26
	v_mul_f32_e32 v27, v88, v27
	v_mul_f32_e32 v28, v88, v28
	v_mul_f32_e32 v29, v88, v29
	v_mul_f32_e32 v22, v88, v22
	v_mul_f32_e32 v23, v88, v23
	v_mul_f32_e32 v24, v88, v24
	v_mul_f32_e32 v25, v88, v25
	v_mul_f32_e32 v18, v88, v18
	v_mul_f32_e32 v19, v88, v19
	v_mul_f32_e32 v20, v88, v20
	v_mul_f32_e32 v21, v88, v21
	v_mul_f32_e32 v14, v88, v14
	v_mul_f32_e32 v15, v88, v15
	v_mul_f32_e32 v16, v88, v16
	v_mul_f32_e32 v17, v88, v17
	v_mul_f32_e32 v10, v88, v10
	v_mul_f32_e32 v11, v88, v11
	v_mul_f32_e32 v12, v88, v12
	v_mul_f32_e32 v13, v88, v13
	v_mul_f32_e32 v6, v88, v6
	v_mul_f32_e32 v7, v88, v7
	v_mul_f32_e32 v8, v88, v8
	v_mul_f32_e32 v9, v88, v9
	v_mul_f32_e32 v2, v88, v2
	v_mul_f32_e32 v3, v88, v3
	v_mul_f32_e32 v4, v88, v4
	v_mul_f32_e32 v5, v88, v5
	s_waitcnt lgkmcnt(0)
	v_lshl_add_u64 v[46:47], v[46:47], 0, v[50:51]
	flat_load_dwordx4 v[46:49], v[46:47] offset:1024
	s_waitcnt vmcnt(0) lgkmcnt(0)
	v_mul_f32_e32 v46, v46, v72
	v_mul_f32_e32 v47, v47, v73
	v_mul_f32_e32 v48, v48, v74
	v_mul_f32_e32 v49, v49, v75
	v_cvt_pk_bf16_f32 v46, v46, v47
	v_cvt_pk_bf16_f32 v47, v48, v49
	global_store_dwordx2 v[58:59], v[46:47], off offset:-3072
	flat_load_dwordx2 v[46:47], v[56:57] offset:72 sc0 sc1
	s_waitcnt vmcnt(0) lgkmcnt(0)
	v_lshl_add_u64 v[46:47], v[46:47], 0, v[50:51]
	flat_load_dwordx4 v[46:49], v[46:47] offset:2048
	s_waitcnt vmcnt(0) lgkmcnt(0)
	v_mul_f32_e32 v46, v46, v76
	v_mul_f32_e32 v47, v47, v77
	v_mul_f32_e32 v48, v48, v78
	v_mul_f32_e32 v49, v49, v79
	v_cvt_pk_bf16_f32 v46, v46, v47
	v_cvt_pk_bf16_f32 v47, v48, v49
	global_store_dwordx2 v[58:59], v[46:47], off offset:-2560
	flat_load_dwordx2 v[46:47], v[56:57] offset:72 sc0 sc1
	s_waitcnt vmcnt(0) lgkmcnt(0)
	v_lshl_add_u64 v[46:47], v[46:47], 0, v[50:51]
	flat_load_dwordx4 v[46:49], v[46:47] offset:3072
	s_waitcnt vmcnt(0) lgkmcnt(0)
	v_mul_f32_e32 v46, v46, v80
	v_mul_f32_e32 v47, v47, v81
	v_mul_f32_e32 v48, v48, v82
	v_mul_f32_e32 v49, v49, v83
	v_cvt_pk_bf16_f32 v46, v46, v47
	v_cvt_pk_bf16_f32 v47, v48, v49
	global_store_dwordx2 v[58:59], v[46:47], off offset:-2048
	flat_load_dwordx2 v[46:47], v[56:57] offset:72 sc0 sc1
	s_waitcnt vmcnt(0) lgkmcnt(0)
	v_lshl_add_u64 v[46:47], v[46:47], 0, v[50:51]
	v_add_co_u32_e32 v46, vcc, s11, v46
	s_nop 1
	v_addc_co_u32_e32 v47, vcc, 0, v47, vcc
	flat_load_dwordx4 v[46:49], v[46:47]
	s_waitcnt vmcnt(0) lgkmcnt(0)
	v_mul_f32_e32 v46, v46, v89
	v_mul_f32_e32 v47, v47, v90
	v_mul_f32_e32 v48, v48, v91
	v_mul_f32_e32 v49, v49, v92
	v_cvt_pk_bf16_f32 v46, v46, v47
	v_cvt_pk_bf16_f32 v47, v48, v49
	global_store_dwordx2 v[58:59], v[46:47], off offset:-1536
	flat_load_dwordx2 v[46:47], v[56:57] offset:72 sc0 sc1
	s_waitcnt vmcnt(0) lgkmcnt(0)
	v_lshl_add_u64 v[46:47], v[46:47], 0, v[50:51]
	v_add_co_u32_e32 v46, vcc, s11, v46
	s_nop 1
	v_addc_co_u32_e32 v47, vcc, 0, v47, vcc
	flat_load_dwordx4 v[46:49], v[46:47] offset:1024
	s_waitcnt vmcnt(0) lgkmcnt(0)
; __device__ __forceinline__ unsigned cvt_pk_bf16(float lo, float hi) { unsigned r; asm volatile("v_cvt_pk_bf16_f32 %0, %1, %2" : "=v"(r) : "v"(lo), "v"(hi)); return r; }
; #define g_mem ARGP(9)
; __global__ void __launch_bounds__(NWAVES * 64, 2) fwd(Args args) {
;     ...
; #pragma unroll
;             for (int j = 0; j < 16; ++j) { const f32x4 g = *((const f32x4*)g_mem + F.lane + 64 * j); u32x2 w; w.x = cvt_pk_bf16(v[j][0] * rs * g[0], v[j][1] * rs * g[1]); w.y = cvt_pk_bf16(v[j][2] * rs * g[2], v[j][3] * rs * g[3]); o8[64 * j] = w; }
	v_mul_f32_e32 v42, v46, v42
	v_mul_f32_e32 v43, v47, v43
	v_mul_f32_e32 v44, v48, v44
	v_mul_f32_e32 v45, v49, v45
	v_cvt_pk_bf16_f32 v42, v42, v43
	v_cvt_pk_bf16_f32 v43, v44, v45
	global_store_dwordx2 v[58:59], v[42:43], off offset:-1024
	flat_load_dwordx2 v[42:43], v[56:57] offset:72 sc0 sc1
	s_waitcnt vmcnt(0) lgkmcnt(0)
	v_lshl_add_u64 v[42:43], v[42:43], 0, v[50:51]
	v_add_co_u32_e32 v42, vcc, s11, v42
	s_nop 1
	v_addc_co_u32_e32 v43, vcc, 0, v43, vcc
	flat_load_dwordx4 v[42:45], v[42:43] offset:2048
	s_waitcnt vmcnt(0) lgkmcnt(0)
	v_mul_f32_e32 v38, v42, v38
	v_mul_f32_e32 v39, v43, v39
	v_mul_f32_e32 v40, v44, v40
	v_mul_f32_e32 v41, v45, v41
	v_cvt_pk_bf16_f32 v38, v38, v39
	v_cvt_pk_bf16_f32 v39, v40, v41
	global_store_dwordx2 v[58:59], v[38:39], off offset:-512
	flat_load_dwordx2 v[38:39], v[56:57] offset:72 sc0 sc1
	s_waitcnt vmcnt(0) lgkmcnt(0)
	v_lshl_add_u64 v[38:39], v[38:39], 0, v[50:51]
	v_add_co_u32_e32 v38, vcc, s11, v38
	s_nop 1
	v_addc_co_u32_e32 v39, vcc, 0, v39, vcc
	flat_load_dwordx4 v[38:41], v[38:39] offset:3072
	s_waitcnt vmcnt(0) lgkmcnt(0)
	v_mul_f32_e32 v34, v38, v34
	v_mul_f32_e32 v35, v39, v35
	v_mul_f32_e32 v36, v40, v36
	v_mul_f32_e32 v37, v41, v37
	v_cvt_pk_bf16_f32 v34, v34, v35
	v_cvt_pk_bf16_f32 v35, v36, v37
	global_store_dwordx2 v[52:53], v[34:35], off offset:-4096
	flat_load_dwordx2 v[34:35], v[56:57] offset:72 sc0 sc1
	s_waitcnt vmcnt(0) lgkmcnt(0)
	v_lshl_add_u64 v[34:35], v[34:35], 0, v[50:51]
	v_add_co_u32_e32 v34, vcc, s12, v34
	s_nop 1
	v_addc_co_u32_e32 v35, vcc, 0, v35, vcc
	flat_load_dwordx4 v[34:37], v[34:35]
	s_waitcnt vmcnt(0) lgkmcnt(0)
	v_mul_f32_e32 v30, v34, v30
	v_mul_f32_e32 v31, v35, v31
	v_mul_f32_e32 v32, v36, v32
	v_mul_f32_e32 v33, v37, v33
	v_cvt_pk_bf16_f32 v30, v30, v31
	v_cvt_pk_bf16_f32 v31, v32, v33
	global_store_dwordx2 v[52:53], v[30:31], off offset:-3584
	flat_load_dwordx2 v[30:31], v[56:57] offset:72 sc0 sc1
	s_waitcnt vmcnt(0) lgkmcnt(0)
	v_lshl_add_u64 v[30:31], v[30:31], 0, v[50:51]
	v_add_co_u32_e32 v30, vcc, s12, v30
	s_nop 1
	v_addc_co_u32_e32 v31, vcc, 0, v31, vcc
	flat_load_dwordx4 v[30:33], v[30:31] offset:1024
	s_waitcnt vmcnt(0) lgkmcnt(0)
	v_mul_f32_e32 v26, v30, v26
	v_mul_f32_e32 v27, v31, v27
	v_mul_f32_e32 v28, v32, v28
	v_mul_f32_e32 v29, v33, v29
	v_cvt_pk_bf16_f32 v26, v26, v27
	v_cvt_pk_bf16_f32 v27, v28, v29
	global_store_dwordx2 v[52:53], v[26:27], off offset:-3072
	flat_load_dwordx2 v[26:27], v[56:57] offset:72 sc0 sc1
	s_waitcnt vmcnt(0) lgkmcnt(0)
	v_lshl_add_u64 v[26:27], v[26:27], 0, v[50:51]
	v_add_co_u32_e32 v26, vcc, s12, v26
	s_nop 1
	v_addc_co_u32_e32 v27, vcc, 0, v27, vcc
	flat_load_dwordx4 v[26:29], v[26:27] offset:2048
	s_waitcnt vmcnt(0) lgkmcnt(0)
	v_mul_f32_e32 v22, v26, v22
	v_mul_f32_e32 v23, v27, v23
	v_mul_f32_e32 v24, v28, v24
	v_mul_f32_e32 v25, v29, v25
	v_cvt_pk_bf16_f32 v22, v22, v23
	v_cvt_pk_bf16_f32 v23, v24, v25
	global_store_dwordx2 v[52:53], v[22:23], off offset:-2560
	flat_load_dwordx2 v[22:23], v[56:57] offset:72 sc0 sc1
	s_waitcnt vmcnt(0) lgkmcnt(0)
	v_lshl_add_u64 v[22:23], v[22:23], 0, v[50:51]
	v_add_co_u32_e32 v22, vcc, s12, v22
	s_nop 1
	v_addc_co_u32_e32 v23, vcc, 0, v23, vcc
	flat_load_dwordx4 v[22:25], v[22:23] offset:3072
	s_waitcnt vmcnt(0) lgkmcnt(0)
	v_mul_f32_e32 v18, v22, v18
	v_mul_f32_e32 v19, v23, v19
	v_mul_f32_e32 v20, v24, v20
	v_mul_f32_e32 v21, v25, v21
	v_cvt_pk_bf16_f32 v18, v18, v19
	v_cvt_pk_bf16_f32 v19, v20, v21
	global_store_dwordx2 v[52:53], v[18:19], off offset:-2048
	flat_load_dwordx2 v[18:19], v[56:57] offset:72 sc0 sc1
	s_waitcnt vmcnt(0) lgkmcnt(0)
	v_lshl_add_u64 v[18:19], v[18:19], 0, v[50:51]
	v_add_co_u32_e32 v18, vcc, s13, v18
	s_nop 1
	v_addc_co_u32_e32 v19, vcc, 0, v19, vcc
	flat_load_dwordx4 v[18:21], v[18:19]
	s_waitcnt vmcnt(0) lgkmcnt(0)
	v_mul_f32_e32 v14, v18, v14
	v_mul_f32_e32 v15, v19, v15
	v_mul_f32_e32 v16, v20, v16
	v_mul_f32_e32 v17, v21, v17
	v_cvt_pk_bf16_f32 v14, v14, v15
	v_cvt_pk_bf16_f32 v15, v16, v17
	global_store_dwordx2 v[52:53], v[14:15], off offset:-1536
	flat_load_dwordx2 v[14:15], v[56:57] offset:72 sc0 sc1
	s_waitcnt vmcnt(0) lgkmcnt(0)
	v_lshl_add_u64 v[14:15], v[14:15], 0, v[50:51]
	v_add_co_u32_e32 v14, vcc, s13, v14
	s_nop 1
	v_addc_co_u32_e32 v15, vcc, 0, v15, vcc
	flat_load_dwordx4 v[14:17], v[14:15] offset:1024
	s_waitcnt vmcnt(0) lgkmcnt(0)
	v_mul_f32_e32 v10, v14, v10
	v_mul_f32_e32 v11, v15, v11
	v_mul_f32_e32 v12, v16, v12
	v_mul_f32_e32 v13, v17, v13
	v_cvt_pk_bf16_f32 v10, v10, v11
	v_cvt_pk_bf16_f32 v11, v12, v13
	global_store_dwordx2 v[52:53], v[10:11], off offset:-1024
	flat_load_dwordx2 v[10:11], v[56:57] offset:72 sc0 sc1
	s_waitcnt vmcnt(0) lgkmcnt(0)
	v_lshl_add_u64 v[10:11], v[10:11], 0, v[50:51]
	v_add_co_u32_e32 v10, vcc, s13, v10
	s_nop 1
	v_addc_co_u32_e32 v11, vcc, 0, v11, vcc
	flat_load_dwordx4 v[10:13], v[10:11] offset:2048
	s_waitcnt vmcnt(0) lgkmcnt(0)
	v_mul_f32_e32 v6, v10, v6
	v_mul_f32_e32 v7, v11, v7
	v_mul_f32_e32 v8, v12, v8
	v_mul_f32_e32 v9, v13, v9
	v_cvt_pk_bf16_f32 v6, v6, v7
	v_cvt_pk_bf16_f32 v7, v8, v9
	global_store_dwordx2 v[52:53], v[6:7], off offset:-512
	flat_load_dwordx2 v[6:7], v[56:57] offset:72 sc0 sc1
	s_waitcnt vmcnt(0) lgkmcnt(0)
	v_lshl_add_u64 v[6:7], v[6:7], 0, v[50:51]
	v_add_co_u32_e32 v6, vcc, s13, v6
	s_nop 1
	v_addc_co_u32_e32 v7, vcc, 0, v7, vcc
	flat_load_dwordx4 v[6:9], v[6:7] offset:3072
	s_waitcnt vmcnt(0) lgkmcnt(0)
	v_mul_f32_e32 v2, v6, v2
	v_mul_f32_e32 v3, v7, v3
	v_mul_f32_e32 v4, v8, v4
	v_mul_f32_e32 v5, v9, v5
	v_cvt_pk_bf16_f32 v2, v2, v3
	v_cvt_pk_bf16_f32 v3, v4, v5
	global_store_dwordx2 v[52:53], v[2:3], off
	v_lshl_add_u64 v[52:53], v[52:53], 0, s[6:7]
	s_cbranch_scc0 .LBB0_77

; __device__ __forceinline__ float bflo(unsigned w) { return __uint_as_float(w << 16); }
; __device__ __forceinline__ float bfhi(unsigned w) { return __uint_as_float(w & 0xffff0000u); }
; #pragma unroll
;     for (int j = 0; j < 8; ++j) mx = fmaxf(mx, fmaxf(fmaxf(fmaxf(fabsf(bflo(w[j].x)), fabsf(bfhi(w[j].x))), fmaxf(fabsf(bflo(w[j].y)), fabsf(bfhi(w[j].y)))), fmaxf(fmaxf(fabsf(bflo(w[j].z)), fabsf(bfhi(w[j].z))), fmaxf(fabsf(bflo(w[j].w)), fabsf(bfhi(w[j].w))))));
; __device__ __forceinline__ void quant_rows2(const bf16_t* s0, const bf16_t* s1, signed char* d0, signed char* d1, int lane, float& step0, float& step1) {
;     const u32x4* p0 = (const u32x4*)s0 + lane; const u32x4* p1 = (const u32x4*)s1 + lane; u32x4 w0[8], w1[8];
; #pragma unroll
;     for (int j = 0; j < 8; ++j) { w0[j] = p0[64 * j]; w1[j] = p1[64 * j]; }
.LBB0_160:
	v_lshl_add_u64 v[2:3], s[78:79], 0, v[30:31]
	v_add_co_u32_e32 v4, vcc, 0x10800000, v2
	s_nop 1
	v_addc_co_u32_e32 v5, vcc, 0, v3, vcc
	global_load_dwordx4 v[42:45], v[4:5], off
	global_load_dwordx4 v[46:49], v[4:5], off offset:1024
	global_load_dwordx4 v[50:53], v[4:5], off offset:2048
	global_load_dwordx4 v[54:57], v[4:5], off offset:3072
	v_add_co_u32_e32 v6, vcc, 0x10802000, v2
	s_waitcnt vmcnt(3)
	v_lshlrev_b32_e32 v83, 16, v42
	v_addc_co_u32_e32 v7, vcc, 0, v3, vcc
	v_add_co_u32_e32 v4, vcc, s13, v2
	global_load_dwordx4 v[58:61], v[6:7], off
	global_load_dwordx4 v[26:29], v[6:7], off offset:1024
	global_load_dwordx4 v[22:25], v[6:7], off offset:2048
	global_load_dwordx4 v[18:21], v[6:7], off offset:3072
	v_addc_co_u32_e32 v5, vcc, 0, v3, vcc
	v_add_co_u32_e32 v2, vcc, s22, v2
	v_and_b32_e32 v84, 0xffff0000, v42
	s_nop 0
	v_addc_co_u32_e32 v3, vcc, 0, v3, vcc
	global_load_dwordx4 v[62:65], v[4:5], off
	global_load_dwordx4 v[66:69], v[4:5], off offset:1024
	global_load_dwordx4 v[70:73], v[4:5], off offset:2048
	global_load_dwordx4 v[74:77], v[4:5], off offset:3072
	global_load_dwordx4 v[14:17], v[2:3], off
	global_load_dwordx4 v[10:13], v[2:3], off offset:1024
	global_load_dwordx4 v[6:9], v[2:3], off offset:2048
	s_nop 0
	global_load_dwordx4 v[2:5], v[2:3], off offset:3072
	v_lshlrev_b32_e32 v85, 16, v43
	v_and_b32_e32 v86, 0xffff0000, v43
	v_lshlrev_b32_e32 v89, 16, v45
	v_and_b32_e32 v90, 0xffff0000, v45
	s_waitcnt vmcnt(14)
	v_lshlrev_b32_e32 v97, 16, v49
	v_and_b32_e32 v98, 0xffff0000, v49
	v_lshlrev_b32_e32 v87, 16, v44
	v_and_b32_e32 v88, 0xffff0000, v44
	v_lshlrev_b32_e32 v91, 16, v46
	v_and_b32_e32 v92, 0xffff0000, v46
	v_lshlrev_b32_e32 v93, 16, v47
	v_and_b32_e32 v94, 0xffff0000, v47
	s_waitcnt vmcnt(13)
	v_lshlrev_b32_e32 v101, 16, v51
	v_and_b32_e32 v102, 0xffff0000, v51
	v_lshlrev_b32_e32 v103, 16, v52
	v_and_b32_e32 v104, 0xffff0000, v52
	v_max_f32_e64 v41, |v84|, |v84|
	v_max_f32_e64 v42, |v83|, |v83|
	v_max_f32_e64 v43, |v86|, |v86|
	v_max_f32_e64 v44, |v85|, |v85|
	v_max_f32_e64 v45, |v90|, |v90|
	v_max_f32_e64 v46, |v89|, |v89|
	v_max_f32_e64 v51, |v98|, |v98|
	v_max_f32_e64 v52, |v97|, |v97|
	v_lshlrev_b32_e32 v95, 16, v48
	v_and_b32_e32 v96, 0xffff0000, v48
	v_lshlrev_b32_e32 v99, 16, v50
	v_and_b32_e32 v100, 0xffff0000, v50
	v_max_f32_e64 v47, |v92|, |v92|
	v_max_f32_e64 v48, |v91|, |v91|
	v_max_f32_e64 v49, |v94|, |v94|
	v_max_f32_e64 v50, |v93|, |v93|
	v_max_f32_e32 v41, v42, v41
	v_max_f32_e32 v42, v44, v43
	v_max_f32_e32 v43, v46, v45
	v_max_f32_e32 v46, v52, v51
	v_max_f32_e32 v44, v48, v47
	v_max_f32_e32 v45, v50, v49
	v_max3_f32 v43, |v87|, |v88|, v43
	v_max3_f32 v46, |v95|, |v96|, v46
	v_lshlrev_b32_e32 v105, 16, v53
	v_max3_f32 v41, v41, v42, v43
	v_max3_f32 v42, v44, v45, v46
	v_and_b32_e32 v106, 0xffff0000, v53
	v_max3_f32 v41, v41, 0, v42
	v_max_f32_e64 v42, |v106|, |v106|
	v_max_f32_e64 v43, |v105|, |v105|
	s_waitcnt vmcnt(12)
	v_lshlrev_b32_e32 v107, 16, v54
	v_and_b32_e32 v108, 0xffff0000, v54
	v_max_f32_e32 v42, v43, v42
	v_max_f32_e64 v43, |v108|, |v108|
	v_max_f32_e64 v44, |v107|, |v107|
	v_lshlrev_b32_e32 v109, 16, v55
	v_and_b32_e32 v110, 0xffff0000, v55
	v_max_f32_e32 v43, v44, v43
	v_max_f32_e64 v44, |v110|, |v110|
	v_max_f32_e64 v45, |v109|, |v109|
	v_lshlrev_b32_e32 v113, 16, v57
	v_and_b32_e32 v114, 0xffff0000, v57
	v_max_f32_e32 v44, v45, v44
	v_max_f32_e64 v45, |v114|, |v114|
	v_max_f32_e64 v46, |v113|, |v113|
	v_max_f32_e64 v78, |v100|, |v100|
	v_max_f32_e64 v79, |v99|, |v99|
	v_max_f32_e64 v80, |v102|, |v102|
	v_max_f32_e64 v81, |v101|, |v101|
	v_lshlrev_b32_e32 v111, 16, v56
	v_and_b32_e32 v112, 0xffff0000, v56
	v_max_f32_e32 v45, v46, v45
	v_max_f32_e32 v47, v79, v78
	v_max_f32_e32 v48, v81, v80
	v_max3_f32 v42, |v103|, |v104|, v42
	v_max3_f32 v45, |v111|, |v112|, v45
	v_max3_f32 v42, v47, v48, v42
	v_max3_f32 v43, v43, v44, v45
	s_waitcnt vmcnt(7)
	v_lshlrev_b32_e32 v115, 16, v62
	v_and_b32_e32 v116, 0xffff0000, v62
	v_max3_f32 v41, v41, v42, v43
	v_max_f32_e64 v42, |v116|, |v116|
	v_max_f32_e64 v43, |v115|, |v115|
	v_lshlrev_b32_e32 v117, 16, v63
	v_and_b32_e32 v118, 0xffff0000, v63
	v_max_f32_e32 v42, v43, v42
	v_max_f32_e64 v43, |v118|, |v118|
	v_max_f32_e64 v44, |v117|, |v117|
	v_lshlrev_b32_e32 v121, 16, v65
	v_and_b32_e32 v122, 0xffff0000, v65
	v_max_f32_e32 v43, v44, v43
	v_max_f32_e64 v44, |v122|, |v122|
	v_max_f32_e64 v45, |v121|, |v121|
	v_lshlrev_b32_e32 v119, 16, v64
	v_and_b32_e32 v120, 0xffff0000, v64
	v_max_f32_e32 v44, v45, v44
	v_max3_f32 v44, |v119|, |v120|, v44
	s_waitcnt vmcnt(6)
	v_lshlrev_b32_e32 v123, 16, v66
	v_and_b32_e32 v124, 0xffff0000, v66
	v_max3_f32 v42, v42, v43, v44
	v_max_f32_e64 v43, |v124|, |v124|
	v_max_f32_e64 v44, |v123|, |v123|
	v_lshlrev_b32_e32 v125, 16, v67
	v_and_b32_e32 v126, 0xffff0000, v67
	v_max_f32_e32 v43, v44, v43
	v_max_f32_e64 v44, |v126|, |v126|
	v_max_f32_e64 v45, |v125|, |v125|
	v_lshlrev_b32_e32 v129, 16, v69
	v_and_b32_e32 v130, 0xffff0000, v69
	v_max_f32_e32 v44, v45, v44
	v_max_f32_e64 v45, |v130|, |v130|
	v_max_f32_e64 v46, |v129|, |v129|
	v_lshlrev_b32_e32 v127, 16, v68
	v_and_b32_e32 v128, 0xffff0000, v68
	v_max_f32_e32 v45, v46, v45
	v_max3_f32 v45, |v127|, |v128|, v45
	v_max3_f32 v43, v43, v44, v45
	s_waitcnt vmcnt(5)
	v_lshlrev_b32_e32 v131, 16, v70
	v_and_b32_e32 v132, 0xffff0000, v70
	v_max3_f32 v41, v41, v42, v43
	v_max_f32_e64 v42, |v132|, |v132|
	v_max_f32_e64 v43, |v131|, |v131|
	v_lshlrev_b32_e32 v133, 16, v71
	v_and_b32_e32 v137, 0xffff0000, v71
	v_max_f32_e32 v42, v43, v42
	v_max_f32_e64 v43, |v137|, |v137|
	v_max_f32_e64 v44, |v133|, |v133|
	v_lshlrev_b32_e32 v140, 16, v73
	v_and_b32_e32 v141, 0xffff0000, v73
	v_max_f32_e32 v43, v44, v43
	v_max_f32_e64 v44, |v141|, |v141|
	v_max_f32_e64 v45, |v140|, |v140|
	v_lshlrev_b32_e32 v138, 16, v72
	v_and_b32_e32 v139, 0xffff0000, v72
	v_max_f32_e32 v44, v45, v44
	v_max3_f32 v44, |v138|, |v139|, v44
	s_waitcnt vmcnt(4)
; __device__ __forceinline__ float bflo(unsigned w) { return __uint_as_float(w << 16); }
; __device__ __forceinline__ float bfhi(unsigned w) { return __uint_as_float(w & 0xffff0000u); }
; #pragma unroll
;     for (int j = 0; j < 8; ++j) mx = fmaxf(mx, fmaxf(fmaxf(fmaxf(fabsf(bflo(w[j].x)), fabsf(bfhi(w[j].x))), fmaxf(fabsf(bflo(w[j].y)), fabsf(bfhi(w[j].y)))), fmaxf(fmaxf(fabsf(bflo(w[j].z)), fabsf(bfhi(w[j].z))), fmaxf(fabsf(bflo(w[j].w)), fabsf(bfhi(w[j].w))))));
; #pragma unroll
;     for (int o = 1; o < 64; o <<= 1) mx = fmaxf(mx, __shfl_xor(mx, o));
;     return mx; }
	v_lshlrev_b32_e32 v142, 16, v74
	v_and_b32_e32 v143, 0xffff0000, v74
	v_max3_f32 v42, v42, v43, v44
	v_max_f32_e64 v43, |v143|, |v143|
	v_max_f32_e64 v44, |v142|, |v142|
	v_lshlrev_b32_e32 v144, 16, v75
	v_and_b32_e32 v145, 0xffff0000, v75
	v_max_f32_e32 v43, v44, v43
	v_max_f32_e64 v44, |v145|, |v145|
	v_max_f32_e64 v45, |v144|, |v144|
	v_lshlrev_b32_e32 v148, 16, v77
	v_and_b32_e32 v149, 0xffff0000, v77
	v_max_f32_e32 v44, v45, v44
	v_max_f32_e64 v45, |v149|, |v149|
	v_max_f32_e64 v46, |v148|, |v148|
	v_lshlrev_b32_e32 v146, 16, v76
	v_and_b32_e32 v147, 0xffff0000, v76
	v_max_f32_e32 v45, v46, v45
	v_max3_f32 v45, |v146|, |v147|, v45
	v_max3_f32 v43, v43, v44, v45
	v_lshlrev_b32_e32 v82, 16, v58
	v_and_b32_e32 v80, 0xffff0000, v58
	v_max3_f32 v156, v41, v42, v43
	v_max_f32_e64 v41, |v80|, |v80|
	v_max_f32_e64 v42, |v82|, |v82|
	v_lshlrev_b32_e32 v81, 16, v59
	v_and_b32_e32 v79, 0xffff0000, v59
	v_max_f32_e32 v41, v42, v41
	v_max_f32_e64 v42, |v79|, |v79|
	v_max_f32_e64 v43, |v81|, |v81|
	v_lshlrev_b32_e32 v76, 16, v61
	v_and_b32_e32 v75, 0xffff0000, v61
	v_max_f32_e32 v42, v43, v42
	v_max_f32_e64 v43, |v75|, |v75|
	v_max_f32_e64 v44, |v76|, |v76|
	v_lshlrev_b32_e32 v78, 16, v60
	v_and_b32_e32 v77, 0xffff0000, v60
	v_max_f32_e32 v43, v44, v43
	v_max3_f32 v43, |v78|, |v77|, v43
	v_lshlrev_b32_e32 v74, 16, v26
	v_and_b32_e32 v72, 0xffff0000, v26
	v_lshlrev_b32_e32 v68, 16, v29
	v_and_b32_e32 v67, 0xffff0000, v29
	v_max3_f32 v41, v41, v42, v43
	v_max_f32_e64 v26, |v72|, |v72|
	v_max_f32_e64 v42, |v74|, |v74|
	v_lshlrev_b32_e32 v73, 16, v27
	v_and_b32_e32 v71, 0xffff0000, v27
	v_lshlrev_b32_e32 v70, 16, v28
	v_and_b32_e32 v69, 0xffff0000, v28
	v_max_f32_e64 v28, |v67|, |v67|
	v_max_f32_e64 v29, |v68|, |v68|
	v_max_f32_e32 v26, v42, v26
	v_max_f32_e64 v27, |v71|, |v71|
	v_max_f32_e64 v42, |v73|, |v73|
	v_max_f32_e32 v28, v29, v28
	v_max_f32_e32 v27, v42, v27
	v_max3_f32 v28, |v70|, |v69|, v28
	v_lshlrev_b32_e32 v66, 16, v22
	v_and_b32_e32 v64, 0xffff0000, v22
	v_lshlrev_b32_e32 v60, 16, v25
	v_and_b32_e32 v59, 0xffff0000, v25
	v_max3_f32 v26, v26, v27, v28
	v_max_f32_e64 v22, |v64|, |v64|
	v_max_f32_e64 v27, |v66|, |v66|
	v_lshlrev_b32_e32 v65, 16, v23
	v_and_b32_e32 v63, 0xffff0000, v23
	v_lshlrev_b32_e32 v62, 16, v24
	v_and_b32_e32 v61, 0xffff0000, v24
	v_max_f32_e64 v24, |v59|, |v59|
	v_max_f32_e64 v25, |v60|, |v60|
	v_max_f32_e32 v22, v27, v22
	v_max_f32_e64 v23, |v63|, |v63|
	v_max_f32_e64 v27, |v65|, |v65|
	v_max_f32_e32 v24, v25, v24
	v_max_f32_e32 v23, v27, v23
	v_max3_f32 v24, |v62|, |v61|, v24
	v_lshlrev_b32_e32 v58, 16, v18
	v_and_b32_e32 v56, 0xffff0000, v18
	v_lshlrev_b32_e32 v52, 16, v21
	v_and_b32_e32 v51, 0xffff0000, v21
	v_max3_f32 v22, v22, v23, v24
	v_max_f32_e64 v18, |v56|, |v56|
	v_max_f32_e64 v23, |v58|, |v58|
	v_lshlrev_b32_e32 v57, 16, v19
	v_and_b32_e32 v55, 0xffff0000, v19
	v_lshlrev_b32_e32 v54, 16, v20
	v_and_b32_e32 v53, 0xffff0000, v20
	v_max_f32_e64 v20, |v51|, |v51|
	v_max_f32_e64 v21, |v52|, |v52|
	v_max_f32_e32 v18, v23, v18
	v_max_f32_e64 v19, |v55|, |v55|
	v_max_f32_e64 v23, |v57|, |v57|
	v_max_f32_e32 v20, v21, v20
	v_max_f32_e32 v19, v23, v19
	v_max3_f32 v20, |v54|, |v53|, v20
	s_waitcnt vmcnt(3)
	v_lshlrev_b32_e32 v50, 16, v14
	v_and_b32_e32 v48, 0xffff0000, v14
	v_lshlrev_b32_e32 v44, 16, v17
	v_and_b32_e32 v43, 0xffff0000, v17
	v_max3_f32 v18, v18, v19, v20
	v_max_f32_e64 v14, |v48|, |v48|
	v_max_f32_e64 v19, |v50|, |v50|
	v_lshlrev_b32_e32 v49, 16, v15
	v_and_b32_e32 v47, 0xffff0000, v15
	v_lshlrev_b32_e32 v46, 16, v16
	v_and_b32_e32 v45, 0xffff0000, v16
	v_max_f32_e64 v16, |v43|, |v43|
	v_max_f32_e64 v17, |v44|, |v44|
	v_max_f32_e32 v14, v19, v14
	v_max_f32_e64 v15, |v47|, |v47|
	v_max_f32_e64 v19, |v49|, |v49|
	v_max_f32_e32 v16, v17, v16
	v_max3_f32 v26, v41, 0, v26
	v_max_f32_e32 v15, v19, v15
	v_max3_f32 v16, |v46|, |v45|, v16
	s_waitcnt vmcnt(2)
	v_lshlrev_b32_e32 v42, 16, v10
	v_and_b32_e32 v29, 0xffff0000, v10
	v_lshlrev_b32_e32 v25, 16, v13
	v_and_b32_e32 v24, 0xffff0000, v13
	v_max3_f32 v18, v26, v22, v18
	v_max3_f32 v14, v14, v15, v16
	v_max_f32_e64 v10, |v29|, |v29|
	v_max_f32_e64 v15, |v42|, |v42|
	v_lshlrev_b32_e32 v41, 16, v11
	v_and_b32_e32 v28, 0xffff0000, v11
	v_lshlrev_b32_e32 v27, 16, v12
	v_and_b32_e32 v26, 0xffff0000, v12
	v_max_f32_e64 v12, |v24|, |v24|
	v_max_f32_e64 v13, |v25|, |v25|
	v_max_f32_e32 v10, v15, v10
	v_max_f32_e64 v11, |v28|, |v28|
	v_max_f32_e64 v15, |v41|, |v41|
	v_max_f32_e32 v12, v13, v12
	v_max_f32_e32 v11, v15, v11
	v_max3_f32 v12, |v27|, |v26|, v12
	v_max3_f32 v10, v10, v11, v12
	s_waitcnt vmcnt(1)
	v_lshlrev_b32_e32 v23, 16, v6
	v_and_b32_e32 v21, 0xffff0000, v6
	v_lshlrev_b32_e32 v17, 16, v9
	v_and_b32_e32 v16, 0xffff0000, v9
	v_max3_f32 v158, v18, v14, v10
	v_max_f32_e64 v6, |v21|, |v21|
	v_max_f32_e64 v10, |v23|, |v23|
	v_lshlrev_b32_e32 v22, 16, v7
	v_and_b32_e32 v20, 0xffff0000, v7
	v_lshlrev_b32_e32 v19, 16, v8
	v_and_b32_e32 v18, 0xffff0000, v8
	v_max_f32_e64 v8, |v16|, |v16|
	v_max_f32_e64 v9, |v17|, |v17|
	v_max_f32_e32 v6, v10, v6
	v_max_f32_e64 v7, |v20|, |v20|
	v_max_f32_e64 v10, |v22|, |v22|
	v_max_f32_e32 v8, v9, v8
	v_max_f32_e32 v7, v10, v7
	v_max3_f32 v8, |v19|, |v18|, v8
	v_max3_f32 v6, v6, v7, v8
	s_waitcnt vmcnt(0)
	v_lshlrev_b32_e32 v15, 16, v2
	v_and_b32_e32 v13, 0xffff0000, v2
	v_lshlrev_b32_e32 v9, 16, v5
	v_and_b32_e32 v8, 0xffff0000, v5
	v_max_f32_e64 v2, |v13|, |v13|
	v_max_f32_e64 v7, |v15|, |v15|
	v_lshlrev_b32_e32 v14, 16, v3
	v_and_b32_e32 v12, 0xffff0000, v3
	v_lshlrev_b32_e32 v11, 16, v4
	v_and_b32_e32 v10, 0xffff0000, v4
	v_max_f32_e64 v4, |v8|, |v8|
	v_max_f32_e64 v5, |v9|, |v9|
	v_max_f32_e32 v2, v7, v2
	v_max_f32_e64 v3, |v12|, |v12|
	v_max_f32_e64 v7, |v14|, |v14|
	v_max_f32_e32 v4, v5, v4
	v_max_f32_e32 v3, v7, v3
	v_max3_f32 v4, |v11|, |v10|, v4
	v_max3_f32 v2, v2, v3, v4
	v_max3_f32 v2, v158, v6, v2
	s_nop 1
	v_mov_b32_dpp v157, v156 quad_perm:[1,0,3,2] row_mask:0xf bank_mask:0xf
	s_nop 1
	v_mov_b32_dpp v3, v2 quad_perm:[1,0,3,2] row_mask:0xf bank_mask:0xf
	s_waitcnt lgkmcnt(0)
; __device__ __forceinline__ float bflo(unsigned w) { return __uint_as_float(w << 16); }
; __device__ __forceinline__ float bfhi(unsigned w) { return __uint_as_float(w & 0xffff0000u); }
; #pragma unroll
;     for (int j = 0; j < 8; ++j) mx = fmaxf(mx, fmaxf(fmaxf(fmaxf(fabsf(bflo(w[j].x)), fabsf(bfhi(w[j].x))), fmaxf(fabsf(bflo(w[j].y)), fabsf(bfhi(w[j].y)))), fmaxf(fmaxf(fabsf(bflo(w[j].z)), fabsf(bfhi(w[j].z))), fmaxf(fabsf(bflo(w[j].w)), fabsf(bfhi(w[j].w))))));
; #pragma unroll
;     for (int o = 1; o < 64; o <<= 1) mx = fmaxf(mx, __shfl_xor(mx, o));
;     return mx; }
; __device__ __forceinline__ void quant_store8(const u32x4 (&w)[8], float inv, signed char* dst, int lane) { u32x2* qp = (u32x2*)dst + lane;
; #pragma unroll
;     for (int j = 0; j < 8; ++j) { const unsigned ww[4] = {w[j].x, w[j].y, w[j].z, w[j].w}; unsigned o2[2];
; #pragma unroll
;         for (int h2 = 0; h2 < 2; ++h2) { const int q0 = (int)rintf(bflo(ww[2 * h2]) * inv), q1 = (int)rintf(bfhi(ww[2 * h2]) * inv), q2 = (int)rintf(bflo(ww[2 * h2 + 1]) * inv), q3 = (int)rintf(bfhi(ww[2 * h2 + 1]) * inv);
;             o2[h2] = (unsigned)(q0 & 255) | ((unsigned)(q1 & 255) << 8) | ((unsigned)(q2 & 255) << 16) | ((unsigned)(q3 & 255) << 24); }
;         u32x2 o; o.x = o2[0]; o.y = o2[1]; qp[64 * j] = o; } }
; __device__ __forceinline__ void quant_rows2(const bf16_t* s0, const bf16_t* s1, signed char* d0, signed char* d1, int lane, float& step0, float& step1) {
;     const u32x4* p0 = (const u32x4*)s0 + lane; const u32x4* p1 = (const u32x4*)s1 + lane; u32x4 w0[8], w1[8];
; #pragma unroll
;     for (int j = 0; j < 8; ++j) { w0[j] = p0[64 * j]; w1[j] = p1[64 * j]; }
;     step0 = fmaxf(absmax8(w0), 1e-30f) * (1.0f / 127.0f); step1 = fmaxf(absmax8(w1), 1e-30f) * (1.0f / 127.0f);
;     quant_store8(w0, 1.0f / step0, d0, lane); quant_store8(w1, 1.0f / step1, d1, lane);
; }
; __global__ void __launch_bounds__(NWAVES * 64, 2) fwd(Args args) {
;     ...
;             for (int p = 0; p < 4; ++p) { const int n = 64 * bx + 8 * F.wave + 2 * p; float s0, s1;
;                 quant_rows2(W_inT + (size_t)(IN_Q0 + n) * DM, W_inT + (size_t)(IN_Q0 + n + 1) * DM, W_inq + (size_t)n * DM, W_inq + (size_t)(n + 1) * DM, F.lane, s0, s1);
;                 if (F.lane == 0) { colq[n] = s0; colq[n + 1] = s1; } }
	v_max_f32_e32 v4, v157, v157
	s_waitcnt lgkmcnt(0)
	v_max_f32_e32 v3, v3, v3
	v_max_f32_e32 v4, v156, v4
	v_max_f32_e32 v2, v2, v3
	s_nop 1
	v_mov_b32_dpp v5, v4 quad_perm:[2,3,0,1] row_mask:0xf bank_mask:0xf
	s_nop 1
	v_mov_b32_dpp v3, v2 quad_perm:[2,3,0,1] row_mask:0xf bank_mask:0xf
	s_waitcnt lgkmcnt(0)
	v_max_f32_e32 v5, v5, v5
	s_waitcnt lgkmcnt(0)
	v_max_f32_e32 v3, v3, v3
	v_max_f32_e32 v4, v4, v5
	v_max_f32_e32 v2, v2, v3
	s_nop 1
	v_mov_b32_dpp v5, v4 row_half_mirror row_mask:0xf bank_mask:0xf
	s_nop 1
	v_mov_b32_dpp v3, v2 row_half_mirror row_mask:0xf bank_mask:0xf
	s_waitcnt lgkmcnt(0)
	v_max_f32_e32 v5, v5, v5
	s_waitcnt lgkmcnt(0)
	v_max_f32_e32 v3, v3, v3
	v_max_f32_e32 v4, v4, v5
	v_max_f32_e32 v2, v2, v3
	s_nop 1
	v_mov_b32_dpp v5, v4 row_mirror row_mask:0xf bank_mask:0xf
	s_nop 1
	v_mov_b32_dpp v3, v2 row_mirror row_mask:0xf bank_mask:0xf
	s_waitcnt lgkmcnt(0)
	v_max_f32_e32 v5, v5, v5
	s_waitcnt lgkmcnt(0)
	v_max_f32_e32 v3, v3, v3
	v_max_f32_e32 v4, v4, v5
	v_max_f32_e32 v2, v2, v3
	ds_bpermute_b32 v5, v38, v4
	ds_bpermute_b32 v3, v38, v2
	s_waitcnt lgkmcnt(1)
	v_max_f32_e32 v5, v5, v5
	s_waitcnt lgkmcnt(0)
	v_max_f32_e32 v3, v3, v3
	v_max_f32_e32 v4, v4, v5
	v_max_f32_e32 v3, v2, v3
	ds_bpermute_b32 v5, v39, v4
	ds_bpermute_b32 v6, v39, v3
	s_waitcnt lgkmcnt(1)
	v_max3_f32 v2, v4, v5, s23
	s_waitcnt lgkmcnt(0)
	v_max3_f32 v3, v3, v6, s23
	v_pk_mul_f32 v[2:3], v[2:3], s[6:7] op_sel_hi:[1,0]
	s_nop 0
	v_div_scale_f32 v4, s[10:11], v2, v2, 1.0
	v_rcp_f32_e32 v5, v4
	s_nop 0
	v_fma_f32 v6, -v4, v5, 1.0
	v_fmac_f32_e32 v5, v6, v5
	v_div_scale_f32 v6, vcc, 1.0, v2, 1.0
	v_mul_f32_e32 v7, v6, v5
	v_fma_f32 v156, -v4, v7, v6
	v_fmac_f32_e32 v7, v156, v5
	v_fma_f32 v4, -v4, v7, v6
	v_div_fmas_f32 v4, v4, v5, v7
	v_div_fixup_f32 v156, v4, v2, 1.0
	v_mul_f32_e32 v7, v156, v84
	v_mul_f32_e32 v6, v156, v83
	v_rndne_f32_e32 v7, v7
	v_mul_f32_e32 v83, v156, v85
	v_rndne_f32_e32 v6, v6
	v_cvt_i32_f32_e32 v7, v7
	v_rndne_f32_e32 v83, v83
	v_mul_f32_e32 v84, v156, v86
	v_cvt_i32_f32_e32 v6, v6
	v_cvt_i32_f32_sdwa v83, v83 dst_sel:WORD_1 dst_unused:UNUSED_PAD src0_sel:DWORD
	v_rndne_f32_e32 v84, v84
	v_cvt_i32_f32_sdwa v84, v84 dst_sel:BYTE_3 dst_unused:UNUSED_PAD src0_sel:DWORD
	v_lshlrev_b32_e32 v7, 8, v7
	v_and_b32_e32 v83, 0xff0000, v83
	v_perm_b32 v6, v7, v6, s26
	v_mul_f32_e32 v7, v156, v88
	v_or3_b32 v84, v6, v84, v83
	v_mul_f32_e32 v6, v156, v87
	v_rndne_f32_e32 v7, v7
	v_mul_f32_e32 v83, v156, v89
	v_rndne_f32_e32 v6, v6
	v_cvt_i32_f32_e32 v7, v7
	v_rndne_f32_e32 v83, v83
	v_mul_f32_e32 v85, v156, v90
	v_cvt_i32_f32_e32 v6, v6
	v_cvt_i32_f32_sdwa v83, v83 dst_sel:WORD_1 dst_unused:UNUSED_PAD src0_sel:DWORD
	v_rndne_f32_e32 v85, v85
	v_cvt_i32_f32_sdwa v85, v85 dst_sel:BYTE_3 dst_unused:UNUSED_PAD src0_sel:DWORD
	v_lshlrev_b32_e32 v7, 8, v7
	v_lshl_add_u64 v[4:5], v[32:33], 0, s[0:1]
	v_and_b32_e32 v83, 0xff0000, v83
	v_perm_b32 v6, v7, v6, s26
	v_or3_b32 v85, v6, v85, v83
	v_add_co_u32_e32 v6, vcc, s27, v4
	v_mul_f32_e32 v83, v156, v91
	s_nop 0
	v_addc_co_u32_e32 v7, vcc, 0, v5, vcc
	v_add_co_u32_e32 v4, vcc, s28, v4
	v_rndne_f32_e32 v83, v83
	s_nop 0
	v_addc_co_u32_e32 v5, vcc, 0, v5, vcc
	global_store_dwordx2 v[4:5], v[84:85], off offset:-4096
	v_mul_f32_e32 v84, v156, v92
	v_rndne_f32_e32 v84, v84
	v_mul_f32_e32 v85, v156, v93
	v_cvt_i32_f32_e32 v84, v84
	v_rndne_f32_e32 v85, v85
	v_mul_f32_e32 v86, v156, v94
	v_cvt_i32_f32_e32 v83, v83
	v_cvt_i32_f32_sdwa v85, v85 dst_sel:WORD_1 dst_unused:UNUSED_PAD src0_sel:DWORD
	v_rndne_f32_e32 v86, v86
	v_cvt_i32_f32_sdwa v86, v86 dst_sel:BYTE_3 dst_unused:UNUSED_PAD src0_sel:DWORD
	v_lshlrev_b32_e32 v84, 8, v84
	v_and_b32_e32 v85, 0xff0000, v85
	v_perm_b32 v83, v84, v83, s26
	v_or3_b32 v84, v83, v86, v85
	v_mul_f32_e32 v85, v156, v96
	v_mul_f32_e32 v83, v156, v95
	v_rndne_f32_e32 v85, v85
	v_mul_f32_e32 v86, v156, v97
	v_rndne_f32_e32 v83, v83
	v_cvt_i32_f32_e32 v85, v85
	v_rndne_f32_e32 v86, v86
	v_mul_f32_e32 v87, v156, v98
	v_cvt_i32_f32_e32 v83, v83
	v_cvt_i32_f32_sdwa v86, v86 dst_sel:WORD_1 dst_unused:UNUSED_PAD src0_sel:DWORD
	v_rndne_f32_e32 v87, v87
	v_cvt_i32_f32_sdwa v87, v87 dst_sel:BYTE_3 dst_unused:UNUSED_PAD src0_sel:DWORD
	v_lshlrev_b32_e32 v85, 8, v85
	v_and_b32_e32 v86, 0xff0000, v86
	v_perm_b32 v83, v85, v83, s26
	v_or3_b32 v85, v83, v87, v86
	global_store_dwordx2 v[6:7], v[84:85], off offset:512
	v_mul_f32_e32 v84, v156, v100
	v_mul_f32_e32 v83, v156, v99
	v_rndne_f32_e32 v84, v84
	v_mul_f32_e32 v85, v156, v101
	v_rndne_f32_e32 v83, v83
	v_cvt_i32_f32_e32 v84, v84
	v_rndne_f32_e32 v85, v85
	v_mul_f32_e32 v86, v156, v102
	v_cvt_i32_f32_e32 v83, v83
	v_cvt_i32_f32_sdwa v85, v85 dst_sel:WORD_1 dst_unused:UNUSED_PAD src0_sel:DWORD
	v_rndne_f32_e32 v86, v86
	v_cvt_i32_f32_sdwa v86, v86 dst_sel:BYTE_3 dst_unused:UNUSED_PAD src0_sel:DWORD
	v_lshlrev_b32_e32 v84, 8, v84
	v_and_b32_e32 v85, 0xff0000, v85
	v_perm_b32 v83, v84, v83, s26
	v_or3_b32 v84, v83, v86, v85
	v_mul_f32_e32 v85, v156, v104
	v_mul_f32_e32 v83, v156, v103
	v_rndne_f32_e32 v85, v85
	v_mul_f32_e32 v86, v156, v105
	v_rndne_f32_e32 v83, v83
	v_cvt_i32_f32_e32 v85, v85
	v_rndne_f32_e32 v86, v86
	v_mul_f32_e32 v87, v156, v106
	v_cvt_i32_f32_e32 v83, v83
	v_cvt_i32_f32_sdwa v86, v86 dst_sel:WORD_1 dst_unused:UNUSED_PAD src0_sel:DWORD
	v_rndne_f32_e32 v87, v87
	v_cvt_i32_f32_sdwa v87, v87 dst_sel:BYTE_3 dst_unused:UNUSED_PAD src0_sel:DWORD
	v_lshlrev_b32_e32 v85, 8, v85
	v_and_b32_e32 v86, 0xff0000, v86
	v_perm_b32 v83, v85, v83, s26
	v_or3_b32 v85, v83, v87, v86
	global_store_dwordx2 v[6:7], v[84:85], off offset:1024
	v_mul_f32_e32 v84, v156, v108
	v_mul_f32_e32 v83, v156, v107
	v_rndne_f32_e32 v84, v84
; __device__ __forceinline__ float bflo(unsigned w) { return __uint_as_float(w << 16); }
; __device__ __forceinline__ float bfhi(unsigned w) { return __uint_as_float(w & 0xffff0000u); }
; __device__ __forceinline__ void quant_store8(const u32x4 (&w)[8], float inv, signed char* dst, int lane) { u32x2* qp = (u32x2*)dst + lane;
; #pragma unroll
;     for (int j = 0; j < 8; ++j) { const unsigned ww[4] = {w[j].x, w[j].y, w[j].z, w[j].w}; unsigned o2[2];
; #pragma unroll
;         for (int h2 = 0; h2 < 2; ++h2) { const int q0 = (int)rintf(bflo(ww[2 * h2]) * inv), q1 = (int)rintf(bfhi(ww[2 * h2]) * inv), q2 = (int)rintf(bflo(ww[2 * h2 + 1]) * inv), q3 = (int)rintf(bfhi(ww[2 * h2 + 1]) * inv);
;             o2[h2] = (unsigned)(q0 & 255) | ((unsigned)(q1 & 255) << 8) | ((unsigned)(q2 & 255) << 16) | ((unsigned)(q3 & 255) << 24); }
;         u32x2 o; o.x = o2[0]; o.y = o2[1]; qp[64 * j] = o; } }
	v_mul_f32_e32 v85, v156, v109
	v_rndne_f32_e32 v83, v83
	v_cvt_i32_f32_e32 v84, v84
	v_rndne_f32_e32 v85, v85
	v_mul_f32_e32 v86, v156, v110
	v_cvt_i32_f32_e32 v83, v83
	v_cvt_i32_f32_sdwa v85, v85 dst_sel:WORD_1 dst_unused:UNUSED_PAD src0_sel:DWORD
	v_rndne_f32_e32 v86, v86
	v_cvt_i32_f32_sdwa v86, v86 dst_sel:BYTE_3 dst_unused:UNUSED_PAD src0_sel:DWORD
	v_lshlrev_b32_e32 v84, 8, v84
	v_and_b32_e32 v85, 0xff0000, v85
	v_perm_b32 v83, v84, v83, s26
	v_or3_b32 v84, v83, v86, v85
	v_mul_f32_e32 v85, v156, v112
	v_mul_f32_e32 v83, v156, v111
	v_rndne_f32_e32 v85, v85
	v_mul_f32_e32 v86, v156, v113
	v_rndne_f32_e32 v83, v83
	v_cvt_i32_f32_e32 v85, v85
	v_rndne_f32_e32 v86, v86
	v_mul_f32_e32 v87, v156, v114
	v_cvt_i32_f32_e32 v83, v83
	v_cvt_i32_f32_sdwa v86, v86 dst_sel:WORD_1 dst_unused:UNUSED_PAD src0_sel:DWORD
	v_rndne_f32_e32 v87, v87
	v_cvt_i32_f32_sdwa v87, v87 dst_sel:BYTE_3 dst_unused:UNUSED_PAD src0_sel:DWORD
	v_lshlrev_b32_e32 v85, 8, v85
	v_and_b32_e32 v86, 0xff0000, v86
	v_perm_b32 v83, v85, v83, s26
	v_or3_b32 v85, v83, v87, v86
	global_store_dwordx2 v[6:7], v[84:85], off offset:1536
	v_mul_f32_e32 v84, v156, v116
	v_mul_f32_e32 v83, v156, v115
	v_rndne_f32_e32 v84, v84
	v_mul_f32_e32 v85, v156, v117
	v_rndne_f32_e32 v83, v83
	v_cvt_i32_f32_e32 v84, v84
	v_rndne_f32_e32 v85, v85
	v_mul_f32_e32 v86, v156, v118
	v_cvt_i32_f32_e32 v83, v83
	v_cvt_i32_f32_sdwa v85, v85 dst_sel:WORD_1 dst_unused:UNUSED_PAD src0_sel:DWORD
	v_rndne_f32_e32 v86, v86
	v_cvt_i32_f32_sdwa v86, v86 dst_sel:BYTE_3 dst_unused:UNUSED_PAD src0_sel:DWORD
	v_lshlrev_b32_e32 v84, 8, v84
	v_and_b32_e32 v85, 0xff0000, v85
	v_perm_b32 v83, v84, v83, s26
	v_or3_b32 v84, v83, v86, v85
	v_mul_f32_e32 v85, v156, v120
	v_mul_f32_e32 v83, v156, v119
	v_rndne_f32_e32 v85, v85
	v_mul_f32_e32 v86, v156, v121
	v_rndne_f32_e32 v83, v83
	v_cvt_i32_f32_e32 v85, v85
	v_rndne_f32_e32 v86, v86
	v_mul_f32_e32 v87, v156, v122
	v_cvt_i32_f32_e32 v83, v83
	v_cvt_i32_f32_sdwa v86, v86 dst_sel:WORD_1 dst_unused:UNUSED_PAD src0_sel:DWORD
	v_rndne_f32_e32 v87, v87
	v_cvt_i32_f32_sdwa v87, v87 dst_sel:BYTE_3 dst_unused:UNUSED_PAD src0_sel:DWORD
	v_lshlrev_b32_e32 v85, 8, v85
	v_and_b32_e32 v86, 0xff0000, v86
	v_perm_b32 v83, v85, v83, s26
	v_or3_b32 v85, v83, v87, v86
	global_store_dwordx2 v[6:7], v[84:85], off offset:2048
	v_mul_f32_e32 v84, v156, v124
	v_mul_f32_e32 v83, v156, v123
	v_rndne_f32_e32 v84, v84
	v_mul_f32_e32 v85, v156, v125
	v_rndne_f32_e32 v83, v83
	v_cvt_i32_f32_e32 v84, v84
	v_rndne_f32_e32 v85, v85
	v_mul_f32_e32 v86, v156, v126
	v_cvt_i32_f32_e32 v83, v83
	v_cvt_i32_f32_sdwa v85, v85 dst_sel:WORD_1 dst_unused:UNUSED_PAD src0_sel:DWORD
	v_rndne_f32_e32 v86, v86
	v_cvt_i32_f32_sdwa v86, v86 dst_sel:BYTE_3 dst_unused:UNUSED_PAD src0_sel:DWORD
	v_lshlrev_b32_e32 v84, 8, v84
	v_and_b32_e32 v85, 0xff0000, v85
	v_perm_b32 v83, v84, v83, s26
	v_or3_b32 v84, v83, v86, v85
	v_mul_f32_e32 v85, v156, v128
	v_mul_f32_e32 v83, v156, v127
	v_rndne_f32_e32 v85, v85
	v_mul_f32_e32 v86, v156, v129
	v_rndne_f32_e32 v83, v83
	v_cvt_i32_f32_e32 v85, v85
	v_rndne_f32_e32 v86, v86
	v_mul_f32_e32 v87, v156, v130
	v_cvt_i32_f32_e32 v83, v83
	v_cvt_i32_f32_sdwa v86, v86 dst_sel:WORD_1 dst_unused:UNUSED_PAD src0_sel:DWORD
	v_rndne_f32_e32 v87, v87
	v_cvt_i32_f32_sdwa v87, v87 dst_sel:BYTE_3 dst_unused:UNUSED_PAD src0_sel:DWORD
	v_lshlrev_b32_e32 v85, 8, v85
	v_and_b32_e32 v86, 0xff0000, v86
	v_perm_b32 v83, v85, v83, s26
	v_or3_b32 v85, v83, v87, v86
	global_store_dwordx2 v[6:7], v[84:85], off offset:2560
	v_mul_f32_e32 v84, v156, v132
	v_mul_f32_e32 v83, v156, v131
	v_rndne_f32_e32 v84, v84
	v_mul_f32_e32 v85, v156, v133
	v_rndne_f32_e32 v83, v83
	v_cvt_i32_f32_e32 v84, v84
	v_rndne_f32_e32 v85, v85
	v_mul_f32_e32 v86, v156, v137
	v_cvt_i32_f32_e32 v83, v83
	v_cvt_i32_f32_sdwa v85, v85 dst_sel:WORD_1 dst_unused:UNUSED_PAD src0_sel:DWORD
	v_rndne_f32_e32 v86, v86
	v_cvt_i32_f32_sdwa v86, v86 dst_sel:BYTE_3 dst_unused:UNUSED_PAD src0_sel:DWORD
	v_lshlrev_b32_e32 v84, 8, v84
	v_and_b32_e32 v85, 0xff0000, v85
	v_perm_b32 v83, v84, v83, s26
	v_or3_b32 v84, v83, v86, v85
	v_mul_f32_e32 v85, v156, v139
	v_mul_f32_e32 v83, v156, v138
	v_rndne_f32_e32 v85, v85
	v_mul_f32_e32 v86, v156, v140
	v_rndne_f32_e32 v83, v83
	v_cvt_i32_f32_e32 v85, v85
	v_rndne_f32_e32 v86, v86
	v_mul_f32_e32 v87, v156, v141
	v_cvt_i32_f32_e32 v83, v83
	v_cvt_i32_f32_sdwa v86, v86 dst_sel:WORD_1 dst_unused:UNUSED_PAD src0_sel:DWORD
	v_rndne_f32_e32 v87, v87
	v_cvt_i32_f32_sdwa v87, v87 dst_sel:BYTE_3 dst_unused:UNUSED_PAD src0_sel:DWORD
	v_lshlrev_b32_e32 v85, 8, v85
	v_and_b32_e32 v86, 0xff0000, v86
	v_perm_b32 v83, v85, v83, s26
	v_or3_b32 v85, v83, v87, v86
	global_store_dwordx2 v[6:7], v[84:85], off offset:3072
	v_mul_f32_e32 v84, v156, v143
	v_mul_f32_e32 v83, v156, v142
	v_rndne_f32_e32 v84, v84
	v_mul_f32_e32 v85, v156, v144
	v_rndne_f32_e32 v83, v83
	v_cvt_i32_f32_e32 v84, v84
	v_rndne_f32_e32 v85, v85
	v_mul_f32_e32 v86, v156, v145
	v_cvt_i32_f32_e32 v83, v83
	v_cvt_i32_f32_sdwa v85, v85 dst_sel:WORD_1 dst_unused:UNUSED_PAD src0_sel:DWORD
	v_rndne_f32_e32 v86, v86
	v_cvt_i32_f32_sdwa v86, v86 dst_sel:BYTE_3 dst_unused:UNUSED_PAD src0_sel:DWORD
	v_lshlrev_b32_e32 v84, 8, v84
	v_and_b32_e32 v85, 0xff0000, v85
	v_perm_b32 v83, v84, v83, s26
	v_or3_b32 v84, v83, v86, v85
	v_mul_f32_e32 v85, v156, v147
	v_mul_f32_e32 v83, v156, v146
	v_rndne_f32_e32 v85, v85
	v_mul_f32_e32 v86, v156, v148
	v_rndne_f32_e32 v83, v83
	v_cvt_i32_f32_e32 v85, v85
	v_rndne_f32_e32 v86, v86
	v_mul_f32_e32 v87, v156, v149
	v_cvt_i32_f32_e32 v83, v83
	v_cvt_i32_f32_sdwa v86, v86 dst_sel:WORD_1 dst_unused:UNUSED_PAD src0_sel:DWORD
	v_rndne_f32_e32 v87, v87
; __device__ __forceinline__ float bflo(unsigned w) { return __uint_as_float(w << 16); }
; __device__ __forceinline__ float bfhi(unsigned w) { return __uint_as_float(w & 0xffff0000u); }
; __device__ __forceinline__ void quant_store8(const u32x4 (&w)[8], float inv, signed char* dst, int lane) { u32x2* qp = (u32x2*)dst + lane;
; #pragma unroll
;     for (int j = 0; j < 8; ++j) { const unsigned ww[4] = {w[j].x, w[j].y, w[j].z, w[j].w}; unsigned o2[2];
; #pragma unroll
;         for (int h2 = 0; h2 < 2; ++h2) { const int q0 = (int)rintf(bflo(ww[2 * h2]) * inv), q1 = (int)rintf(bfhi(ww[2 * h2]) * inv), q2 = (int)rintf(bflo(ww[2 * h2 + 1]) * inv), q3 = (int)rintf(bfhi(ww[2 * h2 + 1]) * inv);
;             o2[h2] = (unsigned)(q0 & 255) | ((unsigned)(q1 & 255) << 8) | ((unsigned)(q2 & 255) << 16) | ((unsigned)(q3 & 255) << 24); }
;         u32x2 o; o.x = o2[0]; o.y = o2[1]; qp[64 * j] = o; } }
; __device__ __forceinline__ void quant_rows2(const bf16_t* s0, const bf16_t* s1, signed char* d0, signed char* d1, int lane, float& step0, float& step1) {
;     const u32x4* p0 = (const u32x4*)s0 + lane; const u32x4* p1 = (const u32x4*)s1 + lane; u32x4 w0[8], w1[8];
; #pragma unroll
;     for (int j = 0; j < 8; ++j) { w0[j] = p0[64 * j]; w1[j] = p1[64 * j]; }
;     step0 = fmaxf(absmax8(w0), 1e-30f) * (1.0f / 127.0f); step1 = fmaxf(absmax8(w1), 1e-30f) * (1.0f / 127.0f);
;     quant_store8(w0, 1.0f / step0, d0, lane); quant_store8(w1, 1.0f / step1, d1, lane);
	v_cvt_i32_f32_sdwa v87, v87 dst_sel:BYTE_3 dst_unused:UNUSED_PAD src0_sel:DWORD
	v_div_scale_f32 v88, s[10:11], v3, v3, 1.0
	v_rcp_f32_e32 v89, v88
	v_lshlrev_b32_e32 v85, 8, v85
	v_and_b32_e32 v86, 0xff0000, v86
	v_perm_b32 v83, v85, v83, s26
	v_or3_b32 v85, v83, v87, v86
	global_store_dwordx2 v[6:7], v[84:85], off offset:3584
	v_fma_f32 v6, -v88, v89, 1.0
	v_fmac_f32_e32 v89, v6, v89
	v_div_scale_f32 v6, vcc, 1.0, v3, 1.0
	v_mul_f32_e32 v7, v6, v89
	v_fma_f32 v83, -v88, v7, v6
	v_fmac_f32_e32 v7, v83, v89
	v_fma_f32 v6, -v88, v7, v6
	v_div_fmas_f32 v6, v6, v89, v7
	v_div_fixup_f32 v83, v6, v3, 1.0
	v_mul_f32_e32 v7, v83, v80
	v_mul_f32_e32 v6, v83, v82
	v_rndne_f32_e32 v7, v7
	v_rndne_f32_e32 v6, v6
	v_cvt_i32_f32_e32 v7, v7
	v_cvt_i32_f32_e32 v6, v6
	v_mul_f32_e32 v77, v83, v77
	v_mul_f32_e32 v80, v83, v81
	v_lshlrev_b32_e32 v7, 8, v7
	v_perm_b32 v6, v7, v6, s26
	v_mul_f32_e32 v7, v83, v78
	v_rndne_f32_e32 v77, v77
	v_mul_f32_e32 v76, v83, v76
	v_rndne_f32_e32 v80, v80
	v_mul_f32_e32 v79, v83, v79
	v_rndne_f32_e32 v7, v7
	v_cvt_i32_f32_e32 v77, v77
	v_rndne_f32_e32 v76, v76
	v_mul_f32_e32 v75, v83, v75
	v_cvt_i32_f32_sdwa v80, v80 dst_sel:WORD_1 dst_unused:UNUSED_PAD src0_sel:DWORD
	v_rndne_f32_e32 v79, v79
	v_cvt_i32_f32_e32 v7, v7
	v_cvt_i32_f32_sdwa v76, v76 dst_sel:WORD_1 dst_unused:UNUSED_PAD src0_sel:DWORD
	v_rndne_f32_e32 v75, v75
	v_cvt_i32_f32_sdwa v79, v79 dst_sel:BYTE_3 dst_unused:UNUSED_PAD src0_sel:DWORD
	v_cvt_i32_f32_sdwa v75, v75 dst_sel:BYTE_3 dst_unused:UNUSED_PAD src0_sel:DWORD
	v_lshlrev_b32_e32 v77, 8, v77
	v_and_b32_e32 v80, 0xff0000, v80
	v_and_b32_e32 v76, 0xff0000, v76
	v_perm_b32 v7, v77, v7, s26
	v_or3_b32 v6, v6, v79, v80
	v_or3_b32 v7, v7, v75, v76
	global_store_dwordx2 v[4:5], v[6:7], off
	v_mul_f32_e32 v7, v83, v72
	v_mul_f32_e32 v6, v83, v74
	v_rndne_f32_e32 v7, v7
	v_rndne_f32_e32 v6, v6
	v_cvt_i32_f32_e32 v7, v7
	v_cvt_i32_f32_e32 v6, v6
	v_mul_f32_e32 v69, v83, v69
	v_mul_f32_e32 v72, v83, v73
	v_lshlrev_b32_e32 v7, 8, v7
	v_perm_b32 v6, v7, v6, s26
	v_mul_f32_e32 v7, v83, v70
	v_rndne_f32_e32 v69, v69
	v_mul_f32_e32 v68, v83, v68
	v_rndne_f32_e32 v72, v72
	v_mul_f32_e32 v71, v83, v71
	v_rndne_f32_e32 v7, v7
	v_cvt_i32_f32_e32 v69, v69
	v_rndne_f32_e32 v68, v68
	v_mul_f32_e32 v67, v83, v67
	v_cvt_i32_f32_sdwa v72, v72 dst_sel:WORD_1 dst_unused:UNUSED_PAD src0_sel:DWORD
	v_rndne_f32_e32 v71, v71
	v_cvt_i32_f32_e32 v7, v7
	v_cvt_i32_f32_sdwa v68, v68 dst_sel:WORD_1 dst_unused:UNUSED_PAD src0_sel:DWORD
	v_rndne_f32_e32 v67, v67
	v_cvt_i32_f32_sdwa v71, v71 dst_sel:BYTE_3 dst_unused:UNUSED_PAD src0_sel:DWORD
	v_cvt_i32_f32_sdwa v67, v67 dst_sel:BYTE_3 dst_unused:UNUSED_PAD src0_sel:DWORD
	v_lshlrev_b32_e32 v69, 8, v69
	v_and_b32_e32 v72, 0xff0000, v72
	v_and_b32_e32 v68, 0xff0000, v68
	v_perm_b32 v7, v69, v7, s26
	v_or3_b32 v6, v6, v71, v72
	v_or3_b32 v7, v7, v67, v68
	global_store_dwordx2 v[4:5], v[6:7], off offset:512
	v_mul_f32_e32 v7, v83, v64
	v_mul_f32_e32 v6, v83, v66
	v_rndne_f32_e32 v7, v7
	v_rndne_f32_e32 v6, v6
	v_cvt_i32_f32_e32 v7, v7
	v_cvt_i32_f32_e32 v6, v6
	v_mul_f32_e32 v61, v83, v61
	v_mul_f32_e32 v64, v83, v65
	v_lshlrev_b32_e32 v7, 8, v7
	v_perm_b32 v6, v7, v6, s26
	v_mul_f32_e32 v7, v83, v62
	v_rndne_f32_e32 v61, v61
	v_mul_f32_e32 v60, v83, v60
	v_rndne_f32_e32 v64, v64
	v_mul_f32_e32 v63, v83, v63
	v_rndne_f32_e32 v7, v7
	v_cvt_i32_f32_e32 v61, v61
	v_rndne_f32_e32 v60, v60
	v_mul_f32_e32 v59, v83, v59
	v_cvt_i32_f32_sdwa v64, v64 dst_sel:WORD_1 dst_unused:UNUSED_PAD src0_sel:DWORD
	v_rndne_f32_e32 v63, v63
	v_cvt_i32_f32_e32 v7, v7
	v_cvt_i32_f32_sdwa v60, v60 dst_sel:WORD_1 dst_unused:UNUSED_PAD src0_sel:DWORD
	v_rndne_f32_e32 v59, v59
	v_cvt_i32_f32_sdwa v63, v63 dst_sel:BYTE_3 dst_unused:UNUSED_PAD src0_sel:DWORD
	v_cvt_i32_f32_sdwa v59, v59 dst_sel:BYTE_3 dst_unused:UNUSED_PAD src0_sel:DWORD
	v_lshlrev_b32_e32 v61, 8, v61
	v_and_b32_e32 v64, 0xff0000, v64
	v_and_b32_e32 v60, 0xff0000, v60
	v_perm_b32 v7, v61, v7, s26
	v_or3_b32 v6, v6, v63, v64
	v_or3_b32 v7, v7, v59, v60
	global_store_dwordx2 v[4:5], v[6:7], off offset:1024
	v_mul_f32_e32 v7, v83, v56
	v_mul_f32_e32 v6, v83, v58
	v_rndne_f32_e32 v7, v7
	v_rndne_f32_e32 v6, v6
	v_cvt_i32_f32_e32 v7, v7
	v_cvt_i32_f32_e32 v6, v6
	v_mul_f32_e32 v53, v83, v53
	v_mul_f32_e32 v56, v83, v57
	v_lshlrev_b32_e32 v7, 8, v7
	v_perm_b32 v6, v7, v6, s26
	v_mul_f32_e32 v7, v83, v54
	v_rndne_f32_e32 v53, v53
	v_mul_f32_e32 v52, v83, v52
	v_rndne_f32_e32 v56, v56
	v_mul_f32_e32 v55, v83, v55
	v_rndne_f32_e32 v7, v7
	v_cvt_i32_f32_e32 v53, v53
	v_rndne_f32_e32 v52, v52
	v_mul_f32_e32 v51, v83, v51
	v_cvt_i32_f32_sdwa v56, v56 dst_sel:WORD_1 dst_unused:UNUSED_PAD src0_sel:DWORD
	v_rndne_f32_e32 v55, v55
	v_cvt_i32_f32_e32 v7, v7
	v_cvt_i32_f32_sdwa v52, v52 dst_sel:WORD_1 dst_unused:UNUSED_PAD src0_sel:DWORD
	v_rndne_f32_e32 v51, v51
	v_cvt_i32_f32_sdwa v55, v55 dst_sel:BYTE_3 dst_unused:UNUSED_PAD src0_sel:DWORD
	v_cvt_i32_f32_sdwa v51, v51 dst_sel:BYTE_3 dst_unused:UNUSED_PAD src0_sel:DWORD
	v_lshlrev_b32_e32 v53, 8, v53
; __device__ __forceinline__ float bflo(unsigned w) { return __uint_as_float(w << 16); }
; __device__ __forceinline__ float bfhi(unsigned w) { return __uint_as_float(w & 0xffff0000u); }
; __device__ __forceinline__ void quant_store8(const u32x4 (&w)[8], float inv, signed char* dst, int lane) { u32x2* qp = (u32x2*)dst + lane;
; #pragma unroll
;     for (int j = 0; j < 8; ++j) { const unsigned ww[4] = {w[j].x, w[j].y, w[j].z, w[j].w}; unsigned o2[2];
; #pragma unroll
;         for (int h2 = 0; h2 < 2; ++h2) { const int q0 = (int)rintf(bflo(ww[2 * h2]) * inv), q1 = (int)rintf(bfhi(ww[2 * h2]) * inv), q2 = (int)rintf(bflo(ww[2 * h2 + 1]) * inv), q3 = (int)rintf(bfhi(ww[2 * h2 + 1]) * inv);
;             o2[h2] = (unsigned)(q0 & 255) | ((unsigned)(q1 & 255) << 8) | ((unsigned)(q2 & 255) << 16) | ((unsigned)(q3 & 255) << 24); }
;         u32x2 o; o.x = o2[0]; o.y = o2[1]; qp[64 * j] = o; } }
; __global__ void __launch_bounds__(NWAVES * 64, 2) fwd(Args args) {
;     ...
;             for (int p = 0; p < 4; ++p) { const int n = 64 * bx + 8 * F.wave + 2 * p; float s0, s1;
;                 quant_rows2(W_inT + (size_t)(IN_Q0 + n) * DM, W_inT + (size_t)(IN_Q0 + n + 1) * DM, W_inq + (size_t)n * DM, W_inq + (size_t)(n + 1) * DM, F.lane, s0, s1);
;                 if (F.lane == 0) { colq[n] = s0; colq[n + 1] = s1; } }
	v_and_b32_e32 v56, 0xff0000, v56
	v_and_b32_e32 v52, 0xff0000, v52
	v_perm_b32 v7, v53, v7, s26
	v_or3_b32 v6, v6, v55, v56
	v_or3_b32 v7, v7, v51, v52
	global_store_dwordx2 v[4:5], v[6:7], off offset:1536
	v_mul_f32_e32 v7, v83, v48
	v_mul_f32_e32 v6, v83, v50
	v_rndne_f32_e32 v7, v7
	v_rndne_f32_e32 v6, v6
	v_cvt_i32_f32_e32 v7, v7
	v_cvt_i32_f32_e32 v6, v6
	v_mul_f32_e32 v45, v83, v45
	v_mul_f32_e32 v48, v83, v49
	v_lshlrev_b32_e32 v7, 8, v7
	v_perm_b32 v6, v7, v6, s26
	v_mul_f32_e32 v7, v83, v46
	v_rndne_f32_e32 v45, v45
	v_mul_f32_e32 v44, v83, v44
	v_rndne_f32_e32 v48, v48
	v_mul_f32_e32 v47, v83, v47
	v_rndne_f32_e32 v7, v7
	v_cvt_i32_f32_e32 v45, v45
	v_rndne_f32_e32 v44, v44
	v_mul_f32_e32 v43, v83, v43
	v_cvt_i32_f32_sdwa v48, v48 dst_sel:WORD_1 dst_unused:UNUSED_PAD src0_sel:DWORD
	v_rndne_f32_e32 v47, v47
	v_cvt_i32_f32_e32 v7, v7
	v_cvt_i32_f32_sdwa v44, v44 dst_sel:WORD_1 dst_unused:UNUSED_PAD src0_sel:DWORD
	v_rndne_f32_e32 v43, v43
	v_cvt_i32_f32_sdwa v47, v47 dst_sel:BYTE_3 dst_unused:UNUSED_PAD src0_sel:DWORD
	v_cvt_i32_f32_sdwa v43, v43 dst_sel:BYTE_3 dst_unused:UNUSED_PAD src0_sel:DWORD
	v_lshlrev_b32_e32 v45, 8, v45
	v_and_b32_e32 v48, 0xff0000, v48
	v_and_b32_e32 v44, 0xff0000, v44
	v_perm_b32 v7, v45, v7, s26
	v_or3_b32 v6, v6, v47, v48
	v_or3_b32 v7, v7, v43, v44
	global_store_dwordx2 v[4:5], v[6:7], off offset:2048
	v_mul_f32_e32 v7, v83, v29
	v_mul_f32_e32 v6, v83, v42
	v_rndne_f32_e32 v7, v7
	v_rndne_f32_e32 v6, v6
	v_cvt_i32_f32_e32 v7, v7
	v_cvt_i32_f32_e32 v6, v6
	v_mul_f32_e32 v26, v83, v26
	v_mul_f32_e32 v29, v83, v41
	v_lshlrev_b32_e32 v7, 8, v7
	v_perm_b32 v6, v7, v6, s26
	v_mul_f32_e32 v7, v83, v27
	v_rndne_f32_e32 v26, v26
	v_mul_f32_e32 v25, v83, v25
	v_rndne_f32_e32 v29, v29
	v_mul_f32_e32 v28, v83, v28
	v_rndne_f32_e32 v7, v7
	v_cvt_i32_f32_e32 v26, v26
	v_rndne_f32_e32 v25, v25
	v_mul_f32_e32 v24, v83, v24
	v_cvt_i32_f32_sdwa v29, v29 dst_sel:WORD_1 dst_unused:UNUSED_PAD src0_sel:DWORD
	v_rndne_f32_e32 v28, v28
	v_cvt_i32_f32_e32 v7, v7
	v_cvt_i32_f32_sdwa v25, v25 dst_sel:WORD_1 dst_unused:UNUSED_PAD src0_sel:DWORD
	v_rndne_f32_e32 v24, v24
	v_cvt_i32_f32_sdwa v28, v28 dst_sel:BYTE_3 dst_unused:UNUSED_PAD src0_sel:DWORD
	v_cvt_i32_f32_sdwa v24, v24 dst_sel:BYTE_3 dst_unused:UNUSED_PAD src0_sel:DWORD
	v_lshlrev_b32_e32 v26, 8, v26
	v_and_b32_e32 v29, 0xff0000, v29
	v_and_b32_e32 v25, 0xff0000, v25
	v_perm_b32 v7, v26, v7, s26
	v_or3_b32 v6, v6, v28, v29
	v_or3_b32 v7, v7, v24, v25
	global_store_dwordx2 v[4:5], v[6:7], off offset:2560
	v_mul_f32_e32 v7, v83, v21
	v_mul_f32_e32 v6, v83, v23
	v_rndne_f32_e32 v7, v7
	v_rndne_f32_e32 v6, v6
	v_cvt_i32_f32_e32 v7, v7
	v_cvt_i32_f32_e32 v6, v6
	v_mul_f32_e32 v18, v83, v18
	v_mul_f32_e32 v21, v83, v22
	v_lshlrev_b32_e32 v7, 8, v7
	v_perm_b32 v6, v7, v6, s26
	v_mul_f32_e32 v7, v83, v19
	v_rndne_f32_e32 v18, v18
	v_mul_f32_e32 v17, v83, v17
	v_rndne_f32_e32 v21, v21
	v_mul_f32_e32 v20, v83, v20
	v_rndne_f32_e32 v7, v7
	v_cvt_i32_f32_e32 v18, v18
	v_rndne_f32_e32 v17, v17
	v_mul_f32_e32 v16, v83, v16
	v_cvt_i32_f32_sdwa v21, v21 dst_sel:WORD_1 dst_unused:UNUSED_PAD src0_sel:DWORD
	v_rndne_f32_e32 v20, v20
	v_cvt_i32_f32_e32 v7, v7
	v_cvt_i32_f32_sdwa v17, v17 dst_sel:WORD_1 dst_unused:UNUSED_PAD src0_sel:DWORD
	v_rndne_f32_e32 v16, v16
	v_cvt_i32_f32_sdwa v20, v20 dst_sel:BYTE_3 dst_unused:UNUSED_PAD src0_sel:DWORD
	v_cvt_i32_f32_sdwa v16, v16 dst_sel:BYTE_3 dst_unused:UNUSED_PAD src0_sel:DWORD
	v_lshlrev_b32_e32 v18, 8, v18
	v_and_b32_e32 v21, 0xff0000, v21
	v_and_b32_e32 v17, 0xff0000, v17
	v_perm_b32 v7, v18, v7, s26
	v_or3_b32 v6, v6, v20, v21
	v_or3_b32 v7, v7, v16, v17
	global_store_dwordx2 v[4:5], v[6:7], off offset:3072
	v_mul_f32_e32 v7, v83, v13
	v_mul_f32_e32 v6, v83, v15
	v_rndne_f32_e32 v7, v7
	v_rndne_f32_e32 v6, v6
	v_cvt_i32_f32_e32 v7, v7
	v_cvt_i32_f32_e32 v6, v6
	v_mul_f32_e32 v10, v83, v10
	v_mul_f32_e32 v13, v83, v14
	v_lshlrev_b32_e32 v7, 8, v7
	v_perm_b32 v6, v7, v6, s26
	v_mul_f32_e32 v7, v83, v11
	v_rndne_f32_e32 v10, v10
	v_mul_f32_e32 v9, v83, v9
	v_rndne_f32_e32 v13, v13
	v_mul_f32_e32 v12, v83, v12
	v_rndne_f32_e32 v7, v7
	v_cvt_i32_f32_e32 v10, v10
	v_rndne_f32_e32 v9, v9
	v_mul_f32_e32 v8, v83, v8
	v_cvt_i32_f32_sdwa v13, v13 dst_sel:WORD_1 dst_unused:UNUSED_PAD src0_sel:DWORD
	v_rndne_f32_e32 v12, v12
	v_cvt_i32_f32_e32 v7, v7
	v_cvt_i32_f32_sdwa v9, v9 dst_sel:WORD_1 dst_unused:UNUSED_PAD src0_sel:DWORD
	v_rndne_f32_e32 v8, v8
	v_cvt_i32_f32_sdwa v12, v12 dst_sel:BYTE_3 dst_unused:UNUSED_PAD src0_sel:DWORD
	v_cvt_i32_f32_sdwa v8, v8 dst_sel:BYTE_3 dst_unused:UNUSED_PAD src0_sel:DWORD
	v_lshlrev_b32_e32 v10, 8, v10
	v_and_b32_e32 v13, 0xff0000, v13
	v_and_b32_e32 v9, 0xff0000, v9
	v_perm_b32 v7, v10, v7, s26
	v_or3_b32 v6, v6, v12, v13
	v_or3_b32 v7, v7, v8, v9
	global_store_dwordx2 v[4:5], v[6:7], off offset:3584
	s_and_saveexec_b64 s[10:11], s[4:5]
	s_cbranch_execz .LBB0_159
	s_add_u32 s30, s78, s7
	s_addc_u32 s31, s79, s12
	global_store_dwordx2 v40, v[2:3], s[30:31]
	s_branch .LBB0_159

; __device__ __forceinline__ float bflo(unsigned w) { return __uint_as_float(w << 16); }
; __device__ __forceinline__ float bfhi(unsigned w) { return __uint_as_float(w & 0xffff0000u); }
; #pragma unroll
;     for (int j = 0; j < 8; ++j) mx = fmaxf(mx, fmaxf(fmaxf(fmaxf(fabsf(bflo(w[j].x)), fabsf(bfhi(w[j].x))), fmaxf(fabsf(bflo(w[j].y)), fabsf(bfhi(w[j].y)))), fmaxf(fmaxf(fabsf(bflo(w[j].z)), fabsf(bfhi(w[j].z))), fmaxf(fabsf(bflo(w[j].w)), fabsf(bfhi(w[j].w))))));
; #pragma unroll
;     for (int o = 1; o < 64; o <<= 1) mx = fmaxf(mx, __shfl_xor(mx, o));
;     return mx; }
; __device__ __forceinline__ void quant_store8(const u32x4 (&w)[8], float inv, signed char* dst, int lane) { u32x2* qp = (u32x2*)dst + lane;
; #pragma unroll
;     for (int j = 0; j < 8; ++j) { const unsigned ww[4] = {w[j].x, w[j].y, w[j].z, w[j].w}; unsigned o2[2];
; #pragma unroll
;         for (int h2 = 0; h2 < 2; ++h2) { const int q0 = (int)rintf(bflo(ww[2 * h2]) * inv), q1 = (int)rintf(bfhi(ww[2 * h2]) * inv), q2 = (int)rintf(bflo(ww[2 * h2 + 1]) * inv), q3 = (int)rintf(bfhi(ww[2 * h2 + 1]) * inv);
;             o2[h2] = (unsigned)(q0 & 255) | ((unsigned)(q1 & 255) << 8) | ((unsigned)(q2 & 255) << 16) | ((unsigned)(q3 & 255) << 24); }
;         u32x2 o; o.x = o2[0]; o.y = o2[1]; qp[64 * j] = o; } }
; __device__ __forceinline__ void quant_rows2(const bf16_t* s0, const bf16_t* s1, signed char* d0, signed char* d1, int lane, float& step0, float& step1) {
;     const u32x4* p0 = (const u32x4*)s0 + lane; const u32x4* p1 = (const u32x4*)s1 + lane; u32x4 w0[8], w1[8];
; #pragma unroll
;     for (int j = 0; j < 8; ++j) { w0[j] = p0[64 * j]; w1[j] = p1[64 * j]; }
;     step0 = fmaxf(absmax8(w0), 1e-30f) * (1.0f / 127.0f); step1 = fmaxf(absmax8(w1), 1e-30f) * (1.0f / 127.0f);
.LBB0_272:
	v_lshl_add_u64 v[2:3], s[78:79], 0, v[30:31]
	v_add_co_u32_e32 v4, vcc, 0x10800000, v2
	s_nop 1
	v_addc_co_u32_e32 v5, vcc, 0, v3, vcc
	global_load_dwordx4 v[42:45], v[4:5], off
	global_load_dwordx4 v[46:49], v[4:5], off offset:1024
	global_load_dwordx4 v[50:53], v[4:5], off offset:2048
	global_load_dwordx4 v[54:57], v[4:5], off offset:3072
	v_add_co_u32_e32 v6, vcc, 0x10802000, v2
	s_waitcnt vmcnt(3)
	v_lshlrev_b32_e32 v83, 16, v42
	v_addc_co_u32_e32 v7, vcc, 0, v3, vcc
	v_add_co_u32_e32 v4, vcc, s23, v2
	global_load_dwordx4 v[58:61], v[6:7], off
	global_load_dwordx4 v[26:29], v[6:7], off offset:1024
	global_load_dwordx4 v[22:25], v[6:7], off offset:2048
	global_load_dwordx4 v[18:21], v[6:7], off offset:3072
	v_addc_co_u32_e32 v5, vcc, 0, v3, vcc
	v_add_co_u32_e32 v2, vcc, s24, v2
	v_and_b32_e32 v84, 0xffff0000, v42
	s_nop 0
	v_addc_co_u32_e32 v3, vcc, 0, v3, vcc
	global_load_dwordx4 v[62:65], v[4:5], off
	global_load_dwordx4 v[66:69], v[4:5], off offset:1024
	global_load_dwordx4 v[70:73], v[4:5], off offset:2048
	global_load_dwordx4 v[74:77], v[4:5], off offset:3072
	global_load_dwordx4 v[14:17], v[2:3], off
	global_load_dwordx4 v[10:13], v[2:3], off offset:1024
	global_load_dwordx4 v[6:9], v[2:3], off offset:2048
	s_nop 0
	global_load_dwordx4 v[2:5], v[2:3], off offset:3072
	v_lshlrev_b32_e32 v85, 16, v43
	v_and_b32_e32 v86, 0xffff0000, v43
	v_lshlrev_b32_e32 v89, 16, v45
	v_and_b32_e32 v90, 0xffff0000, v45
	s_waitcnt vmcnt(14)
	v_lshlrev_b32_e32 v97, 16, v49
	v_and_b32_e32 v98, 0xffff0000, v49
	v_lshlrev_b32_e32 v87, 16, v44
	v_and_b32_e32 v88, 0xffff0000, v44
	v_lshlrev_b32_e32 v91, 16, v46
	v_and_b32_e32 v92, 0xffff0000, v46
	v_lshlrev_b32_e32 v93, 16, v47
	v_and_b32_e32 v94, 0xffff0000, v47
	s_waitcnt vmcnt(13)
	v_lshlrev_b32_e32 v101, 16, v51
	v_and_b32_e32 v102, 0xffff0000, v51
	v_lshlrev_b32_e32 v103, 16, v52
	v_and_b32_e32 v104, 0xffff0000, v52
	v_max_f32_e64 v41, |v84|, |v84|
	v_max_f32_e64 v42, |v83|, |v83|
	v_max_f32_e64 v43, |v86|, |v86|
	v_max_f32_e64 v44, |v85|, |v85|
	v_max_f32_e64 v45, |v90|, |v90|
	v_max_f32_e64 v46, |v89|, |v89|
	v_max_f32_e64 v51, |v98|, |v98|
	v_max_f32_e64 v52, |v97|, |v97|
	v_lshlrev_b32_e32 v95, 16, v48
	v_and_b32_e32 v96, 0xffff0000, v48
	v_lshlrev_b32_e32 v99, 16, v50
	v_and_b32_e32 v100, 0xffff0000, v50
	v_max_f32_e64 v47, |v92|, |v92|
	v_max_f32_e64 v48, |v91|, |v91|
	v_max_f32_e64 v49, |v94|, |v94|
	v_max_f32_e64 v50, |v93|, |v93|
	v_max_f32_e32 v41, v42, v41
	v_max_f32_e32 v42, v44, v43
	v_max_f32_e32 v43, v46, v45
	v_max_f32_e32 v46, v52, v51
	v_max_f32_e32 v44, v48, v47
	v_max_f32_e32 v45, v50, v49
	v_max3_f32 v43, |v87|, |v88|, v43
	v_max3_f32 v46, |v95|, |v96|, v46
	v_lshlrev_b32_e32 v105, 16, v53
	v_max3_f32 v41, v41, v42, v43
	v_max3_f32 v42, v44, v45, v46
	v_and_b32_e32 v106, 0xffff0000, v53
	v_max3_f32 v41, v41, 0, v42
	v_max_f32_e64 v42, |v106|, |v106|
	v_max_f32_e64 v43, |v105|, |v105|
	s_waitcnt vmcnt(12)
	v_lshlrev_b32_e32 v107, 16, v54
	v_and_b32_e32 v108, 0xffff0000, v54
	v_max_f32_e32 v42, v43, v42
	v_max_f32_e64 v43, |v108|, |v108|
	v_max_f32_e64 v44, |v107|, |v107|
	v_lshlrev_b32_e32 v109, 16, v55
	v_and_b32_e32 v110, 0xffff0000, v55
	v_max_f32_e32 v43, v44, v43
	v_max_f32_e64 v44, |v110|, |v110|
	v_max_f32_e64 v45, |v109|, |v109|
	v_lshlrev_b32_e32 v113, 16, v57
	v_and_b32_e32 v114, 0xffff0000, v57
	v_max_f32_e32 v44, v45, v44
	v_max_f32_e64 v45, |v114|, |v114|
	v_max_f32_e64 v46, |v113|, |v113|
	v_max_f32_e64 v78, |v100|, |v100|
	v_max_f32_e64 v79, |v99|, |v99|
	v_max_f32_e64 v80, |v102|, |v102|
	v_max_f32_e64 v81, |v101|, |v101|
	v_lshlrev_b32_e32 v111, 16, v56
	v_and_b32_e32 v112, 0xffff0000, v56
	v_max_f32_e32 v45, v46, v45
	v_max_f32_e32 v47, v79, v78
	v_max_f32_e32 v48, v81, v80
	v_max3_f32 v42, |v103|, |v104|, v42
	v_max3_f32 v45, |v111|, |v112|, v45
	v_max3_f32 v42, v47, v48, v42
	v_max3_f32 v43, v43, v44, v45
	s_waitcnt vmcnt(7)
	v_lshlrev_b32_e32 v115, 16, v62
	v_and_b32_e32 v116, 0xffff0000, v62
	v_max3_f32 v41, v41, v42, v43
	v_max_f32_e64 v42, |v116|, |v116|
	v_max_f32_e64 v43, |v115|, |v115|
	v_lshlrev_b32_e32 v117, 16, v63
	v_and_b32_e32 v118, 0xffff0000, v63
	v_max_f32_e32 v42, v43, v42
	v_max_f32_e64 v43, |v118|, |v118|
	v_max_f32_e64 v44, |v117|, |v117|
	v_lshlrev_b32_e32 v121, 16, v65
	v_and_b32_e32 v122, 0xffff0000, v65
	v_max_f32_e32 v43, v44, v43
	v_max_f32_e64 v44, |v122|, |v122|
	v_max_f32_e64 v45, |v121|, |v121|
	v_lshlrev_b32_e32 v119, 16, v64
	v_and_b32_e32 v120, 0xffff0000, v64
	v_max_f32_e32 v44, v45, v44
	v_max3_f32 v44, |v119|, |v120|, v44
	s_waitcnt vmcnt(6)
	v_lshlrev_b32_e32 v123, 16, v66
	v_and_b32_e32 v124, 0xffff0000, v66
	v_max3_f32 v42, v42, v43, v44
	v_max_f32_e64 v43, |v124|, |v124|
	v_max_f32_e64 v44, |v123|, |v123|
	v_lshlrev_b32_e32 v125, 16, v67
	v_and_b32_e32 v126, 0xffff0000, v67
	v_max_f32_e32 v43, v44, v43
	v_max_f32_e64 v44, |v126|, |v126|
	v_max_f32_e64 v45, |v125|, |v125|
	v_lshlrev_b32_e32 v129, 16, v69
	v_and_b32_e32 v130, 0xffff0000, v69
	v_max_f32_e32 v44, v45, v44
	v_max_f32_e64 v45, |v130|, |v130|
	v_max_f32_e64 v46, |v129|, |v129|
	v_lshlrev_b32_e32 v127, 16, v68
	v_and_b32_e32 v128, 0xffff0000, v68
	v_max_f32_e32 v45, v46, v45
	v_max3_f32 v45, |v127|, |v128|, v45
	v_max3_f32 v43, v43, v44, v45
	s_waitcnt vmcnt(5)
	v_lshlrev_b32_e32 v131, 16, v70
	v_and_b32_e32 v132, 0xffff0000, v70
	v_max3_f32 v41, v41, v42, v43
	v_max_f32_e64 v42, |v132|, |v132|
	v_max_f32_e64 v43, |v131|, |v131|
	v_lshlrev_b32_e32 v133, 16, v71
	v_and_b32_e32 v137, 0xffff0000, v71
	v_max_f32_e32 v42, v43, v42
	v_max_f32_e64 v43, |v137|, |v137|
	v_max_f32_e64 v44, |v133|, |v133|
	v_lshlrev_b32_e32 v140, 16, v73
	v_and_b32_e32 v141, 0xffff0000, v73
	v_max_f32_e32 v43, v44, v43
	v_max_f32_e64 v44, |v141|, |v141|
	v_max_f32_e64 v45, |v140|, |v140|
	v_lshlrev_b32_e32 v138, 16, v72
	v_and_b32_e32 v139, 0xffff0000, v72
	v_max_f32_e32 v44, v45, v44
	v_max3_f32 v44, |v138|, |v139|, v44
	s_waitcnt vmcnt(4)
; __device__ __forceinline__ float bflo(unsigned w) { return __uint_as_float(w << 16); }
; __device__ __forceinline__ float bfhi(unsigned w) { return __uint_as_float(w & 0xffff0000u); }
; #pragma unroll
;     for (int j = 0; j < 8; ++j) mx = fmaxf(mx, fmaxf(fmaxf(fmaxf(fabsf(bflo(w[j].x)), fabsf(bfhi(w[j].x))), fmaxf(fabsf(bflo(w[j].y)), fabsf(bfhi(w[j].y)))), fmaxf(fmaxf(fabsf(bflo(w[j].z)), fabsf(bfhi(w[j].z))), fmaxf(fabsf(bflo(w[j].w)), fabsf(bfhi(w[j].w))))));
; #pragma unroll
;     for (int o = 1; o < 64; o <<= 1) mx = fmaxf(mx, __shfl_xor(mx, o));
;     return mx; }
	v_lshlrev_b32_e32 v142, 16, v74
	v_and_b32_e32 v143, 0xffff0000, v74
	v_max3_f32 v42, v42, v43, v44
	v_max_f32_e64 v43, |v143|, |v143|
	v_max_f32_e64 v44, |v142|, |v142|
	v_lshlrev_b32_e32 v144, 16, v75
	v_and_b32_e32 v145, 0xffff0000, v75
	v_max_f32_e32 v43, v44, v43
	v_max_f32_e64 v44, |v145|, |v145|
	v_max_f32_e64 v45, |v144|, |v144|
	v_lshlrev_b32_e32 v148, 16, v77
	v_and_b32_e32 v149, 0xffff0000, v77
	v_max_f32_e32 v44, v45, v44
	v_max_f32_e64 v45, |v149|, |v149|
	v_max_f32_e64 v46, |v148|, |v148|
	v_lshlrev_b32_e32 v146, 16, v76
	v_and_b32_e32 v147, 0xffff0000, v76
	v_max_f32_e32 v45, v46, v45
	v_max3_f32 v45, |v146|, |v147|, v45
	v_max3_f32 v43, v43, v44, v45
	v_lshlrev_b32_e32 v82, 16, v58
	v_and_b32_e32 v80, 0xffff0000, v58
	v_max3_f32 v157, v41, v42, v43
	v_max_f32_e64 v41, |v80|, |v80|
	v_max_f32_e64 v42, |v82|, |v82|
	v_lshlrev_b32_e32 v81, 16, v59
	v_and_b32_e32 v79, 0xffff0000, v59
	v_max_f32_e32 v41, v42, v41
	v_max_f32_e64 v42, |v79|, |v79|
	v_max_f32_e64 v43, |v81|, |v81|
	v_lshlrev_b32_e32 v76, 16, v61
	v_and_b32_e32 v75, 0xffff0000, v61
	v_max_f32_e32 v42, v43, v42
	v_max_f32_e64 v43, |v75|, |v75|
	v_max_f32_e64 v44, |v76|, |v76|
	v_lshlrev_b32_e32 v78, 16, v60
	v_and_b32_e32 v77, 0xffff0000, v60
	v_max_f32_e32 v43, v44, v43
	v_max3_f32 v43, |v78|, |v77|, v43
	v_lshlrev_b32_e32 v74, 16, v26
	v_and_b32_e32 v72, 0xffff0000, v26
	v_lshlrev_b32_e32 v68, 16, v29
	v_and_b32_e32 v67, 0xffff0000, v29
	v_max3_f32 v41, v41, v42, v43
	v_max_f32_e64 v26, |v72|, |v72|
	v_max_f32_e64 v42, |v74|, |v74|
	v_lshlrev_b32_e32 v73, 16, v27
	v_and_b32_e32 v71, 0xffff0000, v27
	v_lshlrev_b32_e32 v70, 16, v28
	v_and_b32_e32 v69, 0xffff0000, v28
	v_max_f32_e64 v28, |v67|, |v67|
	v_max_f32_e64 v29, |v68|, |v68|
	v_max_f32_e32 v26, v42, v26
	v_max_f32_e64 v27, |v71|, |v71|
	v_max_f32_e64 v42, |v73|, |v73|
	v_max_f32_e32 v28, v29, v28
	v_max_f32_e32 v27, v42, v27
	v_max3_f32 v28, |v70|, |v69|, v28
	v_lshlrev_b32_e32 v66, 16, v22
	v_and_b32_e32 v64, 0xffff0000, v22
	v_lshlrev_b32_e32 v60, 16, v25
	v_and_b32_e32 v59, 0xffff0000, v25
	v_max3_f32 v26, v26, v27, v28
	v_max_f32_e64 v22, |v64|, |v64|
	v_max_f32_e64 v27, |v66|, |v66|
	v_lshlrev_b32_e32 v65, 16, v23
	v_and_b32_e32 v63, 0xffff0000, v23
	v_lshlrev_b32_e32 v62, 16, v24
	v_and_b32_e32 v61, 0xffff0000, v24
	v_max_f32_e64 v24, |v59|, |v59|
	v_max_f32_e64 v25, |v60|, |v60|
	v_max_f32_e32 v22, v27, v22
	v_max_f32_e64 v23, |v63|, |v63|
	v_max_f32_e64 v27, |v65|, |v65|
	v_max_f32_e32 v24, v25, v24
	v_max_f32_e32 v23, v27, v23
	v_max3_f32 v24, |v62|, |v61|, v24
	v_lshlrev_b32_e32 v58, 16, v18
	v_and_b32_e32 v56, 0xffff0000, v18
	v_lshlrev_b32_e32 v52, 16, v21
	v_and_b32_e32 v51, 0xffff0000, v21
	v_max3_f32 v22, v22, v23, v24
	v_max_f32_e64 v18, |v56|, |v56|
	v_max_f32_e64 v23, |v58|, |v58|
	v_lshlrev_b32_e32 v57, 16, v19
	v_and_b32_e32 v55, 0xffff0000, v19
	v_lshlrev_b32_e32 v54, 16, v20
	v_and_b32_e32 v53, 0xffff0000, v20
	v_max_f32_e64 v20, |v51|, |v51|
	v_max_f32_e64 v21, |v52|, |v52|
	v_max_f32_e32 v18, v23, v18
	v_max_f32_e64 v19, |v55|, |v55|
	v_max_f32_e64 v23, |v57|, |v57|
	v_max_f32_e32 v20, v21, v20
	v_max_f32_e32 v19, v23, v19
	v_max3_f32 v20, |v54|, |v53|, v20
	s_waitcnt vmcnt(3)
	v_lshlrev_b32_e32 v50, 16, v14
	v_and_b32_e32 v48, 0xffff0000, v14
	v_lshlrev_b32_e32 v44, 16, v17
	v_and_b32_e32 v43, 0xffff0000, v17
	v_max3_f32 v18, v18, v19, v20
	v_max_f32_e64 v14, |v48|, |v48|
	v_max_f32_e64 v19, |v50|, |v50|
	v_lshlrev_b32_e32 v49, 16, v15
	v_and_b32_e32 v47, 0xffff0000, v15
	v_lshlrev_b32_e32 v46, 16, v16
	v_and_b32_e32 v45, 0xffff0000, v16
	v_max_f32_e64 v16, |v43|, |v43|
	v_max_f32_e64 v17, |v44|, |v44|
	v_max_f32_e32 v14, v19, v14
	v_max_f32_e64 v15, |v47|, |v47|
	v_max_f32_e64 v19, |v49|, |v49|
	v_max_f32_e32 v16, v17, v16
	v_max3_f32 v26, v41, 0, v26
	v_max_f32_e32 v15, v19, v15
	v_max3_f32 v16, |v46|, |v45|, v16
	s_waitcnt vmcnt(2)
	v_lshlrev_b32_e32 v42, 16, v10
	v_and_b32_e32 v29, 0xffff0000, v10
	v_lshlrev_b32_e32 v25, 16, v13
	v_and_b32_e32 v24, 0xffff0000, v13
	v_max3_f32 v18, v26, v22, v18
	v_max3_f32 v14, v14, v15, v16
	v_max_f32_e64 v10, |v29|, |v29|
	v_max_f32_e64 v15, |v42|, |v42|
	v_lshlrev_b32_e32 v41, 16, v11
	v_and_b32_e32 v28, 0xffff0000, v11
	v_lshlrev_b32_e32 v27, 16, v12
	v_and_b32_e32 v26, 0xffff0000, v12
	v_max_f32_e64 v12, |v24|, |v24|
	v_max_f32_e64 v13, |v25|, |v25|
	v_max_f32_e32 v10, v15, v10
	v_max_f32_e64 v11, |v28|, |v28|
	v_max_f32_e64 v15, |v41|, |v41|
	v_max_f32_e32 v12, v13, v12
	v_max_f32_e32 v11, v15, v11
	v_max3_f32 v12, |v27|, |v26|, v12
	v_max3_f32 v10, v10, v11, v12
	s_waitcnt vmcnt(1)
	v_lshlrev_b32_e32 v23, 16, v6
	v_and_b32_e32 v21, 0xffff0000, v6
	v_lshlrev_b32_e32 v17, 16, v9
	v_and_b32_e32 v16, 0xffff0000, v9
	v_max3_f32 v160, v18, v14, v10
	v_max_f32_e64 v6, |v21|, |v21|
	v_max_f32_e64 v10, |v23|, |v23|
	v_lshlrev_b32_e32 v22, 16, v7
	v_and_b32_e32 v20, 0xffff0000, v7
	v_lshlrev_b32_e32 v19, 16, v8
	v_and_b32_e32 v18, 0xffff0000, v8
	v_max_f32_e64 v8, |v16|, |v16|
	v_max_f32_e64 v9, |v17|, |v17|
	v_max_f32_e32 v6, v10, v6
	v_max_f32_e64 v7, |v20|, |v20|
	v_max_f32_e64 v10, |v22|, |v22|
	v_max_f32_e32 v8, v9, v8
	v_max_f32_e32 v7, v10, v7
	v_max3_f32 v8, |v19|, |v18|, v8
	v_max3_f32 v6, v6, v7, v8
	s_waitcnt vmcnt(0)
	v_lshlrev_b32_e32 v15, 16, v2
	v_and_b32_e32 v13, 0xffff0000, v2
	v_lshlrev_b32_e32 v9, 16, v5
	v_and_b32_e32 v8, 0xffff0000, v5
	v_max_f32_e64 v2, |v13|, |v13|
	v_max_f32_e64 v7, |v15|, |v15|
	v_lshlrev_b32_e32 v14, 16, v3
	v_and_b32_e32 v12, 0xffff0000, v3
	v_lshlrev_b32_e32 v11, 16, v4
	v_and_b32_e32 v10, 0xffff0000, v4
	v_max_f32_e64 v4, |v8|, |v8|
	v_max_f32_e64 v5, |v9|, |v9|
	v_max_f32_e32 v2, v7, v2
	v_max_f32_e64 v3, |v12|, |v12|
	v_max_f32_e64 v7, |v14|, |v14|
	v_max_f32_e32 v4, v5, v4
	v_max_f32_e32 v3, v7, v3
	v_max3_f32 v4, |v11|, |v10|, v4
	v_max3_f32 v2, v2, v3, v4
	v_max3_f32 v2, v160, v6, v2
	s_nop 1
	v_mov_b32_dpp v158, v157 quad_perm:[1,0,3,2] row_mask:0xf bank_mask:0xf
	s_nop 1
	v_mov_b32_dpp v3, v2 quad_perm:[1,0,3,2] row_mask:0xf bank_mask:0xf
	s_waitcnt lgkmcnt(0)
; __device__ __forceinline__ float bflo(unsigned w) { return __uint_as_float(w << 16); }
; __device__ __forceinline__ float bfhi(unsigned w) { return __uint_as_float(w & 0xffff0000u); }
; #pragma unroll
;     for (int j = 0; j < 8; ++j) mx = fmaxf(mx, fmaxf(fmaxf(fmaxf(fabsf(bflo(w[j].x)), fabsf(bfhi(w[j].x))), fmaxf(fabsf(bflo(w[j].y)), fabsf(bfhi(w[j].y)))), fmaxf(fmaxf(fabsf(bflo(w[j].z)), fabsf(bfhi(w[j].z))), fmaxf(fabsf(bflo(w[j].w)), fabsf(bfhi(w[j].w))))));
; #pragma unroll
;     for (int o = 1; o < 64; o <<= 1) mx = fmaxf(mx, __shfl_xor(mx, o));
;     return mx; }
; __device__ __forceinline__ void quant_store8(const u32x4 (&w)[8], float inv, signed char* dst, int lane) { u32x2* qp = (u32x2*)dst + lane;
; #pragma unroll
;     for (int j = 0; j < 8; ++j) { const unsigned ww[4] = {w[j].x, w[j].y, w[j].z, w[j].w}; unsigned o2[2];
; #pragma unroll
;         for (int h2 = 0; h2 < 2; ++h2) { const int q0 = (int)rintf(bflo(ww[2 * h2]) * inv), q1 = (int)rintf(bfhi(ww[2 * h2]) * inv), q2 = (int)rintf(bflo(ww[2 * h2 + 1]) * inv), q3 = (int)rintf(bfhi(ww[2 * h2 + 1]) * inv);
;             o2[h2] = (unsigned)(q0 & 255) | ((unsigned)(q1 & 255) << 8) | ((unsigned)(q2 & 255) << 16) | ((unsigned)(q3 & 255) << 24); }
;         u32x2 o; o.x = o2[0]; o.y = o2[1]; qp[64 * j] = o; } }
; __device__ __forceinline__ void quant_rows2(const bf16_t* s0, const bf16_t* s1, signed char* d0, signed char* d1, int lane, float& step0, float& step1) {
;     const u32x4* p0 = (const u32x4*)s0 + lane; const u32x4* p1 = (const u32x4*)s1 + lane; u32x4 w0[8], w1[8];
; #pragma unroll
;     for (int j = 0; j < 8; ++j) { w0[j] = p0[64 * j]; w1[j] = p1[64 * j]; }
;     step0 = fmaxf(absmax8(w0), 1e-30f) * (1.0f / 127.0f); step1 = fmaxf(absmax8(w1), 1e-30f) * (1.0f / 127.0f);
;     quant_store8(w0, 1.0f / step0, d0, lane); quant_store8(w1, 1.0f / step1, d1, lane);
; }
	v_max_f32_e32 v4, v158, v158
	s_waitcnt lgkmcnt(0)
	v_max_f32_e32 v3, v3, v3
	v_max_f32_e32 v4, v157, v4
	v_max_f32_e32 v2, v2, v3
	s_nop 1
	v_mov_b32_dpp v5, v4 quad_perm:[2,3,0,1] row_mask:0xf bank_mask:0xf
	s_nop 1
	v_mov_b32_dpp v3, v2 quad_perm:[2,3,0,1] row_mask:0xf bank_mask:0xf
	s_waitcnt lgkmcnt(0)
	v_max_f32_e32 v5, v5, v5
	s_waitcnt lgkmcnt(0)
	v_max_f32_e32 v3, v3, v3
	v_max_f32_e32 v4, v4, v5
	v_max_f32_e32 v2, v2, v3
	s_nop 1
	v_mov_b32_dpp v5, v4 row_half_mirror row_mask:0xf bank_mask:0xf
	s_nop 1
	v_mov_b32_dpp v3, v2 row_half_mirror row_mask:0xf bank_mask:0xf
	s_waitcnt lgkmcnt(0)
	v_max_f32_e32 v5, v5, v5
	s_waitcnt lgkmcnt(0)
	v_max_f32_e32 v3, v3, v3
	v_max_f32_e32 v4, v4, v5
	v_max_f32_e32 v2, v2, v3
	s_nop 1
	v_mov_b32_dpp v5, v4 row_mirror row_mask:0xf bank_mask:0xf
	s_nop 1
	v_mov_b32_dpp v3, v2 row_mirror row_mask:0xf bank_mask:0xf
	s_waitcnt lgkmcnt(0)
	v_max_f32_e32 v5, v5, v5
	s_waitcnt lgkmcnt(0)
	v_max_f32_e32 v3, v3, v3
	v_max_f32_e32 v4, v4, v5
	v_max_f32_e32 v2, v2, v3
	ds_bpermute_b32 v5, v38, v4
	ds_bpermute_b32 v3, v38, v2
	s_waitcnt lgkmcnt(1)
	v_max_f32_e32 v5, v5, v5
	s_waitcnt lgkmcnt(0)
	v_max_f32_e32 v3, v3, v3
	v_max_f32_e32 v4, v4, v5
	v_max_f32_e32 v3, v2, v3
	ds_bpermute_b32 v5, v39, v4
	ds_bpermute_b32 v6, v39, v3
	s_waitcnt lgkmcnt(1)
	v_max3_f32 v2, v4, v5, s25
	s_waitcnt lgkmcnt(0)
	v_max3_f32 v3, v3, v6, s25
	v_pk_mul_f32 v[2:3], v[2:3], s[8:9] op_sel_hi:[1,0]
	s_nop 0
	v_div_scale_f32 v4, s[12:13], v2, v2, 1.0
	v_rcp_f32_e32 v5, v4
	s_nop 0
	v_fma_f32 v6, -v4, v5, 1.0
	v_fmac_f32_e32 v5, v6, v5
	v_div_scale_f32 v6, vcc, 1.0, v2, 1.0
	v_mul_f32_e32 v7, v6, v5
	v_fma_f32 v157, -v4, v7, v6
	v_fmac_f32_e32 v7, v157, v5
	v_fma_f32 v4, -v4, v7, v6
	v_div_fmas_f32 v4, v4, v5, v7
	v_div_fixup_f32 v157, v4, v2, 1.0
	v_mul_f32_e32 v7, v157, v84
	v_mul_f32_e32 v6, v157, v83
	v_rndne_f32_e32 v7, v7
	v_mul_f32_e32 v83, v157, v85
	v_rndne_f32_e32 v6, v6
	v_cvt_i32_f32_e32 v7, v7
	v_rndne_f32_e32 v83, v83
	v_mul_f32_e32 v84, v157, v86
	v_cvt_i32_f32_e32 v6, v6
	v_cvt_i32_f32_sdwa v83, v83 dst_sel:WORD_1 dst_unused:UNUSED_PAD src0_sel:DWORD
	v_rndne_f32_e32 v84, v84
	v_cvt_i32_f32_sdwa v84, v84 dst_sel:BYTE_3 dst_unused:UNUSED_PAD src0_sel:DWORD
	v_lshlrev_b32_e32 v7, 8, v7
	v_and_b32_e32 v83, 0xff0000, v83
	v_perm_b32 v6, v7, v6, s28
	v_mul_f32_e32 v7, v157, v88
	v_or3_b32 v84, v6, v84, v83
	v_mul_f32_e32 v6, v157, v87
	v_rndne_f32_e32 v7, v7
	v_mul_f32_e32 v83, v157, v89
	v_rndne_f32_e32 v6, v6
	v_cvt_i32_f32_e32 v7, v7
	v_rndne_f32_e32 v83, v83
	v_mul_f32_e32 v85, v157, v90
	v_cvt_i32_f32_e32 v6, v6
	v_cvt_i32_f32_sdwa v83, v83 dst_sel:WORD_1 dst_unused:UNUSED_PAD src0_sel:DWORD
	v_rndne_f32_e32 v85, v85
	v_cvt_i32_f32_sdwa v85, v85 dst_sel:BYTE_3 dst_unused:UNUSED_PAD src0_sel:DWORD
	v_lshlrev_b32_e32 v7, 8, v7
	v_lshl_add_u64 v[4:5], v[32:33], 0, s[0:1]
	v_and_b32_e32 v83, 0xff0000, v83
	v_perm_b32 v6, v7, v6, s28
	v_or3_b32 v85, v6, v85, v83
	v_add_co_u32_e32 v6, vcc, s29, v4
	v_mul_f32_e32 v83, v157, v91
	s_nop 0
	v_addc_co_u32_e32 v7, vcc, 0, v5, vcc
	v_add_co_u32_e32 v4, vcc, s30, v4
	v_rndne_f32_e32 v83, v83
	s_nop 0
	v_addc_co_u32_e32 v5, vcc, 0, v5, vcc
	global_store_dwordx2 v[4:5], v[84:85], off offset:-4096
	v_mul_f32_e32 v84, v157, v92
	v_rndne_f32_e32 v84, v84
	v_mul_f32_e32 v85, v157, v93
	v_cvt_i32_f32_e32 v84, v84
	v_rndne_f32_e32 v85, v85
	v_mul_f32_e32 v86, v157, v94
	v_cvt_i32_f32_e32 v83, v83
	v_cvt_i32_f32_sdwa v85, v85 dst_sel:WORD_1 dst_unused:UNUSED_PAD src0_sel:DWORD
	v_rndne_f32_e32 v86, v86
	v_cvt_i32_f32_sdwa v86, v86 dst_sel:BYTE_3 dst_unused:UNUSED_PAD src0_sel:DWORD
	v_lshlrev_b32_e32 v84, 8, v84
	v_and_b32_e32 v85, 0xff0000, v85
	v_perm_b32 v83, v84, v83, s28
	v_or3_b32 v84, v83, v86, v85
	v_mul_f32_e32 v85, v157, v96
	v_mul_f32_e32 v83, v157, v95
	v_rndne_f32_e32 v85, v85
	v_mul_f32_e32 v86, v157, v97
	v_rndne_f32_e32 v83, v83
	v_cvt_i32_f32_e32 v85, v85
	v_rndne_f32_e32 v86, v86
	v_mul_f32_e32 v87, v157, v98
	v_cvt_i32_f32_e32 v83, v83
	v_cvt_i32_f32_sdwa v86, v86 dst_sel:WORD_1 dst_unused:UNUSED_PAD src0_sel:DWORD
	v_rndne_f32_e32 v87, v87
	v_cvt_i32_f32_sdwa v87, v87 dst_sel:BYTE_3 dst_unused:UNUSED_PAD src0_sel:DWORD
	v_lshlrev_b32_e32 v85, 8, v85
	v_and_b32_e32 v86, 0xff0000, v86
	v_perm_b32 v83, v85, v83, s28
	v_or3_b32 v85, v83, v87, v86
	global_store_dwordx2 v[6:7], v[84:85], off offset:512
	v_mul_f32_e32 v84, v157, v100
	v_mul_f32_e32 v83, v157, v99
	v_rndne_f32_e32 v84, v84
	v_mul_f32_e32 v85, v157, v101
	v_rndne_f32_e32 v83, v83
	v_cvt_i32_f32_e32 v84, v84
	v_rndne_f32_e32 v85, v85
	v_mul_f32_e32 v86, v157, v102
	v_cvt_i32_f32_e32 v83, v83
	v_cvt_i32_f32_sdwa v85, v85 dst_sel:WORD_1 dst_unused:UNUSED_PAD src0_sel:DWORD
	v_rndne_f32_e32 v86, v86
	v_cvt_i32_f32_sdwa v86, v86 dst_sel:BYTE_3 dst_unused:UNUSED_PAD src0_sel:DWORD
	v_lshlrev_b32_e32 v84, 8, v84
	v_and_b32_e32 v85, 0xff0000, v85
	v_perm_b32 v83, v84, v83, s28
	v_or3_b32 v84, v83, v86, v85
	v_mul_f32_e32 v85, v157, v104
	v_mul_f32_e32 v83, v157, v103
	v_rndne_f32_e32 v85, v85
	v_mul_f32_e32 v86, v157, v105
	v_rndne_f32_e32 v83, v83
	v_cvt_i32_f32_e32 v85, v85
	v_rndne_f32_e32 v86, v86
	v_mul_f32_e32 v87, v157, v106
	v_cvt_i32_f32_e32 v83, v83
	v_cvt_i32_f32_sdwa v86, v86 dst_sel:WORD_1 dst_unused:UNUSED_PAD src0_sel:DWORD
	v_rndne_f32_e32 v87, v87
	v_cvt_i32_f32_sdwa v87, v87 dst_sel:BYTE_3 dst_unused:UNUSED_PAD src0_sel:DWORD
	v_lshlrev_b32_e32 v85, 8, v85
	v_and_b32_e32 v86, 0xff0000, v86
	v_perm_b32 v83, v85, v83, s28
	v_or3_b32 v85, v83, v87, v86
	global_store_dwordx2 v[6:7], v[84:85], off offset:1024
	v_mul_f32_e32 v84, v157, v108
	v_mul_f32_e32 v83, v157, v107
	v_rndne_f32_e32 v84, v84
; __device__ __forceinline__ float bflo(unsigned w) { return __uint_as_float(w << 16); }
; __device__ __forceinline__ float bfhi(unsigned w) { return __uint_as_float(w & 0xffff0000u); }
; __device__ __forceinline__ void quant_store8(const u32x4 (&w)[8], float inv, signed char* dst, int lane) { u32x2* qp = (u32x2*)dst + lane;
; #pragma unroll
;     for (int j = 0; j < 8; ++j) { const unsigned ww[4] = {w[j].x, w[j].y, w[j].z, w[j].w}; unsigned o2[2];
; #pragma unroll
;         for (int h2 = 0; h2 < 2; ++h2) { const int q0 = (int)rintf(bflo(ww[2 * h2]) * inv), q1 = (int)rintf(bfhi(ww[2 * h2]) * inv), q2 = (int)rintf(bflo(ww[2 * h2 + 1]) * inv), q3 = (int)rintf(bfhi(ww[2 * h2 + 1]) * inv);
;             o2[h2] = (unsigned)(q0 & 255) | ((unsigned)(q1 & 255) << 8) | ((unsigned)(q2 & 255) << 16) | ((unsigned)(q3 & 255) << 24); }
;         u32x2 o; o.x = o2[0]; o.y = o2[1]; qp[64 * j] = o; } }
	v_mul_f32_e32 v85, v157, v109
	v_rndne_f32_e32 v83, v83
	v_cvt_i32_f32_e32 v84, v84
	v_rndne_f32_e32 v85, v85
	v_mul_f32_e32 v86, v157, v110
	v_cvt_i32_f32_e32 v83, v83
	v_cvt_i32_f32_sdwa v85, v85 dst_sel:WORD_1 dst_unused:UNUSED_PAD src0_sel:DWORD
	v_rndne_f32_e32 v86, v86
	v_cvt_i32_f32_sdwa v86, v86 dst_sel:BYTE_3 dst_unused:UNUSED_PAD src0_sel:DWORD
	v_lshlrev_b32_e32 v84, 8, v84
	v_and_b32_e32 v85, 0xff0000, v85
	v_perm_b32 v83, v84, v83, s28
	v_or3_b32 v84, v83, v86, v85
	v_mul_f32_e32 v85, v157, v112
	v_mul_f32_e32 v83, v157, v111
	v_rndne_f32_e32 v85, v85
	v_mul_f32_e32 v86, v157, v113
	v_rndne_f32_e32 v83, v83
	v_cvt_i32_f32_e32 v85, v85
	v_rndne_f32_e32 v86, v86
	v_mul_f32_e32 v87, v157, v114
	v_cvt_i32_f32_e32 v83, v83
	v_cvt_i32_f32_sdwa v86, v86 dst_sel:WORD_1 dst_unused:UNUSED_PAD src0_sel:DWORD
	v_rndne_f32_e32 v87, v87
	v_cvt_i32_f32_sdwa v87, v87 dst_sel:BYTE_3 dst_unused:UNUSED_PAD src0_sel:DWORD
	v_lshlrev_b32_e32 v85, 8, v85
	v_and_b32_e32 v86, 0xff0000, v86
	v_perm_b32 v83, v85, v83, s28
	v_or3_b32 v85, v83, v87, v86
	global_store_dwordx2 v[6:7], v[84:85], off offset:1536
	v_mul_f32_e32 v84, v157, v116
	v_mul_f32_e32 v83, v157, v115
	v_rndne_f32_e32 v84, v84
	v_mul_f32_e32 v85, v157, v117
	v_rndne_f32_e32 v83, v83
	v_cvt_i32_f32_e32 v84, v84
	v_rndne_f32_e32 v85, v85
	v_mul_f32_e32 v86, v157, v118
	v_cvt_i32_f32_e32 v83, v83
	v_cvt_i32_f32_sdwa v85, v85 dst_sel:WORD_1 dst_unused:UNUSED_PAD src0_sel:DWORD
	v_rndne_f32_e32 v86, v86
	v_cvt_i32_f32_sdwa v86, v86 dst_sel:BYTE_3 dst_unused:UNUSED_PAD src0_sel:DWORD
	v_lshlrev_b32_e32 v84, 8, v84
	v_and_b32_e32 v85, 0xff0000, v85
	v_perm_b32 v83, v84, v83, s28
	v_or3_b32 v84, v83, v86, v85
	v_mul_f32_e32 v85, v157, v120
	v_mul_f32_e32 v83, v157, v119
	v_rndne_f32_e32 v85, v85
	v_mul_f32_e32 v86, v157, v121
	v_rndne_f32_e32 v83, v83
	v_cvt_i32_f32_e32 v85, v85
	v_rndne_f32_e32 v86, v86
	v_mul_f32_e32 v87, v157, v122
	v_cvt_i32_f32_e32 v83, v83
	v_cvt_i32_f32_sdwa v86, v86 dst_sel:WORD_1 dst_unused:UNUSED_PAD src0_sel:DWORD
	v_rndne_f32_e32 v87, v87
	v_cvt_i32_f32_sdwa v87, v87 dst_sel:BYTE_3 dst_unused:UNUSED_PAD src0_sel:DWORD
	v_lshlrev_b32_e32 v85, 8, v85
	v_and_b32_e32 v86, 0xff0000, v86
	v_perm_b32 v83, v85, v83, s28
	v_or3_b32 v85, v83, v87, v86
	global_store_dwordx2 v[6:7], v[84:85], off offset:2048
	v_mul_f32_e32 v84, v157, v124
	v_mul_f32_e32 v83, v157, v123
	v_rndne_f32_e32 v84, v84
	v_mul_f32_e32 v85, v157, v125
	v_rndne_f32_e32 v83, v83
	v_cvt_i32_f32_e32 v84, v84
	v_rndne_f32_e32 v85, v85
	v_mul_f32_e32 v86, v157, v126
	v_cvt_i32_f32_e32 v83, v83
	v_cvt_i32_f32_sdwa v85, v85 dst_sel:WORD_1 dst_unused:UNUSED_PAD src0_sel:DWORD
	v_rndne_f32_e32 v86, v86
	v_cvt_i32_f32_sdwa v86, v86 dst_sel:BYTE_3 dst_unused:UNUSED_PAD src0_sel:DWORD
	v_lshlrev_b32_e32 v84, 8, v84
	v_and_b32_e32 v85, 0xff0000, v85
	v_perm_b32 v83, v84, v83, s28
	v_or3_b32 v84, v83, v86, v85
	v_mul_f32_e32 v85, v157, v128
	v_mul_f32_e32 v83, v157, v127
	v_rndne_f32_e32 v85, v85
	v_mul_f32_e32 v86, v157, v129
	v_rndne_f32_e32 v83, v83
	v_cvt_i32_f32_e32 v85, v85
	v_rndne_f32_e32 v86, v86
	v_mul_f32_e32 v87, v157, v130
	v_cvt_i32_f32_e32 v83, v83
	v_cvt_i32_f32_sdwa v86, v86 dst_sel:WORD_1 dst_unused:UNUSED_PAD src0_sel:DWORD
	v_rndne_f32_e32 v87, v87
	v_cvt_i32_f32_sdwa v87, v87 dst_sel:BYTE_3 dst_unused:UNUSED_PAD src0_sel:DWORD
	v_lshlrev_b32_e32 v85, 8, v85
	v_and_b32_e32 v86, 0xff0000, v86
	v_perm_b32 v83, v85, v83, s28
	v_or3_b32 v85, v83, v87, v86
	global_store_dwordx2 v[6:7], v[84:85], off offset:2560
	v_mul_f32_e32 v84, v157, v132
	v_mul_f32_e32 v83, v157, v131
	v_rndne_f32_e32 v84, v84
	v_mul_f32_e32 v85, v157, v133
	v_rndne_f32_e32 v83, v83
	v_cvt_i32_f32_e32 v84, v84
	v_rndne_f32_e32 v85, v85
	v_mul_f32_e32 v86, v157, v137
	v_cvt_i32_f32_e32 v83, v83
	v_cvt_i32_f32_sdwa v85, v85 dst_sel:WORD_1 dst_unused:UNUSED_PAD src0_sel:DWORD
	v_rndne_f32_e32 v86, v86
	v_cvt_i32_f32_sdwa v86, v86 dst_sel:BYTE_3 dst_unused:UNUSED_PAD src0_sel:DWORD
	v_lshlrev_b32_e32 v84, 8, v84
	v_and_b32_e32 v85, 0xff0000, v85
	v_perm_b32 v83, v84, v83, s28
	v_or3_b32 v84, v83, v86, v85
	v_mul_f32_e32 v85, v157, v139
	v_mul_f32_e32 v83, v157, v138
	v_rndne_f32_e32 v85, v85
	v_mul_f32_e32 v86, v157, v140
	v_rndne_f32_e32 v83, v83
	v_cvt_i32_f32_e32 v85, v85
	v_rndne_f32_e32 v86, v86
	v_mul_f32_e32 v87, v157, v141
	v_cvt_i32_f32_e32 v83, v83
	v_cvt_i32_f32_sdwa v86, v86 dst_sel:WORD_1 dst_unused:UNUSED_PAD src0_sel:DWORD
	v_rndne_f32_e32 v87, v87
	v_cvt_i32_f32_sdwa v87, v87 dst_sel:BYTE_3 dst_unused:UNUSED_PAD src0_sel:DWORD
	v_lshlrev_b32_e32 v85, 8, v85
	v_and_b32_e32 v86, 0xff0000, v86
	v_perm_b32 v83, v85, v83, s28
	v_or3_b32 v85, v83, v87, v86
	global_store_dwordx2 v[6:7], v[84:85], off offset:3072
	v_mul_f32_e32 v84, v157, v143
	v_mul_f32_e32 v83, v157, v142
	v_rndne_f32_e32 v84, v84
	v_mul_f32_e32 v85, v157, v144
	v_rndne_f32_e32 v83, v83
	v_cvt_i32_f32_e32 v84, v84
	v_rndne_f32_e32 v85, v85
	v_mul_f32_e32 v86, v157, v145
	v_cvt_i32_f32_e32 v83, v83
	v_cvt_i32_f32_sdwa v85, v85 dst_sel:WORD_1 dst_unused:UNUSED_PAD src0_sel:DWORD
	v_rndne_f32_e32 v86, v86
	v_cvt_i32_f32_sdwa v86, v86 dst_sel:BYTE_3 dst_unused:UNUSED_PAD src0_sel:DWORD
	v_lshlrev_b32_e32 v84, 8, v84
	v_and_b32_e32 v85, 0xff0000, v85
	v_perm_b32 v83, v84, v83, s28
	v_or3_b32 v84, v83, v86, v85
	v_mul_f32_e32 v85, v157, v147
	v_mul_f32_e32 v83, v157, v146
	v_rndne_f32_e32 v85, v85
	v_mul_f32_e32 v86, v157, v148
	v_rndne_f32_e32 v83, v83
	v_cvt_i32_f32_e32 v85, v85
	v_rndne_f32_e32 v86, v86
	v_mul_f32_e32 v87, v157, v149
	v_cvt_i32_f32_e32 v83, v83
	v_cvt_i32_f32_sdwa v86, v86 dst_sel:WORD_1 dst_unused:UNUSED_PAD src0_sel:DWORD
	v_rndne_f32_e32 v87, v87
; __device__ __forceinline__ float bflo(unsigned w) { return __uint_as_float(w << 16); }
; __device__ __forceinline__ float bfhi(unsigned w) { return __uint_as_float(w & 0xffff0000u); }
; __device__ __forceinline__ void quant_store8(const u32x4 (&w)[8], float inv, signed char* dst, int lane) { u32x2* qp = (u32x2*)dst + lane;
; #pragma unroll
;     for (int j = 0; j < 8; ++j) { const unsigned ww[4] = {w[j].x, w[j].y, w[j].z, w[j].w}; unsigned o2[2];
; #pragma unroll
;         for (int h2 = 0; h2 < 2; ++h2) { const int q0 = (int)rintf(bflo(ww[2 * h2]) * inv), q1 = (int)rintf(bfhi(ww[2 * h2]) * inv), q2 = (int)rintf(bflo(ww[2 * h2 + 1]) * inv), q3 = (int)rintf(bfhi(ww[2 * h2 + 1]) * inv);
;             o2[h2] = (unsigned)(q0 & 255) | ((unsigned)(q1 & 255) << 8) | ((unsigned)(q2 & 255) << 16) | ((unsigned)(q3 & 255) << 24); }
;         u32x2 o; o.x = o2[0]; o.y = o2[1]; qp[64 * j] = o; } }
; __device__ __forceinline__ void quant_rows2(const bf16_t* s0, const bf16_t* s1, signed char* d0, signed char* d1, int lane, float& step0, float& step1) {
;     const u32x4* p0 = (const u32x4*)s0 + lane; const u32x4* p1 = (const u32x4*)s1 + lane; u32x4 w0[8], w1[8];
; #pragma unroll
;     for (int j = 0; j < 8; ++j) { w0[j] = p0[64 * j]; w1[j] = p1[64 * j]; }
;     step0 = fmaxf(absmax8(w0), 1e-30f) * (1.0f / 127.0f); step1 = fmaxf(absmax8(w1), 1e-30f) * (1.0f / 127.0f);
;     quant_store8(w0, 1.0f / step0, d0, lane); quant_store8(w1, 1.0f / step1, d1, lane);
	v_cvt_i32_f32_sdwa v87, v87 dst_sel:BYTE_3 dst_unused:UNUSED_PAD src0_sel:DWORD
	v_div_scale_f32 v88, s[12:13], v3, v3, 1.0
	v_rcp_f32_e32 v89, v88
	v_lshlrev_b32_e32 v85, 8, v85
	v_and_b32_e32 v86, 0xff0000, v86
	v_perm_b32 v83, v85, v83, s28
	v_or3_b32 v85, v83, v87, v86
	global_store_dwordx2 v[6:7], v[84:85], off offset:3584
	v_fma_f32 v6, -v88, v89, 1.0
	v_fmac_f32_e32 v89, v6, v89
	v_div_scale_f32 v6, vcc, 1.0, v3, 1.0
	v_mul_f32_e32 v7, v6, v89
	v_fma_f32 v83, -v88, v7, v6
	v_fmac_f32_e32 v7, v83, v89
	v_fma_f32 v6, -v88, v7, v6
	v_div_fmas_f32 v6, v6, v89, v7
	v_div_fixup_f32 v83, v6, v3, 1.0
	v_mul_f32_e32 v7, v83, v80
	v_mul_f32_e32 v6, v83, v82
	v_rndne_f32_e32 v7, v7
	v_rndne_f32_e32 v6, v6
	v_cvt_i32_f32_e32 v7, v7
	v_cvt_i32_f32_e32 v6, v6
	v_mul_f32_e32 v77, v83, v77
	v_mul_f32_e32 v80, v83, v81
	v_lshlrev_b32_e32 v7, 8, v7
	v_perm_b32 v6, v7, v6, s28
	v_mul_f32_e32 v7, v83, v78
	v_rndne_f32_e32 v77, v77
	v_mul_f32_e32 v76, v83, v76
	v_rndne_f32_e32 v80, v80
	v_mul_f32_e32 v79, v83, v79
	v_rndne_f32_e32 v7, v7
	v_cvt_i32_f32_e32 v77, v77
	v_rndne_f32_e32 v76, v76
	v_mul_f32_e32 v75, v83, v75
	v_cvt_i32_f32_sdwa v80, v80 dst_sel:WORD_1 dst_unused:UNUSED_PAD src0_sel:DWORD
	v_rndne_f32_e32 v79, v79
	v_cvt_i32_f32_e32 v7, v7
	v_cvt_i32_f32_sdwa v76, v76 dst_sel:WORD_1 dst_unused:UNUSED_PAD src0_sel:DWORD
	v_rndne_f32_e32 v75, v75
	v_cvt_i32_f32_sdwa v79, v79 dst_sel:BYTE_3 dst_unused:UNUSED_PAD src0_sel:DWORD
	v_cvt_i32_f32_sdwa v75, v75 dst_sel:BYTE_3 dst_unused:UNUSED_PAD src0_sel:DWORD
	v_lshlrev_b32_e32 v77, 8, v77
	v_and_b32_e32 v80, 0xff0000, v80
	v_and_b32_e32 v76, 0xff0000, v76
	v_perm_b32 v7, v77, v7, s28
	v_or3_b32 v6, v6, v79, v80
	v_or3_b32 v7, v7, v75, v76
	global_store_dwordx2 v[4:5], v[6:7], off
	v_mul_f32_e32 v7, v83, v72
	v_mul_f32_e32 v6, v83, v74
	v_rndne_f32_e32 v7, v7
	v_rndne_f32_e32 v6, v6
	v_cvt_i32_f32_e32 v7, v7
	v_cvt_i32_f32_e32 v6, v6
	v_mul_f32_e32 v69, v83, v69
	v_mul_f32_e32 v72, v83, v73
	v_lshlrev_b32_e32 v7, 8, v7
	v_perm_b32 v6, v7, v6, s28
	v_mul_f32_e32 v7, v83, v70
	v_rndne_f32_e32 v69, v69
	v_mul_f32_e32 v68, v83, v68
	v_rndne_f32_e32 v72, v72
	v_mul_f32_e32 v71, v83, v71
	v_rndne_f32_e32 v7, v7
	v_cvt_i32_f32_e32 v69, v69
	v_rndne_f32_e32 v68, v68
	v_mul_f32_e32 v67, v83, v67
	v_cvt_i32_f32_sdwa v72, v72 dst_sel:WORD_1 dst_unused:UNUSED_PAD src0_sel:DWORD
	v_rndne_f32_e32 v71, v71
	v_cvt_i32_f32_e32 v7, v7
	v_cvt_i32_f32_sdwa v68, v68 dst_sel:WORD_1 dst_unused:UNUSED_PAD src0_sel:DWORD
	v_rndne_f32_e32 v67, v67
	v_cvt_i32_f32_sdwa v71, v71 dst_sel:BYTE_3 dst_unused:UNUSED_PAD src0_sel:DWORD
	v_cvt_i32_f32_sdwa v67, v67 dst_sel:BYTE_3 dst_unused:UNUSED_PAD src0_sel:DWORD
	v_lshlrev_b32_e32 v69, 8, v69
	v_and_b32_e32 v72, 0xff0000, v72
	v_and_b32_e32 v68, 0xff0000, v68
	v_perm_b32 v7, v69, v7, s28
	v_or3_b32 v6, v6, v71, v72
	v_or3_b32 v7, v7, v67, v68
	global_store_dwordx2 v[4:5], v[6:7], off offset:512
	v_mul_f32_e32 v7, v83, v64
	v_mul_f32_e32 v6, v83, v66
	v_rndne_f32_e32 v7, v7
	v_rndne_f32_e32 v6, v6
	v_cvt_i32_f32_e32 v7, v7
	v_cvt_i32_f32_e32 v6, v6
	v_mul_f32_e32 v61, v83, v61
	v_mul_f32_e32 v64, v83, v65
	v_lshlrev_b32_e32 v7, 8, v7
	v_perm_b32 v6, v7, v6, s28
	v_mul_f32_e32 v7, v83, v62
	v_rndne_f32_e32 v61, v61
	v_mul_f32_e32 v60, v83, v60
	v_rndne_f32_e32 v64, v64
	v_mul_f32_e32 v63, v83, v63
	v_rndne_f32_e32 v7, v7
	v_cvt_i32_f32_e32 v61, v61
	v_rndne_f32_e32 v60, v60
	v_mul_f32_e32 v59, v83, v59
	v_cvt_i32_f32_sdwa v64, v64 dst_sel:WORD_1 dst_unused:UNUSED_PAD src0_sel:DWORD
	v_rndne_f32_e32 v63, v63
	v_cvt_i32_f32_e32 v7, v7
	v_cvt_i32_f32_sdwa v60, v60 dst_sel:WORD_1 dst_unused:UNUSED_PAD src0_sel:DWORD
	v_rndne_f32_e32 v59, v59
	v_cvt_i32_f32_sdwa v63, v63 dst_sel:BYTE_3 dst_unused:UNUSED_PAD src0_sel:DWORD
	v_cvt_i32_f32_sdwa v59, v59 dst_sel:BYTE_3 dst_unused:UNUSED_PAD src0_sel:DWORD
	v_lshlrev_b32_e32 v61, 8, v61
	v_and_b32_e32 v64, 0xff0000, v64
	v_and_b32_e32 v60, 0xff0000, v60
	v_perm_b32 v7, v61, v7, s28
	v_or3_b32 v6, v6, v63, v64
	v_or3_b32 v7, v7, v59, v60
	global_store_dwordx2 v[4:5], v[6:7], off offset:1024
	v_mul_f32_e32 v7, v83, v56
	v_mul_f32_e32 v6, v83, v58
	v_rndne_f32_e32 v7, v7
	v_rndne_f32_e32 v6, v6
	v_cvt_i32_f32_e32 v7, v7
	v_cvt_i32_f32_e32 v6, v6
	v_mul_f32_e32 v53, v83, v53
	v_mul_f32_e32 v56, v83, v57
	v_lshlrev_b32_e32 v7, 8, v7
	v_perm_b32 v6, v7, v6, s28
	v_mul_f32_e32 v7, v83, v54
	v_rndne_f32_e32 v53, v53
	v_mul_f32_e32 v52, v83, v52
	v_rndne_f32_e32 v56, v56
	v_mul_f32_e32 v55, v83, v55
	v_rndne_f32_e32 v7, v7
	v_cvt_i32_f32_e32 v53, v53
	v_rndne_f32_e32 v52, v52
	v_mul_f32_e32 v51, v83, v51
	v_cvt_i32_f32_sdwa v56, v56 dst_sel:WORD_1 dst_unused:UNUSED_PAD src0_sel:DWORD
	v_rndne_f32_e32 v55, v55
	v_cvt_i32_f32_e32 v7, v7
	v_cvt_i32_f32_sdwa v52, v52 dst_sel:WORD_1 dst_unused:UNUSED_PAD src0_sel:DWORD
	v_rndne_f32_e32 v51, v51
	v_cvt_i32_f32_sdwa v55, v55 dst_sel:BYTE_3 dst_unused:UNUSED_PAD src0_sel:DWORD
	v_cvt_i32_f32_sdwa v51, v51 dst_sel:BYTE_3 dst_unused:UNUSED_PAD src0_sel:DWORD
	v_lshlrev_b32_e32 v53, 8, v53
; __device__ __forceinline__ float bflo(unsigned w) { return __uint_as_float(w << 16); }
; __device__ __forceinline__ float bfhi(unsigned w) { return __uint_as_float(w & 0xffff0000u); }
; __device__ __forceinline__ void quant_store8(const u32x4 (&w)[8], float inv, signed char* dst, int lane) { u32x2* qp = (u32x2*)dst + lane;
; #pragma unroll
;     for (int j = 0; j < 8; ++j) { const unsigned ww[4] = {w[j].x, w[j].y, w[j].z, w[j].w}; unsigned o2[2];
; #pragma unroll
;         for (int h2 = 0; h2 < 2; ++h2) { const int q0 = (int)rintf(bflo(ww[2 * h2]) * inv), q1 = (int)rintf(bfhi(ww[2 * h2]) * inv), q2 = (int)rintf(bflo(ww[2 * h2 + 1]) * inv), q3 = (int)rintf(bfhi(ww[2 * h2 + 1]) * inv);
;             o2[h2] = (unsigned)(q0 & 255) | ((unsigned)(q1 & 255) << 8) | ((unsigned)(q2 & 255) << 16) | ((unsigned)(q3 & 255) << 24); }
;         u32x2 o; o.x = o2[0]; o.y = o2[1]; qp[64 * j] = o; } }
	v_and_b32_e32 v56, 0xff0000, v56
	v_and_b32_e32 v52, 0xff0000, v52
	v_perm_b32 v7, v53, v7, s28
	v_or3_b32 v6, v6, v55, v56
	v_or3_b32 v7, v7, v51, v52
	global_store_dwordx2 v[4:5], v[6:7], off offset:1536
	v_mul_f32_e32 v7, v83, v48
	v_mul_f32_e32 v6, v83, v50
	v_rndne_f32_e32 v7, v7
	v_rndne_f32_e32 v6, v6
	v_cvt_i32_f32_e32 v7, v7
	v_cvt_i32_f32_e32 v6, v6
	v_mul_f32_e32 v45, v83, v45
	v_mul_f32_e32 v48, v83, v49
	v_lshlrev_b32_e32 v7, 8, v7
	v_perm_b32 v6, v7, v6, s28
	v_mul_f32_e32 v7, v83, v46
	v_rndne_f32_e32 v45, v45
	v_mul_f32_e32 v44, v83, v44
	v_rndne_f32_e32 v48, v48
	v_mul_f32_e32 v47, v83, v47
	v_rndne_f32_e32 v7, v7
	v_cvt_i32_f32_e32 v45, v45
	v_rndne_f32_e32 v44, v44
	v_mul_f32_e32 v43, v83, v43
	v_cvt_i32_f32_sdwa v48, v48 dst_sel:WORD_1 dst_unused:UNUSED_PAD src0_sel:DWORD
	v_rndne_f32_e32 v47, v47
	v_cvt_i32_f32_e32 v7, v7
	v_cvt_i32_f32_sdwa v44, v44 dst_sel:WORD_1 dst_unused:UNUSED_PAD src0_sel:DWORD
	v_rndne_f32_e32 v43, v43
	v_cvt_i32_f32_sdwa v47, v47 dst_sel:BYTE_3 dst_unused:UNUSED_PAD src0_sel:DWORD
	v_cvt_i32_f32_sdwa v43, v43 dst_sel:BYTE_3 dst_unused:UNUSED_PAD src0_sel:DWORD
	v_lshlrev_b32_e32 v45, 8, v45
	v_and_b32_e32 v48, 0xff0000, v48
	v_and_b32_e32 v44, 0xff0000, v44
	v_perm_b32 v7, v45, v7, s28
	v_or3_b32 v6, v6, v47, v48
	v_or3_b32 v7, v7, v43, v44
	global_store_dwordx2 v[4:5], v[6:7], off offset:2048
	v_mul_f32_e32 v7, v83, v29
	v_mul_f32_e32 v6, v83, v42
	v_rndne_f32_e32 v7, v7
	v_rndne_f32_e32 v6, v6
	v_cvt_i32_f32_e32 v7, v7
	v_cvt_i32_f32_e32 v6, v6
	v_mul_f32_e32 v26, v83, v26
	v_mul_f32_e32 v29, v83, v41
	v_lshlrev_b32_e32 v7, 8, v7
	v_perm_b32 v6, v7, v6, s28
	v_mul_f32_e32 v7, v83, v27
	v_rndne_f32_e32 v26, v26
	v_mul_f32_e32 v25, v83, v25
	v_rndne_f32_e32 v29, v29
	v_mul_f32_e32 v28, v83, v28
	v_rndne_f32_e32 v7, v7
	v_cvt_i32_f32_e32 v26, v26
	v_rndne_f32_e32 v25, v25
	v_mul_f32_e32 v24, v83, v24
	v_cvt_i32_f32_sdwa v29, v29 dst_sel:WORD_1 dst_unused:UNUSED_PAD src0_sel:DWORD
	v_rndne_f32_e32 v28, v28
	v_cvt_i32_f32_e32 v7, v7
	v_cvt_i32_f32_sdwa v25, v25 dst_sel:WORD_1 dst_unused:UNUSED_PAD src0_sel:DWORD
	v_rndne_f32_e32 v24, v24
	v_cvt_i32_f32_sdwa v28, v28 dst_sel:BYTE_3 dst_unused:UNUSED_PAD src0_sel:DWORD
	v_cvt_i32_f32_sdwa v24, v24 dst_sel:BYTE_3 dst_unused:UNUSED_PAD src0_sel:DWORD
	v_lshlrev_b32_e32 v26, 8, v26
	v_and_b32_e32 v29, 0xff0000, v29
	v_and_b32_e32 v25, 0xff0000, v25
	v_perm_b32 v7, v26, v7, s28
	v_or3_b32 v6, v6, v28, v29
	v_or3_b32 v7, v7, v24, v25
	global_store_dwordx2 v[4:5], v[6:7], off offset:2560
	v_mul_f32_e32 v7, v83, v21
	v_mul_f32_e32 v6, v83, v23
	v_rndne_f32_e32 v7, v7
	v_rndne_f32_e32 v6, v6
	v_cvt_i32_f32_e32 v7, v7
	v_cvt_i32_f32_e32 v6, v6
	v_mul_f32_e32 v18, v83, v18
	v_mul_f32_e32 v21, v83, v22
	v_lshlrev_b32_e32 v7, 8, v7
	v_perm_b32 v6, v7, v6, s28
	v_mul_f32_e32 v7, v83, v19
	v_rndne_f32_e32 v18, v18
	v_mul_f32_e32 v17, v83, v17
	v_rndne_f32_e32 v21, v21
	v_mul_f32_e32 v20, v83, v20
	v_rndne_f32_e32 v7, v7
	v_cvt_i32_f32_e32 v18, v18
	v_rndne_f32_e32 v17, v17
	v_mul_f32_e32 v16, v83, v16
	v_cvt_i32_f32_sdwa v21, v21 dst_sel:WORD_1 dst_unused:UNUSED_PAD src0_sel:DWORD
	v_rndne_f32_e32 v20, v20
	v_cvt_i32_f32_e32 v7, v7
	v_cvt_i32_f32_sdwa v17, v17 dst_sel:WORD_1 dst_unused:UNUSED_PAD src0_sel:DWORD
	v_rndne_f32_e32 v16, v16
	v_cvt_i32_f32_sdwa v20, v20 dst_sel:BYTE_3 dst_unused:UNUSED_PAD src0_sel:DWORD
	v_cvt_i32_f32_sdwa v16, v16 dst_sel:BYTE_3 dst_unused:UNUSED_PAD src0_sel:DWORD
	v_lshlrev_b32_e32 v18, 8, v18
	v_and_b32_e32 v21, 0xff0000, v21
	v_and_b32_e32 v17, 0xff0000, v17
	v_perm_b32 v7, v18, v7, s28
	v_or3_b32 v6, v6, v20, v21
	v_or3_b32 v7, v7, v16, v17
	global_store_dwordx2 v[4:5], v[6:7], off offset:3072
	v_mul_f32_e32 v7, v83, v13
	v_mul_f32_e32 v6, v83, v15
	v_rndne_f32_e32 v7, v7
	v_rndne_f32_e32 v6, v6
	v_cvt_i32_f32_e32 v7, v7
	v_cvt_i32_f32_e32 v6, v6
	v_mul_f32_e32 v10, v83, v10
	v_mul_f32_e32 v13, v83, v14
	v_lshlrev_b32_e32 v7, 8, v7
	v_perm_b32 v6, v7, v6, s28
	v_mul_f32_e32 v7, v83, v11
	v_rndne_f32_e32 v10, v10
	v_mul_f32_e32 v9, v83, v9
	v_rndne_f32_e32 v13, v13
	v_mul_f32_e32 v12, v83, v12
	v_rndne_f32_e32 v7, v7
	v_cvt_i32_f32_e32 v10, v10
	v_rndne_f32_e32 v9, v9
	v_mul_f32_e32 v8, v83, v8
	v_cvt_i32_f32_sdwa v13, v13 dst_sel:WORD_1 dst_unused:UNUSED_PAD src0_sel:DWORD
	v_rndne_f32_e32 v12, v12
	v_cvt_i32_f32_e32 v7, v7
	v_cvt_i32_f32_sdwa v9, v9 dst_sel:WORD_1 dst_unused:UNUSED_PAD src0_sel:DWORD
	v_rndne_f32_e32 v8, v8
	v_cvt_i32_f32_sdwa v12, v12 dst_sel:BYTE_3 dst_unused:UNUSED_PAD src0_sel:DWORD
	v_cvt_i32_f32_sdwa v8, v8 dst_sel:BYTE_3 dst_unused:UNUSED_PAD src0_sel:DWORD
	v_lshlrev_b32_e32 v10, 8, v10
	v_and_b32_e32 v13, 0xff0000, v13
	v_and_b32_e32 v9, 0xff0000, v9
	v_perm_b32 v7, v10, v7, s28
	v_or3_b32 v6, v6, v12, v13
	v_or3_b32 v7, v7, v8, v9
	global_store_dwordx2 v[4:5], v[6:7], off offset:3584
	s_and_saveexec_b64 s[12:13], s[6:7]
	s_cbranch_execz .LBB0_271
	s_add_u32 s34, s78, s9
	s_addc_u32 s35, s79, s22
	global_store_dwordx2 v40, v[2:3], s[34:35]
	s_branch .LBB0_271

; __device__ __forceinline__ void partialSM(f32x16& p0, f32x16& p1, float& m_reg, float& mn, float& alpha, bool allow) {
;     ...
;     for (int r = 0; r < 16; ++r) p0[r] = fmaf(p0[r], C2, mnL);
; #pragma unroll
;     for (int r = 0; r < 16; ++r) p1[r] = fmaf(p1[r], C2, mnL);
; #pragma unroll
;     for (int r = 0; r < 16; ++r) p0[r] = __builtin_amdgcn_exp2f(p0[r]);
; }
; __device__ __forceinline__ void finishSM(f32x16& p0, f32x16& p1, float alpha, float& l_reg, bf16x8& pa0, bf16x8& pa1, bf16x8& pa2, bf16x8& pa3) {
; #pragma unroll
;     for (int r = 0; r < 16; ++r) p1[r] = __builtin_amdgcn_exp2f(p1[r]);
;     float ps = 0;
; #pragma unroll
;     for (int r = 0; r < 16; ++r) ps += p0[r];
; #pragma unroll
;     for (int r = 0; r < 16; ++r) ps += p1[r];
;     { auto rr = __builtin_amdgcn_permlane32_swap(__float_as_uint(ps), __float_as_uint(ps), false, false);
;       ps = __uint_as_float(rr[0]) + __uint_as_float(rr[1]); }
;     l_reg = l_reg * alpha + ps;
;     ...
;     PK4(p0, 0, pa0); PK4(p0, 8, pa1); PK4(p1, 0, pa2); PK4(p1, 8, pa3);
; template <int VB>
; __device__ __forceinline__ void pv_tile(f32x16* o, int vb0, bf16x8 pa0, bf16x8 pa1, bf16x8 pa2, bf16x8 pa3) {
;     ...
;     PV_D0(0); PV_D0(1); PV_D0(2); PV_D0(3);
.LBB0_808:
	v_cndmask_b32_e64 v109, v109, v201, s[6:7]
	v_mul_f32_e32 v109, 0xbe0293ee, v109
	v_fmamk_f32 v150, v66, 0x3e0293ee, v109
	v_fmamk_f32 v151, v67, 0x3e0293ee, v109
	v_fmamk_f32 v157, v81, 0x3e0293ee, v109
	v_exp_f32_e32 v81, v150
	v_fmamk_f32 v68, v68, 0x3e0293ee, v109
	v_fmamk_f32 v67, v83, 0x3e0293ee, v109
	v_exp_f32_e32 v83, v151
	v_fmamk_f32 v69, v69, 0x3e0293ee, v109
	v_fmamk_f32 v155, v79, 0x3e0293ee, v109
	v_exp_f32_e32 v79, v68
	v_fmamk_f32 v70, v70, 0x3e0293ee, v109
	v_fmamk_f32 v66, v82, 0x3e0293ee, v109
	v_exp_f32_e32 v82, v69
	v_fmamk_f32 v71, v71, 0x3e0293ee, v109
	v_fmamk_f32 v72, v72, 0x3e0293ee, v109
	v_fmamk_f32 v73, v73, 0x3e0293ee, v109
	v_fmamk_f32 v74, v74, 0x3e0293ee, v109
	v_fmamk_f32 v75, v75, 0x3e0293ee, v109
	v_fmamk_f32 v152, v76, 0x3e0293ee, v109
	v_fmamk_f32 v153, v77, 0x3e0293ee, v109
	v_fmamk_f32 v154, v78, 0x3e0293ee, v109
	v_fmamk_f32 v156, v80, 0x3e0293ee, v109
	v_fmamk_f32 v84, v84, 0x3e0293ee, v109
	v_fmamk_f32 v85, v85, 0x3e0293ee, v109
	v_fmamk_f32 v86, v86, 0x3e0293ee, v109
	v_fmamk_f32 v87, v87, 0x3e0293ee, v109
	v_fmamk_f32 v88, v88, 0x3e0293ee, v109
	v_fmamk_f32 v89, v89, 0x3e0293ee, v109
	v_fmamk_f32 v90, v90, 0x3e0293ee, v109
	v_fmamk_f32 v91, v91, 0x3e0293ee, v109
	v_fmamk_f32 v92, v92, 0x3e0293ee, v109
	v_fmamk_f32 v93, v93, 0x3e0293ee, v109
	v_fmamk_f32 v94, v94, 0x3e0293ee, v109
	v_exp_f32_e32 v77, v70
	v_fmamk_f32 v95, v95, 0x3e0293ee, v109
	v_fmamk_f32 v96, v96, 0x3e0293ee, v109
	v_fmac_f32_e32 v109, 0x3e0293ee, v97
	v_exp_f32_e32 v97, v66
	v_add_f32_e32 v66, 0, v81
	v_exp_f32_e32 v80, v71
	v_add_f32_e32 v66, v83, v66
	v_exp_f32_e32 v76, v72
	v_add_f32_e32 v66, v79, v66
	v_exp_f32_e32 v78, v73
	v_add_f32_e32 v66, v82, v66
	v_exp_f32_e32 v73, v74
	v_add_f32_e32 v66, v77, v66
	v_exp_f32_e32 v75, v75
	v_add_f32_e32 v66, v80, v66
	v_exp_f32_e32 v71, v152
	v_add_f32_e32 v66, v76, v66
	v_exp_f32_e32 v74, v153
	v_add_f32_e32 v66, v78, v66
	v_exp_f32_e32 v69, v154
	v_add_f32_e32 v66, v73, v66
	v_exp_f32_e32 v72, v155
	v_add_f32_e32 v66, v75, v66
	v_exp_f32_e32 v68, v156
	v_add_f32_e32 v66, v71, v66
	v_exp_f32_e32 v70, v157
	v_add_f32_e32 v66, v74, v66
	v_add_f32_e32 v66, v69, v66
	v_exp_f32_e32 v150, v67
	v_add_f32_e32 v66, v72, v66
	v_exp_f32_e32 v151, v84
	v_add_f32_e32 v66, v68, v66
	v_exp_f32_e32 v152, v85
	v_add_f32_e32 v66, v70, v66
	v_exp_f32_e32 v153, v86
	v_add_f32_e32 v66, v97, v66
	v_exp_f32_e32 v154, v87
	v_add_f32_e32 v66, v150, v66
	v_exp_f32_e32 v88, v88
	v_add_f32_e32 v66, v151, v66
	v_exp_f32_e32 v89, v89
	v_add_f32_e32 v66, v152, v66
	v_exp_f32_e32 v90, v90
	v_add_f32_e32 v66, v153, v66
	v_exp_f32_e32 v91, v91
	v_add_f32_e32 v66, v154, v66
	v_exp_f32_e32 v92, v92
	v_add_f32_e32 v66, v88, v66
	v_exp_f32_e32 v93, v93
	v_add_f32_e32 v66, v89, v66
	v_exp_f32_e32 v94, v94
	v_add_f32_e32 v66, v90, v66
	v_exp_f32_e32 v95, v95
	v_add_f32_e32 v66, v91, v66
	v_exp_f32_e32 v96, v96
	v_add_f32_e32 v66, v92, v66
	v_exp_f32_e32 v109, v109
	v_add_f32_e32 v66, v93, v66
	v_add_f32_e32 v66, v94, v66
	v_add_f32_e32 v66, v95, v66
	v_add_f32_e32 v66, v96, v66
	v_add_f32_e32 v66, v109, v66
	v_mov_b32_e32 v67, v66
	s_nop 1
	v_permlane32_swap_b32_e32 v66, v67
	v_cvt_pk_bf16_f32 v84, v81, v83
	v_cvt_pk_bf16_f32 v85, v79, v82
	v_cvt_pk_bf16_f32 v86, v77, v80
	v_cvt_pk_bf16_f32 v87, v76, v78
	v_cvt_pk_bf16_f32 v76, v73, v75
	v_cvt_pk_bf16_f32 v77, v71, v74
	v_cvt_pk_bf16_f32 v78, v69, v72
	v_cvt_pk_bf16_f32 v79, v68, v70
	v_cvt_pk_bf16_f32 v68, v97, v150
	v_cvt_pk_bf16_f32 v69, v151, v152
	v_cvt_pk_bf16_f32 v70, v153, v154
	v_cvt_pk_bf16_f32 v71, v88, v89
	v_cvt_pk_bf16_f32 v72, v90, v91
	v_cvt_pk_bf16_f32 v73, v92, v93
	v_cvt_pk_bf16_f32 v74, v94, v95
	v_cvt_pk_bf16_f32 v75, v96, v109
	s_nop 0
	v_permlane32_swap_b32_e32 v84, v86
	v_permlane32_swap_b32_e32 v85, v87
	v_permlane32_swap_b32_e32 v76, v78
	v_permlane32_swap_b32_e32 v77, v79
	v_permlane32_swap_b32_e32 v68, v70
	v_permlane32_swap_b32_e32 v69, v71
	v_permlane32_swap_b32_e32 v72, v74
	v_permlane32_swap_b32_e32 v73, v75
	ds_read_b64_tr_b16 v[80:81], v190 offset:0x4000
	ds_read_b64_tr_b16 v[82:83], v190 offset:0x4800
	ds_read_b64_tr_b16 v[88:89], v190 offset:0x5000
	ds_read_b64_tr_b16 v[90:91], v190 offset:0x5800
	ds_read_b64_tr_b16 v[92:93], v190 offset:0x6000
	ds_read_b64_tr_b16 v[94:95], v190 offset:0x6800
	ds_read_b64_tr_b16 v[150:151], v190 offset:0x7000
	ds_read_b64_tr_b16 v[152:153], v190 offset:0x7800
	s_waitcnt lgkmcnt(0)
	s_nop 0
	v_mfma_f32_32x32x16_bf16 v[50:65], v[84:87], v[80:83], v[50:65]
	ds_read_b64_tr_b16 v[80:81], v190 offset:0x4200
	ds_read_b64_tr_b16 v[82:83], v190 offset:0x4a00
	v_mfma_f32_32x32x16_bf16 v[50:65], v[76:79], v[88:91], v[50:65]
	ds_read_b64_tr_b16 v[88:89], v190 offset:0x5200
	ds_read_b64_tr_b16 v[90:91], v190 offset:0x5a00
	v_mfma_f32_32x32x16_bf16 v[50:65], v[68:71], v[92:95], v[50:65]
	ds_read_b64_tr_b16 v[92:93], v190 offset:0x6200
	ds_read_b64_tr_b16 v[94:95], v190 offset:0x6a00
	ds_read_b64_tr_b16 v[154:155], v190 offset:0x7200
	ds_read_b64_tr_b16 v[156:157], v190 offset:0x7a00
	s_waitcnt lgkmcnt(0)
	v_mfma_f32_32x32x16_bf16 v[50:65], v[72:75], v[150:153], v[50:65]
	v_mfma_f32_32x32x16_bf16 v[34:49], v[84:87], v[80:83], v[34:49]
	ds_read_b64_tr_b16 v[80:81], v190 offset:0x4400
	ds_read_b64_tr_b16 v[82:83], v190 offset:0x4c00
	v_mfma_f32_32x32x16_bf16 v[34:49], v[76:79], v[88:91], v[34:49]
	ds_read_b64_tr_b16 v[88:89], v190 offset:0x5400
	ds_read_b64_tr_b16 v[90:91], v190 offset:0x5c00
	v_mfma_f32_32x32x16_bf16 v[34:49], v[68:71], v[92:95], v[34:49]
	ds_read_b64_tr_b16 v[92:93], v190 offset:0x6400
	ds_read_b64_tr_b16 v[94:95], v190 offset:0x6c00
	ds_read_b64_tr_b16 v[150:151], v190 offset:0x7400
	ds_read_b64_tr_b16 v[152:153], v190 offset:0x7c00
	s_waitcnt lgkmcnt(0)
; __device__ __forceinline__ unsigned cvt_pk_bf16(float lo, float hi) { unsigned r; asm volatile("v_cvt_pk_bf16_f32 %0, %1, %2" : "=v"(r) : "v"(lo), "v"(hi)); return r; }
; #define SBAR() __builtin_amdgcn_sched_barrier(0)
; __device__ __forceinline__ int crow(int r, int hi) { return (r & 3) + 8 * (r >> 2) + 4 * hi; }
; #define SEAM_K0() do { VMWN(NQL); SWRITE_HK(0); SBAR(); } while (0)
; __device__ __forceinline__ int crow(int r, int hi) { return (r & 3) + 8 * (r >> 2) + 4 * hi; }
; __device__ __forceinline__ void moba_block(const BlockRef& cur, const BlockRef& nxt, char* lds, Seam& S) {
;     ...
;     finishSM(pB0, pB1, alB, l_reg, pa0, pa1, pa2, pa3); SBAR(); pv_tile<1>(o, vb0, pa0, pa1, pa2, pa3);
;     SBAR(); SEAM_K0();
;     if (hi == 0) li_l[r32] = l_reg; asm volatile("s_waitcnt lgkmcnt(0)" ::: "memory");
;     float rli[16];
; #pragma unroll
;     for (int r = 0; r < 16; ++r) rli[r] = __builtin_amdgcn_rcpf(li_l[crow(r, hi)]);
;     char* Ow = (char*)(cur.O + (size_t)(wid * QBLK) * LDO);
;     char* stg = lds + OSTG_OFF + wid * 4608;
;     unsigned st_w = (unsigned)(4 * hi * 144 + r32 * 2), st_r = (unsigned)((lane >> 3) * 144 + (lane & 7) * 16), g_off = (unsigned)((lane >> 3) * (LDO * 2) + (lane & 7) * 16);
;     asm volatile("" : "+v"(st_w), "+v"(st_r), "+v"(g_off));
; #pragma unroll
;     for (int h2 = 0; h2 < 2; ++h2) {
; #pragma unroll
;         for (int r = 0; r < 16; ++r)
; #pragma unroll
;             for (int dd = 0; dd < 2; ++dd) { const float v = o[2 * h2 + dd][r] * rli[r]; const float vn = __shfl_xor(v, 1);
;                 if ((r32 & 1) == 0) *(unsigned*)(stg + ((r & 3) + 8 * (r >> 2)) * 144 + dd * 64 + st_w) = cvt_pk_bf16(v, vn); }
;         asm volatile("s_waitcnt lgkmcnt(0)" ::: "memory");
	v_mfma_f32_32x32x16_bf16 v[34:49], v[72:75], v[154:157], v[34:49]
	v_mfma_f32_32x32x16_bf16 v[2:17], v[84:87], v[80:83], v[2:17]
	ds_read_b64_tr_b16 v[80:81], v190 offset:0x4600
	ds_read_b64_tr_b16 v[82:83], v190 offset:0x4e00
	v_mfma_f32_32x32x16_bf16 v[2:17], v[76:79], v[88:91], v[2:17]
	ds_read_b64_tr_b16 v[88:89], v190 offset:0x5600
	ds_read_b64_tr_b16 v[90:91], v190 offset:0x5e00
	v_mfma_f32_32x32x16_bf16 v[2:17], v[68:71], v[92:95], v[2:17]
	ds_read_b64_tr_b16 v[92:93], v190 offset:0x6600
	ds_read_b64_tr_b16 v[94:95], v190 offset:0x6e00
	ds_read_b64_tr_b16 v[154:155], v190 offset:0x7600
	ds_read_b64_tr_b16 v[156:157], v190 offset:0x7e00
	s_waitcnt lgkmcnt(0)
	v_mfma_f32_32x32x16_bf16 v[2:17], v[72:75], v[150:153], v[2:17]
	v_mfma_f32_32x32x16_bf16 v[18:33], v[84:87], v[80:83], v[18:33]
	v_mfma_f32_32x32x16_bf16 v[18:33], v[76:79], v[88:91], v[18:33]
	v_mfma_f32_32x32x16_bf16 v[18:33], v[68:71], v[92:95], v[18:33]
	v_mfma_f32_32x32x16_bf16 v[18:33], v[72:75], v[154:157], v[18:33]
	s_waitcnt vmcnt(8)
	s_waitcnt vmcnt(9)
	ds_write_b128 v187, v[142:145] offset:32768
	s_waitcnt vmcnt(8)
	ds_write_b128 v187, v[146:149] offset:40960
	s_and_saveexec_b64 s[6:7], s[4:5]
	v_add_f32_e32 v68, v106, v107
	v_fmac_f32_e32 v68, v191, v204
	v_add_f32_e32 v66, v66, v67
	v_fmac_f32_e32 v66, v68, v108
	ds_write_b32 v189, v66
	s_or_b64 exec, exec, s[6:7]
	s_waitcnt lgkmcnt(0)
	ds_read_b128 v[78:81], v188
	s_movk_i32 s1, 0x90
	v_and_b32_e32 v84, 64, v180
	v_add_u32_e32 v84, 64, v84
	ds_read_b128 v[74:77], v188 offset:32
	ds_read_b128 v[70:73], v188 offset:64
	ds_read_b128 v[66:69], v188 offset:96
	s_waitcnt lgkmcnt(3)
	v_rcp_f32_e32 v82, v78
	v_mul_u32_u24_e32 v78, 0x240, v184
	v_lshl_or_b32 v86, v183, 1, v78
	v_lshrrev_b32_e32 v78, 3, v186
	v_mad_u32_u24 v83, v78, s1, v185
	v_lshl_or_b32 v162, v78, 13, v185
	v_xor_b32_e32 v78, 1, v180
	v_cmp_lt_i32_e32 vcc, v78, v84
	v_mul_f32_e32 v84, v50, v82
	s_mulk_i32 s77, 0x1200
	v_cndmask_b32_e32 v78, v180, v78, vcc
	v_lshlrev_b32_e32 v78, 2, v78
	s_nop 1
	v_mov_b32_dpp v85, v84 quad_perm:[1,0,3,2] row_mask:0xf bank_mask:0xf
	s_add_i32 s0, s77, 0
	s_add_i32 s0, s0, 0x13000
	v_and_b32_e32 v50, 1, v181
	v_cmp_eq_u32_e64 s[4:5], 0, v50
	v_add_u32_e32 v50, s0, v86
	s_and_saveexec_b64 s[6:7], s[4:5]
	s_cbranch_execz .LBB0_812
	s_waitcnt lgkmcnt(0)
	v_cvt_pk_bf16_f32 v84, v84, v85
	ds_write_b32 v50, v84
.LBB0_812:
	s_or_b64 exec, exec, s[6:7]
	v_mul_f32_e32 v34, v34, v82
	s_nop 1
	v_mov_b32_dpp v84, v34 quad_perm:[1,0,3,2] row_mask:0xf bank_mask:0xf
	s_and_saveexec_b64 s[6:7], s[4:5]
	s_cbranch_execz .LBB0_814
	s_waitcnt lgkmcnt(0)
	v_cvt_pk_bf16_f32 v34, v34, v84
	ds_write_b32 v50, v34 offset:64
.LBB0_814:
	s_or_b64 exec, exec, s[6:7]
	v_rcp_f32_e32 v79, v79
	s_nop 0
	v_mul_f32_e32 v34, v51, v79
	s_nop 1
	v_mov_b32_dpp v51, v34 quad_perm:[1,0,3,2] row_mask:0xf bank_mask:0xf
	s_and_saveexec_b64 s[6:7], s[4:5]
	s_cbranch_execz .LBB0_816
	s_waitcnt lgkmcnt(0)
	v_cvt_pk_bf16_f32 v34, v34, v51
	ds_write_b32 v50, v34 offset:144
.LBB0_816:
	s_or_b64 exec, exec, s[6:7]
	v_mul_f32_e32 v34, v35, v79
	s_nop 1
	v_mov_b32_dpp v35, v34 quad_perm:[1,0,3,2] row_mask:0xf bank_mask:0xf
	s_and_saveexec_b64 s[6:7], s[4:5]
	s_cbranch_execz .LBB0_818
	s_waitcnt lgkmcnt(0)
	v_cvt_pk_bf16_f32 v34, v34, v35
	ds_write_b32 v50, v34 offset:208
.LBB0_818:
	s_or_b64 exec, exec, s[6:7]
	s_waitcnt lgkmcnt(1)
	v_rcp_f32_e32 v51, v80
	s_nop 0
	v_mul_f32_e32 v34, v52, v51
	s_waitcnt lgkmcnt(0)
	s_nop 1
	v_mov_b32_dpp v35, v34 quad_perm:[1,0,3,2] row_mask:0xf bank_mask:0xf
	s_and_saveexec_b64 s[6:7], s[4:5]
	s_cbranch_execz .LBB0_820
	s_waitcnt lgkmcnt(0)
	v_cvt_pk_bf16_f32 v34, v34, v35
	ds_write_b32 v50, v34 offset:288
.LBB0_820:
	s_or_b64 exec, exec, s[6:7]
	v_mul_f32_e32 v34, v36, v51
	s_waitcnt lgkmcnt(0)
	s_nop 1
	v_mov_b32_dpp v35, v34 quad_perm:[1,0,3,2] row_mask:0xf bank_mask:0xf
	s_and_saveexec_b64 s[6:7], s[4:5]
	s_cbranch_execz .LBB0_822
	s_waitcnt lgkmcnt(0)
	v_cvt_pk_bf16_f32 v34, v34, v35
	ds_write_b32 v50, v34 offset:352
.LBB0_822:
	s_or_b64 exec, exec, s[6:7]
	v_rcp_f32_e32 v36, v81
	s_nop 0
	v_mul_f32_e32 v34, v53, v36
	s_waitcnt lgkmcnt(0)
	s_nop 1
	v_mov_b32_dpp v35, v34 quad_perm:[1,0,3,2] row_mask:0xf bank_mask:0xf
	s_and_saveexec_b64 s[6:7], s[4:5]
	s_cbranch_execz .LBB0_824
	s_waitcnt lgkmcnt(0)
	v_cvt_pk_bf16_f32 v34, v34, v35
	ds_write_b32 v50, v34 offset:432
.LBB0_824:
	s_or_b64 exec, exec, s[6:7]
	v_mul_f32_e32 v34, v37, v36
	s_waitcnt lgkmcnt(0)
	s_nop 1
	v_mov_b32_dpp v35, v34 quad_perm:[1,0,3,2] row_mask:0xf bank_mask:0xf
	s_and_saveexec_b64 s[6:7], s[4:5]
	s_cbranch_execz .LBB0_826
	s_waitcnt lgkmcnt(0)
	v_cvt_pk_bf16_f32 v34, v34, v35
	ds_write_b32 v50, v34 offset:496
.LBB0_826:
	s_or_b64 exec, exec, s[6:7]
	v_rcp_f32_e32 v37, v74
	s_nop 0
	v_mul_f32_e32 v34, v54, v37
	s_waitcnt lgkmcnt(0)
	s_nop 1
	v_mov_b32_dpp v35, v34 quad_perm:[1,0,3,2] row_mask:0xf bank_mask:0xf
	s_and_saveexec_b64 s[6:7], s[4:5]
	s_cbranch_execz .LBB0_828
	s_waitcnt lgkmcnt(0)
	v_cvt_pk_bf16_f32 v34, v34, v35
	ds_write_b32 v50, v34 offset:1152
.LBB0_828:
	s_or_b64 exec, exec, s[6:7]
	v_mul_f32_e32 v34, v38, v37
	s_waitcnt lgkmcnt(0)
	s_nop 1
	v_mov_b32_dpp v35, v34 quad_perm:[1,0,3,2] row_mask:0xf bank_mask:0xf
	s_and_saveexec_b64 s[6:7], s[4:5]
	s_cbranch_execz .LBB0_830
	s_waitcnt lgkmcnt(0)
	v_cvt_pk_bf16_f32 v34, v34, v35
	ds_write_b32 v50, v34 offset:1216
.LBB0_830:
	s_or_b64 exec, exec, s[6:7]
	v_rcp_f32_e32 v38, v75
	s_nop 0
	v_mul_f32_e32 v34, v55, v38
	s_waitcnt lgkmcnt(0)
	s_nop 1
	v_mov_b32_dpp v35, v34 quad_perm:[1,0,3,2] row_mask:0xf bank_mask:0xf
	s_and_saveexec_b64 s[6:7], s[4:5]
	s_cbranch_execz .LBB0_832
	s_waitcnt lgkmcnt(0)
	v_cvt_pk_bf16_f32 v34, v34, v35
	ds_write_b32 v50, v34 offset:1296
; __device__ __forceinline__ unsigned cvt_pk_bf16(float lo, float hi) { unsigned r; asm volatile("v_cvt_pk_bf16_f32 %0, %1, %2" : "=v"(r) : "v"(lo), "v"(hi)); return r; }
; __device__ __forceinline__ void moba_block(const BlockRef& cur, const BlockRef& nxt, char* lds, Seam& S) {
;     ...
;     for (int h2 = 0; h2 < 2; ++h2) {
; #pragma unroll
;         for (int r = 0; r < 16; ++r)
; #pragma unroll
;             for (int dd = 0; dd < 2; ++dd) { const float v = o[2 * h2 + dd][r] * rli[r]; const float vn = __shfl_xor(v, 1);
;                 if ((r32 & 1) == 0) *(unsigned*)(stg + ((r & 3) + 8 * (r >> 2)) * 144 + dd * 64 + st_w) = cvt_pk_bf16(v, vn); }
.LBB0_832:
	s_or_b64 exec, exec, s[6:7]
	v_mul_f32_e32 v34, v39, v38
	s_waitcnt lgkmcnt(0)
	s_nop 1
	v_mov_b32_dpp v35, v34 quad_perm:[1,0,3,2] row_mask:0xf bank_mask:0xf
	s_and_saveexec_b64 s[6:7], s[4:5]
	s_cbranch_execz .LBB0_834
	s_waitcnt lgkmcnt(0)
	v_cvt_pk_bf16_f32 v34, v34, v35
	ds_write_b32 v50, v34 offset:1360
.LBB0_834:
	s_or_b64 exec, exec, s[6:7]
	v_rcp_f32_e32 v39, v76
	s_nop 0
	v_mul_f32_e32 v34, v56, v39
	s_waitcnt lgkmcnt(0)
	s_nop 1
	v_mov_b32_dpp v35, v34 quad_perm:[1,0,3,2] row_mask:0xf bank_mask:0xf
	s_and_saveexec_b64 s[6:7], s[4:5]
	s_cbranch_execz .LBB0_836
	s_waitcnt lgkmcnt(0)
	v_cvt_pk_bf16_f32 v34, v34, v35
	ds_write_b32 v50, v34 offset:1440
.LBB0_836:
	s_or_b64 exec, exec, s[6:7]
	v_mul_f32_e32 v34, v40, v39
	s_waitcnt lgkmcnt(0)
	s_nop 1
	v_mov_b32_dpp v35, v34 quad_perm:[1,0,3,2] row_mask:0xf bank_mask:0xf
	s_and_saveexec_b64 s[6:7], s[4:5]
	s_cbranch_execz .LBB0_838
	s_waitcnt lgkmcnt(0)
	v_cvt_pk_bf16_f32 v34, v34, v35
	ds_write_b32 v50, v34 offset:1504
.LBB0_838:
	s_or_b64 exec, exec, s[6:7]
	v_rcp_f32_e32 v40, v77
	s_nop 0
	v_mul_f32_e32 v34, v57, v40
	s_waitcnt lgkmcnt(0)
	s_nop 1
	v_mov_b32_dpp v35, v34 quad_perm:[1,0,3,2] row_mask:0xf bank_mask:0xf
	s_and_saveexec_b64 s[6:7], s[4:5]
	s_cbranch_execz .LBB0_840
	s_waitcnt lgkmcnt(0)
	v_cvt_pk_bf16_f32 v34, v34, v35
	ds_write_b32 v50, v34 offset:1584
.LBB0_840:
	s_or_b64 exec, exec, s[6:7]
	v_mul_f32_e32 v34, v41, v40
	s_waitcnt lgkmcnt(0)
	s_nop 1
	v_mov_b32_dpp v35, v34 quad_perm:[1,0,3,2] row_mask:0xf bank_mask:0xf
	s_and_saveexec_b64 s[6:7], s[4:5]
	s_cbranch_execz .LBB0_842
	s_waitcnt lgkmcnt(0)
	v_cvt_pk_bf16_f32 v34, v34, v35
	ds_write_b32 v50, v34 offset:1648
.LBB0_842:
	s_or_b64 exec, exec, s[6:7]
	v_rcp_f32_e32 v41, v70
	s_nop 0
	v_mul_f32_e32 v34, v58, v41
	s_waitcnt lgkmcnt(0)
	s_nop 1
	v_mov_b32_dpp v35, v34 quad_perm:[1,0,3,2] row_mask:0xf bank_mask:0xf
	s_and_saveexec_b64 s[6:7], s[4:5]
	s_cbranch_execz .LBB0_844
	s_waitcnt lgkmcnt(0)
	v_cvt_pk_bf16_f32 v34, v34, v35
	ds_write_b32 v50, v34 offset:2304
.LBB0_844:
	s_or_b64 exec, exec, s[6:7]
	v_mul_f32_e32 v34, v42, v41
	s_waitcnt lgkmcnt(0)
	s_nop 1
	v_mov_b32_dpp v35, v34 quad_perm:[1,0,3,2] row_mask:0xf bank_mask:0xf
	s_and_saveexec_b64 s[6:7], s[4:5]
	s_cbranch_execz .LBB0_846
	s_waitcnt lgkmcnt(0)
	v_cvt_pk_bf16_f32 v34, v34, v35
	ds_write_b32 v50, v34 offset:2368
.LBB0_846:
	s_or_b64 exec, exec, s[6:7]
	v_rcp_f32_e32 v42, v71
	s_nop 0
	v_mul_f32_e32 v34, v59, v42
	s_waitcnt lgkmcnt(0)
	s_nop 1
	v_mov_b32_dpp v35, v34 quad_perm:[1,0,3,2] row_mask:0xf bank_mask:0xf
	s_and_saveexec_b64 s[6:7], s[4:5]
	s_cbranch_execz .LBB0_848
	s_waitcnt lgkmcnt(0)
	v_cvt_pk_bf16_f32 v34, v34, v35
	ds_write_b32 v50, v34 offset:2448
.LBB0_848:
	s_or_b64 exec, exec, s[6:7]
	v_mul_f32_e32 v34, v43, v42
	s_waitcnt lgkmcnt(0)
	s_nop 1
	v_mov_b32_dpp v35, v34 quad_perm:[1,0,3,2] row_mask:0xf bank_mask:0xf
	s_and_saveexec_b64 s[6:7], s[4:5]
	s_cbranch_execz .LBB0_850
	s_waitcnt lgkmcnt(0)
	v_cvt_pk_bf16_f32 v34, v34, v35
	ds_write_b32 v50, v34 offset:2512
.LBB0_850:
	s_or_b64 exec, exec, s[6:7]
	v_rcp_f32_e32 v43, v72
	s_nop 0
	v_mul_f32_e32 v34, v60, v43
	s_waitcnt lgkmcnt(0)
	s_nop 1
	v_mov_b32_dpp v35, v34 quad_perm:[1,0,3,2] row_mask:0xf bank_mask:0xf
	s_and_saveexec_b64 s[6:7], s[4:5]
	s_cbranch_execz .LBB0_852
	s_waitcnt lgkmcnt(0)
	v_cvt_pk_bf16_f32 v34, v34, v35
	ds_write_b32 v50, v34 offset:2592
.LBB0_852:
	s_or_b64 exec, exec, s[6:7]
	v_mul_f32_e32 v34, v44, v43
	s_waitcnt lgkmcnt(0)
	s_nop 1
	v_mov_b32_dpp v35, v34 quad_perm:[1,0,3,2] row_mask:0xf bank_mask:0xf
	s_and_saveexec_b64 s[6:7], s[4:5]
	s_cbranch_execz .LBB0_854
	s_waitcnt lgkmcnt(0)
	v_cvt_pk_bf16_f32 v34, v34, v35
	ds_write_b32 v50, v34 offset:2656
.LBB0_854:
	s_or_b64 exec, exec, s[6:7]
	v_rcp_f32_e32 v44, v73
	s_nop 0
	v_mul_f32_e32 v34, v61, v44
	s_waitcnt lgkmcnt(0)
	s_nop 1
	v_mov_b32_dpp v35, v34 quad_perm:[1,0,3,2] row_mask:0xf bank_mask:0xf
	s_and_saveexec_b64 s[6:7], s[4:5]
	s_cbranch_execz .LBB0_856
	s_waitcnt lgkmcnt(0)
	v_cvt_pk_bf16_f32 v34, v34, v35
	ds_write_b32 v50, v34 offset:2736
.LBB0_856:
	s_or_b64 exec, exec, s[6:7]
	v_mul_f32_e32 v34, v45, v44
	s_waitcnt lgkmcnt(0)
	s_nop 1
	v_mov_b32_dpp v35, v34 quad_perm:[1,0,3,2] row_mask:0xf bank_mask:0xf
	s_and_saveexec_b64 s[6:7], s[4:5]
	s_cbranch_execz .LBB0_858
	s_waitcnt lgkmcnt(0)
	v_cvt_pk_bf16_f32 v34, v34, v35
	ds_write_b32 v50, v34 offset:2800
.LBB0_858:
	s_or_b64 exec, exec, s[6:7]
	v_rcp_f32_e32 v45, v66
	s_nop 0
	v_mul_f32_e32 v34, v62, v45
	s_waitcnt lgkmcnt(0)
	s_nop 1
	v_mov_b32_dpp v35, v34 quad_perm:[1,0,3,2] row_mask:0xf bank_mask:0xf
	s_and_saveexec_b64 s[6:7], s[4:5]
	s_cbranch_execz .LBB0_860
	s_waitcnt lgkmcnt(0)
	v_cvt_pk_bf16_f32 v34, v34, v35
	ds_write_b32 v50, v34 offset:3456
.LBB0_860:
	s_or_b64 exec, exec, s[6:7]
	v_mul_f32_e32 v34, v46, v45
	s_waitcnt lgkmcnt(0)
	s_nop 1
	v_mov_b32_dpp v35, v34 quad_perm:[1,0,3,2] row_mask:0xf bank_mask:0xf
	s_and_saveexec_b64 s[6:7], s[4:5]
	s_cbranch_execz .LBB0_862
	s_waitcnt lgkmcnt(0)
	v_cvt_pk_bf16_f32 v34, v34, v35
	ds_write_b32 v50, v34 offset:3520
.LBB0_862:
	s_or_b64 exec, exec, s[6:7]
	v_rcp_f32_e32 v46, v67
	s_nop 0
	v_mul_f32_e32 v34, v63, v46
	s_waitcnt lgkmcnt(0)
	s_nop 1
	v_mov_b32_dpp v35, v34 quad_perm:[1,0,3,2] row_mask:0xf bank_mask:0xf
	s_and_saveexec_b64 s[6:7], s[4:5]
	s_cbranch_execz .LBB0_864
	s_waitcnt lgkmcnt(0)
	v_cvt_pk_bf16_f32 v34, v34, v35
	ds_write_b32 v50, v34 offset:3600
.LBB0_864:
	s_or_b64 exec, exec, s[6:7]
	v_mul_f32_e32 v34, v47, v46
	s_waitcnt lgkmcnt(0)
	s_nop 1
	v_mov_b32_dpp v35, v34 quad_perm:[1,0,3,2] row_mask:0xf bank_mask:0xf
	s_and_saveexec_b64 s[6:7], s[4:5]
	s_cbranch_execz .LBB0_866
	s_waitcnt lgkmcnt(0)
	v_cvt_pk_bf16_f32 v34, v34, v35
	ds_write_b32 v50, v34 offset:3664
; __device__ __forceinline__ unsigned cvt_pk_bf16(float lo, float hi) { unsigned r; asm volatile("v_cvt_pk_bf16_f32 %0, %1, %2" : "=v"(r) : "v"(lo), "v"(hi)); return r; }
; __device__ __forceinline__ void moba_block(const BlockRef& cur, const BlockRef& nxt, char* lds, Seam& S) {
;     ...
;             for (int dd = 0; dd < 2; ++dd) { const float v = o[2 * h2 + dd][r] * rli[r]; const float vn = __shfl_xor(v, 1);
;                 if ((r32 & 1) == 0) *(unsigned*)(stg + ((r & 3) + 8 * (r >> 2)) * 144 + dd * 64 + st_w) = cvt_pk_bf16(v, vn); }
;         asm volatile("s_waitcnt lgkmcnt(0)" ::: "memory");
; #pragma unroll
;         for (int j = 0; j < 4; ++j) { const u32x4 w = *(const u32x4*)(stg + j * 8 * 144 + st_r); *(u32x4*)(Ow + (size_t)j * 8 * (LDO * 2) + h2 * 128 + g_off) = w; }
;         asm volatile("s_waitcnt lgkmcnt(0)" ::: "memory");
;     }
.LBB0_866:
	s_or_b64 exec, exec, s[6:7]
	v_rcp_f32_e32 v47, v68
	s_nop 0
	v_mul_f32_e32 v34, v64, v47
	s_waitcnt lgkmcnt(0)
	s_nop 1
	v_mov_b32_dpp v35, v34 quad_perm:[1,0,3,2] row_mask:0xf bank_mask:0xf
	s_and_saveexec_b64 s[6:7], s[4:5]
	s_cbranch_execz .LBB0_868
	s_waitcnt lgkmcnt(0)
	v_cvt_pk_bf16_f32 v34, v34, v35
	ds_write_b32 v50, v34 offset:3744
.LBB0_868:
	s_or_b64 exec, exec, s[6:7]
	v_mul_f32_e32 v34, v48, v47
	s_waitcnt lgkmcnt(0)
	s_nop 1
	v_mov_b32_dpp v35, v34 quad_perm:[1,0,3,2] row_mask:0xf bank_mask:0xf
	s_and_saveexec_b64 s[6:7], s[4:5]
	s_cbranch_execz .LBB0_870
	s_waitcnt lgkmcnt(0)
	v_cvt_pk_bf16_f32 v34, v34, v35
	ds_write_b32 v50, v34 offset:3808
.LBB0_870:
	s_or_b64 exec, exec, s[6:7]
	v_rcp_f32_e32 v48, v69
	s_nop 0
	v_mul_f32_e32 v34, v65, v48
	s_waitcnt lgkmcnt(0)
	s_nop 1
	v_mov_b32_dpp v35, v34 quad_perm:[1,0,3,2] row_mask:0xf bank_mask:0xf
	s_and_saveexec_b64 s[6:7], s[4:5]
	s_cbranch_execz .LBB0_872
	s_waitcnt lgkmcnt(0)
	v_cvt_pk_bf16_f32 v34, v34, v35
	ds_write_b32 v50, v34 offset:3888
.LBB0_872:
	s_or_b64 exec, exec, s[6:7]
	v_mul_f32_e32 v34, v49, v48
	s_waitcnt lgkmcnt(0)
	s_nop 1
	v_mov_b32_dpp v35, v34 quad_perm:[1,0,3,2] row_mask:0xf bank_mask:0xf
	s_and_saveexec_b64 s[6:7], s[4:5]
	s_cbranch_execz .LBB0_874
	s_waitcnt lgkmcnt(0)
	v_cvt_pk_bf16_f32 v34, v34, v35
	ds_write_b32 v50, v34 offset:3952
.LBB0_874:
	s_or_b64 exec, exec, s[6:7]
	s_waitcnt lgkmcnt(0)
	v_add_u32_e32 v49, s0, v83
	ds_read_b128 v[52:55], v49
	ds_read_b128 v[56:59], v49 offset:1152
	s_ashr_i32 s77, s76, 31
	s_lshl_b64 s[6:7], s[76:77], 13
	s_add_u32 s0, s70, s6
	s_addc_u32 s1, s71, s7
	s_waitcnt lgkmcnt(2)
	v_lshl_add_u64 v[34:35], s[0:1], 0, v[162:163]
	s_waitcnt lgkmcnt(1)
	global_store_dwordx4 v162, v[52:55], s[0:1]
	s_mov_b32 s0, 0x10000
	v_mul_f32_e32 v2, v2, v82
	v_add_co_u32_e32 v52, vcc, s0, v34
	s_nop 1
	v_addc_co_u32_e32 v53, vcc, 0, v35, vcc
	s_waitcnt lgkmcnt(0)
	global_store_dwordx4 v[52:53], v[56:59], off
	ds_read_b128 v[52:55], v49 offset:2304
	ds_read_b128 v[56:59], v49 offset:3456
	v_add_co_u32_e32 v60, vcc, 0x20000, v34
	s_nop 1
	v_addc_co_u32_e32 v61, vcc, 0, v35, vcc
	s_waitcnt lgkmcnt(1)
	global_store_dwordx4 v[60:61], v[52:55], off
	s_nop 1
	v_add_co_u32_e32 v52, vcc, 0x30000, v34
	s_nop 1
	v_addc_co_u32_e32 v53, vcc, 0, v35, vcc
	s_waitcnt lgkmcnt(0)
	global_store_dwordx4 v[52:53], v[56:59], off
	s_nop 1
	v_mov_b32_dpp v52, v2 quad_perm:[1,0,3,2] row_mask:0xf bank_mask:0xf
	s_waitcnt lgkmcnt(0)
	s_and_saveexec_b64 s[6:7], s[4:5]
	s_cbranch_execz .LBB0_876
	s_waitcnt lgkmcnt(0)
	v_cvt_pk_bf16_f32 v2, v2, v52
	ds_write_b32 v50, v2
.LBB0_876:
	s_or_b64 exec, exec, s[6:7]
	v_mul_f32_e32 v2, v18, v82
	s_nop 1
	v_mov_b32_dpp v18, v2 quad_perm:[1,0,3,2] row_mask:0xf bank_mask:0xf
	s_and_saveexec_b64 s[6:7], s[4:5]
	s_cbranch_execz .LBB0_878
	s_waitcnt lgkmcnt(0)
	v_cvt_pk_bf16_f32 v2, v2, v18
	ds_write_b32 v50, v2 offset:64
.LBB0_878:
	s_or_b64 exec, exec, s[6:7]
	v_mul_f32_e32 v2, v3, v79
	s_nop 1
	v_mov_b32_dpp v3, v2 quad_perm:[1,0,3,2] row_mask:0xf bank_mask:0xf
	s_and_saveexec_b64 s[6:7], s[4:5]
	s_cbranch_execz .LBB0_880
	s_waitcnt lgkmcnt(0)
	v_cvt_pk_bf16_f32 v2, v2, v3
	ds_write_b32 v50, v2 offset:144
.LBB0_880:
	s_or_b64 exec, exec, s[6:7]
	v_mul_f32_e32 v2, v19, v79
	s_waitcnt lgkmcnt(0)
	s_nop 1
	v_mov_b32_dpp v3, v2 quad_perm:[1,0,3,2] row_mask:0xf bank_mask:0xf
	s_and_saveexec_b64 s[6:7], s[4:5]
	s_cbranch_execz .LBB0_882
	s_waitcnt lgkmcnt(0)
	v_cvt_pk_bf16_f32 v2, v2, v3
	ds_write_b32 v50, v2 offset:208
.LBB0_882:
	s_or_b64 exec, exec, s[6:7]
	v_mul_f32_e32 v2, v4, v51
	s_waitcnt lgkmcnt(0)
	s_nop 1
	v_mov_b32_dpp v3, v2 quad_perm:[1,0,3,2] row_mask:0xf bank_mask:0xf
	s_and_saveexec_b64 s[6:7], s[4:5]
	s_cbranch_execz .LBB0_884
	s_waitcnt lgkmcnt(0)
	v_cvt_pk_bf16_f32 v2, v2, v3
	ds_write_b32 v50, v2 offset:288
.LBB0_884:
	s_or_b64 exec, exec, s[6:7]
	v_mul_f32_e32 v2, v20, v51
	s_waitcnt lgkmcnt(0)
	s_nop 1
	v_mov_b32_dpp v3, v2 quad_perm:[1,0,3,2] row_mask:0xf bank_mask:0xf
	s_and_saveexec_b64 s[6:7], s[4:5]
	s_cbranch_execz .LBB0_886
	s_waitcnt lgkmcnt(0)
	v_cvt_pk_bf16_f32 v2, v2, v3
	ds_write_b32 v50, v2 offset:352
.LBB0_886:
	s_or_b64 exec, exec, s[6:7]
	v_mul_f32_e32 v2, v5, v36
	s_waitcnt lgkmcnt(0)
	s_nop 1
	v_mov_b32_dpp v3, v2 quad_perm:[1,0,3,2] row_mask:0xf bank_mask:0xf
	s_and_saveexec_b64 s[6:7], s[4:5]
	s_cbranch_execz .LBB0_888
	s_waitcnt lgkmcnt(0)
	v_cvt_pk_bf16_f32 v2, v2, v3
	ds_write_b32 v50, v2 offset:432
.LBB0_888:
	s_or_b64 exec, exec, s[6:7]
	v_mul_f32_e32 v2, v21, v36
	s_waitcnt lgkmcnt(0)
	s_nop 1
	v_mov_b32_dpp v3, v2 quad_perm:[1,0,3,2] row_mask:0xf bank_mask:0xf
	s_and_saveexec_b64 s[6:7], s[4:5]
	s_cbranch_execz .LBB0_890
	s_waitcnt lgkmcnt(0)
	v_cvt_pk_bf16_f32 v2, v2, v3
	ds_write_b32 v50, v2 offset:496
.LBB0_890:
	s_or_b64 exec, exec, s[6:7]
	v_mul_f32_e32 v2, v6, v37
	s_waitcnt lgkmcnt(0)
	s_nop 1
	v_mov_b32_dpp v3, v2 quad_perm:[1,0,3,2] row_mask:0xf bank_mask:0xf
	s_and_saveexec_b64 s[6:7], s[4:5]
	s_cbranch_execz .LBB0_892
	s_waitcnt lgkmcnt(0)
	v_cvt_pk_bf16_f32 v2, v2, v3
	ds_write_b32 v50, v2 offset:1152
.LBB0_892:
	s_or_b64 exec, exec, s[6:7]
	v_mul_f32_e32 v2, v22, v37
	s_waitcnt lgkmcnt(0)
	s_nop 1
	v_mov_b32_dpp v3, v2 quad_perm:[1,0,3,2] row_mask:0xf bank_mask:0xf
	s_and_saveexec_b64 s[6:7], s[4:5]
	s_cbranch_execz .LBB0_894
	s_waitcnt lgkmcnt(0)
	v_cvt_pk_bf16_f32 v2, v2, v3
	ds_write_b32 v50, v2 offset:1216
.LBB0_894:
	s_or_b64 exec, exec, s[6:7]
	v_mul_f32_e32 v2, v7, v38
	s_waitcnt lgkmcnt(0)
	s_nop 1
	v_mov_b32_dpp v3, v2 quad_perm:[1,0,3,2] row_mask:0xf bank_mask:0xf
	s_and_saveexec_b64 s[6:7], s[4:5]
	s_cbranch_execz .LBB0_896
	s_waitcnt lgkmcnt(0)
	v_cvt_pk_bf16_f32 v2, v2, v3
	ds_write_b32 v50, v2 offset:1296
; __device__ __forceinline__ unsigned cvt_pk_bf16(float lo, float hi) { unsigned r; asm volatile("v_cvt_pk_bf16_f32 %0, %1, %2" : "=v"(r) : "v"(lo), "v"(hi)); return r; }
; __device__ __forceinline__ void moba_block(const BlockRef& cur, const BlockRef& nxt, char* lds, Seam& S) {
;     ...
;     for (int h2 = 0; h2 < 2; ++h2) {
; #pragma unroll
;         for (int r = 0; r < 16; ++r)
; #pragma unroll
;             for (int dd = 0; dd < 2; ++dd) { const float v = o[2 * h2 + dd][r] * rli[r]; const float vn = __shfl_xor(v, 1);
;                 if ((r32 & 1) == 0) *(unsigned*)(stg + ((r & 3) + 8 * (r >> 2)) * 144 + dd * 64 + st_w) = cvt_pk_bf16(v, vn); }
.LBB0_896:
	s_or_b64 exec, exec, s[6:7]
	v_mul_f32_e32 v2, v23, v38
	s_waitcnt lgkmcnt(0)
	s_nop 1
	v_mov_b32_dpp v3, v2 quad_perm:[1,0,3,2] row_mask:0xf bank_mask:0xf
	s_and_saveexec_b64 s[6:7], s[4:5]
	s_cbranch_execz .LBB0_898
	s_waitcnt lgkmcnt(0)
	v_cvt_pk_bf16_f32 v2, v2, v3
	ds_write_b32 v50, v2 offset:1360
.LBB0_898:
	s_or_b64 exec, exec, s[6:7]
	v_mul_f32_e32 v2, v8, v39
	s_waitcnt lgkmcnt(0)
	s_nop 1
	v_mov_b32_dpp v3, v2 quad_perm:[1,0,3,2] row_mask:0xf bank_mask:0xf
	s_and_saveexec_b64 s[6:7], s[4:5]
	s_cbranch_execz .LBB0_900
	s_waitcnt lgkmcnt(0)
	v_cvt_pk_bf16_f32 v2, v2, v3
	ds_write_b32 v50, v2 offset:1440
.LBB0_900:
	s_or_b64 exec, exec, s[6:7]
	v_mul_f32_e32 v2, v24, v39
	s_waitcnt lgkmcnt(0)
	s_nop 1
	v_mov_b32_dpp v3, v2 quad_perm:[1,0,3,2] row_mask:0xf bank_mask:0xf
	s_and_saveexec_b64 s[6:7], s[4:5]
	s_cbranch_execz .LBB0_902
	s_waitcnt lgkmcnt(0)
	v_cvt_pk_bf16_f32 v2, v2, v3
	ds_write_b32 v50, v2 offset:1504
.LBB0_902:
	s_or_b64 exec, exec, s[6:7]
	v_mul_f32_e32 v2, v9, v40
	s_waitcnt lgkmcnt(0)
	s_nop 1
	v_mov_b32_dpp v3, v2 quad_perm:[1,0,3,2] row_mask:0xf bank_mask:0xf
	s_and_saveexec_b64 s[6:7], s[4:5]
	s_cbranch_execz .LBB0_904
	s_waitcnt lgkmcnt(0)
	v_cvt_pk_bf16_f32 v2, v2, v3
	ds_write_b32 v50, v2 offset:1584
.LBB0_904:
	s_or_b64 exec, exec, s[6:7]
	v_mul_f32_e32 v2, v25, v40
	s_waitcnt lgkmcnt(0)
	s_nop 1
	v_mov_b32_dpp v3, v2 quad_perm:[1,0,3,2] row_mask:0xf bank_mask:0xf
	s_and_saveexec_b64 s[6:7], s[4:5]
	s_cbranch_execz .LBB0_906
	s_waitcnt lgkmcnt(0)
	v_cvt_pk_bf16_f32 v2, v2, v3
	ds_write_b32 v50, v2 offset:1648
.LBB0_906:
	s_or_b64 exec, exec, s[6:7]
	v_mul_f32_e32 v2, v10, v41
	s_waitcnt lgkmcnt(0)
	s_nop 1
	v_mov_b32_dpp v3, v2 quad_perm:[1,0,3,2] row_mask:0xf bank_mask:0xf
	s_and_saveexec_b64 s[6:7], s[4:5]
	s_cbranch_execz .LBB0_908
	s_waitcnt lgkmcnt(0)
	v_cvt_pk_bf16_f32 v2, v2, v3
	ds_write_b32 v50, v2 offset:2304
.LBB0_908:
	s_or_b64 exec, exec, s[6:7]
	v_mul_f32_e32 v2, v26, v41
	s_waitcnt lgkmcnt(0)
	s_nop 1
	v_mov_b32_dpp v3, v2 quad_perm:[1,0,3,2] row_mask:0xf bank_mask:0xf
	s_and_saveexec_b64 s[6:7], s[4:5]
	s_cbranch_execz .LBB0_910
	s_waitcnt lgkmcnt(0)
	v_cvt_pk_bf16_f32 v2, v2, v3
	ds_write_b32 v50, v2 offset:2368
.LBB0_910:
	s_or_b64 exec, exec, s[6:7]
	v_mul_f32_e32 v2, v11, v42
	s_waitcnt lgkmcnt(0)
	s_nop 1
	v_mov_b32_dpp v3, v2 quad_perm:[1,0,3,2] row_mask:0xf bank_mask:0xf
	s_and_saveexec_b64 s[6:7], s[4:5]
	s_cbranch_execz .LBB0_912
	s_waitcnt lgkmcnt(0)
	v_cvt_pk_bf16_f32 v2, v2, v3
	ds_write_b32 v50, v2 offset:2448
.LBB0_912:
	s_or_b64 exec, exec, s[6:7]
	v_mul_f32_e32 v2, v27, v42
	s_waitcnt lgkmcnt(0)
	s_nop 1
	v_mov_b32_dpp v3, v2 quad_perm:[1,0,3,2] row_mask:0xf bank_mask:0xf
	s_and_saveexec_b64 s[6:7], s[4:5]
	s_cbranch_execz .LBB0_914
	s_waitcnt lgkmcnt(0)
	v_cvt_pk_bf16_f32 v2, v2, v3
	ds_write_b32 v50, v2 offset:2512
.LBB0_914:
	s_or_b64 exec, exec, s[6:7]
	v_mul_f32_e32 v2, v12, v43
	s_waitcnt lgkmcnt(0)
	s_nop 1
	v_mov_b32_dpp v3, v2 quad_perm:[1,0,3,2] row_mask:0xf bank_mask:0xf
	s_and_saveexec_b64 s[6:7], s[4:5]
	s_cbranch_execz .LBB0_916
	s_waitcnt lgkmcnt(0)
	v_cvt_pk_bf16_f32 v2, v2, v3
	ds_write_b32 v50, v2 offset:2592
.LBB0_916:
	s_or_b64 exec, exec, s[6:7]
	v_mul_f32_e32 v2, v28, v43
	s_waitcnt lgkmcnt(0)
	s_nop 1
	v_mov_b32_dpp v3, v2 quad_perm:[1,0,3,2] row_mask:0xf bank_mask:0xf
	s_and_saveexec_b64 s[6:7], s[4:5]
	s_cbranch_execz .LBB0_918
	s_waitcnt lgkmcnt(0)
	v_cvt_pk_bf16_f32 v2, v2, v3
	ds_write_b32 v50, v2 offset:2656
.LBB0_918:
	s_or_b64 exec, exec, s[6:7]
	v_mul_f32_e32 v2, v13, v44
	s_waitcnt lgkmcnt(0)
	s_nop 1
	v_mov_b32_dpp v3, v2 quad_perm:[1,0,3,2] row_mask:0xf bank_mask:0xf
	s_and_saveexec_b64 s[6:7], s[4:5]
	s_cbranch_execz .LBB0_920
	s_waitcnt lgkmcnt(0)
	v_cvt_pk_bf16_f32 v2, v2, v3
	ds_write_b32 v50, v2 offset:2736
.LBB0_920:
	s_or_b64 exec, exec, s[6:7]
	v_mul_f32_e32 v2, v29, v44
	s_waitcnt lgkmcnt(0)
	s_nop 1
	v_mov_b32_dpp v3, v2 quad_perm:[1,0,3,2] row_mask:0xf bank_mask:0xf
	s_and_saveexec_b64 s[6:7], s[4:5]
	s_cbranch_execz .LBB0_922
	s_waitcnt lgkmcnt(0)
	v_cvt_pk_bf16_f32 v2, v2, v3
	ds_write_b32 v50, v2 offset:2800
.LBB0_922:
	s_or_b64 exec, exec, s[6:7]
	v_mul_f32_e32 v2, v14, v45
	s_waitcnt lgkmcnt(0)
	s_nop 1
	v_mov_b32_dpp v3, v2 quad_perm:[1,0,3,2] row_mask:0xf bank_mask:0xf
	s_and_saveexec_b64 s[6:7], s[4:5]
	s_cbranch_execz .LBB0_924
	s_waitcnt lgkmcnt(0)
	v_cvt_pk_bf16_f32 v2, v2, v3
	ds_write_b32 v50, v2 offset:3456
.LBB0_924:
	s_or_b64 exec, exec, s[6:7]
	v_mul_f32_e32 v2, v30, v45
	s_waitcnt lgkmcnt(0)
	s_nop 1
	v_mov_b32_dpp v3, v2 quad_perm:[1,0,3,2] row_mask:0xf bank_mask:0xf
	s_and_saveexec_b64 s[6:7], s[4:5]
	s_cbranch_execz .LBB0_926
	s_waitcnt lgkmcnt(0)
	v_cvt_pk_bf16_f32 v2, v2, v3
	ds_write_b32 v50, v2 offset:3520
.LBB0_926:
	s_or_b64 exec, exec, s[6:7]
	v_mul_f32_e32 v2, v15, v46
	s_waitcnt lgkmcnt(0)
	s_nop 1
	v_mov_b32_dpp v3, v2 quad_perm:[1,0,3,2] row_mask:0xf bank_mask:0xf
	s_and_saveexec_b64 s[6:7], s[4:5]
	s_cbranch_execz .LBB0_928
	s_waitcnt lgkmcnt(0)
	v_cvt_pk_bf16_f32 v2, v2, v3
	ds_write_b32 v50, v2 offset:3600
.LBB0_928:
	s_or_b64 exec, exec, s[6:7]
	v_mul_f32_e32 v2, v31, v46
	s_waitcnt lgkmcnt(0)
	s_nop 1
	v_mov_b32_dpp v3, v2 quad_perm:[1,0,3,2] row_mask:0xf bank_mask:0xf
	s_and_saveexec_b64 s[6:7], s[4:5]
	s_cbranch_execz .LBB0_930
	s_waitcnt lgkmcnt(0)
	v_cvt_pk_bf16_f32 v2, v2, v3
	ds_write_b32 v50, v2 offset:3664
.LBB0_930:
	s_or_b64 exec, exec, s[6:7]
	v_mul_f32_e32 v2, v16, v47
	s_waitcnt lgkmcnt(0)
	s_nop 1
	v_mov_b32_dpp v3, v2 quad_perm:[1,0,3,2] row_mask:0xf bank_mask:0xf
	s_and_saveexec_b64 s[6:7], s[4:5]
	s_cbranch_execz .LBB0_932
	s_waitcnt lgkmcnt(0)
	v_cvt_pk_bf16_f32 v2, v2, v3
	ds_write_b32 v50, v2 offset:3744
.LBB0_932:
	s_or_b64 exec, exec, s[6:7]
	v_mul_f32_e32 v2, v32, v47
	s_waitcnt lgkmcnt(0)
	s_nop 1
	v_mov_b32_dpp v3, v2 quad_perm:[1,0,3,2] row_mask:0xf bank_mask:0xf
	s_and_saveexec_b64 s[6:7], s[4:5]
	s_cbranch_execz .LBB0_934
	s_waitcnt lgkmcnt(0)
	v_cvt_pk_bf16_f32 v2, v2, v3
	ds_write_b32 v50, v2 offset:3808
.LBB0_934:
	s_or_b64 exec, exec, s[6:7]
	v_mul_f32_e32 v2, v17, v48
	s_waitcnt lgkmcnt(0)
	s_nop 1
	v_mov_b32_dpp v3, v2 quad_perm:[1,0,3,2] row_mask:0xf bank_mask:0xf
	s_and_saveexec_b64 s[6:7], s[4:5]
	s_cbranch_execz .LBB0_936
	s_waitcnt lgkmcnt(0)
	v_cvt_pk_bf16_f32 v2, v2, v3
	ds_write_b32 v50, v2 offset:3888
.LBB0_936:
	s_or_b64 exec, exec, s[6:7]
	v_mul_f32_e32 v2, v33, v48
	s_waitcnt lgkmcnt(0)
	s_nop 1
	v_mov_b32_dpp v3, v2 quad_perm:[1,0,3,2] row_mask:0xf bank_mask:0xf
	s_and_saveexec_b64 s[6:7], s[4:5]
	s_cbranch_execz .LBB0_938
	s_waitcnt lgkmcnt(0)
	v_cvt_pk_bf16_f32 v2, v2, v3
	ds_write_b32 v50, v2 offset:3952

; __device__ __forceinline__ void gc_unit(LAS unsigned char* lds, int unit, const bf16_t* proj, const bf16_t* dSt, const float* gnorm, bf16_t* omix, int tid, int wave, int lane) {
;     const int n = unit & 63, bh = unit >> 6, b = bh >> 3, h = bh & 7;
;     const size_t row0 = (size_t)b * SEQ + n * 64;
;     bf16x8 sfr[8];
;     { const bf16_t* sp = dSt + ((size_t)unit * 256 + 32 * wave + (lane & 31)) * 128 + (lane >> 5) * 8;
; #pragma unroll
;       for (int ks = 0; ks < 8; ++ks) sfr[ks] = *(const bf16x8*)(sp + ks * 16); }
;     { const int t = tid >> 3, c0 = (tid & 7) * 16; const bf16_t* qp = proj + (row0 + t) * PROJ_LD + C_GQ + h * 128 + c0;
;       const u32x4 q0 = *(const u32x4*)qp, q1 = *(const u32x4*)(qp + 8), k0 = *(const u32x4*)(qp + (C_GK - C_GQ)), k1 = *(const u32x4*)(qp + (C_GK - C_GQ) + 8);
;       u32x4 vr[4]; load_v(vr, proj + row0 * PROJ_LD + C_GV + h * 256, tid);
;       *(LAS u32x4*)(lds + L_QD + t * 272 + c0 * 2) = q0; *(LAS u32x4*)(lds + L_QD + t * 272 + c0 * 2 + 16) = q1;
;       *(LAS u32x4*)(lds + L_KI + t * 272 + c0 * 2) = k0; *(LAS u32x4*)(lds + L_KI + t * 272 + c0 * 2 + 16) = k1;
;       store_v(lds, L_VT, vr, tid); }
;     __syncthreads();
;     const int r = lane & 31, hh = lane >> 5;
;     if (wave < 4) { const int ct = wave & 1, st = wave >> 1; f32x16 acc = {};
; #pragma unroll
;         for (int ks = 0; ks < 8; ++ks) { const bf16x8 a = *(const LAS bf16x8*)(lds + L_QD + (ct * 32 + r) * 272 + ks * 32 + hh * 16), bb = *(const LAS bf16x8*)(lds + L_KI + (st * 32 + r) * 272 + ks * 32 + hh * 16);
;             acc = __builtin_amdgcn_mfma_f32_32x32x16_bf16(a, bb, acc, 0, 0, 0); }
; #pragma unroll
;         for (int i = 0; i < 16; ++i) { const int c = ct * 32 + crow(i, hh), s2 = st * 32 + r; const float val = (s2 <= c) ? acc[i] : 0.f;
;             *(LAS unsigned short*)(lds + L_AT + c * 144 + s2 * 2) = f2bf1(val); } }
;     __syncthreads();
;     f32x16 o0 = {}, o1 = {};
;     { const int vbase = (int)(uintptr_t)(lds + L_VT + (wave >> 2) * 16384) + mb::v_rd_base(lane); bf16x8 vf[4];
;       switch (wave & 3) {
;           case 0: GLA_FRAG(vf[0], vbase, 0, 0); GLA_FRAG(vf[1], vbase, 0, 1); GLA_FRAG(vf[2], vbase, 0, 2); GLA_FRAG(vf[3], vbase, 0, 3); break;
;           case 1: GLA_FRAG(vf[0], vbase, 1, 0); GLA_FRAG(vf[1], vbase, 1, 1); GLA_FRAG(vf[2], vbase, 1, 2); GLA_FRAG(vf[3], vbase, 1, 3); break;
.LBB0_1006:
	s_cmp_lt_i32 s96, 6
	s_cselect_b64 s[4:5], -1, 0
	s_and_b64 s[0:1], s[4:5], s[0:1]
	s_cmpk_lt_i32 s94, 0x800
	s_cselect_b64 s[4:5], -1, 0
	s_and_b64 s[4:5], s[0:1], s[4:5]
	s_andn2_b64 vcc, exec, s[4:5]
	s_cbranch_vccnz .LBB0_1022
	v_lshrrev_b32_e32 v80, 3, v0
	v_and_b32_e32 v9, 48, v80
	v_lshrrev_b32_e32 v11, 2, v0
	v_readlane_b32 s3, v254, 5
	v_readlane_b32 s41, v254, 8
	v_and_or_b32 v9, v11, 8, v9
	s_lshl_b32 s3, s41, 5
	v_lshrrev_b32_e32 v9, 1, v9
	v_readlane_b32 s40, v254, 0
	v_and_b32_e32 v3, 31, v0
	v_lshlrev_b32_e32 v8, 12, v0
	v_and_or_b32 v9, v0, 3, v9
	s_cmpk_lt_u32 s40, 0x100
	v_or_b32_e32 v78, s3, v3
	v_lshrrev_b32_e32 v5, 5, v182
	v_and_b32_e32 v8, 0x4000, v8
	v_lshrrev_b32_e32 v11, 4, v0
	v_lshlrev_b32_e32 v9, 9, v9
	v_bfe_u32 v12, v0, 3, 2
	s_cselect_b64 s[42:43], -1, 0
	s_and_b32 s3, s3, 32
	s_movk_i32 s33, 0x110
	v_and_or_b32 v11, v11, 4, v12
	v_add3_u32 v12, 0, v8, v9
	v_or_b32_e32 v8, s3, v3
	s_lshl_b32 s4, s41, 4
	v_lshl_or_b32 v9, v5, 2, s3
	v_mad_u32_u24 v13, v8, s33, 0
	v_and_or_b32 v8, s4, 32, v3
	v_or_b32_e32 v19, 1, v9
	v_cmp_gt_u32_e64 s[6:7], v8, v19
	v_or_b32_e32 v19, 2, v9
	v_cmp_gt_u32_e64 s[8:9], v8, v19
	v_or_b32_e32 v19, 3, v9
	v_cmp_gt_u32_e64 s[10:11], v8, v19
	v_or_b32_e32 v19, 8, v9
	v_cmp_gt_u32_e64 s[12:13], v8, v19
	v_or_b32_e32 v19, 9, v9
	v_cmp_gt_u32_e64 s[14:15], v8, v19
	v_or_b32_e32 v19, 10, v9
	v_cmp_gt_u32_e64 s[16:17], v8, v19
	v_or_b32_e32 v19, 11, v9
	v_cmp_gt_u32_e64 s[18:19], v8, v19
	v_or_b32_e32 v19, 16, v9
	v_cmp_gt_u32_e64 s[20:21], v8, v19
	v_or_b32_e32 v19, 17, v9
	v_cmp_gt_u32_e64 s[22:23], v8, v19
	v_or_b32_e32 v19, 18, v9
	v_cmp_gt_u32_e64 s[24:25], v8, v19
	v_or_b32_e32 v19, 19, v9
	v_cmp_gt_u32_e64 s[26:27], v8, v19
	v_or_b32_e32 v19, 24, v9
	s_add_i32 s3, 0, 0x11800
	v_cmp_gt_u32_e64 s[28:29], v8, v19
	v_or_b32_e32 v19, 25, v9
	v_mov_b32_e32 v16, s3
	v_lshl_add_u32 v17, v8, 1, s3
	v_cmp_gt_u32_e64 s[4:5], v8, v9
	v_mul_u32_u24_e32 v18, 0x90, v9
	v_cmp_gt_u32_e64 s[30:31], v8, v19
	v_or_b32_e32 v19, 26, v9
	v_or_b32_e32 v9, 27, v9
	s_lshl_b32 s3, s41, 12
	v_mad_u32_u24 v15, v8, s33, 0
	v_cmp_gt_u32_e64 s[34:35], v8, v19
	v_cmp_gt_u32_e64 s[36:37], v8, v9
	s_and_b32 s3, s3, 0x7fffc000
	v_lshlrev_b32_e32 v8, 3, v0
	v_lshlrev_b32_e32 v9, 4, v182
	v_lshlrev_b32_e32 v20, 1, v0
	s_add_i32 s3, s3, 0
	v_and_b32_e32 v19, 0xc0, v9
	v_and_b32_e32 v20, 32, v20
	v_and_b32_e32 v8, 0x118, v8
	s_add_i32 s3, s3, 0x9800
	v_or3_b32 v8, v19, v20, v8
	v_mov_b32_e32 v79, 0
	s_movk_i32 s38, 0x90
	v_add_u32_e32 v81, s3, v8
	v_or_b32_e32 v8, 32, v182
	v_readlane_b32 s44, v254, 9
	v_mad_u32_u24 v7, v80, s33, 0
	v_mad_u32_u24 v19, v3, s38, v16
	v_mad_u32_u24 v16, v8, s38, v16
	v_mad_u32_u24 v3, v3, s33, 0
	v_mad_u32_u24 v20, v8, s33, 0
	s_movk_i32 s33, 0x1040
	v_add_u32_e32 v98, 0, v9
	v_lshlrev_b32_e32 v8, 3, v182
	v_mov_b32_e32 v9, v79
	v_readlane_b32 s45, v254, 10
	s_ashr_i32 s95, s94, 31
	v_lshlrev_b32_e32 v14, 4, v5
	s_bfe_u32 s3, s40, 0x20006
	v_mad_u32_u24 v5, v5, s33, 0
	s_lshl_b32 s33, s41, 3
	v_lshl_add_u64 v[82:83], s[44:45], 0, v[8:9]
	s_mul_i32 s52, s41, 0x2080
	v_lshlrev_b64 v[8:9], 8, v[78:79]
	s_lshl_b64 s[40:41], s[94:95], 16
	v_and_b32_e32 v22, 32, v0
	v_lshlrev_b32_e32 v2, 4, v0
	v_lshl_add_u64 v[8:9], s[40:41], 0, v[8:9]
	v_lshrrev_b32_e32 v22, 1, v22
	v_and_b32_e32 v2, 0x70, v2
	v_lshlrev_b32_e32 v4, 5, v0
	v_or_b32_e32 v8, v8, v22
	v_and_b32_e32 v4, 0xe0, v4
	v_mul_u32_u24_e32 v6, 0x1800, v80
	v_lshlrev_b32_e32 v10, 1, v2
	v_lshlrev_b32_e32 v11, 6, v11
	v_lshlrev_b32_e32 v21, 2, v78
	s_or_b32 s53, s33, 1
	v_lshl_add_u64 v[8:9], s[76:77], 0, v[8:9]
	s_mov_b64 s[40:41], 0xe0
	s_ashr_i32 s89, s88, 31
	v_lshlrev_b32_e32 v90, 1, v2
	v_mbcnt_lo_u32_b32 v2, -1, 0
	s_mov_b32 s39, 0
	s_mul_i32 s54, s53, 0x410
	s_or_b32 s55, s33, 2
	s_or_b32 s56, s33, 3
	s_or_b32 s57, s33, 4
	s_or_b32 s58, s33, 5
	s_or_b32 s59, s33, 6
	s_or_b32 s60, s33, 7
	s_lshl_b32 s61, s94, 6
	s_lshl_b32 s62, s88, 6
	v_lshl_add_u64 v[84:85], v[8:9], 0, s[40:41]
	s_lshl_b64 s[44:45], s[88:89], 16
	v_mov_b64_e32 v[86:87], s[92:93]
	s_movk_i32 s63, 0x3000
	v_mov_b64_e32 v[88:89], s[90:91]
	v_mov_b32_e32 v99, 0x3000
	v_mov_b32_e32 v91, v79
	v_lshlrev_b32_e32 v92, 1, v6
	v_mov_b32_e32 v93, v79
	v_lshlrev_b32_e32 v94, 1, v4
	v_mov_b32_e32 v95, v79
	s_mov_b64 s[46:47], 0x1000
	s_movk_i32 s64, 0x1000
	v_add_u32_e32 v100, v7, v10
	v_add_u32_e32 v101, v12, v11
	v_add_u32_e32 v102, v13, v14
	v_add_u32_e32 v103, v15, v14
	v_add_u32_e32 v104, v17, v18
	v_add_u32_e32 v105, v19, v14
	v_add_u32_e32 v106, v16, v14
	v_add_u32_e32 v107, v3, v14
	v_add_u32_e32 v108, v20, v14
	v_add_u32_e32 v109, v5, v21
	v_mov_b32_e32 v110, 0x358637bd
	s_mov_b32 s65, 0xf800000
	v_mov_b32_e32 v111, 0x260
	s_movk_i32 s66, 0x2000
	v_mbcnt_hi_u32_b32 v112, -1, v2
	v_mad_u64_u32 v[176:177], vcc, v80, s63, v[88:89]
	v_lshl_add_u64 v[178:179], s[90:91], 0, v[92:93]
	s_nop 0
	v_lshl_add_u64 v[176:177], v[176:177], 0, v[90:91]
	v_lshl_add_u64 v[178:179], v[178:179], 0, v[94:95]
	s_nop 0
	v_lshl_add_u64 v[178:179], v[178:179], 0, s[46:47]
	s_mov_b32 vcc_lo, s94
	s_and_b32 vcc_hi, s61, 0xfc0
	s_ashr_i32 s40, vcc_lo, 9
	s_lshl_b32 s40, s40, 12
	s_or_b32 s40, s40, vcc_hi
	s_mul_i32 s40, s40, 0x3000
	s_bfe_u32 vcc_hi, vcc_lo, 0x30006
	s_lshl_b32 vcc_hi, vcc_hi, 8
	s_add_u32 s40, s40, vcc_hi
	s_mov_b32 s41, 0
	v_lshl_add_u64 v[248:249], v[176:177], 0, s[40:41]
	s_add_u32 s40, s40, vcc_hi
	s_nop 0
	v_lshl_add_u64 v[250:251], v[178:179], 0, s[40:41]
	global_load_dwordx4 v[188:191], v[248:249], off
	global_load_dwordx4 v[184:187], v[248:249], off offset:16
	global_load_dwordx4 v[196:199], v[248:249], off offset:2048
	global_load_dwordx4 v[192:195], v[248:249], off offset:2064
	global_load_dwordx4 v[200:203], v[250:251], off
	global_load_dwordx4 v[208:211], v[250:251], off offset:16
	global_load_dwordx4 v[204:207], v[250:251], off offset:32
	global_load_dwordx4 v[212:215], v[250:251], off offset:48
	global_load_dwordx4 v[220:223], v[84:85], off offset:-224
	global_load_dwordx4 v[216:219], v[84:85], off offset:-192
	global_load_dwordx4 v[244:247], v[84:85], off offset:-160
	global_load_dwordx4 v[240:243], v[84:85], off offset:-128
	global_load_dwordx4 v[236:239], v[84:85], off offset:-96
	global_load_dwordx4 v[232:235], v[84:85], off offset:-64
	global_load_dwordx4 v[228:231], v[84:85], off offset:-32
	global_load_dwordx4 v[224:227], v[84:85], off
	flat_load_dwordx2 v[96:97], v[86:87] offset:48 sc0 sc1
	s_waitcnt vmcnt(0) lgkmcnt(0)
	v_lshlrev_b32_e32 v172, 4, v182
	v_mov_b32_e32 v173, 0
	s_nop 0
	v_lshl_add_u64 v[172:173], v[96:97], 0, v[172:173]
	global_load_dwordx4 v[172:175], v[172:173], off
	s_waitcnt vmcnt(0)
	s_branch .LBB0_1009
; #define LAS __attribute__((address_space(3)))
; __device__ __forceinline__ void gc_unit(LAS unsigned char* lds, int unit, const bf16_t* proj, const bf16_t* dSt, const float* gnorm, bf16_t* omix, int tid, int wave, int lane) {
;     ...
;     { const bf16_t* sp = dSt + ((size_t)unit * 256 + 32 * wave + (lane & 31)) * 128 + (lane >> 5) * 8;
; #pragma unroll
;       for (int ks = 0; ks < 8; ++ks) sfr[ks] = *(const bf16x8*)(sp + ks * 16); }
;     { const int t = tid >> 3, c0 = (tid & 7) * 16; const bf16_t* qp = proj + (row0 + t) * PROJ_LD + C_GQ + h * 128 + c0;
;       const u32x4 q0 = *(const u32x4*)qp, q1 = *(const u32x4*)(qp + 8), k0 = *(const u32x4*)(qp + (C_GK - C_GQ)), k1 = *(const u32x4*)(qp + (C_GK - C_GQ) + 8);
;       u32x4 vr[4]; load_v(vr, proj + row0 * PROJ_LD + C_GV + h * 256, tid);
;     ...
;       for (int ss = 0; ss < 4; ++ss) { const bf16x8 a0 = *(const LAS bf16x8*)(lds + L_AT + r * 144 + ss * 32 + hh * 16), a1 = *(const LAS bf16x8*)(lds + L_AT + (32 + r) * 144 + ss * 32 + hh * 16);
;           o0 = __builtin_amdgcn_mfma_f32_32x32x16_bf16(a0, vf[ss], o0, 0, 0, 0); o1 = __builtin_amdgcn_mfma_f32_32x32x16_bf16(a1, vf[ss], o1, 0, 0, 0); } }
;     {
; #pragma unroll
;       for (int ks = 0; ks < 8; ++ks) { const bf16x8 bb = sfr[ks];
;           const bf16x8 a0 = *(const LAS bf16x8*)(lds + L_QD + r * 272 + ks * 32 + hh * 16), a1 = *(const LAS bf16x8*)(lds + L_QD + (32 + r) * 272 + ks * 32 + hh * 16);
;           o0 = __builtin_amdgcn_mfma_f32_32x32x16_bf16(a0, bb, o0, 0, 0, 0); o1 = __builtin_amdgcn_mfma_f32_32x32x16_bf16(a1, bb, o1, 0, 0, 0); } }
;     __syncthreads();
; #pragma unroll
;     for (int i = 0; i < 16; ++i) { const int c = crow(i, hh); *(LAS float*)(lds + L_OT + c * 1040 + (32 * wave + r) * 4) = o0[i]; *(LAS float*)(lds + L_OT + (32 + c) * 1040 + (32 * wave + r) * 4) = o1[i]; }
;     __syncthreads();
;     const f32x4 g = *((const f32x4*)gnorm + lane);
; #pragma unroll
;     for (int rr = 0; rr < 8; ++rr) { const int c = 8 * wave + rr; const f32x4 v = *(const LAS f32x4*)(lds + L_OT + c * 1040 + lane * 16);
;         float ss = (v[0] * v[0] + v[1] * v[1]) + (v[2] * v[2] + v[3] * v[3]);
; #pragma unroll
;         for (int o = 1; o < 64; o <<= 1) ss += __shfl_xor(ss, o);
;         const float rs = 1.0f / sqrtf(ss * (1.0f / 256.0f) + EPS);
;         const u32x2 gw2 = *((const u32x2*)(proj + (row0 + c) * PROJ_LD + C_GOUT + h * 256) + lane);
.LBB0_1008:
	ds_read_b128 v[2:5], v105
	ds_read_b128 v[114:117], v105 offset:32
	ds_read_b128 v[22:25], v106
	ds_read_b128 v[118:121], v106 offset:32
	s_lshl_b32 s38, s38, 1
	s_add_u32 s50, s48, s33
	s_waitcnt lgkmcnt(3)
	v_mfma_f32_32x32x16_bf16 v[2:17], v[2:5], v[18:21], 0
	s_addc_u32 s51, s49, 0
	s_mul_i32 s40, s51, 0x3000
	s_mul_hi_u32 s41, s50, 0x3000
	s_add_i32 s41, s41, s40
	s_mul_i32 s40, s50, 0x3000
	s_add_u32 s40, s90, s40
	s_addc_u32 s41, s91, s41
	s_waitcnt lgkmcnt(1)
	v_mfma_f32_32x32x16_bf16 v[18:33], v[22:25], v[18:21], 0
	v_lshlrev_b32_e32 v78, 4, v182
	s_add_u32 s40, s40, s38
	s_addc_u32 s41, s41, 0
	v_lshlrev_b32_e32 v122, 3, v182
	v_add_u32_e32 v122, 0x2000, v122
	v_mov_b32_e32 v123, 0
	v_mov_b32_e32 v124, 0x3000
	v_mov_b32_e32 v125, 0
	v_lshl_add_u64 v[122:123], s[40:41], 0, v[122:123]
	global_load_dwordx2 v[126:127], v[122:123], off
	v_lshl_add_u64 v[122:123], v[122:123], 0, v[124:125]
	global_load_dwordx2 v[128:129], v[122:123], off
	v_lshl_add_u64 v[122:123], v[122:123], 0, v[124:125]
	global_load_dwordx2 v[130:131], v[122:123], off
	v_lshl_add_u64 v[122:123], v[122:123], 0, v[124:125]
	global_load_dwordx2 v[132:133], v[122:123], off
	v_lshl_add_u64 v[122:123], v[122:123], 0, v[124:125]
	global_load_dwordx2 v[134:135], v[122:123], off
	v_lshl_add_u64 v[122:123], v[122:123], 0, v[124:125]
	global_load_dwordx2 v[136:137], v[122:123], off
	v_lshl_add_u64 v[122:123], v[122:123], 0, v[124:125]
	global_load_dwordx2 v[138:139], v[122:123], off
	v_lshl_add_u64 v[122:123], v[122:123], 0, v[124:125]
	global_load_dwordx2 v[140:141], v[122:123], off
	v_lshl_add_u64 v[84:85], v[84:85], 0, s[44:45]
	s_add_i32 vcc_lo, s94, s88
	s_add_i32 vcc_hi, s61, s62
	s_cmpk_lt_i32 vcc_lo, 0x800
	s_cselect_b32 vcc_lo, vcc_lo, s94
	s_cselect_b32 vcc_hi, vcc_hi, s61
	s_and_b32 vcc_hi, vcc_hi, 0xfc0
	s_ashr_i32 s40, vcc_lo, 9
	s_lshl_b32 s40, s40, 12
	s_or_b32 s40, s40, vcc_hi
	s_mul_i32 s40, s40, 0x3000
	s_bfe_u32 vcc_hi, vcc_lo, 0x30006
	s_lshl_b32 vcc_hi, vcc_hi, 8
	s_add_u32 s40, s40, vcc_hi
	s_mov_b32 s41, 0
	v_lshl_add_u64 v[248:249], v[176:177], 0, s[40:41]
	s_add_u32 s40, s40, vcc_hi
	s_nop 0
	v_lshl_add_u64 v[250:251], v[178:179], 0, s[40:41]
	global_load_dwordx4 v[188:191], v[248:249], off
	global_load_dwordx4 v[184:187], v[248:249], off offset:16
	global_load_dwordx4 v[196:199], v[248:249], off offset:2048
	global_load_dwordx4 v[192:195], v[248:249], off offset:2064
	global_load_dwordx4 v[200:203], v[250:251], off
	global_load_dwordx4 v[208:211], v[250:251], off offset:16
	global_load_dwordx4 v[204:207], v[250:251], off offset:32
	global_load_dwordx4 v[212:215], v[250:251], off offset:48
	global_load_dwordx4 v[220:223], v[84:85], off offset:-224
	global_load_dwordx4 v[216:219], v[84:85], off offset:-192
	global_load_dwordx4 v[244:247], v[84:85], off offset:-160
	global_load_dwordx4 v[240:243], v[84:85], off offset:-128
	global_load_dwordx4 v[236:239], v[84:85], off offset:-96
	global_load_dwordx4 v[232:235], v[84:85], off offset:-64
	global_load_dwordx4 v[228:231], v[84:85], off offset:-32
	global_load_dwordx4 v[224:227], v[84:85], off
	v_mfma_f32_32x32x16_bf16 v[2:17], v[114:117], v[74:77], v[2:17]
	s_waitcnt lgkmcnt(0)
	v_mfma_f32_32x32x16_bf16 v[18:33], v[118:121], v[74:77], v[18:33]
	ds_read_b128 v[74:77], v105 offset:64
	ds_read_b128 v[114:117], v105 offset:96
	s_waitcnt lgkmcnt(1)
	v_mfma_f32_32x32x16_bf16 v[2:17], v[74:77], v[70:73], v[2:17]
	ds_read_b128 v[74:77], v106 offset:64
	ds_read_b128 v[118:121], v106 offset:96
	s_waitcnt lgkmcnt(1)
	v_mfma_f32_32x32x16_bf16 v[18:33], v[74:77], v[70:73], v[18:33]
	v_mfma_f32_32x32x16_bf16 v[2:17], v[114:117], v[66:69], v[2:17]
	s_waitcnt lgkmcnt(0)
	v_mfma_f32_32x32x16_bf16 v[18:33], v[118:121], v[66:69], v[18:33]
	ds_read_b128 v[66:69], v107 offset:4096
	ds_read_b128 v[70:73], v107 offset:4128
	s_waitcnt lgkmcnt(1)
	v_mfma_f32_32x32x16_bf16 v[2:17], v[66:69], v[38:41], v[2:17]
	ds_read_b128 v[66:69], v108 offset:4096
	ds_read_b128 v[74:77], v108 offset:4128
	s_waitcnt lgkmcnt(1)
	v_mfma_f32_32x32x16_bf16 v[18:33], v[66:69], v[38:41], v[18:33]
	v_mfma_f32_32x32x16_bf16 v[2:17], v[70:73], v[34:37], v[2:17]
	s_waitcnt lgkmcnt(0)
	v_mfma_f32_32x32x16_bf16 v[18:33], v[74:77], v[34:37], v[18:33]
	ds_read_b128 v[34:37], v107 offset:4160
	ds_read_b128 v[38:41], v107 offset:4192
	s_waitcnt lgkmcnt(1)
	v_mfma_f32_32x32x16_bf16 v[2:17], v[34:37], v[62:65], v[2:17]
	ds_read_b128 v[34:37], v108 offset:4160
	ds_read_b128 v[66:69], v108 offset:4192
	s_waitcnt lgkmcnt(1)
	v_mfma_f32_32x32x16_bf16 v[18:33], v[34:37], v[62:65], v[18:33]
	v_mfma_f32_32x32x16_bf16 v[2:17], v[38:41], v[58:61], v[2:17]
	ds_read_b128 v[34:37], v107 offset:4224
	ds_read_b128 v[38:41], v107 offset:4256
	s_waitcnt lgkmcnt(2)
	v_mfma_f32_32x32x16_bf16 v[18:33], v[66:69], v[58:61], v[18:33]
	s_waitcnt lgkmcnt(1)
	v_mfma_f32_32x32x16_bf16 v[2:17], v[34:37], v[54:57], v[2:17]
	ds_read_b128 v[34:37], v108 offset:4224
	ds_read_b128 v[58:61], v108 offset:4256
	s_waitcnt lgkmcnt(1)
	v_mfma_f32_32x32x16_bf16 v[18:33], v[34:37], v[54:57], v[18:33]
	v_mfma_f32_32x32x16_bf16 v[2:17], v[38:41], v[50:53], v[2:17]
	ds_read_b128 v[34:37], v107 offset:4288
	ds_read_b128 v[38:41], v107 offset:4320
	s_waitcnt lgkmcnt(2)
	v_mfma_f32_32x32x16_bf16 v[18:33], v[58:61], v[50:53], v[18:33]
	s_waitcnt lgkmcnt(1)
	v_mfma_f32_32x32x16_bf16 v[2:17], v[34:37], v[46:49], v[2:17]
	ds_read_b128 v[34:37], v108 offset:4288
	ds_read_b128 v[50:53], v108 offset:4320
	s_waitcnt lgkmcnt(0)
	s_barrier
; #define LAS __attribute__((address_space(3)))
; __device__ __forceinline__ int crow(int r, int hi) { return (r & 3) + 8 * (r >> 2) + 4 * hi; }
; __device__ __forceinline__ int crow(int r, int hi) { return (r & 3) + 8 * (r >> 2) + 4 * hi; }
; __device__ __forceinline__ void gc_unit(LAS unsigned char* lds, int unit, const bf16_t* proj, const bf16_t* dSt, const float* gnorm, bf16_t* omix, int tid, int wave, int lane) {
;     ...
;       for (int ks = 0; ks < 8; ++ks) { const bf16x8 bb = sfr[ks];
;           const bf16x8 a0 = *(const LAS bf16x8*)(lds + L_QD + r * 272 + ks * 32 + hh * 16), a1 = *(const LAS bf16x8*)(lds + L_QD + (32 + r) * 272 + ks * 32 + hh * 16);
;           o0 = __builtin_amdgcn_mfma_f32_32x32x16_bf16(a0, bb, o0, 0, 0, 0); o1 = __builtin_amdgcn_mfma_f32_32x32x16_bf16(a1, bb, o1, 0, 0, 0); } }
;     __syncthreads();
; #pragma unroll
;     for (int i = 0; i < 16; ++i) { const int c = crow(i, hh); *(LAS float*)(lds + L_OT + c * 1040 + (32 * wave + r) * 4) = o0[i]; *(LAS float*)(lds + L_OT + (32 + c) * 1040 + (32 * wave + r) * 4) = o1[i]; }
;     __syncthreads();
;     const f32x4 g = *((const f32x4*)gnorm + lane);
; #pragma unroll
;     for (int rr = 0; rr < 8; ++rr) { const int c = 8 * wave + rr; const f32x4 v = *(const LAS f32x4*)(lds + L_OT + c * 1040 + lane * 16);
;         float ss = (v[0] * v[0] + v[1] * v[1]) + (v[2] * v[2] + v[3] * v[3]);
; #pragma unroll
;         for (int o = 1; o < 64; o <<= 1) ss += __shfl_xor(ss, o);
;         const float rs = 1.0f / sqrtf(ss * (1.0f / 256.0f) + EPS);
	v_mfma_f32_32x32x16_bf16 v[18:33], v[34:37], v[46:49], v[18:33]
	v_mfma_f32_32x32x16_bf16 v[2:17], v[38:41], v[42:45], v[2:17]
	v_mfma_f32_32x32x16_bf16 v[18:33], v[50:53], v[42:45], v[18:33]
	s_nop 10
	ds_write_b32 v109, v2 offset:4096
	v_add_u32_e32 v2, s52, v98
	ds_write_b32 v109, v18 offset:37376
	ds_write_b32 v109, v3 offset:5136
	ds_write_b32 v109, v19 offset:38416
	ds_write_b32 v109, v4 offset:6176
	ds_write_b32 v109, v20 offset:39456
	ds_write_b32 v109, v5 offset:7216
	ds_write_b32 v109, v21 offset:40496
	ds_write_b32 v109, v6 offset:12416
	ds_write_b32 v109, v22 offset:45696
	ds_write_b32 v109, v7 offset:13456
	ds_write_b32 v109, v23 offset:46736
	ds_write_b32 v109, v8 offset:14496
	ds_write_b32 v109, v24 offset:47776
	ds_write_b32 v109, v9 offset:15536
	ds_write_b32 v109, v25 offset:48816
	ds_write_b32 v109, v10 offset:20736
	ds_write_b32 v109, v26 offset:54016
	ds_write_b32 v109, v11 offset:21776
	ds_write_b32 v109, v27 offset:55056
	ds_write_b32 v109, v12 offset:22816
	ds_write_b32 v109, v28 offset:56096
	ds_write_b32 v109, v13 offset:23856
	ds_write_b32 v109, v29 offset:57136
	ds_write_b32 v109, v14 offset:29056
	ds_write_b32 v109, v30 offset:62336
	ds_write_b32 v109, v15 offset:30096
	ds_write_b32 v109, v31 offset:63376
	ds_write_b32 v109, v16 offset:31136
	ds_write_b32 v109, v32 offset:64416
	ds_write_b32 v109, v17 offset:32176
	ds_write_b32 v109, v33 offset:65456
	s_waitcnt lgkmcnt(0)
	s_barrier
	ds_read_b128 v[14:17], v2 offset:4096
	v_and_b32_e32 v2, 64, v112
	v_add_u32_e32 v6, 64, v2
	s_waitcnt lgkmcnt(0)
	v_mul_f32_e32 v2, v15, v15
	v_mul_f32_e32 v3, v17, v17
	v_fmac_f32_e32 v2, v14, v14
	v_fmac_f32_e32 v3, v16, v16
	v_add_f32_e32 v4, v2, v3
	v_xor_b32_e32 v2, 1, v112
	v_cmp_lt_i32_e32 vcc, v2, v6
	s_nop 1
	v_cndmask_b32_e32 v2, v112, v2, vcc
	v_lshlrev_b32_e32 v8, 2, v2
	s_nop 1
	v_mov_b32_dpp v5, v4 quad_perm:[1,0,3,2] row_mask:0xf bank_mask:0xf
	v_lshl_add_u64 v[2:3], v[96:97], 0, v[78:79]
	v_lshlrev_b32_e32 v78, 3, v182
	s_waitcnt lgkmcnt(0)
	v_add_f32_e32 v7, v4, v5
	v_xor_b32_e32 v4, 2, v112
	v_cmp_lt_i32_e32 vcc, v4, v6
	s_nop 1
	v_cndmask_b32_e32 v4, v112, v4, vcc
	v_lshlrev_b32_e32 v9, 2, v4
	v_lshl_add_u64 v[4:5], s[40:41], 0, v[78:79]
	v_add_co_u32_e32 v4, vcc, s66, v4
	s_nop 1
	v_mov_b32_dpp v10, v7 quad_perm:[2,3,0,1] row_mask:0xf bank_mask:0xf
	s_nop 0
	v_addc_co_u32_e32 v5, vcc, 0, v5, vcc
	v_xor_b32_e32 v4, 4, v112
	v_cmp_lt_i32_e32 vcc, v4, v6
	s_waitcnt lgkmcnt(0)
	v_add_f32_e32 v7, v7, v10
	v_cndmask_b32_e32 v4, v112, v4, vcc
	v_lshlrev_b32_e32 v10, 2, v4
	s_nop 1
	v_mov_b32_dpp v11, v7 row_half_mirror row_mask:0xf bank_mask:0xf
	s_waitcnt lgkmcnt(0)
	v_add_f32_e32 v7, v7, v11
	v_xor_b32_e32 v11, 8, v112
	v_cmp_lt_i32_e32 vcc, v11, v6
	s_nop 1
	v_cndmask_b32_e32 v11, v112, v11, vcc
	v_lshlrev_b32_e32 v11, 2, v11
	s_nop 1
	v_mov_b32_dpp v12, v7 row_mirror row_mask:0xf bank_mask:0xf
	s_waitcnt lgkmcnt(0)
	v_add_f32_e32 v7, v7, v12
	v_xor_b32_e32 v12, 16, v112
	v_cmp_lt_i32_e32 vcc, v12, v6
	s_nop 1
	v_cndmask_b32_e32 v12, v112, v12, vcc
	v_lshlrev_b32_e32 v12, 2, v12
	ds_bpermute_b32 v13, v12, v7
	s_waitcnt lgkmcnt(0)
	v_add_f32_e32 v7, v7, v13
	v_xor_b32_e32 v13, 32, v112
	v_cmp_lt_i32_e32 vcc, v13, v6
	s_nop 1
	v_cndmask_b32_e32 v6, v112, v13, vcc
	v_lshlrev_b32_e32 v13, 2, v6
	ds_bpermute_b32 v6, v13, v7
	s_waitcnt lgkmcnt(0)
	v_add_f32_e32 v6, v7, v6
	v_fmamk_f32 v6, v6, 0x3b800000, v110
	v_mul_f32_e32 v7, 0x4f800000, v6
	v_cmp_gt_f32_e32 vcc, s65, v6
	s_nop 1
	v_cndmask_b32_e32 v6, v6, v7, vcc
	v_sqrt_f32_e32 v7, v6
	s_nop 0
	v_add_u32_e32 v20, -1, v7
	v_fma_f32 v21, -v20, v7, v6
	v_cmp_ge_f32_e64 s[40:41], 0, v21
	v_add_u32_e32 v21, 1, v7
	s_nop 0
	v_cndmask_b32_e64 v20, v7, v20, s[40:41]
	v_fma_f32 v7, -v21, v7, v6
	v_cmp_lt_f32_e64 s[40:41], 0, v7
	s_nop 1
	v_cndmask_b32_e64 v7, v20, v21, s[40:41]
	v_mul_f32_e32 v20, 0x37800000, v7
	v_cndmask_b32_e32 v7, v7, v20, vcc
	v_cmp_class_f32_e32 vcc, v6, v111
	s_nop 1
	v_cndmask_b32_e32 v20, v7, v6, vcc
	v_div_scale_f32 v21, s[40:41], v20, v20, 1.0
	v_rcp_f32_e32 v22, v21
	v_lshl_add_u64 v[6:7], v[82:83], 0, s[38:39]
	v_fma_f32 v23, -v21, v22, 1.0
	v_fmac_f32_e32 v22, v23, v22
	v_div_scale_f32 v23, vcc, 1.0, v20, 1.0
	v_mul_f32_e32 v24, v23, v22
	v_fma_f32 v25, -v21, v24, v23
	v_fmac_f32_e32 v24, v25, v22
	v_fma_f32 v21, -v21, v24, v23
	v_div_fmas_f32 v21, v21, v22, v24
	s_waitcnt vmcnt(16)
; #define LAS __attribute__((address_space(3)))
; __device__ __forceinline__ unsigned cvt_pk_bf16(float lo, float hi) { unsigned r; asm volatile("v_cvt_pk_bf16_f32 %0, %1, %2" : "=v"(r) : "v"(lo), "v"(hi)); return r; }
; __device__ __forceinline__ float bflo(unsigned w) { return __uint_as_float(w << 16); }
; __device__ __forceinline__ float bfhi(unsigned w) { return __uint_as_float(w & 0xffff0000u); }
; __device__ __forceinline__ void gc_unit(LAS unsigned char* lds, int unit, const bf16_t* proj, const bf16_t* dSt, const float* gnorm, bf16_t* omix, int tid, int wave, int lane) {
;     ...
;     const f32x4 g = *((const f32x4*)gnorm + lane);
; #pragma unroll
;     for (int rr = 0; rr < 8; ++rr) { const int c = 8 * wave + rr; const f32x4 v = *(const LAS f32x4*)(lds + L_OT + c * 1040 + lane * 16);
;         float ss = (v[0] * v[0] + v[1] * v[1]) + (v[2] * v[2] + v[3] * v[3]);
; #pragma unroll
;         for (int o = 1; o < 64; o <<= 1) ss += __shfl_xor(ss, o);
;         const float rs = 1.0f / sqrtf(ss * (1.0f / 256.0f) + EPS);
;         const u32x2 gw2 = *((const u32x2*)(proj + (row0 + c) * PROJ_LD + C_GOUT + h * 256) + lane);
;         const float z0 = bflo(gw2.x), z1 = bfhi(gw2.x), z2 = bflo(gw2.y), z3 = bfhi(gw2.y);
;         const float p0 = v[0] * rs * g[0] * (z0 / (1.0f + __expf(-z0))), p1 = v[1] * rs * g[1] * (z1 / (1.0f + __expf(-z1)));
;         const float p2 = v[2] * rs * g[2] * (z2 / (1.0f + __expf(-z2))), p3 = v[3] * rs * g[3] * (z3 / (1.0f + __expf(-z3)));
;         u32x2 w; w.x = cvt_pk_bf16(p0, p1); w.y = cvt_pk_bf16(p2, p3); *((u32x2*)(omix + (row0 + c) * DM + h * 256) + lane) = w; }
	v_mov_b32_e32 v2, v172
	v_mov_b32_e32 v3, v173
	v_mov_b32_e32 v4, v174
	v_mov_b32_e32 v5, v175
	v_mov_b32_e32 v18, v126
	v_mov_b32_e32 v19, v127
	v_lshlrev_b32_e32 v22, 16, v18
	v_mul_f32_e32 v23, 0xbfb8aa3b, v22
	v_exp_f32_e32 v23, v23
	v_div_fixup_f32 v20, v21, v20, 1.0
	v_and_b32_e32 v18, 0xffff0000, v18
	v_mul_f32_e32 v14, v14, v20
	v_add_f32_e32 v21, 1.0, v23
	v_div_scale_f32 v23, s[40:41], v21, v21, v22
	v_rcp_f32_e32 v24, v23
	v_mul_f32_e32 v14, v2, v14
	v_lshlrev_b32_e32 v25, 16, v19
	v_mul_f32_e32 v15, v15, v20
	v_fma_f32 v26, -v23, v24, 1.0
	v_fmac_f32_e32 v24, v26, v24
	v_div_scale_f32 v26, vcc, v22, v21, v22
	v_mul_f32_e32 v27, v26, v24
	v_fma_f32 v28, -v23, v27, v26
	v_fmac_f32_e32 v27, v28, v24
	v_fma_f32 v23, -v23, v27, v26
	v_mul_f32_e32 v26, 0xbfb8aa3b, v18
	v_exp_f32_e32 v26, v26
	v_div_fmas_f32 v23, v23, v24, v27
	v_div_fixup_f32 v21, v23, v21, v22
	v_mul_f32_e32 v14, v21, v14
	v_add_f32_e32 v22, 1.0, v26
	v_div_scale_f32 v23, s[40:41], v22, v22, v18
	v_rcp_f32_e32 v24, v23
	v_mul_f32_e32 v15, v3, v15
	v_and_b32_e32 v19, 0xffff0000, v19
	v_mul_f32_e32 v16, v16, v20
	v_fma_f32 v21, -v23, v24, 1.0
	v_fmac_f32_e32 v24, v21, v24
	v_div_scale_f32 v21, vcc, v18, v22, v18
	v_mul_f32_e32 v26, v21, v24
	v_fma_f32 v27, -v23, v26, v21
	v_fmac_f32_e32 v26, v27, v24
	v_fma_f32 v21, -v23, v26, v21
	v_mul_f32_e32 v23, 0xbfb8aa3b, v25
	v_exp_f32_e32 v23, v23
	v_div_fmas_f32 v21, v21, v24, v26
	v_div_fixup_f32 v18, v21, v22, v18
	v_mul_f32_e32 v15, v18, v15
	v_add_f32_e32 v21, 1.0, v23
	v_div_scale_f32 v22, s[40:41], v21, v21, v25
	v_rcp_f32_e32 v23, v22
	v_mul_f32_e32 v16, v4, v16
	v_mul_f32_e32 v17, v17, v20
	v_mul_f32_e32 v17, v5, v17
	v_fma_f32 v18, -v22, v23, 1.0
	v_fmac_f32_e32 v23, v18, v23
	v_div_scale_f32 v18, vcc, v25, v21, v25
	v_mul_f32_e32 v24, v18, v23
	v_fma_f32 v26, -v22, v24, v18
	v_fmac_f32_e32 v24, v26, v23
	v_fma_f32 v18, -v22, v24, v18
	v_mul_f32_e32 v22, 0xbfb8aa3b, v19
	v_exp_f32_e32 v22, v22
	v_div_fmas_f32 v18, v18, v23, v24
	v_div_fixup_f32 v18, v18, v21, v25
	v_mul_f32_e32 v16, v18, v16
	v_add_f32_e32 v21, 1.0, v22
	v_div_scale_f32 v22, s[40:41], v21, v21, v19
	v_rcp_f32_e32 v23, v22
	s_lshl_b64 s[40:41], s[50:51], 13
	s_add_u32 s50, s48, s53
	s_addc_u32 s51, s49, 0
	v_fma_f32 v18, -v22, v23, 1.0
	v_fmac_f32_e32 v23, v18, v23
	v_div_scale_f32 v18, vcc, v19, v21, v19
	v_mul_f32_e32 v20, v18, v23
	v_fma_f32 v24, -v22, v20, v18
	v_fmac_f32_e32 v20, v24, v23
	v_fma_f32 v18, -v22, v20, v18
	v_div_fmas_f32 v18, v18, v23, v20
	v_div_fixup_f32 v18, v18, v21, v19
	v_mul_f32_e32 v17, v18, v17
	v_cvt_pk_bf16_f32 v14, v14, v15
	v_cvt_pk_bf16_f32 v15, v16, v17
	v_lshl_add_u64 v[16:17], v[6:7], 0, s[40:41]
	s_mul_i32 s40, s51, 0x3000
	s_mul_hi_u32 s41, s50, 0x3000
	s_add_i32 s41, s41, s40
	s_mul_i32 s40, s50, 0x3000
	s_add_u32 s40, s90, s40
	s_addc_u32 s41, s91, s41
	s_add_u32 s40, s40, s38
	s_addc_u32 s41, s41, 0
	v_lshl_add_u64 v[20:21], s[40:41], 0, v[78:79]
	v_add_co_u32_e32 v20, vcc, s66, v20
	global_store_dwordx2 v[16:17], v[14:15], off
	s_nop 0
	v_addc_co_u32_e32 v21, vcc, 0, v21, vcc
	v_add_u32_e32 v14, s54, v98
	ds_read_b128 v[16:19], v14 offset:4096
	s_waitcnt lgkmcnt(0)
	v_mul_f32_e32 v15, v17, v17
	v_mul_f32_e32 v22, v19, v19
	v_fmac_f32_e32 v15, v16, v16
	v_fmac_f32_e32 v22, v18, v18
	v_add_f32_e32 v15, v15, v22
	s_nop 1
	v_add_f32_dpp v15, v15, v15 quad_perm:[1,0,3,2] row_mask:0xf bank_mask:0xf
	s_nop 1
	v_add_f32_dpp v15, v15, v15 quad_perm:[2,3,0,1] row_mask:0xf bank_mask:0xf
	s_nop 1
	v_add_f32_dpp v15, v15, v15 row_half_mirror row_mask:0xf bank_mask:0xf
	s_nop 1
	v_add_f32_dpp v15, v15, v15 row_mirror row_mask:0xf bank_mask:0xf
	v_mov_b32_e32 v22, v15
	s_nop 1
	v_permlane16_swap_b32_e32 v15, v22
	s_nop 0
	v_add_f32_e32 v15, v15, v22
	v_mov_b32_e32 v22, v15
	s_nop 1
	v_permlane32_swap_b32_e32 v15, v22
	s_nop 0
	v_add_f32_e32 v15, v15, v22
	v_fmamk_f32 v15, v15, 0x3b800000, v110
	v_mul_f32_e32 v22, 0x4f800000, v15
	v_cmp_gt_f32_e32 vcc, s65, v15
	s_nop 1
	v_cndmask_b32_e32 v15, v15, v22, vcc
	v_sqrt_f32_e32 v22, v15
	s_nop 0
	v_add_u32_e32 v23, -1, v22
	v_fma_f32 v24, -v23, v22, v15
	v_cmp_ge_f32_e64 s[40:41], 0, v24
	v_add_u32_e32 v24, 1, v22
	s_nop 0
	v_cndmask_b32_e64 v23, v22, v23, s[40:41]
	v_fma_f32 v22, -v24, v22, v15
	v_cmp_lt_f32_e64 s[40:41], 0, v22
	s_nop 1
	v_cndmask_b32_e64 v22, v23, v24, s[40:41]
	v_mul_f32_e32 v23, 0x37800000, v22
	v_cndmask_b32_e32 v22, v22, v23, vcc
	v_cmp_class_f32_e32 vcc, v15, v111
	s_nop 1
	v_cndmask_b32_e32 v15, v22, v15, vcc
	v_div_scale_f32 v22, s[40:41], v15, v15, 1.0
	v_rcp_f32_e32 v23, v22
	s_nop 0
	v_fma_f32 v24, -v22, v23, 1.0
	v_fmac_f32_e32 v23, v24, v23
	v_div_scale_f32 v24, vcc, 1.0, v15, 1.0
	v_mul_f32_e32 v25, v24, v23
	v_fma_f32 v26, -v22, v25, v24
	v_fmac_f32_e32 v25, v26, v23
	v_fma_f32 v22, -v22, v25, v24
	v_div_fmas_f32 v22, v22, v23, v25
	v_mov_b32_e32 v20, v128
	v_mov_b32_e32 v21, v129
	v_lshlrev_b32_e32 v23, 16, v20
	v_mul_f32_e32 v24, 0xbfb8aa3b, v23
	v_exp_f32_e32 v24, v24
	v_and_b32_e32 v20, 0xffff0000, v20
	v_div_fixup_f32 v15, v22, v15, 1.0
	v_mul_f32_e32 v16, v16, v15
	v_add_f32_e32 v24, 1.0, v24
	v_div_scale_f32 v25, s[40:41], v24, v24, v23
	v_rcp_f32_e32 v26, v25
	v_mul_f32_e32 v16, v2, v16
	v_lshlrev_b32_e32 v22, 16, v21
	v_mul_f32_e32 v17, v17, v15
	v_fma_f32 v27, -v25, v26, 1.0
	v_fmac_f32_e32 v26, v27, v26
	v_div_scale_f32 v27, vcc, v23, v24, v23
	v_mul_f32_e32 v28, v27, v26
	v_fma_f32 v29, -v25, v28, v27
	v_fmac_f32_e32 v28, v29, v26
	v_fma_f32 v25, -v25, v28, v27
	v_mul_f32_e32 v27, 0xbfb8aa3b, v20
	v_exp_f32_e32 v27, v27
	v_div_fmas_f32 v25, v25, v26, v28
	v_div_fixup_f32 v23, v25, v24, v23
	v_mul_f32_e32 v16, v23, v16
; #define LAS __attribute__((address_space(3)))
; __device__ __forceinline__ unsigned cvt_pk_bf16(float lo, float hi) { unsigned r; asm volatile("v_cvt_pk_bf16_f32 %0, %1, %2" : "=v"(r) : "v"(lo), "v"(hi)); return r; }
; __device__ __forceinline__ float bflo(unsigned w) { return __uint_as_float(w << 16); }
; __device__ __forceinline__ float bfhi(unsigned w) { return __uint_as_float(w & 0xffff0000u); }
; __device__ __forceinline__ void gc_unit(LAS unsigned char* lds, int unit, const bf16_t* proj, const bf16_t* dSt, const float* gnorm, bf16_t* omix, int tid, int wave, int lane) {
;     ...
;     for (int rr = 0; rr < 8; ++rr) { const int c = 8 * wave + rr; const f32x4 v = *(const LAS f32x4*)(lds + L_OT + c * 1040 + lane * 16);
;         float ss = (v[0] * v[0] + v[1] * v[1]) + (v[2] * v[2] + v[3] * v[3]);
; #pragma unroll
;         for (int o = 1; o < 64; o <<= 1) ss += __shfl_xor(ss, o);
;         const float rs = 1.0f / sqrtf(ss * (1.0f / 256.0f) + EPS);
;         const u32x2 gw2 = *((const u32x2*)(proj + (row0 + c) * PROJ_LD + C_GOUT + h * 256) + lane);
;         const float z0 = bflo(gw2.x), z1 = bfhi(gw2.x), z2 = bflo(gw2.y), z3 = bfhi(gw2.y);
;         const float p0 = v[0] * rs * g[0] * (z0 / (1.0f + __expf(-z0))), p1 = v[1] * rs * g[1] * (z1 / (1.0f + __expf(-z1)));
;         const float p2 = v[2] * rs * g[2] * (z2 / (1.0f + __expf(-z2))), p3 = v[3] * rs * g[3] * (z3 / (1.0f + __expf(-z3)));
;         u32x2 w; w.x = cvt_pk_bf16(p0, p1); w.y = cvt_pk_bf16(p2, p3); *((u32x2*)(omix + (row0 + c) * DM + h * 256) + lane) = w; }
	v_add_f32_e32 v24, 1.0, v27
	v_div_scale_f32 v25, s[40:41], v24, v24, v20
	v_rcp_f32_e32 v26, v25
	v_mul_f32_e32 v17, v3, v17
	v_and_b32_e32 v21, 0xffff0000, v21
	v_mul_f32_e32 v18, v18, v15
	v_fma_f32 v23, -v25, v26, 1.0
	v_fmac_f32_e32 v26, v23, v26
	v_div_scale_f32 v23, vcc, v20, v24, v20
	v_mul_f32_e32 v27, v23, v26
	v_fma_f32 v28, -v25, v27, v23
	v_fmac_f32_e32 v27, v28, v26
	v_fma_f32 v23, -v25, v27, v23
	v_mul_f32_e32 v25, 0xbfb8aa3b, v22
	v_exp_f32_e32 v25, v25
	v_div_fmas_f32 v23, v23, v26, v27
	v_div_fixup_f32 v20, v23, v24, v20
	v_mul_f32_e32 v17, v20, v17
	v_add_f32_e32 v23, 1.0, v25
	v_div_scale_f32 v24, s[40:41], v23, v23, v22
	v_rcp_f32_e32 v25, v24
	v_mul_f32_e32 v15, v19, v15
	v_mul_f32_e32 v18, v4, v18
	v_mul_f32_e32 v15, v5, v15
	v_fma_f32 v20, -v24, v25, 1.0
	v_fmac_f32_e32 v25, v20, v25
	v_div_scale_f32 v20, vcc, v22, v23, v22
	v_mul_f32_e32 v26, v20, v25
	v_fma_f32 v27, -v24, v26, v20
	v_fmac_f32_e32 v26, v27, v25
	v_fma_f32 v20, -v24, v26, v20
	v_mul_f32_e32 v24, 0xbfb8aa3b, v21
	v_exp_f32_e32 v24, v24
	v_div_fmas_f32 v20, v20, v25, v26
	v_div_fixup_f32 v20, v20, v23, v22
	v_mul_f32_e32 v18, v20, v18
	v_add_f32_e32 v22, 1.0, v24
	v_div_scale_f32 v23, s[40:41], v22, v22, v21
	v_rcp_f32_e32 v24, v23
	s_lshl_b64 s[40:41], s[50:51], 13
	s_add_u32 s50, s48, s55
	s_addc_u32 s51, s49, 0
	v_fma_f32 v19, -v23, v24, 1.0
	v_fmac_f32_e32 v24, v19, v24
	v_div_scale_f32 v19, vcc, v21, v22, v21
	v_mul_f32_e32 v20, v19, v24
	v_fma_f32 v25, -v23, v20, v19
	v_fmac_f32_e32 v20, v25, v24
	v_fma_f32 v19, -v23, v20, v19
	v_div_fmas_f32 v19, v19, v24, v20
	v_div_fixup_f32 v19, v19, v22, v21
	v_mul_f32_e32 v15, v19, v15
	v_cvt_pk_bf16_f32 v16, v16, v17
	v_cvt_pk_bf16_f32 v17, v18, v15
	v_lshl_add_u64 v[18:19], v[6:7], 0, s[40:41]
	s_mul_i32 s40, s51, 0x3000
	s_mul_hi_u32 s41, s50, 0x3000
	s_add_i32 s41, s41, s40
	s_mul_i32 s40, s50, 0x3000
	s_add_u32 s40, s90, s40
	s_addc_u32 s41, s91, s41
	s_add_u32 s40, s40, s38
	s_addc_u32 s41, s41, 0
	v_lshl_add_u64 v[20:21], s[40:41], 0, v[78:79]
	v_add_co_u32_e32 v20, vcc, s66, v20
	global_store_dwordx2 v[18:19], v[16:17], off
	s_nop 0
	v_addc_co_u32_e32 v21, vcc, 0, v21, vcc
	ds_read_b128 v[16:19], v14 offset:5136
	s_waitcnt lgkmcnt(0)
	v_mul_f32_e32 v15, v17, v17
	v_mul_f32_e32 v22, v19, v19
	v_fmac_f32_e32 v15, v16, v16
	v_fmac_f32_e32 v22, v18, v18
	v_add_f32_e32 v15, v15, v22
	s_nop 1
	v_add_f32_dpp v15, v15, v15 quad_perm:[1,0,3,2] row_mask:0xf bank_mask:0xf
	s_nop 1
	v_add_f32_dpp v15, v15, v15 quad_perm:[2,3,0,1] row_mask:0xf bank_mask:0xf
	s_nop 1
	v_add_f32_dpp v15, v15, v15 row_half_mirror row_mask:0xf bank_mask:0xf
	s_nop 1
	v_add_f32_dpp v15, v15, v15 row_mirror row_mask:0xf bank_mask:0xf
	v_mov_b32_e32 v22, v15
	s_nop 1
	v_permlane16_swap_b32_e32 v15, v22
	s_nop 0
	v_add_f32_e32 v15, v15, v22
	v_mov_b32_e32 v22, v15
	s_nop 1
	v_permlane32_swap_b32_e32 v15, v22
	s_nop 0
	v_add_f32_e32 v15, v15, v22
	v_fmamk_f32 v15, v15, 0x3b800000, v110
	v_mul_f32_e32 v22, 0x4f800000, v15
	v_cmp_gt_f32_e32 vcc, s65, v15
	s_nop 1
	v_cndmask_b32_e32 v15, v15, v22, vcc
	v_sqrt_f32_e32 v22, v15
	s_nop 0
	v_add_u32_e32 v23, -1, v22
	v_fma_f32 v24, -v23, v22, v15
	v_cmp_ge_f32_e64 s[40:41], 0, v24
	v_add_u32_e32 v24, 1, v22
	s_nop 0
	v_cndmask_b32_e64 v23, v22, v23, s[40:41]
	v_fma_f32 v22, -v24, v22, v15
	v_cmp_lt_f32_e64 s[40:41], 0, v22
	s_nop 1
	v_cndmask_b32_e64 v22, v23, v24, s[40:41]
	v_mul_f32_e32 v23, 0x37800000, v22
	v_cndmask_b32_e32 v22, v22, v23, vcc
	v_cmp_class_f32_e32 vcc, v15, v111
	s_nop 1
	v_cndmask_b32_e32 v15, v22, v15, vcc
	v_div_scale_f32 v22, s[40:41], v15, v15, 1.0
	v_rcp_f32_e32 v23, v22
	s_nop 0
	v_fma_f32 v24, -v22, v23, 1.0
	v_fmac_f32_e32 v23, v24, v23
	v_div_scale_f32 v24, vcc, 1.0, v15, 1.0
	v_mul_f32_e32 v25, v24, v23
	v_fma_f32 v26, -v22, v25, v24
	v_fmac_f32_e32 v25, v26, v23
	v_fma_f32 v22, -v22, v25, v24
	v_div_fmas_f32 v22, v22, v23, v25
	v_mov_b32_e32 v20, v130
	v_mov_b32_e32 v21, v131
	v_lshlrev_b32_e32 v23, 16, v20
	v_mul_f32_e32 v24, 0xbfb8aa3b, v23
	v_exp_f32_e32 v24, v24
	v_and_b32_e32 v20, 0xffff0000, v20
	v_div_fixup_f32 v15, v22, v15, 1.0
	v_mul_f32_e32 v16, v16, v15
	v_add_f32_e32 v24, 1.0, v24
	v_div_scale_f32 v25, s[40:41], v24, v24, v23
	v_rcp_f32_e32 v26, v25
	v_mul_f32_e32 v16, v2, v16
	v_lshlrev_b32_e32 v22, 16, v21
	v_mul_f32_e32 v17, v17, v15
	v_fma_f32 v27, -v25, v26, 1.0
	v_fmac_f32_e32 v26, v27, v26
	v_div_scale_f32 v27, vcc, v23, v24, v23
	v_mul_f32_e32 v28, v27, v26
	v_fma_f32 v29, -v25, v28, v27
	v_fmac_f32_e32 v28, v29, v26
	v_fma_f32 v25, -v25, v28, v27
	v_mul_f32_e32 v27, 0xbfb8aa3b, v20
	v_exp_f32_e32 v27, v27
	v_div_fmas_f32 v25, v25, v26, v28
	v_div_fixup_f32 v23, v25, v24, v23
	v_mul_f32_e32 v16, v23, v16
	v_add_f32_e32 v24, 1.0, v27
	v_div_scale_f32 v25, s[40:41], v24, v24, v20
	v_rcp_f32_e32 v26, v25
	v_mul_f32_e32 v17, v3, v17
	v_and_b32_e32 v21, 0xffff0000, v21
	v_mul_f32_e32 v18, v18, v15
	v_fma_f32 v23, -v25, v26, 1.0
	v_fmac_f32_e32 v26, v23, v26
	v_div_scale_f32 v23, vcc, v20, v24, v20
	v_mul_f32_e32 v27, v23, v26
	v_fma_f32 v28, -v25, v27, v23
	v_fmac_f32_e32 v27, v28, v26
	v_fma_f32 v23, -v25, v27, v23
	v_mul_f32_e32 v25, 0xbfb8aa3b, v22
	v_exp_f32_e32 v25, v25
	v_div_fmas_f32 v23, v23, v26, v27
	v_div_fixup_f32 v20, v23, v24, v20
	v_mul_f32_e32 v17, v20, v17
	v_add_f32_e32 v23, 1.0, v25
	v_div_scale_f32 v24, s[40:41], v23, v23, v22
	v_rcp_f32_e32 v25, v24
	v_mul_f32_e32 v15, v19, v15
	v_mul_f32_e32 v18, v4, v18
	v_mul_f32_e32 v15, v5, v15
	v_fma_f32 v20, -v24, v25, 1.0
	v_fmac_f32_e32 v25, v20, v25
	v_div_scale_f32 v20, vcc, v22, v23, v22
	v_mul_f32_e32 v26, v20, v25
	v_fma_f32 v27, -v24, v26, v20
	v_fmac_f32_e32 v26, v27, v25
	v_fma_f32 v20, -v24, v26, v20
	v_mul_f32_e32 v24, 0xbfb8aa3b, v21
	v_exp_f32_e32 v24, v24
	v_div_fmas_f32 v20, v20, v25, v26
	v_div_fixup_f32 v20, v20, v23, v22
	v_mul_f32_e32 v18, v20, v18
	v_add_f32_e32 v22, 1.0, v24
	v_div_scale_f32 v23, s[40:41], v22, v22, v21
	v_rcp_f32_e32 v24, v23
	s_lshl_b64 s[40:41], s[50:51], 13
	s_add_u32 s50, s48, s56
	s_addc_u32 s51, s49, 0
	v_fma_f32 v19, -v23, v24, 1.0
	v_fmac_f32_e32 v24, v19, v24
	v_div_scale_f32 v19, vcc, v21, v22, v21
	v_mul_f32_e32 v20, v19, v24
	v_fma_f32 v25, -v23, v20, v19
	v_fmac_f32_e32 v20, v25, v24
	v_fma_f32 v19, -v23, v20, v19
	v_div_fmas_f32 v19, v19, v24, v20
	v_div_fixup_f32 v19, v19, v22, v21
	v_mul_f32_e32 v15, v19, v15
	v_cvt_pk_bf16_f32 v16, v16, v17
	v_cvt_pk_bf16_f32 v17, v18, v15
	v_lshl_add_u64 v[18:19], v[6:7], 0, s[40:41]
	s_mul_i32 s40, s51, 0x3000
	s_mul_hi_u32 s41, s50, 0x3000
	s_add_i32 s41, s41, s40
	s_mul_i32 s40, s50, 0x3000
	s_add_u32 s40, s90, s40
	s_addc_u32 s41, s91, s41
	s_add_u32 s40, s40, s38
	s_addc_u32 s41, s41, 0
	v_lshl_add_u64 v[20:21], s[40:41], 0, v[78:79]
	v_add_co_u32_e32 v20, vcc, s66, v20
	global_store_dwordx2 v[18:19], v[16:17], off
	s_nop 0
	v_addc_co_u32_e32 v21, vcc, 0, v21, vcc
	ds_read_b128 v[16:19], v14 offset:6176
	s_waitcnt lgkmcnt(0)
; #define LAS __attribute__((address_space(3)))
; __device__ __forceinline__ unsigned cvt_pk_bf16(float lo, float hi) { unsigned r; asm volatile("v_cvt_pk_bf16_f32 %0, %1, %2" : "=v"(r) : "v"(lo), "v"(hi)); return r; }
; __device__ __forceinline__ float bflo(unsigned w) { return __uint_as_float(w << 16); }
; __device__ __forceinline__ float bfhi(unsigned w) { return __uint_as_float(w & 0xffff0000u); }
; __device__ __forceinline__ void gc_unit(LAS unsigned char* lds, int unit, const bf16_t* proj, const bf16_t* dSt, const float* gnorm, bf16_t* omix, int tid, int wave, int lane) {
;     ...
;     for (int rr = 0; rr < 8; ++rr) { const int c = 8 * wave + rr; const f32x4 v = *(const LAS f32x4*)(lds + L_OT + c * 1040 + lane * 16);
;         float ss = (v[0] * v[0] + v[1] * v[1]) + (v[2] * v[2] + v[3] * v[3]);
; #pragma unroll
;         for (int o = 1; o < 64; o <<= 1) ss += __shfl_xor(ss, o);
;         const float rs = 1.0f / sqrtf(ss * (1.0f / 256.0f) + EPS);
;         const u32x2 gw2 = *((const u32x2*)(proj + (row0 + c) * PROJ_LD + C_GOUT + h * 256) + lane);
;         const float z0 = bflo(gw2.x), z1 = bfhi(gw2.x), z2 = bflo(gw2.y), z3 = bfhi(gw2.y);
;         const float p0 = v[0] * rs * g[0] * (z0 / (1.0f + __expf(-z0))), p1 = v[1] * rs * g[1] * (z1 / (1.0f + __expf(-z1)));
;         const float p2 = v[2] * rs * g[2] * (z2 / (1.0f + __expf(-z2))), p3 = v[3] * rs * g[3] * (z3 / (1.0f + __expf(-z3)));
;         u32x2 w; w.x = cvt_pk_bf16(p0, p1); w.y = cvt_pk_bf16(p2, p3); *((u32x2*)(omix + (row0 + c) * DM + h * 256) + lane) = w; }
	v_mul_f32_e32 v15, v17, v17
	v_mul_f32_e32 v22, v19, v19
	v_fmac_f32_e32 v15, v16, v16
	v_fmac_f32_e32 v22, v18, v18
	v_add_f32_e32 v15, v15, v22
	s_nop 1
	v_add_f32_dpp v15, v15, v15 quad_perm:[1,0,3,2] row_mask:0xf bank_mask:0xf
	s_nop 1
	v_add_f32_dpp v15, v15, v15 quad_perm:[2,3,0,1] row_mask:0xf bank_mask:0xf
	s_nop 1
	v_add_f32_dpp v15, v15, v15 row_half_mirror row_mask:0xf bank_mask:0xf
	s_nop 1
	v_add_f32_dpp v15, v15, v15 row_mirror row_mask:0xf bank_mask:0xf
	v_mov_b32_e32 v22, v15
	s_nop 1
	v_permlane16_swap_b32_e32 v15, v22
	s_nop 0
	v_add_f32_e32 v15, v15, v22
	v_mov_b32_e32 v22, v15
	s_nop 1
	v_permlane32_swap_b32_e32 v15, v22
	s_nop 0
	v_add_f32_e32 v15, v15, v22
	v_fmamk_f32 v15, v15, 0x3b800000, v110
	v_mul_f32_e32 v22, 0x4f800000, v15
	v_cmp_gt_f32_e32 vcc, s65, v15
	s_nop 1
	v_cndmask_b32_e32 v15, v15, v22, vcc
	v_sqrt_f32_e32 v22, v15
	s_nop 0
	v_add_u32_e32 v23, -1, v22
	v_fma_f32 v24, -v23, v22, v15
	v_cmp_ge_f32_e64 s[40:41], 0, v24
	v_add_u32_e32 v24, 1, v22
	s_nop 0
	v_cndmask_b32_e64 v23, v22, v23, s[40:41]
	v_fma_f32 v22, -v24, v22, v15
	v_cmp_lt_f32_e64 s[40:41], 0, v22
	s_nop 1
	v_cndmask_b32_e64 v22, v23, v24, s[40:41]
	v_mul_f32_e32 v23, 0x37800000, v22
	v_cndmask_b32_e32 v22, v22, v23, vcc
	v_cmp_class_f32_e32 vcc, v15, v111
	s_nop 1
	v_cndmask_b32_e32 v15, v22, v15, vcc
	v_div_scale_f32 v22, s[40:41], v15, v15, 1.0
	v_rcp_f32_e32 v23, v22
	s_nop 0
	v_fma_f32 v24, -v22, v23, 1.0
	v_fmac_f32_e32 v23, v24, v23
	v_div_scale_f32 v24, vcc, 1.0, v15, 1.0
	v_mul_f32_e32 v25, v24, v23
	v_fma_f32 v26, -v22, v25, v24
	v_fmac_f32_e32 v25, v26, v23
	v_fma_f32 v22, -v22, v25, v24
	v_div_fmas_f32 v22, v22, v23, v25
	v_mov_b32_e32 v20, v132
	v_mov_b32_e32 v21, v133
	v_lshlrev_b32_e32 v23, 16, v20
	v_mul_f32_e32 v24, 0xbfb8aa3b, v23
	v_exp_f32_e32 v24, v24
	v_and_b32_e32 v20, 0xffff0000, v20
	v_div_fixup_f32 v15, v22, v15, 1.0
	v_mul_f32_e32 v16, v16, v15
	v_add_f32_e32 v24, 1.0, v24
	v_div_scale_f32 v25, s[40:41], v24, v24, v23
	v_rcp_f32_e32 v26, v25
	v_mul_f32_e32 v16, v2, v16
	v_lshlrev_b32_e32 v22, 16, v21
	v_mul_f32_e32 v17, v17, v15
	v_fma_f32 v27, -v25, v26, 1.0
	v_fmac_f32_e32 v26, v27, v26
	v_div_scale_f32 v27, vcc, v23, v24, v23
	v_mul_f32_e32 v28, v27, v26
	v_fma_f32 v29, -v25, v28, v27
	v_fmac_f32_e32 v28, v29, v26
	v_fma_f32 v25, -v25, v28, v27
	v_mul_f32_e32 v27, 0xbfb8aa3b, v20
	v_exp_f32_e32 v27, v27
	v_div_fmas_f32 v25, v25, v26, v28
	v_div_fixup_f32 v23, v25, v24, v23
	v_mul_f32_e32 v16, v23, v16
	v_add_f32_e32 v24, 1.0, v27
	v_div_scale_f32 v25, s[40:41], v24, v24, v20
	v_rcp_f32_e32 v26, v25
	v_mul_f32_e32 v17, v3, v17
	v_and_b32_e32 v21, 0xffff0000, v21
	v_mul_f32_e32 v18, v18, v15
	v_fma_f32 v23, -v25, v26, 1.0
	v_fmac_f32_e32 v26, v23, v26
	v_div_scale_f32 v23, vcc, v20, v24, v20
	v_mul_f32_e32 v27, v23, v26
	v_fma_f32 v28, -v25, v27, v23
	v_fmac_f32_e32 v27, v28, v26
	v_fma_f32 v23, -v25, v27, v23
	v_mul_f32_e32 v25, 0xbfb8aa3b, v22
	v_exp_f32_e32 v25, v25
	v_div_fmas_f32 v23, v23, v26, v27
	v_div_fixup_f32 v20, v23, v24, v20
	v_mul_f32_e32 v17, v20, v17
	v_add_f32_e32 v23, 1.0, v25
	v_div_scale_f32 v24, s[40:41], v23, v23, v22
	v_rcp_f32_e32 v25, v24
	v_mul_f32_e32 v15, v19, v15
	v_mul_f32_e32 v18, v4, v18
	v_mul_f32_e32 v15, v5, v15
	v_fma_f32 v20, -v24, v25, 1.0
	v_fmac_f32_e32 v25, v20, v25
	v_div_scale_f32 v20, vcc, v22, v23, v22
	v_mul_f32_e32 v26, v20, v25
	v_fma_f32 v27, -v24, v26, v20
	v_fmac_f32_e32 v26, v27, v25
	v_fma_f32 v20, -v24, v26, v20
	v_mul_f32_e32 v24, 0xbfb8aa3b, v21
	v_exp_f32_e32 v24, v24
	v_div_fmas_f32 v20, v20, v25, v26
	v_div_fixup_f32 v20, v20, v23, v22
	v_mul_f32_e32 v18, v20, v18
	v_add_f32_e32 v22, 1.0, v24
	v_div_scale_f32 v23, s[40:41], v22, v22, v21
	v_rcp_f32_e32 v24, v23
	s_lshl_b64 s[40:41], s[50:51], 13
	s_add_u32 s50, s48, s57
	s_addc_u32 s51, s49, 0
	v_fma_f32 v19, -v23, v24, 1.0
	v_fmac_f32_e32 v24, v19, v24
	v_div_scale_f32 v19, vcc, v21, v22, v21
	v_mul_f32_e32 v20, v19, v24
	v_fma_f32 v25, -v23, v20, v19
	v_fmac_f32_e32 v20, v25, v24
	v_fma_f32 v19, -v23, v20, v19
	v_div_fmas_f32 v19, v19, v24, v20
	v_div_fixup_f32 v19, v19, v22, v21
	v_mul_f32_e32 v15, v19, v15
	v_cvt_pk_bf16_f32 v16, v16, v17
	v_cvt_pk_bf16_f32 v17, v18, v15
	v_lshl_add_u64 v[18:19], v[6:7], 0, s[40:41]
	s_mul_i32 s40, s51, 0x3000
	s_mul_hi_u32 s41, s50, 0x3000
	s_add_i32 s41, s41, s40
	s_mul_i32 s40, s50, 0x3000
	s_add_u32 s40, s90, s40
	s_addc_u32 s41, s91, s41
	s_add_u32 s40, s40, s38
	s_addc_u32 s41, s41, 0
	v_lshl_add_u64 v[20:21], s[40:41], 0, v[78:79]
	v_add_co_u32_e32 v20, vcc, s66, v20
	global_store_dwordx2 v[18:19], v[16:17], off
	s_nop 0
	v_addc_co_u32_e32 v21, vcc, 0, v21, vcc
	ds_read_b128 v[16:19], v14 offset:7216
	s_waitcnt lgkmcnt(0)
; #define LAS __attribute__((address_space(3)))
; __device__ __forceinline__ unsigned cvt_pk_bf16(float lo, float hi) { unsigned r; asm volatile("v_cvt_pk_bf16_f32 %0, %1, %2" : "=v"(r) : "v"(lo), "v"(hi)); return r; }
; __device__ __forceinline__ float bflo(unsigned w) { return __uint_as_float(w << 16); }
; __device__ __forceinline__ float bfhi(unsigned w) { return __uint_as_float(w & 0xffff0000u); }
; __device__ __forceinline__ void gc_unit(LAS unsigned char* lds, int unit, const bf16_t* proj, const bf16_t* dSt, const float* gnorm, bf16_t* omix, int tid, int wave, int lane) {
;     ...
;     for (int rr = 0; rr < 8; ++rr) { const int c = 8 * wave + rr; const f32x4 v = *(const LAS f32x4*)(lds + L_OT + c * 1040 + lane * 16);
;         float ss = (v[0] * v[0] + v[1] * v[1]) + (v[2] * v[2] + v[3] * v[3]);
; #pragma unroll
;         for (int o = 1; o < 64; o <<= 1) ss += __shfl_xor(ss, o);
;         const float rs = 1.0f / sqrtf(ss * (1.0f / 256.0f) + EPS);
;         const u32x2 gw2 = *((const u32x2*)(proj + (row0 + c) * PROJ_LD + C_GOUT + h * 256) + lane);
;         const float z0 = bflo(gw2.x), z1 = bfhi(gw2.x), z2 = bflo(gw2.y), z3 = bfhi(gw2.y);
;         const float p0 = v[0] * rs * g[0] * (z0 / (1.0f + __expf(-z0))), p1 = v[1] * rs * g[1] * (z1 / (1.0f + __expf(-z1)));
;         const float p2 = v[2] * rs * g[2] * (z2 / (1.0f + __expf(-z2))), p3 = v[3] * rs * g[3] * (z3 / (1.0f + __expf(-z3)));
;         u32x2 w; w.x = cvt_pk_bf16(p0, p1); w.y = cvt_pk_bf16(p2, p3); *((u32x2*)(omix + (row0 + c) * DM + h * 256) + lane) = w; }
	v_mul_f32_e32 v15, v17, v17
	v_mul_f32_e32 v22, v19, v19
	v_fmac_f32_e32 v15, v16, v16
	v_fmac_f32_e32 v22, v18, v18
	v_add_f32_e32 v15, v15, v22
	s_nop 1
	v_add_f32_dpp v15, v15, v15 quad_perm:[1,0,3,2] row_mask:0xf bank_mask:0xf
	s_nop 1
	v_add_f32_dpp v15, v15, v15 quad_perm:[2,3,0,1] row_mask:0xf bank_mask:0xf
	s_nop 1
	v_add_f32_dpp v15, v15, v15 row_half_mirror row_mask:0xf bank_mask:0xf
	s_nop 1
	v_add_f32_dpp v15, v15, v15 row_mirror row_mask:0xf bank_mask:0xf
	v_mov_b32_e32 v22, v15
	s_nop 1
	v_permlane16_swap_b32_e32 v15, v22
	s_nop 0
	v_add_f32_e32 v15, v15, v22
	v_mov_b32_e32 v22, v15
	s_nop 1
	v_permlane32_swap_b32_e32 v15, v22
	s_nop 0
	v_add_f32_e32 v15, v15, v22
	v_fmamk_f32 v15, v15, 0x3b800000, v110
	v_mul_f32_e32 v22, 0x4f800000, v15
	v_cmp_gt_f32_e32 vcc, s65, v15
	s_nop 1
	v_cndmask_b32_e32 v15, v15, v22, vcc
	v_sqrt_f32_e32 v22, v15
	s_nop 0
	v_add_u32_e32 v23, -1, v22
	v_fma_f32 v24, -v23, v22, v15
	v_cmp_ge_f32_e64 s[40:41], 0, v24
	v_add_u32_e32 v24, 1, v22
	s_nop 0
	v_cndmask_b32_e64 v23, v22, v23, s[40:41]
	v_fma_f32 v22, -v24, v22, v15
	v_cmp_lt_f32_e64 s[40:41], 0, v22
	s_nop 1
	v_cndmask_b32_e64 v22, v23, v24, s[40:41]
	v_mul_f32_e32 v23, 0x37800000, v22
	v_cndmask_b32_e32 v22, v22, v23, vcc
	v_cmp_class_f32_e32 vcc, v15, v111
	s_nop 1
	v_cndmask_b32_e32 v15, v22, v15, vcc
	v_div_scale_f32 v22, s[40:41], v15, v15, 1.0
	v_rcp_f32_e32 v23, v22
	s_nop 0
	v_fma_f32 v24, -v22, v23, 1.0
	v_fmac_f32_e32 v23, v24, v23
	v_div_scale_f32 v24, vcc, 1.0, v15, 1.0
	v_mul_f32_e32 v25, v24, v23
	v_fma_f32 v26, -v22, v25, v24
	v_fmac_f32_e32 v25, v26, v23
	v_fma_f32 v22, -v22, v25, v24
	v_div_fmas_f32 v22, v22, v23, v25
	v_mov_b32_e32 v20, v134
	v_mov_b32_e32 v21, v135
	v_lshlrev_b32_e32 v23, 16, v20
	v_mul_f32_e32 v24, 0xbfb8aa3b, v23
	v_exp_f32_e32 v24, v24
	v_and_b32_e32 v20, 0xffff0000, v20
	v_div_fixup_f32 v15, v22, v15, 1.0
	v_mul_f32_e32 v16, v16, v15
	v_add_f32_e32 v24, 1.0, v24
	v_div_scale_f32 v25, s[40:41], v24, v24, v23
	v_rcp_f32_e32 v26, v25
	v_mul_f32_e32 v16, v2, v16
	v_lshlrev_b32_e32 v22, 16, v21
	v_mul_f32_e32 v17, v17, v15
	v_fma_f32 v27, -v25, v26, 1.0
	v_fmac_f32_e32 v26, v27, v26
	v_div_scale_f32 v27, vcc, v23, v24, v23
	v_mul_f32_e32 v28, v27, v26
	v_fma_f32 v29, -v25, v28, v27
	v_fmac_f32_e32 v28, v29, v26
	v_fma_f32 v25, -v25, v28, v27
	v_mul_f32_e32 v27, 0xbfb8aa3b, v20
	v_exp_f32_e32 v27, v27
	v_div_fmas_f32 v25, v25, v26, v28
	v_div_fixup_f32 v23, v25, v24, v23
	v_mul_f32_e32 v16, v23, v16
	v_add_f32_e32 v24, 1.0, v27
	v_div_scale_f32 v25, s[40:41], v24, v24, v20
	v_rcp_f32_e32 v26, v25
	v_mul_f32_e32 v17, v3, v17
	v_and_b32_e32 v21, 0xffff0000, v21
	v_mul_f32_e32 v18, v18, v15
	v_fma_f32 v23, -v25, v26, 1.0
	v_fmac_f32_e32 v26, v23, v26
	v_div_scale_f32 v23, vcc, v20, v24, v20
	v_mul_f32_e32 v27, v23, v26
	v_fma_f32 v28, -v25, v27, v23
	v_fmac_f32_e32 v27, v28, v26
	v_fma_f32 v23, -v25, v27, v23
	v_mul_f32_e32 v25, 0xbfb8aa3b, v22
	v_exp_f32_e32 v25, v25
	v_div_fmas_f32 v23, v23, v26, v27
	v_div_fixup_f32 v20, v23, v24, v20
	v_mul_f32_e32 v17, v20, v17
	v_add_f32_e32 v23, 1.0, v25
	v_div_scale_f32 v24, s[40:41], v23, v23, v22
	v_rcp_f32_e32 v25, v24
	v_mul_f32_e32 v15, v19, v15
	v_mul_f32_e32 v18, v4, v18
	v_mul_f32_e32 v15, v5, v15
	v_fma_f32 v20, -v24, v25, 1.0
	v_fmac_f32_e32 v25, v20, v25
	v_div_scale_f32 v20, vcc, v22, v23, v22
	v_mul_f32_e32 v26, v20, v25
	v_fma_f32 v27, -v24, v26, v20
	v_fmac_f32_e32 v26, v27, v25
	v_fma_f32 v20, -v24, v26, v20
	v_mul_f32_e32 v24, 0xbfb8aa3b, v21
	v_exp_f32_e32 v24, v24
	v_div_fmas_f32 v20, v20, v25, v26
	v_div_fixup_f32 v20, v20, v23, v22
	v_mul_f32_e32 v18, v20, v18
	v_add_f32_e32 v22, 1.0, v24
	v_div_scale_f32 v23, s[40:41], v22, v22, v21
	v_rcp_f32_e32 v24, v23
	s_lshl_b64 s[40:41], s[50:51], 13
	s_add_u32 s50, s48, s58
	s_addc_u32 s51, s49, 0
	v_fma_f32 v19, -v23, v24, 1.0
	v_fmac_f32_e32 v24, v19, v24
	v_div_scale_f32 v19, vcc, v21, v22, v21
	v_mul_f32_e32 v20, v19, v24
	v_fma_f32 v25, -v23, v20, v19
	v_fmac_f32_e32 v20, v25, v24
	v_fma_f32 v19, -v23, v20, v19
	v_div_fmas_f32 v19, v19, v24, v20
	v_div_fixup_f32 v19, v19, v22, v21
	v_mul_f32_e32 v15, v19, v15
	v_cvt_pk_bf16_f32 v16, v16, v17
	v_cvt_pk_bf16_f32 v17, v18, v15
	v_lshl_add_u64 v[18:19], v[6:7], 0, s[40:41]
	s_mul_i32 s40, s51, 0x3000
	s_mul_hi_u32 s41, s50, 0x3000
	s_add_i32 s41, s41, s40
	s_mul_i32 s40, s50, 0x3000
	s_add_u32 s40, s90, s40
	s_addc_u32 s41, s91, s41
	s_add_u32 s40, s40, s38
	s_addc_u32 s41, s41, 0
	v_lshl_add_u64 v[20:21], s[40:41], 0, v[78:79]
	v_add_co_u32_e32 v20, vcc, s66, v20
	global_store_dwordx2 v[18:19], v[16:17], off
	s_nop 0
	v_addc_co_u32_e32 v21, vcc, 0, v21, vcc
	ds_read_b128 v[16:19], v14 offset:8256
	s_waitcnt lgkmcnt(0)
; #define LAS __attribute__((address_space(3)))
; __device__ __forceinline__ unsigned cvt_pk_bf16(float lo, float hi) { unsigned r; asm volatile("v_cvt_pk_bf16_f32 %0, %1, %2" : "=v"(r) : "v"(lo), "v"(hi)); return r; }
; __device__ __forceinline__ float bflo(unsigned w) { return __uint_as_float(w << 16); }
; __device__ __forceinline__ float bfhi(unsigned w) { return __uint_as_float(w & 0xffff0000u); }
; __device__ __forceinline__ void gc_unit(LAS unsigned char* lds, int unit, const bf16_t* proj, const bf16_t* dSt, const float* gnorm, bf16_t* omix, int tid, int wave, int lane) {
;     ...
;     for (int rr = 0; rr < 8; ++rr) { const int c = 8 * wave + rr; const f32x4 v = *(const LAS f32x4*)(lds + L_OT + c * 1040 + lane * 16);
;         float ss = (v[0] * v[0] + v[1] * v[1]) + (v[2] * v[2] + v[3] * v[3]);
; #pragma unroll
;         for (int o = 1; o < 64; o <<= 1) ss += __shfl_xor(ss, o);
;         const float rs = 1.0f / sqrtf(ss * (1.0f / 256.0f) + EPS);
;         const u32x2 gw2 = *((const u32x2*)(proj + (row0 + c) * PROJ_LD + C_GOUT + h * 256) + lane);
;         const float z0 = bflo(gw2.x), z1 = bfhi(gw2.x), z2 = bflo(gw2.y), z3 = bfhi(gw2.y);
;         const float p0 = v[0] * rs * g[0] * (z0 / (1.0f + __expf(-z0))), p1 = v[1] * rs * g[1] * (z1 / (1.0f + __expf(-z1)));
;         const float p2 = v[2] * rs * g[2] * (z2 / (1.0f + __expf(-z2))), p3 = v[3] * rs * g[3] * (z3 / (1.0f + __expf(-z3)));
;         u32x2 w; w.x = cvt_pk_bf16(p0, p1); w.y = cvt_pk_bf16(p2, p3); *((u32x2*)(omix + (row0 + c) * DM + h * 256) + lane) = w; }
	v_mul_f32_e32 v15, v17, v17
	v_mul_f32_e32 v22, v19, v19
	v_fmac_f32_e32 v15, v16, v16
	v_fmac_f32_e32 v22, v18, v18
	v_add_f32_e32 v15, v15, v22
	s_nop 1
	v_add_f32_dpp v15, v15, v15 quad_perm:[1,0,3,2] row_mask:0xf bank_mask:0xf
	s_nop 1
	v_add_f32_dpp v15, v15, v15 quad_perm:[2,3,0,1] row_mask:0xf bank_mask:0xf
	s_nop 1
	v_add_f32_dpp v15, v15, v15 row_half_mirror row_mask:0xf bank_mask:0xf
	s_nop 1
	v_add_f32_dpp v15, v15, v15 row_mirror row_mask:0xf bank_mask:0xf
	v_mov_b32_e32 v22, v15
	s_nop 1
	v_permlane16_swap_b32_e32 v15, v22
	s_nop 0
	v_add_f32_e32 v15, v15, v22
	v_mov_b32_e32 v22, v15
	s_nop 1
	v_permlane32_swap_b32_e32 v15, v22
	s_nop 0
	v_add_f32_e32 v15, v15, v22
	v_fmamk_f32 v15, v15, 0x3b800000, v110
	v_mul_f32_e32 v22, 0x4f800000, v15
	v_cmp_gt_f32_e32 vcc, s65, v15
	s_nop 1
	v_cndmask_b32_e32 v15, v15, v22, vcc
	v_sqrt_f32_e32 v22, v15
	s_nop 0
	v_add_u32_e32 v23, -1, v22
	v_fma_f32 v24, -v23, v22, v15
	v_cmp_ge_f32_e64 s[40:41], 0, v24
	v_add_u32_e32 v24, 1, v22
	s_nop 0
	v_cndmask_b32_e64 v23, v22, v23, s[40:41]
	v_fma_f32 v22, -v24, v22, v15
	v_cmp_lt_f32_e64 s[40:41], 0, v22
	s_nop 1
	v_cndmask_b32_e64 v22, v23, v24, s[40:41]
	v_mul_f32_e32 v23, 0x37800000, v22
	v_cndmask_b32_e32 v22, v22, v23, vcc
	v_cmp_class_f32_e32 vcc, v15, v111
	s_nop 1
	v_cndmask_b32_e32 v15, v22, v15, vcc
	v_div_scale_f32 v22, s[40:41], v15, v15, 1.0
	v_rcp_f32_e32 v23, v22
	s_nop 0
	v_fma_f32 v24, -v22, v23, 1.0
	v_fmac_f32_e32 v23, v24, v23
	v_div_scale_f32 v24, vcc, 1.0, v15, 1.0
	v_mul_f32_e32 v25, v24, v23
	v_fma_f32 v26, -v22, v25, v24
	v_fmac_f32_e32 v25, v26, v23
	v_fma_f32 v22, -v22, v25, v24
	v_div_fmas_f32 v22, v22, v23, v25
	v_mov_b32_e32 v20, v136
	v_mov_b32_e32 v21, v137
	v_lshlrev_b32_e32 v23, 16, v20
	v_mul_f32_e32 v24, 0xbfb8aa3b, v23
	v_exp_f32_e32 v24, v24
	v_and_b32_e32 v20, 0xffff0000, v20
	v_div_fixup_f32 v15, v22, v15, 1.0
	v_mul_f32_e32 v16, v16, v15
	v_add_f32_e32 v24, 1.0, v24
	v_div_scale_f32 v25, s[40:41], v24, v24, v23
	v_rcp_f32_e32 v26, v25
	v_mul_f32_e32 v16, v2, v16
	v_lshlrev_b32_e32 v22, 16, v21
	v_mul_f32_e32 v17, v17, v15
	v_fma_f32 v27, -v25, v26, 1.0
	v_fmac_f32_e32 v26, v27, v26
	v_div_scale_f32 v27, vcc, v23, v24, v23
	v_mul_f32_e32 v28, v27, v26
	v_fma_f32 v29, -v25, v28, v27
	v_fmac_f32_e32 v28, v29, v26
	v_fma_f32 v25, -v25, v28, v27
	v_mul_f32_e32 v27, 0xbfb8aa3b, v20
	v_exp_f32_e32 v27, v27
	v_div_fmas_f32 v25, v25, v26, v28
	v_div_fixup_f32 v23, v25, v24, v23
	v_mul_f32_e32 v16, v23, v16
	v_add_f32_e32 v24, 1.0, v27
	v_div_scale_f32 v25, s[40:41], v24, v24, v20
	v_rcp_f32_e32 v26, v25
	v_mul_f32_e32 v17, v3, v17
	v_and_b32_e32 v21, 0xffff0000, v21
	v_mul_f32_e32 v18, v18, v15
	v_fma_f32 v23, -v25, v26, 1.0
	v_fmac_f32_e32 v26, v23, v26
	v_div_scale_f32 v23, vcc, v20, v24, v20
	v_mul_f32_e32 v27, v23, v26
	v_fma_f32 v28, -v25, v27, v23
	v_fmac_f32_e32 v27, v28, v26
	v_fma_f32 v23, -v25, v27, v23
	v_mul_f32_e32 v25, 0xbfb8aa3b, v22
	v_exp_f32_e32 v25, v25
	v_div_fmas_f32 v23, v23, v26, v27
	v_div_fixup_f32 v20, v23, v24, v20
	v_mul_f32_e32 v17, v20, v17
	v_add_f32_e32 v23, 1.0, v25
	v_div_scale_f32 v24, s[40:41], v23, v23, v22
	v_rcp_f32_e32 v25, v24
	v_mul_f32_e32 v15, v19, v15
	v_mul_f32_e32 v18, v4, v18
	v_mul_f32_e32 v15, v5, v15
	v_fma_f32 v20, -v24, v25, 1.0
	v_fmac_f32_e32 v25, v20, v25
	v_div_scale_f32 v20, vcc, v22, v23, v22
	v_mul_f32_e32 v26, v20, v25
	v_fma_f32 v27, -v24, v26, v20
	v_fmac_f32_e32 v26, v27, v25
	v_fma_f32 v20, -v24, v26, v20
	v_mul_f32_e32 v24, 0xbfb8aa3b, v21
	v_exp_f32_e32 v24, v24
	v_div_fmas_f32 v20, v20, v25, v26
	v_div_fixup_f32 v20, v20, v23, v22
	v_mul_f32_e32 v18, v20, v18
	v_add_f32_e32 v22, 1.0, v24
	v_div_scale_f32 v23, s[40:41], v22, v22, v21
	v_rcp_f32_e32 v24, v23
	s_lshl_b64 s[40:41], s[50:51], 13
	s_add_u32 s50, s48, s59
	s_addc_u32 s51, s49, 0
	v_fma_f32 v19, -v23, v24, 1.0
	v_fmac_f32_e32 v24, v19, v24
	v_div_scale_f32 v19, vcc, v21, v22, v21
	v_mul_f32_e32 v20, v19, v24
	v_fma_f32 v25, -v23, v20, v19
	v_fmac_f32_e32 v20, v25, v24
	v_fma_f32 v19, -v23, v20, v19
	v_div_fmas_f32 v19, v19, v24, v20
	v_div_fixup_f32 v19, v19, v22, v21
	v_mul_f32_e32 v15, v19, v15
	v_cvt_pk_bf16_f32 v16, v16, v17
	v_cvt_pk_bf16_f32 v17, v18, v15
	v_lshl_add_u64 v[18:19], v[6:7], 0, s[40:41]
	s_mul_i32 s40, s51, 0x3000
	s_mul_hi_u32 s41, s50, 0x3000
	s_add_i32 s41, s41, s40
	s_mul_i32 s40, s50, 0x3000
	s_add_u32 s40, s90, s40
	s_addc_u32 s41, s91, s41
	s_add_u32 s40, s40, s38
	s_addc_u32 s41, s41, 0
	v_lshl_add_u64 v[20:21], s[40:41], 0, v[78:79]
	v_add_co_u32_e32 v20, vcc, s66, v20
	global_store_dwordx2 v[18:19], v[16:17], off
	s_nop 0
	v_addc_co_u32_e32 v21, vcc, 0, v21, vcc
	ds_read_b128 v[16:19], v14 offset:9296
	s_waitcnt lgkmcnt(0)
; #define LAS __attribute__((address_space(3)))
; __device__ __forceinline__ unsigned cvt_pk_bf16(float lo, float hi) { unsigned r; asm volatile("v_cvt_pk_bf16_f32 %0, %1, %2" : "=v"(r) : "v"(lo), "v"(hi)); return r; }
; __device__ __forceinline__ float bflo(unsigned w) { return __uint_as_float(w << 16); }
; __device__ __forceinline__ float bfhi(unsigned w) { return __uint_as_float(w & 0xffff0000u); }
; __device__ __forceinline__ void gc_unit(LAS unsigned char* lds, int unit, const bf16_t* proj, const bf16_t* dSt, const float* gnorm, bf16_t* omix, int tid, int wave, int lane) {
;     ...
;     for (int rr = 0; rr < 8; ++rr) { const int c = 8 * wave + rr; const f32x4 v = *(const LAS f32x4*)(lds + L_OT + c * 1040 + lane * 16);
;         float ss = (v[0] * v[0] + v[1] * v[1]) + (v[2] * v[2] + v[3] * v[3]);
; #pragma unroll
;         for (int o = 1; o < 64; o <<= 1) ss += __shfl_xor(ss, o);
;         const float rs = 1.0f / sqrtf(ss * (1.0f / 256.0f) + EPS);
;         const u32x2 gw2 = *((const u32x2*)(proj + (row0 + c) * PROJ_LD + C_GOUT + h * 256) + lane);
;         const float z0 = bflo(gw2.x), z1 = bfhi(gw2.x), z2 = bflo(gw2.y), z3 = bfhi(gw2.y);
;         const float p0 = v[0] * rs * g[0] * (z0 / (1.0f + __expf(-z0))), p1 = v[1] * rs * g[1] * (z1 / (1.0f + __expf(-z1)));
;         const float p2 = v[2] * rs * g[2] * (z2 / (1.0f + __expf(-z2))), p3 = v[3] * rs * g[3] * (z3 / (1.0f + __expf(-z3)));
;         u32x2 w; w.x = cvt_pk_bf16(p0, p1); w.y = cvt_pk_bf16(p2, p3); *((u32x2*)(omix + (row0 + c) * DM + h * 256) + lane) = w; }
	v_mul_f32_e32 v15, v17, v17
	v_mul_f32_e32 v22, v19, v19
	v_fmac_f32_e32 v15, v16, v16
	v_fmac_f32_e32 v22, v18, v18
	v_add_f32_e32 v15, v15, v22
	s_nop 1
	v_add_f32_dpp v15, v15, v15 quad_perm:[1,0,3,2] row_mask:0xf bank_mask:0xf
	s_nop 1
	v_add_f32_dpp v15, v15, v15 quad_perm:[2,3,0,1] row_mask:0xf bank_mask:0xf
	s_nop 1
	v_add_f32_dpp v15, v15, v15 row_half_mirror row_mask:0xf bank_mask:0xf
	s_nop 1
	v_add_f32_dpp v15, v15, v15 row_mirror row_mask:0xf bank_mask:0xf
	v_mov_b32_e32 v22, v15
	s_nop 1
	v_permlane16_swap_b32_e32 v15, v22
	s_nop 0
	v_add_f32_e32 v15, v15, v22
	v_mov_b32_e32 v22, v15
	s_nop 1
	v_permlane32_swap_b32_e32 v15, v22
	s_nop 0
	v_add_f32_e32 v15, v15, v22
	v_fmamk_f32 v15, v15, 0x3b800000, v110
	v_mul_f32_e32 v22, 0x4f800000, v15
	v_cmp_gt_f32_e32 vcc, s65, v15
	s_nop 1
	v_cndmask_b32_e32 v15, v15, v22, vcc
	v_sqrt_f32_e32 v22, v15
	s_nop 0
	v_add_u32_e32 v23, -1, v22
	v_fma_f32 v24, -v23, v22, v15
	v_cmp_ge_f32_e64 s[40:41], 0, v24
	v_add_u32_e32 v24, 1, v22
	s_nop 0
	v_cndmask_b32_e64 v23, v22, v23, s[40:41]
	v_fma_f32 v22, -v24, v22, v15
	v_cmp_lt_f32_e64 s[40:41], 0, v22
	s_nop 1
	v_cndmask_b32_e64 v22, v23, v24, s[40:41]
	v_mul_f32_e32 v23, 0x37800000, v22
	v_cndmask_b32_e32 v22, v22, v23, vcc
	v_cmp_class_f32_e32 vcc, v15, v111
	s_nop 1
	v_cndmask_b32_e32 v15, v22, v15, vcc
	v_div_scale_f32 v22, s[40:41], v15, v15, 1.0
	v_rcp_f32_e32 v23, v22
	s_nop 0
	v_fma_f32 v24, -v22, v23, 1.0
	v_fmac_f32_e32 v23, v24, v23
	v_div_scale_f32 v24, vcc, 1.0, v15, 1.0
	v_mul_f32_e32 v25, v24, v23
	v_fma_f32 v26, -v22, v25, v24
	v_fmac_f32_e32 v25, v26, v23
	v_fma_f32 v22, -v22, v25, v24
	v_div_fmas_f32 v22, v22, v23, v25
	v_mov_b32_e32 v20, v138
	v_mov_b32_e32 v21, v139
	v_lshlrev_b32_e32 v23, 16, v20
	v_mul_f32_e32 v24, 0xbfb8aa3b, v23
	v_exp_f32_e32 v24, v24
	v_and_b32_e32 v20, 0xffff0000, v20
	v_div_fixup_f32 v15, v22, v15, 1.0
	v_mul_f32_e32 v16, v16, v15
	v_add_f32_e32 v24, 1.0, v24
	v_div_scale_f32 v25, s[40:41], v24, v24, v23
	v_rcp_f32_e32 v26, v25
	v_mul_f32_e32 v16, v2, v16
	v_lshlrev_b32_e32 v22, 16, v21
	v_mul_f32_e32 v17, v17, v15
	v_fma_f32 v27, -v25, v26, 1.0
	v_fmac_f32_e32 v26, v27, v26
	v_div_scale_f32 v27, vcc, v23, v24, v23
	v_mul_f32_e32 v28, v27, v26
	v_fma_f32 v29, -v25, v28, v27
	v_fmac_f32_e32 v28, v29, v26
	v_fma_f32 v25, -v25, v28, v27
	v_mul_f32_e32 v27, 0xbfb8aa3b, v20
	v_exp_f32_e32 v27, v27
	v_div_fmas_f32 v25, v25, v26, v28
	v_div_fixup_f32 v23, v25, v24, v23
	v_mul_f32_e32 v16, v23, v16
	v_add_f32_e32 v24, 1.0, v27
	v_div_scale_f32 v25, s[40:41], v24, v24, v20
	v_rcp_f32_e32 v26, v25
	v_mul_f32_e32 v17, v3, v17
	v_and_b32_e32 v21, 0xffff0000, v21
	v_mul_f32_e32 v18, v18, v15
	v_fma_f32 v23, -v25, v26, 1.0
	v_fmac_f32_e32 v26, v23, v26
	v_div_scale_f32 v23, vcc, v20, v24, v20
	v_mul_f32_e32 v27, v23, v26
	v_fma_f32 v28, -v25, v27, v23
	v_fmac_f32_e32 v27, v28, v26
	v_fma_f32 v23, -v25, v27, v23
	v_mul_f32_e32 v25, 0xbfb8aa3b, v22
	v_exp_f32_e32 v25, v25
	v_div_fmas_f32 v23, v23, v26, v27
	v_div_fixup_f32 v20, v23, v24, v20
	v_mul_f32_e32 v17, v20, v17
	v_add_f32_e32 v23, 1.0, v25
	v_div_scale_f32 v24, s[40:41], v23, v23, v22
	v_rcp_f32_e32 v25, v24
	v_mul_f32_e32 v15, v19, v15
	v_mul_f32_e32 v18, v4, v18
	v_mul_f32_e32 v15, v5, v15
	v_fma_f32 v20, -v24, v25, 1.0
	v_fmac_f32_e32 v25, v20, v25
	v_div_scale_f32 v20, vcc, v22, v23, v22
	v_mul_f32_e32 v26, v20, v25
	v_fma_f32 v27, -v24, v26, v20
	v_fmac_f32_e32 v26, v27, v25
	v_fma_f32 v20, -v24, v26, v20
	v_mul_f32_e32 v24, 0xbfb8aa3b, v21
	v_exp_f32_e32 v24, v24
	v_div_fmas_f32 v20, v20, v25, v26
	v_div_fixup_f32 v20, v20, v23, v22
	v_mul_f32_e32 v18, v20, v18
	v_add_f32_e32 v22, 1.0, v24
	v_div_scale_f32 v23, s[40:41], v22, v22, v21
	v_rcp_f32_e32 v24, v23
	s_lshl_b64 s[40:41], s[50:51], 13
	s_add_u32 s48, s48, s60
	s_addc_u32 s49, s49, 0
	v_fma_f32 v19, -v23, v24, 1.0
	v_fmac_f32_e32 v24, v19, v24
	v_div_scale_f32 v19, vcc, v21, v22, v21
	v_mul_f32_e32 v20, v19, v24
	v_fma_f32 v25, -v23, v20, v19
	v_fmac_f32_e32 v20, v25, v24
	v_fma_f32 v19, -v23, v20, v19
	v_div_fmas_f32 v19, v19, v24, v20
	v_div_fixup_f32 v19, v19, v22, v21
	v_mul_f32_e32 v15, v19, v15
	v_cvt_pk_bf16_f32 v16, v16, v17
	v_cvt_pk_bf16_f32 v17, v18, v15
	v_lshl_add_u64 v[18:19], v[6:7], 0, s[40:41]
	s_mul_i32 s40, s49, 0x3000
	s_mul_hi_u32 s41, s48, 0x3000
	s_add_i32 s41, s41, s40
	s_mul_i32 s40, s48, 0x3000
	s_add_u32 s40, s90, s40
	s_addc_u32 s41, s91, s41
	s_add_u32 s40, s40, s38
	s_addc_u32 s41, s41, 0
	global_store_dwordx2 v[18:19], v[16:17], off
	v_lshl_add_u64 v[18:19], s[40:41], 0, v[78:79]
	v_add_co_u32_e32 v18, vcc, s66, v18
	ds_read_b128 v[14:17], v14 offset:10336
	s_nop 0
	v_addc_co_u32_e32 v19, vcc, 0, v19, vcc
	s_add_i32 s94, s94, s88
	s_waitcnt lgkmcnt(0)
	v_mul_f32_e32 v20, v15, v15
	v_mul_f32_e32 v21, v17, v17
	v_fmac_f32_e32 v20, v14, v14
	v_fmac_f32_e32 v21, v16, v16
	v_add_f32_e32 v20, v20, v21
	ds_bpermute_b32 v8, v8, v20
	s_add_i32 s61, s61, s62
	s_waitcnt lgkmcnt(0)
	v_add_f32_e32 v8, v20, v8
	ds_bpermute_b32 v9, v9, v8
	s_waitcnt lgkmcnt(0)
	v_add_f32_e32 v8, v8, v9
	ds_bpermute_b32 v9, v10, v8
	s_waitcnt lgkmcnt(0)
	v_add_f32_e32 v8, v8, v9
	ds_bpermute_b32 v9, v11, v8
	s_waitcnt lgkmcnt(0)
	v_add_f32_e32 v8, v8, v9
	ds_bpermute_b32 v9, v12, v8
	s_waitcnt lgkmcnt(0)
	v_add_f32_e32 v8, v8, v9
	ds_bpermute_b32 v9, v13, v8
	s_waitcnt lgkmcnt(0)
; #define LAS __attribute__((address_space(3)))
; __device__ __forceinline__ unsigned cvt_pk_bf16(float lo, float hi) { unsigned r; asm volatile("v_cvt_pk_bf16_f32 %0, %1, %2" : "=v"(r) : "v"(lo), "v"(hi)); return r; }
; __device__ __forceinline__ float bflo(unsigned w) { return __uint_as_float(w << 16); }
; __device__ __forceinline__ float bfhi(unsigned w) { return __uint_as_float(w & 0xffff0000u); }
; #define gla_norm_g ARGP(6)
; __device__ __forceinline__ void gc_unit(LAS unsigned char* lds, int unit, const bf16_t* proj, const bf16_t* dSt, const float* gnorm, bf16_t* omix, int tid, int wave, int lane) {
;     ...
;     for (int rr = 0; rr < 8; ++rr) { const int c = 8 * wave + rr; const f32x4 v = *(const LAS f32x4*)(lds + L_OT + c * 1040 + lane * 16);
;         float ss = (v[0] * v[0] + v[1] * v[1]) + (v[2] * v[2] + v[3] * v[3]);
; #pragma unroll
;         for (int o = 1; o < 64; o <<= 1) ss += __shfl_xor(ss, o);
;         const float rs = 1.0f / sqrtf(ss * (1.0f / 256.0f) + EPS);
;         const u32x2 gw2 = *((const u32x2*)(proj + (row0 + c) * PROJ_LD + C_GOUT + h * 256) + lane);
;         const float z0 = bflo(gw2.x), z1 = bfhi(gw2.x), z2 = bflo(gw2.y), z3 = bfhi(gw2.y);
;         const float p0 = v[0] * rs * g[0] * (z0 / (1.0f + __expf(-z0))), p1 = v[1] * rs * g[1] * (z1 / (1.0f + __expf(-z1)));
;         const float p2 = v[2] * rs * g[2] * (z2 / (1.0f + __expf(-z2))), p3 = v[3] * rs * g[3] * (z3 / (1.0f + __expf(-z3)));
;         u32x2 w; w.x = cvt_pk_bf16(p0, p1); w.y = cvt_pk_bf16(p2, p3); *((u32x2*)(omix + (row0 + c) * DM + h * 256) + lane) = w; }
;     __syncthreads();
; __global__ void __launch_bounds__(NWAVES * 64, 2) fwd(Args args) {
;     ...
;         for (int un = F.vcu; un < 2048; un += F.G) gla::gc_unit(F.lds, un, proj, dSt, gla_norm_g, omix, F.tid, F.wave, F.lane);
	v_add_f32_e32 v8, v8, v9
	v_fmamk_f32 v8, v8, 0x3b800000, v110
	v_mul_f32_e32 v9, 0x4f800000, v8
	v_cmp_gt_f32_e32 vcc, s65, v8
	s_nop 1
	v_cndmask_b32_e32 v8, v8, v9, vcc
	v_sqrt_f32_e32 v9, v8
	s_nop 0
	v_add_u32_e32 v10, -1, v9
	v_fma_f32 v11, -v10, v9, v8
	v_cmp_ge_f32_e64 s[40:41], 0, v11
	v_add_u32_e32 v11, 1, v9
	s_nop 0
	v_cndmask_b32_e64 v10, v9, v10, s[40:41]
	v_fma_f32 v9, -v11, v9, v8
	v_cmp_lt_f32_e64 s[40:41], 0, v9
	s_nop 1
	v_cndmask_b32_e64 v9, v10, v11, s[40:41]
	v_mul_f32_e32 v10, 0x37800000, v9
	v_cndmask_b32_e32 v9, v9, v10, vcc
	v_cmp_class_f32_e32 vcc, v8, v111
	s_nop 1
	v_cndmask_b32_e32 v8, v9, v8, vcc
	v_div_scale_f32 v9, s[40:41], v8, v8, 1.0
	v_rcp_f32_e32 v10, v9
	s_nop 0
	v_fma_f32 v11, -v9, v10, 1.0
	v_fmac_f32_e32 v10, v11, v10
	v_div_scale_f32 v11, vcc, 1.0, v8, 1.0
	v_mul_f32_e32 v12, v11, v10
	v_fma_f32 v13, -v9, v12, v11
	v_fmac_f32_e32 v12, v13, v10
	v_fma_f32 v9, -v9, v12, v11
	v_div_fmas_f32 v9, v9, v10, v12
	v_mov_b32_e32 v18, v140
	v_mov_b32_e32 v19, v141
	v_lshlrev_b32_e32 v10, 16, v18
	v_mul_f32_e32 v11, 0xbfb8aa3b, v10
	v_exp_f32_e32 v11, v11
	v_div_fixup_f32 v8, v9, v8, 1.0
	v_and_b32_e32 v9, 0xffff0000, v18
	v_mul_f32_e32 v14, v14, v8
	v_add_f32_e32 v11, 1.0, v11
	v_div_scale_f32 v13, s[40:41], v11, v11, v10
	v_rcp_f32_e32 v18, v13
	v_mul_f32_e32 v2, v2, v14
	v_lshlrev_b32_e32 v12, 16, v19
	v_and_b32_e32 v19, 0xffff0000, v19
	v_fma_f32 v14, -v13, v18, 1.0
	v_fmac_f32_e32 v18, v14, v18
	v_div_scale_f32 v14, vcc, v10, v11, v10
	v_mul_f32_e32 v20, v14, v18
	v_fma_f32 v21, -v13, v20, v14
	v_fmac_f32_e32 v20, v21, v18
	v_fma_f32 v13, -v13, v20, v14
	v_mul_f32_e32 v14, 0xbfb8aa3b, v9
	v_exp_f32_e32 v14, v14
	v_div_fmas_f32 v13, v13, v18, v20
	v_div_fixup_f32 v10, v13, v11, v10
	v_mul_f32_e32 v2, v10, v2
	v_add_f32_e32 v11, 1.0, v14
	v_div_scale_f32 v13, s[40:41], v11, v11, v9
	v_rcp_f32_e32 v14, v13
	v_mul_f32_e32 v10, v15, v8
	v_mul_f32_e32 v3, v3, v10
	v_fma_f32 v10, -v13, v14, 1.0
	v_fmac_f32_e32 v14, v10, v14
	v_div_scale_f32 v10, vcc, v9, v11, v9
	v_mul_f32_e32 v15, v10, v14
	v_fma_f32 v18, -v13, v15, v10
	v_fmac_f32_e32 v15, v18, v14
	v_fma_f32 v10, -v13, v15, v10
	v_mul_f32_e32 v13, 0xbfb8aa3b, v12
	v_exp_f32_e32 v13, v13
	v_div_fmas_f32 v10, v10, v14, v15
	v_div_fixup_f32 v9, v10, v11, v9
	v_mul_f32_e32 v3, v9, v3
	v_add_f32_e32 v10, 1.0, v13
	v_div_scale_f32 v11, s[40:41], v10, v10, v12
	v_rcp_f32_e32 v13, v11
	v_mul_f32_e32 v9, v16, v8
	v_mul_f32_e32 v4, v4, v9
	v_mul_f32_e32 v8, v17, v8
	v_fma_f32 v9, -v11, v13, 1.0
	v_fmac_f32_e32 v13, v9, v13
	v_div_scale_f32 v9, vcc, v12, v10, v12
	v_mul_f32_e32 v14, v9, v13
	v_fma_f32 v15, -v11, v14, v9
	v_fmac_f32_e32 v14, v15, v13
	v_fma_f32 v9, -v11, v14, v9
	v_mul_f32_e32 v11, 0xbfb8aa3b, v19
	v_exp_f32_e32 v11, v11
	v_div_fmas_f32 v9, v9, v13, v14
	v_div_fixup_f32 v9, v9, v10, v12
	v_mul_f32_e32 v5, v5, v8
	v_add_f32_e32 v10, 1.0, v11
	v_div_scale_f32 v11, s[40:41], v10, v10, v19
	v_rcp_f32_e32 v12, v11
	v_mul_f32_e32 v4, v9, v4
	s_lshl_b64 s[40:41], s[48:49], 13
	v_cvt_pk_bf16_f32 v2, v2, v3
	v_fma_f32 v8, -v11, v12, 1.0
	v_fmac_f32_e32 v12, v8, v12
	v_div_scale_f32 v8, vcc, v19, v10, v19
	v_mul_f32_e32 v9, v8, v12
	v_fma_f32 v13, -v11, v9, v8
	v_fmac_f32_e32 v9, v13, v12
	v_fma_f32 v8, -v11, v9, v8
	v_div_fmas_f32 v8, v8, v12, v9
	v_div_fixup_f32 v8, v8, v10, v19
	v_mul_f32_e32 v5, v8, v5
	v_cvt_pk_bf16_f32 v3, v4, v5
	v_lshl_add_u64 v[4:5], v[6:7], 0, s[40:41]
	s_cmpk_lt_i32 s94, 0x800
	global_store_dwordx2 v[4:5], v[2:3], off
	s_barrier
	s_cbranch_scc0 .LBB0_1022
; #define LAS __attribute__((address_space(3)))
; __device__ __forceinline__ int crow(int r, int hi) { return (r & 3) + 8 * (r >> 2) + 4 * hi; }
; __device__ __forceinline__ int crow(int r, int hi) { return (r & 3) + 8 * (r >> 2) + 4 * hi; }
; __device__ __forceinline__ unsigned short f2bf1(float x) { return (unsigned short)(cvt_pk_bf16(x, 0.f) & 0xffffu); }
; __device__ __forceinline__ void gc_unit(LAS unsigned char* lds, int unit, const bf16_t* proj, const bf16_t* dSt, const float* gnorm, bf16_t* omix, int tid, int wave, int lane) {
;     ...
;     { const bf16_t* sp = dSt + ((size_t)unit * 256 + 32 * wave + (lane & 31)) * 128 + (lane >> 5) * 8;
; #pragma unroll
;       for (int ks = 0; ks < 8; ++ks) sfr[ks] = *(const bf16x8*)(sp + ks * 16); }
;     { const int t = tid >> 3, c0 = (tid & 7) * 16; const bf16_t* qp = proj + (row0 + t) * PROJ_LD + C_GQ + h * 128 + c0;
;       const u32x4 q0 = *(const u32x4*)qp, q1 = *(const u32x4*)(qp + 8), k0 = *(const u32x4*)(qp + (C_GK - C_GQ)), k1 = *(const u32x4*)(qp + (C_GK - C_GQ) + 8);
;       u32x4 vr[4]; load_v(vr, proj + row0 * PROJ_LD + C_GV + h * 256, tid);
;       *(LAS u32x4*)(lds + L_QD + t * 272 + c0 * 2) = q0; *(LAS u32x4*)(lds + L_QD + t * 272 + c0 * 2 + 16) = q1;
;       *(LAS u32x4*)(lds + L_KI + t * 272 + c0 * 2) = k0; *(LAS u32x4*)(lds + L_KI + t * 272 + c0 * 2 + 16) = k1;
;       store_v(lds, L_VT, vr, tid); }
;     __syncthreads();
;     const int r = lane & 31, hh = lane >> 5;
;     if (wave < 4) { const int ct = wave & 1, st = wave >> 1; f32x16 acc = {};
; #pragma unroll
;         for (int ks = 0; ks < 8; ++ks) { const bf16x8 a = *(const LAS bf16x8*)(lds + L_QD + (ct * 32 + r) * 272 + ks * 32 + hh * 16), bb = *(const LAS bf16x8*)(lds + L_KI + (st * 32 + r) * 272 + ks * 32 + hh * 16);
;             acc = __builtin_amdgcn_mfma_f32_32x32x16_bf16(a, bb, acc, 0, 0, 0); }
; #pragma unroll
;         for (int i = 0; i < 16; ++i) { const int c = ct * 32 + crow(i, hh), s2 = st * 32 + r; const float val = (s2 <= c) ? acc[i] : 0.f;
;             *(LAS unsigned short*)(lds + L_AT + c * 144 + s2 * 2) = f2bf1(val); } }
.LBB0_1009:
	s_ashr_i32 s40, s94, 9
	s_ashr_i32 s41, s40, 31
	s_and_b32 s38, s61, 0xfc0
	s_lshl_b64 s[48:49], s[40:41], 12
	s_or_b32 s48, s48, s38
	v_or_b32_e32 v2, s48, v80
	v_mad_u64_u32 v[2:3], s[40:41], v2, s63, v[88:89]
	s_bfe_u32 s50, s94, 0x30006
	s_mul_i32 s40, s49, 0x3000
	s_mul_hi_u32 s41, s48, 0x3000
	s_lshl_b32 s38, s50, 8
	s_add_i32 s41, s41, s40
	s_mul_i32 s40, s48, 0x3000
	s_add_u32 s40, s90, s40
	v_mad_i32_i24 v3, s49, v99, v3
	s_addc_u32 s41, s91, s41
	s_lshl_b32 s50, s50, 9
	v_lshl_add_u64 v[2:3], v[2:3], 0, s[38:39]
	s_add_u32 s40, s40, s50
	v_lshl_add_u64 v[14:15], v[2:3], 0, v[90:91]
	s_addc_u32 s41, s41, 0
	s_nop 0
	v_lshl_add_u64 v[18:19], s[40:41], 0, v[92:93]
	v_lshl_add_u64 v[18:19], v[18:19], 0, v[94:95]
	v_lshl_add_u64 v[30:31], v[18:19], 0, s[46:47]
	v_add_co_u32_e32 v18, vcc, s64, v18
	s_nop 1
	v_addc_co_u32_e32 v19, vcc, 0, v19, vcc
	s_nop 0
	s_nop 0
	s_nop 0
	s_andn2_b64 vcc, exec, s[42:43]
	s_waitcnt vmcnt(8)
	ds_write_b128 v100, v[188:191] offset:4096
	ds_write_b128 v100, v[184:187] offset:4112
	ds_write_b128 v100, v[196:199] offset:21504
	ds_write_b128 v100, v[192:195] offset:21520
	ds_write_b128 v101, v[200:203] offset:38912
	ds_write_b128 v101, v[208:211] offset:38928
	ds_write_b128 v101, v[204:207] offset:38944
	ds_write_b128 v101, v[212:215] offset:38960
	v_mov_b32_e32 v34, v216
	v_mov_b32_e32 v35, v217
	v_mov_b32_e32 v36, v218
	v_mov_b32_e32 v37, v219
	v_mov_b32_e32 v38, v220
	v_mov_b32_e32 v39, v221
	v_mov_b32_e32 v40, v222
	v_mov_b32_e32 v41, v223
	v_mov_b32_e32 v42, v224
	v_mov_b32_e32 v43, v225
	v_mov_b32_e32 v44, v226
	v_mov_b32_e32 v45, v227
	v_mov_b32_e32 v46, v228
	v_mov_b32_e32 v47, v229
	v_mov_b32_e32 v48, v230
	v_mov_b32_e32 v49, v231
	v_mov_b32_e32 v50, v232
	v_mov_b32_e32 v51, v233
	v_mov_b32_e32 v52, v234
	v_mov_b32_e32 v53, v235
	v_mov_b32_e32 v54, v236
	v_mov_b32_e32 v55, v237
	v_mov_b32_e32 v56, v238
	v_mov_b32_e32 v57, v239
	v_mov_b32_e32 v58, v240
	v_mov_b32_e32 v59, v241
	v_mov_b32_e32 v60, v242
	v_mov_b32_e32 v61, v243
	v_mov_b32_e32 v62, v244
	v_mov_b32_e32 v63, v245
	v_mov_b32_e32 v64, v246
	v_mov_b32_e32 v65, v247
	s_waitcnt lgkmcnt(0)
	s_barrier
	s_cbranch_vccnz .LBB0_1011
	ds_read_b128 v[2:5], v102 offset:4096
	ds_read_b128 v[6:9], v103 offset:21504
	ds_read_b128 v[18:21], v102 offset:4128
	ds_read_b128 v[22:25], v103 offset:21536
	s_waitcnt lgkmcnt(2)
	v_mfma_f32_32x32x16_bf16 v[2:17], v[2:5], v[6:9], 0
	s_waitcnt lgkmcnt(0)
	v_mfma_f32_32x32x16_bf16 v[2:17], v[18:21], v[22:25], v[2:17]
	ds_read_b128 v[18:21], v102 offset:4160
	ds_read_b128 v[22:25], v103 offset:21568
	ds_read_b128 v[26:29], v102 offset:4192
	ds_read_b128 v[30:33], v103 offset:21600
	s_waitcnt lgkmcnt(2)
	v_mfma_f32_32x32x16_bf16 v[2:17], v[18:21], v[22:25], v[2:17]
	s_waitcnt lgkmcnt(0)
	v_mfma_f32_32x32x16_bf16 v[2:17], v[26:29], v[30:33], v[2:17]
	ds_read_b128 v[18:21], v102 offset:4224
	ds_read_b128 v[22:25], v103 offset:21632
	ds_read_b128 v[26:29], v102 offset:4256
	ds_read_b128 v[30:33], v103 offset:21664
	s_waitcnt lgkmcnt(2)
	v_mfma_f32_32x32x16_bf16 v[2:17], v[18:21], v[22:25], v[2:17]
	s_waitcnt lgkmcnt(0)
	v_mfma_f32_32x32x16_bf16 v[2:17], v[26:29], v[30:33], v[2:17]
	ds_read_b128 v[18:21], v102 offset:4288
	ds_read_b128 v[22:25], v103 offset:21696
	ds_read_b128 v[26:29], v102 offset:4320
	ds_read_b128 v[30:33], v103 offset:21728
	s_waitcnt lgkmcnt(2)
	v_mfma_f32_32x32x16_bf16 v[2:17], v[18:21], v[22:25], v[2:17]
	s_waitcnt lgkmcnt(0)
	v_mfma_f32_32x32x16_bf16 v[2:17], v[26:29], v[30:33], v[2:17]
	s_nop 11
	v_cndmask_b32_e64 v2, v2, 0, s[4:5]
	v_cvt_pk_bf16_f32 v2, v2, v79
	v_cndmask_b32_e64 v3, v3, 0, s[6:7]
	ds_write_b16 v104, v2
	v_cvt_pk_bf16_f32 v2, v3, v79
	v_cndmask_b32_e64 v4, v4, 0, s[8:9]
	ds_write_b16 v104, v2 offset:144
	v_cvt_pk_bf16_f32 v2, v4, v79
	v_cndmask_b32_e64 v5, v5, 0, s[10:11]
	ds_write_b16 v104, v2 offset:288
	v_cvt_pk_bf16_f32 v2, v5, v79
	v_cndmask_b32_e64 v6, v6, 0, s[12:13]
	ds_write_b16 v104, v2 offset:432
	v_cvt_pk_bf16_f32 v2, v6, v79
	v_cndmask_b32_e64 v7, v7, 0, s[14:15]
	ds_write_b16 v104, v2 offset:1152
	v_cvt_pk_bf16_f32 v2, v7, v79
	v_cndmask_b32_e64 v8, v8, 0, s[16:17]
	ds_write_b16 v104, v2 offset:1296
	v_cvt_pk_bf16_f32 v2, v8, v79
	v_cndmask_b32_e64 v9, v9, 0, s[18:19]
	ds_write_b16 v104, v2 offset:1440
	v_cvt_pk_bf16_f32 v2, v9, v79
	v_cndmask_b32_e64 v10, v10, 0, s[20:21]
	ds_write_b16 v104, v2 offset:1584
	v_cvt_pk_bf16_f32 v2, v10, v79
	v_cndmask_b32_e64 v11, v11, 0, s[22:23]
	ds_write_b16 v104, v2 offset:2304
	v_cvt_pk_bf16_f32 v2, v11, v79
	v_cndmask_b32_e64 v12, v12, 0, s[24:25]
	ds_write_b16 v104, v2 offset:2448
	v_cvt_pk_bf16_f32 v2, v12, v79
	v_cndmask_b32_e64 v13, v13, 0, s[26:27]
	ds_write_b16 v104, v2 offset:2592
	v_cvt_pk_bf16_f32 v2, v13, v79
	v_cndmask_b32_e64 v14, v14, 0, s[28:29]
	ds_write_b16 v104, v2 offset:2736
	v_cvt_pk_bf16_f32 v2, v14, v79
	v_cndmask_b32_e64 v15, v15, 0, s[30:31]
	ds_write_b16 v104, v2 offset:3456
	v_cvt_pk_bf16_f32 v2, v15, v79
	v_cndmask_b32_e64 v16, v16, 0, s[34:35]
	ds_write_b16 v104, v2 offset:3600
	v_cvt_pk_bf16_f32 v2, v16, v79
	v_cndmask_b32_e64 v17, v17, 0, s[36:37]
	ds_write_b16 v104, v2 offset:3744
	v_cvt_pk_bf16_f32 v2, v17, v79
	ds_write_b16 v104, v2 offset:3888

; __device__ __forceinline__ float bflo(unsigned w) { return __uint_as_float(w << 16); }
; __device__ __forceinline__ float bfhi(unsigned w) { return __uint_as_float(w & 0xffff0000u); }
; #pragma unroll
;     for (int j = 0; j < 8; ++j) mx = fmaxf(mx, fmaxf(fmaxf(fmaxf(fabsf(bflo(w[j].x)), fabsf(bfhi(w[j].x))), fmaxf(fabsf(bflo(w[j].y)), fabsf(bfhi(w[j].y)))), fmaxf(fmaxf(fabsf(bflo(w[j].z)), fabsf(bfhi(w[j].z))), fmaxf(fabsf(bflo(w[j].w)), fabsf(bfhi(w[j].w))))));
; #pragma unroll
;     for (int o = 1; o < 64; o <<= 1) mx = fmaxf(mx, __shfl_xor(mx, o));
;     return mx; }
; __device__ __forceinline__ void quant_store8(const u32x4 (&w)[8], float inv, signed char* dst, int lane) { u32x2* qp = (u32x2*)dst + lane;
; #pragma unroll
;     for (int j = 0; j < 8; ++j) { const unsigned ww[4] = {w[j].x, w[j].y, w[j].z, w[j].w}; unsigned o2[2];
; #pragma unroll
;         for (int h2 = 0; h2 < 2; ++h2) { const int q0 = (int)rintf(bflo(ww[2 * h2]) * inv), q1 = (int)rintf(bfhi(ww[2 * h2]) * inv), q2 = (int)rintf(bflo(ww[2 * h2 + 1]) * inv), q3 = (int)rintf(bfhi(ww[2 * h2 + 1]) * inv);
;             o2[h2] = (unsigned)(q0 & 255) | ((unsigned)(q1 & 255) << 8) | ((unsigned)(q2 & 255) << 16) | ((unsigned)(q3 & 255) << 24); }
;         u32x2 o; o.x = o2[0]; o.y = o2[1]; qp[64 * j] = o; } }
; __device__ __forceinline__ void quant_rows2(const bf16_t* s0, const bf16_t* s1, signed char* d0, signed char* d1, int lane, float& step0, float& step1) {
;     const u32x4* p0 = (const u32x4*)s0 + lane; const u32x4* p1 = (const u32x4*)s1 + lane; u32x4 w0[8], w1[8];
; #pragma unroll
;     for (int j = 0; j < 8; ++j) { w0[j] = p0[64 * j]; w1[j] = p1[64 * j]; }
;     step0 = fmaxf(absmax8(w0), 1e-30f) * (1.0f / 127.0f); step1 = fmaxf(absmax8(w1), 1e-30f) * (1.0f / 127.0f);
; __global__ void __launch_bounds__(NWAVES * 64, 2) fwd(Args args) {
;     ...
;         for (int row = gw; row < T; row += 2 * NGW) { const int row2 = row + NGW;
;             const float pa = part[(size_t)row * 64 + F.lane], pb = part[(size_t)row2 * 64 + F.lane];
;             float st0, st1; quant_rows2(hb + (size_t)row * DM, hb + (size_t)row2 * DM, hq + (size_t)row * DM, hq + (size_t)row2 * DM, F.lane, st0, st1);
.LBB0_1392:
	s_ashr_i32 s23, s22, 31
	s_lshl_b64 s[6:7], s[22:23], 13
	s_waitcnt lgkmcnt(0)
	v_lshl_add_u64 v[2:3], v[18:19], 0, s[6:7]
	global_load_dwordx4 v[30:33], v[2:3], off offset:1024
	global_load_dwordx4 v[42:45], v[2:3], off offset:2048
	global_load_dwordx4 v[46:49], v[2:3], off
	global_load_dwordx4 v[50:53], v[2:3], off offset:3072
	s_add_i32 s24, s22, s68
	s_ashr_i32 s25, s24, 31
	s_lshl_b64 s[6:7], s[24:25], 13
	v_lshl_add_u64 v[62:63], v[18:19], 0, s[6:7]
	v_add_co_u32_e32 v70, vcc, s3, v2
	global_load_dwordx4 v[54:57], v[62:63], off
	s_nop 0
	v_addc_co_u32_e32 v71, vcc, 0, v3, vcc
	global_load_dwordx4 v[10:13], v[62:63], off offset:1024
	global_load_dwordx4 v[6:9], v[62:63], off offset:2048
	global_load_dwordx4 v[2:5], v[62:63], off offset:3072
	global_load_dwordx4 v[58:61], v[70:71], off
	v_add_co_u32_e32 v74, vcc, s3, v62
	s_lshl_b64 s[6:7], s[22:23], 8
	s_nop 0
	v_addc_co_u32_e32 v75, vcc, 0, v63, vcc
	global_load_dwordx4 v[62:65], v[70:71], off offset:1024
	global_load_dwordx4 v[66:69], v[70:71], off offset:2048
	s_nop 0
	global_load_dwordx4 v[70:73], v[70:71], off offset:3072
	s_lshl_b64 s[26:27], s[22:23], 12
	s_waitcnt vmcnt(11)
	v_lshlrev_b32_e32 v104, 16, v30
	v_and_b32_e32 v105, 0xffff0000, v30
	v_lshlrev_b32_e32 v106, 16, v31
	v_and_b32_e32 v107, 0xffff0000, v31
	v_lshlrev_b32_e32 v110, 16, v33
	v_and_b32_e32 v111, 0xffff0000, v33
	s_waitcnt vmcnt(10)
	v_lshlrev_b32_e32 v112, 16, v42
	v_and_b32_e32 v113, 0xffff0000, v42
	v_lshlrev_b32_e32 v118, 16, v45
	v_and_b32_e32 v119, 0xffff0000, v45
	s_waitcnt vmcnt(9)
	v_lshlrev_b32_e32 v126, 16, v49
	v_and_b32_e32 v127, 0xffff0000, v49
	v_lshlrev_b32_e32 v108, 16, v32
	v_and_b32_e32 v109, 0xffff0000, v32
	v_lshlrev_b32_e32 v114, 16, v43
	v_and_b32_e32 v115, 0xffff0000, v43
	v_lshlrev_b32_e32 v116, 16, v44
	v_and_b32_e32 v117, 0xffff0000, v44
	v_lshlrev_b32_e32 v120, 16, v46
	v_and_b32_e32 v121, 0xffff0000, v46
	v_lshlrev_b32_e32 v122, 16, v47
	v_and_b32_e32 v123, 0xffff0000, v47
	v_lshlrev_b32_e32 v124, 16, v48
	v_and_b32_e32 v125, 0xffff0000, v48
	v_max_f32_e64 v29, |v105|, |v105|
	v_max_f32_e64 v30, |v104|, |v104|
	v_max_f32_e64 v31, |v107|, |v107|
	v_max_f32_e64 v32, |v106|, |v106|
	v_max_f32_e64 v33, |v111|, |v111|
	v_max_f32_e64 v42, |v110|, |v110|
	v_max_f32_e64 v43, |v113|, |v113|
	v_max_f32_e64 v44, |v112|, |v112|
	v_max_f32_e64 v47, |v119|, |v119|
	v_max_f32_e64 v48, |v118|, |v118|
	s_waitcnt vmcnt(8)
	v_lshlrev_b32_e32 v128, 16, v50
	v_and_b32_e32 v129, 0xffff0000, v50
	v_max_f32_e64 v78, |v127|, |v127|
	v_max_f32_e64 v79, |v126|, |v126|
	v_max_f32_e64 v45, |v115|, |v115|
	v_max_f32_e64 v46, |v114|, |v114|
	v_max_f32_e64 v49, |v121|, |v121|
	v_max_f32_e64 v50, |v120|, |v120|
	v_max_f32_e64 v76, |v123|, |v123|
	v_max_f32_e64 v77, |v122|, |v122|
	v_max_f32_e32 v29, v30, v29
	v_max_f32_e32 v30, v32, v31
	v_max_f32_e32 v31, v42, v33
	v_max_f32_e32 v32, v44, v43
	v_max_f32_e32 v42, v48, v47
	v_max_f32_e64 v43, |v129|, |v129|
	v_max_f32_e64 v44, |v128|, |v128|
	v_max_f32_e32 v47, v79, v78
	v_max_f32_e32 v33, v46, v45
	v_max_f32_e32 v45, v50, v49
	v_max_f32_e32 v46, v77, v76
	v_max3_f32 v31, |v108|, |v109|, v31
	v_max_f32_e32 v43, v44, v43
	v_max3_f32 v44, |v124|, |v125|, v47
	v_max3_f32 v42, |v116|, |v117|, v42
	v_max3_f32 v29, v29, v30, v31
	v_max3_f32 v31, v45, v46, v44
	v_lshlrev_b32_e32 v130, 16, v51
	v_and_b32_e32 v131, 0xffff0000, v51
	v_max3_f32 v30, v32, v33, v42
	v_max3_f32 v29, v31, 0, v29
	v_max_f32_e64 v31, |v131|, |v131|
	v_max_f32_e64 v32, |v130|, |v130|
	v_lshlrev_b32_e32 v134, 16, v53
	v_and_b32_e32 v135, 0xffff0000, v53
	v_max_f32_e32 v31, v32, v31
	v_max_f32_e64 v32, |v135|, |v135|
	v_max_f32_e64 v33, |v134|, |v134|
	v_lshlrev_b32_e32 v132, 16, v52
	v_and_b32_e32 v133, 0xffff0000, v52
	v_max_f32_e32 v32, v33, v32
	v_max3_f32 v32, |v132|, |v133|, v32
	v_max3_f32 v31, v43, v31, v32
	s_waitcnt vmcnt(3)
	v_lshlrev_b32_e32 v136, 16, v58
	v_and_b32_e32 v137, 0xffff0000, v58
	v_max3_f32 v29, v29, v30, v31
	v_max_f32_e64 v30, |v137|, |v137|
	v_max_f32_e64 v31, |v136|, |v136|
	v_lshlrev_b32_e32 v138, 16, v59
	v_and_b32_e32 v139, 0xffff0000, v59
	v_max_f32_e32 v30, v31, v30
	v_max_f32_e64 v31, |v139|, |v139|
	v_max_f32_e64 v32, |v138|, |v138|
	v_lshlrev_b32_e32 v142, 16, v61
	v_and_b32_e32 v143, 0xffff0000, v61
	v_max_f32_e32 v31, v32, v31
	v_max_f32_e64 v32, |v143|, |v143|
	v_max_f32_e64 v33, |v142|, |v142|
	v_lshlrev_b32_e32 v140, 16, v60
	v_and_b32_e32 v141, 0xffff0000, v60
	v_max_f32_e32 v32, v33, v32
	v_max3_f32 v32, |v140|, |v141|, v32
	s_waitcnt vmcnt(2)
	v_lshlrev_b32_e32 v144, 16, v62
	v_and_b32_e32 v145, 0xffff0000, v62
	v_max3_f32 v30, v30, v31, v32
	v_max_f32_e64 v31, |v145|, |v145|
	v_max_f32_e64 v32, |v144|, |v144|
	v_lshlrev_b32_e32 v146, 16, v63
	v_and_b32_e32 v147, 0xffff0000, v63
	v_max_f32_e32 v31, v32, v31
	v_max_f32_e64 v32, |v147|, |v147|
	v_max_f32_e64 v33, |v146|, |v146|
	v_lshlrev_b32_e32 v150, 16, v65
	v_and_b32_e32 v151, 0xffff0000, v65
	v_max_f32_e32 v32, v33, v32
	v_max_f32_e64 v33, |v151|, |v151|
	v_max_f32_e64 v42, |v150|, |v150|
	v_lshlrev_b32_e32 v148, 16, v64
	v_and_b32_e32 v149, 0xffff0000, v64
	v_max_f32_e32 v33, v42, v33
	v_max3_f32 v33, |v148|, |v149|, v33
	v_max3_f32 v31, v31, v32, v33
	s_waitcnt vmcnt(1)
	v_lshlrev_b32_e32 v152, 16, v66
	v_and_b32_e32 v153, 0xffff0000, v66
	v_max3_f32 v29, v29, v30, v31
	v_max_f32_e64 v30, |v153|, |v153|
	v_max_f32_e64 v31, |v152|, |v152|
	v_lshlrev_b32_e32 v154, 16, v67
	v_and_b32_e32 v155, 0xffff0000, v67
	v_max_f32_e32 v30, v31, v30
	v_max_f32_e64 v31, |v155|, |v155|
	v_max_f32_e64 v32, |v154|, |v154|
	v_lshlrev_b32_e32 v158, 16, v69
	v_and_b32_e32 v159, 0xffff0000, v69
	v_max_f32_e32 v31, v32, v31
	v_max_f32_e64 v32, |v159|, |v159|
	v_max_f32_e64 v33, |v158|, |v158|
	v_lshlrev_b32_e32 v156, 16, v68
	v_and_b32_e32 v157, 0xffff0000, v68
	v_max_f32_e32 v32, v33, v32
	v_max3_f32 v32, |v156|, |v157|, v32
	s_waitcnt vmcnt(0)
; __device__ __forceinline__ float bflo(unsigned w) { return __uint_as_float(w << 16); }
; __device__ __forceinline__ float bfhi(unsigned w) { return __uint_as_float(w & 0xffff0000u); }
; #pragma unroll
;     for (int j = 0; j < 8; ++j) mx = fmaxf(mx, fmaxf(fmaxf(fmaxf(fabsf(bflo(w[j].x)), fabsf(bfhi(w[j].x))), fmaxf(fabsf(bflo(w[j].y)), fabsf(bfhi(w[j].y)))), fmaxf(fmaxf(fabsf(bflo(w[j].z)), fabsf(bfhi(w[j].z))), fmaxf(fabsf(bflo(w[j].w)), fabsf(bfhi(w[j].w))))));
; #pragma unroll
;     for (int o = 1; o < 64; o <<= 1) mx = fmaxf(mx, __shfl_xor(mx, o));
;     return mx; }
; __device__ __forceinline__ void quant_rows2(const bf16_t* s0, const bf16_t* s1, signed char* d0, signed char* d1, int lane, float& step0, float& step1) {
;     const u32x4* p0 = (const u32x4*)s0 + lane; const u32x4* p1 = (const u32x4*)s1 + lane; u32x4 w0[8], w1[8];
; #pragma unroll
;     for (int j = 0; j < 8; ++j) { w0[j] = p0[64 * j]; w1[j] = p1[64 * j]; }
;     step0 = fmaxf(absmax8(w0), 1e-30f) * (1.0f / 127.0f); step1 = fmaxf(absmax8(w1), 1e-30f) * (1.0f / 127.0f);
	v_lshlrev_b32_e32 v160, 16, v70
	v_and_b32_e32 v161, 0xffff0000, v70
	v_max3_f32 v30, v30, v31, v32
	v_max_f32_e64 v31, |v161|, |v161|
	v_max_f32_e64 v32, |v160|, |v160|
	v_lshlrev_b32_e32 v162, 16, v71
	v_and_b32_e32 v163, 0xffff0000, v71
	v_max_f32_e32 v31, v32, v31
	v_max_f32_e64 v32, |v163|, |v163|
	v_max_f32_e64 v33, |v162|, |v162|
	v_lshlrev_b32_e32 v166, 16, v73
	v_and_b32_e32 v93, 0xffff0000, v73
	v_max_f32_e32 v32, v33, v32
	v_max_f32_e64 v33, |v93|, |v93|
	v_max_f32_e64 v42, |v166|, |v166|
	v_lshlrev_b32_e32 v164, 16, v72
	v_and_b32_e32 v165, 0xffff0000, v72
	v_max_f32_e32 v33, v42, v33
	v_max3_f32 v33, |v164|, |v165|, v33
	v_max3_f32 v31, v31, v32, v33
	v_max3_f32 v29, v29, v30, v31
	global_load_dwordx4 v[30:33], v[74:75], off
	global_load_dwordx4 v[42:45], v[74:75], off offset:1024
	global_load_dwordx4 v[96:99], v[74:75], off offset:2048
	global_load_dwordx4 v[100:103], v[74:75], off offset:3072
	s_nop 1
	v_mov_b32_dpp v46, v29 quad_perm:[1,0,3,2] row_mask:0xf bank_mask:0xf
	v_lshlrev_b32_e32 v95, 16, v54
	v_and_b32_e32 v92, 0xffff0000, v54
	v_lshlrev_b32_e32 v94, 16, v55
	v_and_b32_e32 v91, 0xffff0000, v55
	s_waitcnt lgkmcnt(0)
	v_max_f32_e32 v46, v46, v46
	v_max_f32_e32 v167, v29, v46
	v_max_f32_e64 v29, |v92|, |v92|
	v_max_f32_e64 v46, |v95|, |v95|
	v_max_f32_e32 v29, v46, v29
	v_max_f32_e64 v46, |v91|, |v91|
	v_max_f32_e64 v47, |v94|, |v94|
	v_lshlrev_b32_e32 v88, 16, v57
	v_and_b32_e32 v87, 0xffff0000, v57
	v_max_f32_e32 v46, v47, v46
	v_max_f32_e64 v47, |v87|, |v87|
	v_max_f32_e64 v48, |v88|, |v88|
	v_lshlrev_b32_e32 v90, 16, v56
	v_and_b32_e32 v89, 0xffff0000, v56
	v_max_f32_e32 v47, v48, v47
	v_max3_f32 v47, |v90|, |v89|, v47
	v_lshlrev_b32_e32 v86, 16, v10
	v_and_b32_e32 v84, 0xffff0000, v10
	v_lshlrev_b32_e32 v80, 16, v13
	v_and_b32_e32 v79, 0xffff0000, v13
	v_max3_f32 v29, v29, v46, v47
	v_max_f32_e64 v10, |v84|, |v84|
	v_max_f32_e64 v46, |v86|, |v86|
	v_lshlrev_b32_e32 v85, 16, v11
	v_and_b32_e32 v83, 0xffff0000, v11
	v_lshlrev_b32_e32 v82, 16, v12
	v_and_b32_e32 v81, 0xffff0000, v12
	v_max_f32_e64 v12, |v79|, |v79|
	v_max_f32_e64 v13, |v80|, |v80|
	v_max_f32_e32 v10, v46, v10
	v_max_f32_e64 v11, |v83|, |v83|
	v_max_f32_e64 v46, |v85|, |v85|
	v_max_f32_e32 v12, v13, v12
	v_max_f32_e32 v11, v46, v11
	v_max3_f32 v12, |v82|, |v81|, v12
	v_lshlrev_b32_e32 v78, 16, v6
	v_and_b32_e32 v76, 0xffff0000, v6
	v_lshlrev_b32_e32 v72, 16, v9
	v_and_b32_e32 v71, 0xffff0000, v9
	v_max3_f32 v10, v10, v11, v12
	v_max_f32_e64 v6, |v76|, |v76|
	v_max_f32_e64 v11, |v78|, |v78|
	v_lshlrev_b32_e32 v77, 16, v7
	v_and_b32_e32 v75, 0xffff0000, v7
	v_lshlrev_b32_e32 v74, 16, v8
	v_and_b32_e32 v73, 0xffff0000, v8
	v_max_f32_e64 v8, |v71|, |v71|
	v_max_f32_e64 v9, |v72|, |v72|
	v_max_f32_e32 v6, v11, v6
	v_max_f32_e64 v7, |v75|, |v75|
	v_max_f32_e64 v11, |v77|, |v77|
	v_max_f32_e32 v8, v9, v8
	v_max_f32_e32 v7, v11, v7
	v_max3_f32 v8, |v74|, |v73|, v8
	v_lshlrev_b32_e32 v70, 16, v2
	v_and_b32_e32 v68, 0xffff0000, v2
	v_lshlrev_b32_e32 v64, 16, v5
	v_and_b32_e32 v63, 0xffff0000, v5
	v_max3_f32 v6, v6, v7, v8
	v_max_f32_e64 v2, |v68|, |v68|
	v_max_f32_e64 v7, |v70|, |v70|
	v_lshlrev_b32_e32 v69, 16, v3
	v_and_b32_e32 v67, 0xffff0000, v3
	v_lshlrev_b32_e32 v66, 16, v4
	v_and_b32_e32 v65, 0xffff0000, v4
	v_max_f32_e64 v4, |v63|, |v63|
	v_max_f32_e64 v5, |v64|, |v64|
	v_max_f32_e32 v2, v7, v2
	v_max_f32_e64 v3, |v67|, |v67|
	v_max_f32_e64 v7, |v69|, |v69|
	v_max_f32_e32 v4, v5, v4
	v_max_f32_e32 v3, v7, v3
	v_max3_f32 v4, |v66|, |v65|, v4
	s_waitcnt vmcnt(3)
	v_lshlrev_b32_e32 v62, 16, v30
	v_and_b32_e32 v60, 0xffff0000, v30
	v_max3_f32 v2, v2, v3, v4
	v_max_f32_e64 v3, |v60|, |v60|
	v_max_f32_e64 v4, |v62|, |v62|
	v_lshlrev_b32_e32 v61, 16, v31
	v_and_b32_e32 v59, 0xffff0000, v31
	v_max3_f32 v10, v29, 0, v10
	v_max_f32_e32 v3, v4, v3
	v_max_f32_e64 v4, |v59|, |v59|
	v_max_f32_e64 v5, |v61|, |v61|
	v_lshlrev_b32_e32 v56, 16, v33
	v_and_b32_e32 v55, 0xffff0000, v33
	v_max3_f32 v2, v10, v6, v2
	v_max_f32_e32 v4, v5, v4
	v_max_f32_e64 v5, |v55|, |v55|
	v_max_f32_e64 v6, |v56|, |v56|
	v_lshlrev_b32_e32 v58, 16, v32
	v_and_b32_e32 v57, 0xffff0000, v32
	v_max_f32_e32 v5, v6, v5
	v_max3_f32 v5, |v58|, |v57|, v5
	s_waitcnt vmcnt(2)
	v_lshlrev_b32_e32 v54, 16, v42
	v_and_b32_e32 v52, 0xffff0000, v42
	v_max3_f32 v3, v3, v4, v5
	v_max_f32_e64 v4, |v52|, |v52|
	v_max_f32_e64 v5, |v54|, |v54|
	v_lshlrev_b32_e32 v53, 16, v43
	v_and_b32_e32 v51, 0xffff0000, v43
	v_max_f32_e32 v4, v5, v4
	v_max_f32_e64 v5, |v51|, |v51|
	v_max_f32_e64 v6, |v53|, |v53|
	v_lshlrev_b32_e32 v48, 16, v45
	v_and_b32_e32 v47, 0xffff0000, v45
	v_max_f32_e32 v5, v6, v5
	v_max_f32_e64 v6, |v47|, |v47|
	v_max_f32_e64 v7, |v48|, |v48|
	v_lshlrev_b32_e32 v50, 16, v44
	v_and_b32_e32 v49, 0xffff0000, v44
	v_max_f32_e32 v6, v7, v6
	v_max3_f32 v6, |v50|, |v49|, v6
	v_max3_f32 v4, v4, v5, v6
	s_waitcnt vmcnt(1)
	v_lshlrev_b32_e32 v46, 16, v96
	v_and_b32_e32 v44, 0xffff0000, v96
	v_max3_f32 v2, v2, v3, v4
	v_max_f32_e64 v3, |v44|, |v44|
	v_max_f32_e64 v4, |v46|, |v46|
	v_lshlrev_b32_e32 v45, 16, v97
	v_and_b32_e32 v43, 0xffff0000, v97
	v_max_f32_e32 v3, v4, v3
	v_max_f32_e64 v4, |v43|, |v43|
	v_max_f32_e64 v5, |v45|, |v45|
	v_lshlrev_b32_e32 v32, 16, v99
	v_and_b32_e32 v31, 0xffff0000, v99
	v_max_f32_e32 v4, v5, v4
	v_max_f32_e64 v5, |v31|, |v31|
	v_max_f32_e64 v6, |v32|, |v32|
	v_lshlrev_b32_e32 v42, 16, v98
	v_and_b32_e32 v33, 0xffff0000, v98
	v_max_f32_e32 v5, v6, v5
	v_max3_f32 v5, |v42|, |v33|, v5
	s_waitcnt vmcnt(0)
; __device__ __forceinline__ float bflo(unsigned w) { return __uint_as_float(w << 16); }
; __device__ __forceinline__ float bfhi(unsigned w) { return __uint_as_float(w & 0xffff0000u); }
; #pragma unroll
;     for (int j = 0; j < 8; ++j) mx = fmaxf(mx, fmaxf(fmaxf(fmaxf(fabsf(bflo(w[j].x)), fabsf(bfhi(w[j].x))), fmaxf(fabsf(bflo(w[j].y)), fabsf(bfhi(w[j].y)))), fmaxf(fmaxf(fabsf(bflo(w[j].z)), fabsf(bfhi(w[j].z))), fmaxf(fabsf(bflo(w[j].w)), fabsf(bfhi(w[j].w))))));
; #pragma unroll
;     for (int o = 1; o < 64; o <<= 1) mx = fmaxf(mx, __shfl_xor(mx, o));
;     return mx; }
; __device__ __forceinline__ void quant_store8(const u32x4 (&w)[8], float inv, signed char* dst, int lane) { u32x2* qp = (u32x2*)dst + lane;
; #pragma unroll
;     for (int j = 0; j < 8; ++j) { const unsigned ww[4] = {w[j].x, w[j].y, w[j].z, w[j].w}; unsigned o2[2];
; #pragma unroll
;         for (int h2 = 0; h2 < 2; ++h2) { const int q0 = (int)rintf(bflo(ww[2 * h2]) * inv), q1 = (int)rintf(bfhi(ww[2 * h2]) * inv), q2 = (int)rintf(bflo(ww[2 * h2 + 1]) * inv), q3 = (int)rintf(bfhi(ww[2 * h2 + 1]) * inv);
;             o2[h2] = (unsigned)(q0 & 255) | ((unsigned)(q1 & 255) << 8) | ((unsigned)(q2 & 255) << 16) | ((unsigned)(q3 & 255) << 24); }
;         u32x2 o; o.x = o2[0]; o.y = o2[1]; qp[64 * j] = o; } }
; __device__ __forceinline__ void quant_rows2(const bf16_t* s0, const bf16_t* s1, signed char* d0, signed char* d1, int lane, float& step0, float& step1) {
;     const u32x4* p0 = (const u32x4*)s0 + lane; const u32x4* p1 = (const u32x4*)s1 + lane; u32x4 w0[8], w1[8];
; #pragma unroll
;     for (int j = 0; j < 8; ++j) { w0[j] = p0[64 * j]; w1[j] = p1[64 * j]; }
;     step0 = fmaxf(absmax8(w0), 1e-30f) * (1.0f / 127.0f); step1 = fmaxf(absmax8(w1), 1e-30f) * (1.0f / 127.0f);
;     quant_store8(w0, 1.0f / step0, d0, lane); quant_store8(w1, 1.0f / step1, d1, lane);
	v_lshlrev_b32_e32 v30, 16, v100
	v_and_b32_e32 v12, 0xffff0000, v100
	v_max3_f32 v3, v3, v4, v5
	v_max_f32_e64 v4, |v12|, |v12|
	v_max_f32_e64 v5, |v30|, |v30|
	v_lshlrev_b32_e32 v29, 16, v101
	v_and_b32_e32 v10, 0xffff0000, v101
	v_max_f32_e32 v4, v5, v4
	v_max_f32_e64 v5, |v10|, |v10|
	v_max_f32_e64 v6, |v29|, |v29|
	v_max_f32_e32 v5, v6, v5
	v_lshlrev_b32_e32 v7, 16, v103
	v_and_b32_e32 v6, 0xffff0000, v103
	v_max_f32_e64 v11, |v6|, |v6|
	v_max_f32_e64 v13, |v7|, |v7|
	v_lshlrev_b32_e32 v9, 16, v102
	v_and_b32_e32 v8, 0xffff0000, v102
	v_max_f32_e32 v11, v13, v11
	v_max3_f32 v11, |v9|, |v8|, v11
	v_max3_f32 v4, v4, v5, v11
	s_nop 1
	v_mov_b32_dpp v168, v167 quad_perm:[2,3,0,1] row_mask:0xf bank_mask:0xf
	v_max3_f32 v2, v2, v3, v4
	s_nop 1
	v_mov_b32_dpp v3, v2 quad_perm:[1,0,3,2] row_mask:0xf bank_mask:0xf
	s_waitcnt lgkmcnt(0)
	v_max_f32_e32 v4, v168, v168
	v_max_f32_e32 v4, v167, v4
	s_waitcnt lgkmcnt(0)
	v_max_f32_e32 v3, v3, v3
	s_nop 1
	v_mov_b32_dpp v5, v4 row_half_mirror row_mask:0xf bank_mask:0xf
	v_max_f32_e32 v11, v2, v3
	s_nop 1
	v_mov_b32_dpp v13, v11 quad_perm:[2,3,0,1] row_mask:0xf bank_mask:0xf
	v_lshl_add_u64 v[2:3], v[16:17], 0, s[6:7]
	s_lshl_b64 s[6:7], s[24:25], 8
	s_waitcnt lgkmcnt(0)
	v_max_f32_e32 v5, v5, v5
	v_max_f32_e32 v4, v4, v5
	s_waitcnt lgkmcnt(0)
	v_max_f32_e32 v13, v13, v13
	s_nop 1
	v_mov_b32_dpp v5, v4 row_mirror row_mask:0xf bank_mask:0xf
	v_max_f32_e32 v11, v11, v13
	s_nop 1
	v_mov_b32_dpp v13, v11 row_half_mirror row_mask:0xf bank_mask:0xf
	s_waitcnt lgkmcnt(0)
	v_max_f32_e32 v5, v5, v5
	v_max_f32_e32 v96, v4, v5
	s_waitcnt lgkmcnt(0)
	v_max_f32_e32 v4, v13, v13
	ds_bpermute_b32 v97, v26, v96
	v_max_f32_e32 v11, v11, v4
	s_nop 1
	v_mov_b32_dpp v13, v11 row_mirror row_mask:0xf bank_mask:0xf
	v_lshl_add_u64 v[4:5], v[16:17], 0, s[6:7]
	s_waitcnt lgkmcnt(0)
	v_max_f32_e32 v97, v97, v97
	v_max_f32_e32 v96, v96, v97
	s_waitcnt lgkmcnt(0)
	v_max_f32_e32 v13, v13, v13
	ds_bpermute_b32 v97, v27, v96
	v_max_f32_e32 v98, v11, v13
	ds_bpermute_b32 v99, v26, v98
	global_load_dword v13, v[2:3], off
	global_load_dword v11, v[4:5], off
	s_waitcnt lgkmcnt(1)
	v_max3_f32 v2, v96, v97, s28
	v_mul_f32_e32 v4, 0x3c010204, v2
	s_waitcnt lgkmcnt(0)
	v_max_f32_e32 v2, v99, v99
	v_max_f32_e32 v2, v98, v2
	ds_bpermute_b32 v3, v27, v2
	v_div_scale_f32 v96, s[6:7], v4, v4, 1.0
	v_rcp_f32_e32 v97, v96
	s_lshl_b64 s[6:7], s[24:25], 12
	s_waitcnt lgkmcnt(0)
	v_max3_f32 v2, v2, v3, s28
	v_mul_f32_e32 v5, 0x3c010204, v2
	v_fma_f32 v2, -v96, v97, 1.0
	v_fmac_f32_e32 v97, v2, v97
	v_div_scale_f32 v2, vcc, 1.0, v4, 1.0
	v_mul_f32_e32 v3, v2, v97
	v_fma_f32 v98, -v96, v3, v2
	v_fmac_f32_e32 v3, v98, v97
	v_fma_f32 v2, -v96, v3, v2
	v_div_fmas_f32 v2, v2, v97, v3
	v_div_fixup_f32 v98, v2, v4, 1.0
	v_mul_f32_e32 v97, v98, v121
	v_mul_f32_e32 v96, v98, v120
	v_rndne_f32_e32 v97, v97
	v_mul_f32_e32 v99, v98, v122
	v_rndne_f32_e32 v96, v96
	v_cvt_i32_f32_e32 v97, v97
	v_rndne_f32_e32 v99, v99
	v_mul_f32_e32 v100, v98, v123
	v_cvt_i32_f32_e32 v96, v96
	v_cvt_i32_f32_sdwa v99, v99 dst_sel:WORD_1 dst_unused:UNUSED_PAD src0_sel:DWORD
	v_rndne_f32_e32 v100, v100
	v_cvt_i32_f32_sdwa v100, v100 dst_sel:BYTE_3 dst_unused:UNUSED_PAD src0_sel:DWORD
	v_lshlrev_b32_e32 v97, 8, v97
	v_and_b32_e32 v99, 0xff0000, v99
	v_perm_b32 v96, v97, v96, s29
	v_or3_b32 v96, v96, v100, v99
	v_mul_f32_e32 v99, v98, v125
	v_mul_f32_e32 v97, v98, v124
	v_rndne_f32_e32 v99, v99
	v_mul_f32_e32 v100, v98, v126
	v_rndne_f32_e32 v97, v97
	v_cvt_i32_f32_e32 v99, v99
	v_rndne_f32_e32 v100, v100
	v_mul_f32_e32 v101, v98, v127
	v_cvt_i32_f32_e32 v97, v97
	v_cvt_i32_f32_sdwa v100, v100 dst_sel:WORD_1 dst_unused:UNUSED_PAD src0_sel:DWORD
	v_rndne_f32_e32 v101, v101
	v_cvt_i32_f32_sdwa v101, v101 dst_sel:BYTE_3 dst_unused:UNUSED_PAD src0_sel:DWORD
	v_lshlrev_b32_e32 v99, 8, v99
	v_and_b32_e32 v100, 0xff0000, v100
	v_perm_b32 v97, v99, v97, s29
	v_lshl_add_u64 v[2:3], v[20:21], 0, s[26:27]
	v_or3_b32 v97, v97, v101, v100
	global_store_dwordx2 v[2:3], v[96:97], off
	v_mul_f32_e32 v97, v98, v105
	v_mul_f32_e32 v96, v98, v104
	v_rndne_f32_e32 v97, v97
	v_mul_f32_e32 v99, v98, v106
	v_rndne_f32_e32 v96, v96
	v_cvt_i32_f32_e32 v97, v97
	v_rndne_f32_e32 v99, v99
	v_mul_f32_e32 v100, v98, v107
	v_cvt_i32_f32_e32 v96, v96
	v_cvt_i32_f32_sdwa v99, v99 dst_sel:WORD_1 dst_unused:UNUSED_PAD src0_sel:DWORD
	v_rndne_f32_e32 v100, v100
	v_cvt_i32_f32_sdwa v100, v100 dst_sel:BYTE_3 dst_unused:UNUSED_PAD src0_sel:DWORD
	v_lshlrev_b32_e32 v97, 8, v97
	v_and_b32_e32 v99, 0xff0000, v99
	v_perm_b32 v96, v97, v96, s29
	v_or3_b32 v96, v96, v100, v99
	v_mul_f32_e32 v99, v98, v109
	v_mul_f32_e32 v97, v98, v108
	v_rndne_f32_e32 v99, v99
	v_mul_f32_e32 v100, v98, v110
	v_rndne_f32_e32 v97, v97
	v_cvt_i32_f32_e32 v99, v99
	v_rndne_f32_e32 v100, v100
	v_mul_f32_e32 v101, v98, v111
	v_cvt_i32_f32_e32 v97, v97
	v_cvt_i32_f32_sdwa v100, v100 dst_sel:WORD_1 dst_unused:UNUSED_PAD src0_sel:DWORD
	v_rndne_f32_e32 v101, v101
	v_cvt_i32_f32_sdwa v101, v101 dst_sel:BYTE_3 dst_unused:UNUSED_PAD src0_sel:DWORD
	v_lshlrev_b32_e32 v99, 8, v99
	v_and_b32_e32 v100, 0xff0000, v100
	v_perm_b32 v97, v99, v97, s29
	v_or3_b32 v97, v97, v101, v100
	global_store_dwordx2 v[2:3], v[96:97], off offset:512
	v_mul_f32_e32 v97, v98, v113
	v_mul_f32_e32 v96, v98, v112
	v_rndne_f32_e32 v97, v97
	v_mul_f32_e32 v99, v98, v114
	v_rndne_f32_e32 v96, v96
	v_cvt_i32_f32_e32 v97, v97
	v_rndne_f32_e32 v99, v99
	v_mul_f32_e32 v100, v98, v115
	v_cvt_i32_f32_e32 v96, v96
	v_cvt_i32_f32_sdwa v99, v99 dst_sel:WORD_1 dst_unused:UNUSED_PAD src0_sel:DWORD
	v_rndne_f32_e32 v100, v100
	v_cvt_i32_f32_sdwa v100, v100 dst_sel:BYTE_3 dst_unused:UNUSED_PAD src0_sel:DWORD
; __device__ __forceinline__ float bflo(unsigned w) { return __uint_as_float(w << 16); }
; __device__ __forceinline__ float bfhi(unsigned w) { return __uint_as_float(w & 0xffff0000u); }
; __device__ __forceinline__ void quant_store8(const u32x4 (&w)[8], float inv, signed char* dst, int lane) { u32x2* qp = (u32x2*)dst + lane;
; #pragma unroll
;     for (int j = 0; j < 8; ++j) { const unsigned ww[4] = {w[j].x, w[j].y, w[j].z, w[j].w}; unsigned o2[2];
; #pragma unroll
;         for (int h2 = 0; h2 < 2; ++h2) { const int q0 = (int)rintf(bflo(ww[2 * h2]) * inv), q1 = (int)rintf(bfhi(ww[2 * h2]) * inv), q2 = (int)rintf(bflo(ww[2 * h2 + 1]) * inv), q3 = (int)rintf(bfhi(ww[2 * h2 + 1]) * inv);
;             o2[h2] = (unsigned)(q0 & 255) | ((unsigned)(q1 & 255) << 8) | ((unsigned)(q2 & 255) << 16) | ((unsigned)(q3 & 255) << 24); }
;         u32x2 o; o.x = o2[0]; o.y = o2[1]; qp[64 * j] = o; } }
	v_lshlrev_b32_e32 v97, 8, v97
	v_and_b32_e32 v99, 0xff0000, v99
	v_perm_b32 v96, v97, v96, s29
	v_or3_b32 v96, v96, v100, v99
	v_mul_f32_e32 v99, v98, v117
	v_mul_f32_e32 v97, v98, v116
	v_rndne_f32_e32 v99, v99
	v_mul_f32_e32 v100, v98, v118
	v_rndne_f32_e32 v97, v97
	v_cvt_i32_f32_e32 v99, v99
	v_rndne_f32_e32 v100, v100
	v_mul_f32_e32 v101, v98, v119
	v_cvt_i32_f32_e32 v97, v97
	v_cvt_i32_f32_sdwa v100, v100 dst_sel:WORD_1 dst_unused:UNUSED_PAD src0_sel:DWORD
	v_rndne_f32_e32 v101, v101
	v_cvt_i32_f32_sdwa v101, v101 dst_sel:BYTE_3 dst_unused:UNUSED_PAD src0_sel:DWORD
	v_lshlrev_b32_e32 v99, 8, v99
	v_and_b32_e32 v100, 0xff0000, v100
	v_perm_b32 v97, v99, v97, s29
	v_or3_b32 v97, v97, v101, v100
	global_store_dwordx2 v[2:3], v[96:97], off offset:1024
	v_mul_f32_e32 v97, v98, v129
	v_mul_f32_e32 v96, v98, v128
	v_rndne_f32_e32 v97, v97
	v_mul_f32_e32 v99, v98, v130
	v_rndne_f32_e32 v96, v96
	v_cvt_i32_f32_e32 v97, v97
	v_rndne_f32_e32 v99, v99
	v_mul_f32_e32 v100, v98, v131
	v_cvt_i32_f32_e32 v96, v96
	v_cvt_i32_f32_sdwa v99, v99 dst_sel:WORD_1 dst_unused:UNUSED_PAD src0_sel:DWORD
	v_rndne_f32_e32 v100, v100
	v_cvt_i32_f32_sdwa v100, v100 dst_sel:BYTE_3 dst_unused:UNUSED_PAD src0_sel:DWORD
	v_lshlrev_b32_e32 v97, 8, v97
	v_and_b32_e32 v99, 0xff0000, v99
	v_perm_b32 v96, v97, v96, s29
	v_or3_b32 v96, v96, v100, v99
	v_mul_f32_e32 v99, v98, v133
	v_mul_f32_e32 v97, v98, v132
	v_rndne_f32_e32 v99, v99
	v_mul_f32_e32 v100, v98, v134
	v_rndne_f32_e32 v97, v97
	v_cvt_i32_f32_e32 v99, v99
	v_rndne_f32_e32 v100, v100
	v_mul_f32_e32 v101, v98, v135
	v_cvt_i32_f32_e32 v97, v97
	v_cvt_i32_f32_sdwa v100, v100 dst_sel:WORD_1 dst_unused:UNUSED_PAD src0_sel:DWORD
	v_rndne_f32_e32 v101, v101
	v_cvt_i32_f32_sdwa v101, v101 dst_sel:BYTE_3 dst_unused:UNUSED_PAD src0_sel:DWORD
	v_lshlrev_b32_e32 v99, 8, v99
	v_and_b32_e32 v100, 0xff0000, v100
	v_perm_b32 v97, v99, v97, s29
	v_or3_b32 v97, v97, v101, v100
	global_store_dwordx2 v[2:3], v[96:97], off offset:1536
	v_mul_f32_e32 v97, v98, v137
	v_mul_f32_e32 v96, v98, v136
	v_rndne_f32_e32 v97, v97
	v_mul_f32_e32 v99, v98, v138
	v_rndne_f32_e32 v96, v96
	v_cvt_i32_f32_e32 v97, v97
	v_rndne_f32_e32 v99, v99
	v_mul_f32_e32 v100, v98, v139
	v_cvt_i32_f32_e32 v96, v96
	v_cvt_i32_f32_sdwa v99, v99 dst_sel:WORD_1 dst_unused:UNUSED_PAD src0_sel:DWORD
	v_rndne_f32_e32 v100, v100
	v_cvt_i32_f32_sdwa v100, v100 dst_sel:BYTE_3 dst_unused:UNUSED_PAD src0_sel:DWORD
	v_lshlrev_b32_e32 v97, 8, v97
	v_and_b32_e32 v99, 0xff0000, v99
	v_perm_b32 v96, v97, v96, s29
	v_or3_b32 v96, v96, v100, v99
	v_mul_f32_e32 v99, v98, v141
	v_mul_f32_e32 v97, v98, v140
	v_rndne_f32_e32 v99, v99
	v_mul_f32_e32 v100, v98, v142
	v_rndne_f32_e32 v97, v97
	v_cvt_i32_f32_e32 v99, v99
	v_rndne_f32_e32 v100, v100
	v_mul_f32_e32 v101, v98, v143
	v_cvt_i32_f32_e32 v97, v97
	v_cvt_i32_f32_sdwa v100, v100 dst_sel:WORD_1 dst_unused:UNUSED_PAD src0_sel:DWORD
	v_rndne_f32_e32 v101, v101
	v_cvt_i32_f32_sdwa v101, v101 dst_sel:BYTE_3 dst_unused:UNUSED_PAD src0_sel:DWORD
	v_lshlrev_b32_e32 v99, 8, v99
	v_and_b32_e32 v100, 0xff0000, v100
	v_perm_b32 v97, v99, v97, s29
	v_or3_b32 v97, v97, v101, v100
	global_store_dwordx2 v[2:3], v[96:97], off offset:2048
	v_mul_f32_e32 v97, v98, v145
	v_mul_f32_e32 v96, v98, v144
	v_rndne_f32_e32 v97, v97
	v_mul_f32_e32 v99, v98, v146
	v_rndne_f32_e32 v96, v96
	v_cvt_i32_f32_e32 v97, v97
	v_rndne_f32_e32 v99, v99
	v_mul_f32_e32 v100, v98, v147
	v_cvt_i32_f32_e32 v96, v96
	v_cvt_i32_f32_sdwa v99, v99 dst_sel:WORD_1 dst_unused:UNUSED_PAD src0_sel:DWORD
	v_rndne_f32_e32 v100, v100
	v_cvt_i32_f32_sdwa v100, v100 dst_sel:BYTE_3 dst_unused:UNUSED_PAD src0_sel:DWORD
	v_lshlrev_b32_e32 v97, 8, v97
	v_and_b32_e32 v99, 0xff0000, v99
	v_perm_b32 v96, v97, v96, s29
	v_or3_b32 v96, v96, v100, v99
	v_mul_f32_e32 v99, v98, v149
	v_mul_f32_e32 v97, v98, v148
	v_rndne_f32_e32 v99, v99
	v_mul_f32_e32 v100, v98, v150
	v_rndne_f32_e32 v97, v97
	v_cvt_i32_f32_e32 v99, v99
	v_rndne_f32_e32 v100, v100
	v_mul_f32_e32 v101, v98, v151
	v_cvt_i32_f32_e32 v97, v97
	v_cvt_i32_f32_sdwa v100, v100 dst_sel:WORD_1 dst_unused:UNUSED_PAD src0_sel:DWORD
	v_rndne_f32_e32 v101, v101
	v_cvt_i32_f32_sdwa v101, v101 dst_sel:BYTE_3 dst_unused:UNUSED_PAD src0_sel:DWORD
	v_lshlrev_b32_e32 v99, 8, v99
	v_and_b32_e32 v100, 0xff0000, v100
	v_perm_b32 v97, v99, v97, s29
	v_or3_b32 v97, v97, v101, v100
	global_store_dwordx2 v[2:3], v[96:97], off offset:2560
	v_mul_f32_e32 v97, v98, v153
	v_mul_f32_e32 v96, v98, v152
	v_rndne_f32_e32 v97, v97
	v_mul_f32_e32 v99, v98, v154
	v_rndne_f32_e32 v96, v96
	v_cvt_i32_f32_e32 v97, v97
	v_rndne_f32_e32 v99, v99
	v_mul_f32_e32 v100, v98, v155
	v_cvt_i32_f32_e32 v96, v96
	v_cvt_i32_f32_sdwa v99, v99 dst_sel:WORD_1 dst_unused:UNUSED_PAD src0_sel:DWORD
	v_rndne_f32_e32 v100, v100
	v_cvt_i32_f32_sdwa v100, v100 dst_sel:BYTE_3 dst_unused:UNUSED_PAD src0_sel:DWORD
	v_lshlrev_b32_e32 v97, 8, v97
	v_and_b32_e32 v99, 0xff0000, v99
	v_perm_b32 v96, v97, v96, s29
	v_or3_b32 v96, v96, v100, v99
	v_mul_f32_e32 v99, v98, v157
	v_mul_f32_e32 v97, v98, v156
	v_rndne_f32_e32 v99, v99
	v_mul_f32_e32 v100, v98, v158
	v_rndne_f32_e32 v97, v97
	v_cvt_i32_f32_e32 v99, v99
	v_rndne_f32_e32 v100, v100
	v_mul_f32_e32 v101, v98, v159
	v_cvt_i32_f32_e32 v97, v97
	v_cvt_i32_f32_sdwa v100, v100 dst_sel:WORD_1 dst_unused:UNUSED_PAD src0_sel:DWORD
	v_rndne_f32_e32 v101, v101
	v_cvt_i32_f32_sdwa v101, v101 dst_sel:BYTE_3 dst_unused:UNUSED_PAD src0_sel:DWORD
	v_lshlrev_b32_e32 v99, 8, v99
	v_and_b32_e32 v100, 0xff0000, v100
	v_perm_b32 v97, v99, v97, s29
	v_or3_b32 v97, v97, v101, v100
	global_store_dwordx2 v[2:3], v[96:97], off offset:3072
	v_mul_f32_e32 v97, v98, v161
; __device__ __forceinline__ float bflo(unsigned w) { return __uint_as_float(w << 16); }
; __device__ __forceinline__ float bfhi(unsigned w) { return __uint_as_float(w & 0xffff0000u); }
; __device__ __forceinline__ void quant_store8(const u32x4 (&w)[8], float inv, signed char* dst, int lane) { u32x2* qp = (u32x2*)dst + lane;
; #pragma unroll
;     for (int j = 0; j < 8; ++j) { const unsigned ww[4] = {w[j].x, w[j].y, w[j].z, w[j].w}; unsigned o2[2];
; #pragma unroll
;         for (int h2 = 0; h2 < 2; ++h2) { const int q0 = (int)rintf(bflo(ww[2 * h2]) * inv), q1 = (int)rintf(bfhi(ww[2 * h2]) * inv), q2 = (int)rintf(bflo(ww[2 * h2 + 1]) * inv), q3 = (int)rintf(bfhi(ww[2 * h2 + 1]) * inv);
;             o2[h2] = (unsigned)(q0 & 255) | ((unsigned)(q1 & 255) << 8) | ((unsigned)(q2 & 255) << 16) | ((unsigned)(q3 & 255) << 24); }
;         u32x2 o; o.x = o2[0]; o.y = o2[1]; qp[64 * j] = o; } }
; __global__ void __launch_bounds__(NWAVES * 64, 2) fwd(Args args) {
;     ...
;             const float rsa = 1.0f / sqrtf(wave_sum(pa) * (1.0f / DM) + EPS), rsb = 1.0f / sqrtf(wave_sum(pb) * (1.0f / DM) + EPS);
	v_mul_f32_e32 v96, v98, v160
	v_rndne_f32_e32 v97, v97
	v_mul_f32_e32 v99, v98, v162
	v_rndne_f32_e32 v96, v96
	v_cvt_i32_f32_e32 v97, v97
	v_rndne_f32_e32 v99, v99
	v_mul_f32_e32 v100, v98, v163
	v_cvt_i32_f32_e32 v96, v96
	v_cvt_i32_f32_sdwa v99, v99 dst_sel:WORD_1 dst_unused:UNUSED_PAD src0_sel:DWORD
	v_rndne_f32_e32 v100, v100
	v_cvt_i32_f32_sdwa v100, v100 dst_sel:BYTE_3 dst_unused:UNUSED_PAD src0_sel:DWORD
	v_lshlrev_b32_e32 v97, 8, v97
	v_and_b32_e32 v99, 0xff0000, v99
	v_perm_b32 v96, v97, v96, s29
	v_or3_b32 v96, v96, v100, v99
	v_mul_f32_e32 v99, v98, v165
	v_mul_f32_e32 v100, v98, v166
	v_rndne_f32_e32 v99, v99
	v_rndne_f32_e32 v100, v100
	v_cvt_i32_f32_e32 v99, v99
	v_cvt_i32_f32_sdwa v100, v100 dst_sel:WORD_1 dst_unused:UNUSED_PAD src0_sel:DWORD
	v_mul_f32_e32 v97, v98, v164
	v_rndne_f32_e32 v97, v97
	v_mul_f32_e32 v93, v98, v93
	v_cvt_i32_f32_e32 v97, v97
	v_rndne_f32_e32 v93, v93
	v_cvt_i32_f32_sdwa v93, v93 dst_sel:BYTE_3 dst_unused:UNUSED_PAD src0_sel:DWORD
	v_lshlrev_b32_e32 v98, 8, v99
	v_and_b32_e32 v99, 0xff0000, v100
	v_div_scale_f32 v100, s[26:27], v5, v5, 1.0
	v_rcp_f32_e32 v101, v100
	v_perm_b32 v97, v98, v97, s29
	v_or3_b32 v97, v97, v93, v99
	global_store_dwordx2 v[2:3], v[96:97], off offset:3584
	v_fma_f32 v2, -v100, v101, 1.0
	v_fmac_f32_e32 v101, v2, v101
	v_div_scale_f32 v2, vcc, 1.0, v5, 1.0
	v_mul_f32_e32 v3, v2, v101
	v_fma_f32 v93, -v100, v3, v2
	v_fmac_f32_e32 v3, v93, v101
	v_fma_f32 v2, -v100, v3, v2
	v_div_fmas_f32 v2, v2, v101, v3
	v_div_fixup_f32 v96, v2, v5, 1.0
	v_mul_f32_e32 v12, v96, v12
	v_mul_f32_e32 v30, v96, v30
	v_rndne_f32_e32 v12, v12
	v_mul_f32_e32 v29, v96, v29
	v_rndne_f32_e32 v30, v30
	v_cvt_i32_f32_e32 v12, v12
	v_rndne_f32_e32 v29, v29
	v_mul_f32_e32 v10, v96, v10
	v_cvt_i32_f32_e32 v30, v30
	v_cvt_i32_f32_sdwa v29, v29 dst_sel:WORD_1 dst_unused:UNUSED_PAD src0_sel:DWORD
	v_rndne_f32_e32 v10, v10
	v_cvt_i32_f32_sdwa v10, v10 dst_sel:BYTE_3 dst_unused:UNUSED_PAD src0_sel:DWORD
	v_lshlrev_b32_e32 v12, 8, v12
	v_mul_f32_e32 v9, v96, v9
	v_and_b32_e32 v29, 0xff0000, v29
	v_perm_b32 v12, v12, v30, s29
	v_rndne_f32_e32 v9, v9
	v_or3_b32 v10, v12, v10, v29
	s_waitcnt vmcnt(9)
	s_nop 1
	v_mov_b32_dpp v12, v13 quad_perm:[1,0,3,2] row_mask:0xf bank_mask:0xf
	v_cvt_i32_f32_e32 v29, v9
	s_waitcnt vmcnt(8)
	s_nop 1
	v_mov_b32_dpp v9, v11 quad_perm:[1,0,3,2] row_mask:0xf bank_mask:0xf
	v_mul_f32_e32 v7, v96, v7
	v_rndne_f32_e32 v7, v7
	s_waitcnt lgkmcnt(0)
	v_add_f32_e32 v12, v13, v12
	s_nop 1
	v_mov_b32_dpp v13, v12 quad_perm:[2,3,0,1] row_mask:0xf bank_mask:0xf
	s_waitcnt lgkmcnt(0)
	v_add_f32_e32 v9, v11, v9
	s_nop 1
	v_mov_b32_dpp v11, v9 quad_perm:[2,3,0,1] row_mask:0xf bank_mask:0xf
	v_cvt_i32_f32_sdwa v30, v7 dst_sel:WORD_1 dst_unused:UNUSED_PAD src0_sel:DWORD
	v_mul_f32_e32 v44, v96, v44
	s_waitcnt lgkmcnt(0)
	v_add_f32_e32 v12, v12, v13
	s_nop 1
	v_mov_b32_dpp v13, v12 row_half_mirror row_mask:0xf bank_mask:0xf
	s_waitcnt lgkmcnt(0)
	v_add_f32_e32 v9, v9, v11
	s_nop 1
	v_mov_b32_dpp v11, v9 row_half_mirror row_mask:0xf bank_mask:0xf
	v_mul_f32_e32 v33, v96, v33
	v_mul_f32_e32 v46, v96, v46
	s_waitcnt lgkmcnt(0)
	v_add_f32_e32 v7, v12, v13
	s_nop 1
	v_mov_b32_dpp v12, v7 row_mirror row_mask:0xf bank_mask:0xf
	s_waitcnt lgkmcnt(0)
	v_add_f32_e32 v9, v9, v11
	s_nop 1
	v_mov_b32_dpp v11, v9 row_mirror row_mask:0xf bank_mask:0xf
	v_rndne_f32_e32 v44, v44
	v_mul_f32_e32 v45, v96, v45
	v_mul_f32_e32 v42, v96, v42
	v_rndne_f32_e32 v33, v33
	v_mul_f32_e32 v32, v96, v32
	v_rndne_f32_e32 v46, v46
	v_cvt_i32_f32_e32 v44, v44
	v_rndne_f32_e32 v45, v45
	v_mul_f32_e32 v43, v96, v43
	v_rndne_f32_e32 v42, v42
	v_cvt_i32_f32_e32 v33, v33
	v_rndne_f32_e32 v32, v32
	v_mul_f32_e32 v31, v96, v31
	v_mul_f32_e32 v8, v96, v8
	s_waitcnt lgkmcnt(0)
	v_add_f32_e32 v7, v7, v12
	s_waitcnt lgkmcnt(0)
	v_add_f32_e32 v9, v9, v11
	v_cvt_i32_f32_e32 v46, v46
	v_cvt_i32_f32_sdwa v45, v45 dst_sel:WORD_1 dst_unused:UNUSED_PAD src0_sel:DWORD
	v_rndne_f32_e32 v43, v43
	v_cvt_i32_f32_e32 v42, v42
	v_cvt_i32_f32_sdwa v32, v32 dst_sel:WORD_1 dst_unused:UNUSED_PAD src0_sel:DWORD
	v_rndne_f32_e32 v31, v31
	v_rndne_f32_e32 v8, v8
	ds_bpermute_b32 v12, v26, v7
	ds_bpermute_b32 v11, v26, v9
	v_cvt_i32_f32_sdwa v43, v43 dst_sel:BYTE_3 dst_unused:UNUSED_PAD src0_sel:DWORD
	v_cvt_i32_f32_sdwa v31, v31 dst_sel:BYTE_3 dst_unused:UNUSED_PAD src0_sel:DWORD
	v_cvt_i32_f32_e32 v8, v8
	v_mul_f32_e32 v92, v96, v92
	v_mul_f32_e32 v89, v96, v89
	v_mul_f32_e32 v84, v96, v84
	v_mul_f32_e32 v81, v96, v81
	v_mul_f32_e32 v76, v96, v76
	v_mul_f32_e32 v73, v96, v73
	v_mul_f32_e32 v68, v96, v68
	v_mul_f32_e32 v65, v96, v65
	v_mul_f32_e32 v60, v96, v60
	v_mul_f32_e32 v57, v96, v57
	v_mul_f32_e32 v52, v96, v52
	v_mul_f32_e32 v49, v96, v49
	v_mul_f32_e32 v93, v96, v95
	v_rndne_f32_e32 v92, v92
	v_mul_f32_e32 v94, v96, v94
	v_mul_f32_e32 v90, v96, v90
	v_rndne_f32_e32 v89, v89
	v_mul_f32_e32 v88, v96, v88
	v_mul_f32_e32 v86, v96, v86
	v_rndne_f32_e32 v84, v84
	v_mul_f32_e32 v85, v96, v85
	v_mul_f32_e32 v82, v96, v82
	v_rndne_f32_e32 v81, v81
	v_mul_f32_e32 v80, v96, v80
	v_mul_f32_e32 v78, v96, v78
	v_rndne_f32_e32 v76, v76
	v_mul_f32_e32 v77, v96, v77
	v_mul_f32_e32 v74, v96, v74
	v_rndne_f32_e32 v73, v73
	v_mul_f32_e32 v72, v96, v72
	v_mul_f32_e32 v70, v96, v70
	v_rndne_f32_e32 v68, v68
	v_mul_f32_e32 v69, v96, v69
	v_mul_f32_e32 v66, v96, v66
	v_rndne_f32_e32 v65, v65
	v_mul_f32_e32 v64, v96, v64
	v_mul_f32_e32 v62, v96, v62
	v_rndne_f32_e32 v60, v60
	v_mul_f32_e32 v61, v96, v61
	v_mul_f32_e32 v58, v96, v58
	v_rndne_f32_e32 v57, v57
	v_mul_f32_e32 v56, v96, v56
	v_mul_f32_e32 v54, v96, v54
	v_rndne_f32_e32 v52, v52
	v_mul_f32_e32 v53, v96, v53
; __device__ __forceinline__ float bflo(unsigned w) { return __uint_as_float(w << 16); }
; __device__ __forceinline__ float bfhi(unsigned w) { return __uint_as_float(w & 0xffff0000u); }
; __device__ __forceinline__ void quant_store8(const u32x4 (&w)[8], float inv, signed char* dst, int lane) { u32x2* qp = (u32x2*)dst + lane;
; #pragma unroll
;     for (int j = 0; j < 8; ++j) { const unsigned ww[4] = {w[j].x, w[j].y, w[j].z, w[j].w}; unsigned o2[2];
; #pragma unroll
;         for (int h2 = 0; h2 < 2; ++h2) { const int q0 = (int)rintf(bflo(ww[2 * h2]) * inv), q1 = (int)rintf(bfhi(ww[2 * h2]) * inv), q2 = (int)rintf(bflo(ww[2 * h2 + 1]) * inv), q3 = (int)rintf(bfhi(ww[2 * h2 + 1]) * inv);
;             o2[h2] = (unsigned)(q0 & 255) | ((unsigned)(q1 & 255) << 8) | ((unsigned)(q2 & 255) << 16) | ((unsigned)(q3 & 255) << 24); }
;         u32x2 o; o.x = o2[0]; o.y = o2[1]; qp[64 * j] = o; } }
; __global__ void __launch_bounds__(NWAVES * 64, 2) fwd(Args args) {
;     ...
;             const float rsa = 1.0f / sqrtf(wave_sum(pa) * (1.0f / DM) + EPS), rsb = 1.0f / sqrtf(wave_sum(pb) * (1.0f / DM) + EPS);
	v_mul_f32_e32 v50, v96, v50
	v_rndne_f32_e32 v49, v49
	v_mul_f32_e32 v48, v96, v48
	v_lshlrev_b32_e32 v44, 8, v44
	v_lshlrev_b32_e32 v33, 8, v33
	v_mul_f32_e32 v6, v96, v6
	v_rndne_f32_e32 v93, v93
	v_cvt_i32_f32_e32 v92, v92
	v_rndne_f32_e32 v94, v94
	v_mul_f32_e32 v91, v96, v91
	v_rndne_f32_e32 v90, v90
	v_cvt_i32_f32_e32 v89, v89
	v_rndne_f32_e32 v88, v88
	v_mul_f32_e32 v87, v96, v87
	v_rndne_f32_e32 v86, v86
	v_cvt_i32_f32_e32 v84, v84
	v_rndne_f32_e32 v85, v85
	v_mul_f32_e32 v83, v96, v83
	v_rndne_f32_e32 v82, v82
	v_cvt_i32_f32_e32 v81, v81
	v_rndne_f32_e32 v80, v80
	v_mul_f32_e32 v79, v96, v79
	v_rndne_f32_e32 v78, v78
	v_cvt_i32_f32_e32 v76, v76
	v_rndne_f32_e32 v77, v77
	v_mul_f32_e32 v75, v96, v75
	v_rndne_f32_e32 v74, v74
	v_cvt_i32_f32_e32 v73, v73
	v_rndne_f32_e32 v72, v72
	v_mul_f32_e32 v71, v96, v71
	v_rndne_f32_e32 v70, v70
	v_cvt_i32_f32_e32 v68, v68
	v_rndne_f32_e32 v69, v69
	v_mul_f32_e32 v67, v96, v67
	v_rndne_f32_e32 v66, v66
	v_cvt_i32_f32_e32 v65, v65
	v_rndne_f32_e32 v64, v64
	v_mul_f32_e32 v63, v96, v63
	v_rndne_f32_e32 v62, v62
	v_cvt_i32_f32_e32 v60, v60
	v_rndne_f32_e32 v61, v61
	v_mul_f32_e32 v59, v96, v59
	v_rndne_f32_e32 v58, v58
	v_cvt_i32_f32_e32 v57, v57
	v_rndne_f32_e32 v56, v56
	v_mul_f32_e32 v55, v96, v55
	v_rndne_f32_e32 v54, v54
	v_cvt_i32_f32_e32 v52, v52
	v_rndne_f32_e32 v53, v53
	v_mul_f32_e32 v51, v96, v51
	v_rndne_f32_e32 v50, v50
	v_cvt_i32_f32_e32 v49, v49
	v_rndne_f32_e32 v48, v48
	v_mul_f32_e32 v47, v96, v47
	v_and_b32_e32 v45, 0xff0000, v45
	v_perm_b32 v44, v44, v46, s29
	v_and_b32_e32 v32, 0xff0000, v32
	v_perm_b32 v33, v33, v42, s29
	v_rndne_f32_e32 v6, v6
	v_cvt_i32_f32_e32 v93, v93
	v_cvt_i32_f32_sdwa v94, v94 dst_sel:WORD_1 dst_unused:UNUSED_PAD src0_sel:DWORD
	v_rndne_f32_e32 v91, v91
	v_cvt_i32_f32_e32 v90, v90
	v_cvt_i32_f32_sdwa v88, v88 dst_sel:WORD_1 dst_unused:UNUSED_PAD src0_sel:DWORD
	v_rndne_f32_e32 v87, v87
	v_cvt_i32_f32_e32 v86, v86
	v_cvt_i32_f32_sdwa v85, v85 dst_sel:WORD_1 dst_unused:UNUSED_PAD src0_sel:DWORD
	v_rndne_f32_e32 v83, v83
	v_cvt_i32_f32_e32 v82, v82
	v_cvt_i32_f32_sdwa v80, v80 dst_sel:WORD_1 dst_unused:UNUSED_PAD src0_sel:DWORD
	v_rndne_f32_e32 v79, v79
	v_cvt_i32_f32_e32 v78, v78
	v_cvt_i32_f32_sdwa v77, v77 dst_sel:WORD_1 dst_unused:UNUSED_PAD src0_sel:DWORD
	v_rndne_f32_e32 v75, v75
	v_cvt_i32_f32_e32 v74, v74
	v_cvt_i32_f32_sdwa v72, v72 dst_sel:WORD_1 dst_unused:UNUSED_PAD src0_sel:DWORD
	v_rndne_f32_e32 v71, v71
	v_cvt_i32_f32_e32 v70, v70
	v_cvt_i32_f32_sdwa v69, v69 dst_sel:WORD_1 dst_unused:UNUSED_PAD src0_sel:DWORD
	v_rndne_f32_e32 v67, v67
	v_cvt_i32_f32_e32 v66, v66
	v_cvt_i32_f32_sdwa v64, v64 dst_sel:WORD_1 dst_unused:UNUSED_PAD src0_sel:DWORD
	v_rndne_f32_e32 v63, v63
	v_cvt_i32_f32_e32 v62, v62
	v_cvt_i32_f32_sdwa v61, v61 dst_sel:WORD_1 dst_unused:UNUSED_PAD src0_sel:DWORD
	v_rndne_f32_e32 v59, v59
	v_cvt_i32_f32_e32 v58, v58
	v_cvt_i32_f32_sdwa v56, v56 dst_sel:WORD_1 dst_unused:UNUSED_PAD src0_sel:DWORD
	v_rndne_f32_e32 v55, v55
	v_cvt_i32_f32_e32 v54, v54
	v_cvt_i32_f32_sdwa v53, v53 dst_sel:WORD_1 dst_unused:UNUSED_PAD src0_sel:DWORD
	v_rndne_f32_e32 v51, v51
	v_cvt_i32_f32_e32 v50, v50
	v_cvt_i32_f32_sdwa v48, v48 dst_sel:WORD_1 dst_unused:UNUSED_PAD src0_sel:DWORD
	v_rndne_f32_e32 v47, v47
	v_or3_b32 v44, v44, v43, v45
	v_or3_b32 v45, v33, v31, v32
	v_cvt_i32_f32_sdwa v13, v6 dst_sel:BYTE_3 dst_unused:UNUSED_PAD src0_sel:DWORD
	v_lshlrev_b32_e32 v31, 8, v8
	s_waitcnt lgkmcnt(1)
	v_add_f32_e32 v6, v7, v12
	s_waitcnt lgkmcnt(0)
	v_add_f32_e32 v8, v9, v11
	v_cvt_i32_f32_sdwa v91, v91 dst_sel:BYTE_3 dst_unused:UNUSED_PAD src0_sel:DWORD
	v_cvt_i32_f32_sdwa v87, v87 dst_sel:BYTE_3 dst_unused:UNUSED_PAD src0_sel:DWORD
	v_cvt_i32_f32_sdwa v83, v83 dst_sel:BYTE_3 dst_unused:UNUSED_PAD src0_sel:DWORD
	v_cvt_i32_f32_sdwa v79, v79 dst_sel:BYTE_3 dst_unused:UNUSED_PAD src0_sel:DWORD
	v_cvt_i32_f32_sdwa v75, v75 dst_sel:BYTE_3 dst_unused:UNUSED_PAD src0_sel:DWORD
	v_cvt_i32_f32_sdwa v71, v71 dst_sel:BYTE_3 dst_unused:UNUSED_PAD src0_sel:DWORD
	v_cvt_i32_f32_sdwa v67, v67 dst_sel:BYTE_3 dst_unused:UNUSED_PAD src0_sel:DWORD
	v_cvt_i32_f32_sdwa v63, v63 dst_sel:BYTE_3 dst_unused:UNUSED_PAD src0_sel:DWORD
	v_cvt_i32_f32_sdwa v59, v59 dst_sel:BYTE_3 dst_unused:UNUSED_PAD src0_sel:DWORD
	v_cvt_i32_f32_sdwa v55, v55 dst_sel:BYTE_3 dst_unused:UNUSED_PAD src0_sel:DWORD
	v_cvt_i32_f32_sdwa v51, v51 dst_sel:BYTE_3 dst_unused:UNUSED_PAD src0_sel:DWORD
	v_cvt_i32_f32_sdwa v47, v47 dst_sel:BYTE_3 dst_unused:UNUSED_PAD src0_sel:DWORD
	ds_bpermute_b32 v7, v27, v6
	ds_bpermute_b32 v9, v27, v8
	v_lshlrev_b32_e32 v92, 8, v92
	v_lshlrev_b32_e32 v89, 8, v89
	v_lshlrev_b32_e32 v84, 8, v84
	v_lshlrev_b32_e32 v81, 8, v81
	v_lshlrev_b32_e32 v76, 8, v76
	v_lshlrev_b32_e32 v73, 8, v73
	v_lshlrev_b32_e32 v68, 8, v68
	v_lshlrev_b32_e32 v65, 8, v65
	v_lshlrev_b32_e32 v60, 8, v60
	v_lshlrev_b32_e32 v57, 8, v57
	v_lshlrev_b32_e32 v52, 8, v52
	v_lshlrev_b32_e32 v49, 8, v49
	v_and_b32_e32 v94, 0xff0000, v94
	v_perm_b32 v92, v92, v93, s29
	v_and_b32_e32 v88, 0xff0000, v88
	v_perm_b32 v89, v89, v90, s29
	v_and_b32_e32 v85, 0xff0000, v85
	v_perm_b32 v84, v84, v86, s29
	v_and_b32_e32 v80, 0xff0000, v80
	v_perm_b32 v81, v81, v82, s29
	v_and_b32_e32 v77, 0xff0000, v77
	v_perm_b32 v76, v76, v78, s29
	v_and_b32_e32 v72, 0xff0000, v72
	v_perm_b32 v73, v73, v74, s29
	v_and_b32_e32 v69, 0xff0000, v69
	v_perm_b32 v68, v68, v70, s29
	v_and_b32_e32 v64, 0xff0000, v64
	v_perm_b32 v65, v65, v66, s29
	v_and_b32_e32 v61, 0xff0000, v61
	v_perm_b32 v60, v60, v62, s29
	v_and_b32_e32 v56, 0xff0000, v56
	v_perm_b32 v57, v57, v58, s29
	v_and_b32_e32 v53, 0xff0000, v53
	v_perm_b32 v52, v52, v54, s29
	v_and_b32_e32 v48, 0xff0000, v48
	v_perm_b32 v49, v49, v50, s29
	v_and_b32_e32 v11, 0xff0000, v30
	v_perm_b32 v12, v31, v29, s29
	v_lshl_add_u64 v[2:3], v[20:21], 0, s[6:7]
	v_or3_b32 v92, v92, v91, v94
	v_or3_b32 v93, v89, v87, v88
	v_or3_b32 v84, v84, v83, v85
	v_or3_b32 v85, v81, v79, v80
	v_or3_b32 v76, v76, v75, v77
	v_or3_b32 v77, v73, v71, v72
	v_or3_b32 v68, v68, v67, v69
	v_or3_b32 v69, v65, v63, v64
	v_or3_b32 v60, v60, v59, v61
	v_or3_b32 v61, v57, v55, v56
	v_or3_b32 v52, v52, v51, v53
	v_or3_b32 v53, v49, v47, v48
	v_or3_b32 v11, v12, v13, v11
	global_store_dwordx2 v[2:3], v[92:93], off
	global_store_dwordx2 v[2:3], v[84:85], off offset:512
	global_store_dwordx2 v[2:3], v[76:77], off offset:1024
	global_store_dwordx2 v[2:3], v[68:69], off offset:1536
	global_store_dwordx2 v[2:3], v[60:61], off offset:2048
	global_store_dwordx2 v[2:3], v[52:53], off offset:2560
	global_store_dwordx2 v[2:3], v[44:45], off offset:3072
	global_store_dwordx2 v[2:3], v[10:11], off offset:3584
	s_and_saveexec_b64 s[26:27], s[4:5]
	s_cbranch_execz .LBB0_1391
; __global__ void __launch_bounds__(NWAVES * 64, 2) fwd(Args args) {
;     ...
;             const float rsa = 1.0f / sqrtf(wave_sum(pa) * (1.0f / DM) + EPS), rsb = 1.0f / sqrtf(wave_sum(pb) * (1.0f / DM) + EPS);
;             if (F.lane == 0) { rowq2[row] = rsa * st0; rowq2[row2] = rsb * st1; }
	s_waitcnt lgkmcnt(0)
	v_add_f32_e32 v2, v8, v9
	v_fmamk_f32 v2, v2, 0x39800000, v14
	v_mul_f32_e32 v3, 0x4f800000, v2
	v_cmp_gt_f32_e32 vcc, s30, v2
	v_add_f32_e32 v6, v6, v7
	v_fmamk_f32 v6, v6, 0x39800000, v14
	v_cndmask_b32_e32 v2, v2, v3, vcc
	v_sqrt_f32_e32 v3, v2
	v_mul_f32_e32 v7, 0x4f800000, v6
	v_add_u32_e32 v8, -1, v3
	v_fma_f32 v10, -v8, v3, v2
	v_add_u32_e32 v9, 1, v3
	v_cmp_ge_f32_e64 s[6:7], 0, v10
	s_nop 1
	v_cndmask_b32_e64 v8, v3, v8, s[6:7]
	v_fma_f32 v3, -v9, v3, v2
	v_cmp_lt_f32_e64 s[6:7], 0, v3
	s_nop 1
	v_cndmask_b32_e64 v3, v8, v9, s[6:7]
	v_cmp_gt_f32_e64 s[6:7], s30, v6
	v_mul_f32_e32 v8, 0x37800000, v3
	v_cndmask_b32_e32 v3, v3, v8, vcc
	v_cndmask_b32_e64 v6, v6, v7, s[6:7]
	v_sqrt_f32_e32 v7, v6
	v_cmp_class_f32_e32 vcc, v2, v28
	s_nop 1
	v_cndmask_b32_e32 v2, v3, v2, vcc
	v_add_u32_e32 v3, -1, v7
	v_fma_f32 v8, -v3, v7, v6
	v_cmp_ge_f32_e32 vcc, 0, v8
	v_add_u32_e32 v8, 1, v7
	s_nop 0
	v_cndmask_b32_e32 v3, v7, v3, vcc
	v_fma_f32 v7, -v8, v7, v6
	v_cmp_lt_f32_e32 vcc, 0, v7
	s_nop 1
	v_cndmask_b32_e32 v3, v3, v8, vcc
	v_div_scale_f32 v8, s[34:35], v2, v2, 1.0
	v_rcp_f32_e32 v9, v8
	v_mul_f32_e32 v7, 0x37800000, v3
	v_cndmask_b32_e64 v3, v3, v7, s[6:7]
	v_cmp_class_f32_e32 vcc, v6, v28
	s_nop 1
	v_cndmask_b32_e32 v3, v3, v6, vcc
	v_fma_f32 v6, -v8, v9, 1.0
	v_fmac_f32_e32 v9, v6, v9
	v_div_scale_f32 v6, vcc, 1.0, v2, 1.0
	v_mul_f32_e32 v7, v6, v9
	v_fma_f32 v10, -v8, v7, v6
	v_fmac_f32_e32 v7, v10, v9
	v_fma_f32 v6, -v8, v7, v6
	v_div_scale_f32 v8, s[6:7], v3, v3, 1.0
	v_rcp_f32_e32 v10, v8
	v_div_fmas_f32 v6, v6, v9, v7
	v_div_fixup_f32 v2, v6, v2, 1.0
	s_lshl_b64 s[6:7], s[22:23], 2
	v_fma_f32 v6, -v8, v10, 1.0
	v_fmac_f32_e32 v10, v6, v10
	v_div_scale_f32 v6, vcc, 1.0, v3, 1.0
	v_mul_f32_e32 v7, v6, v10
	v_fma_f32 v9, -v8, v7, v6
	v_fmac_f32_e32 v7, v9, v10
	v_fma_f32 v6, -v8, v7, v6
	v_div_fmas_f32 v6, v6, v10, v7
	v_div_fixup_f32 v3, v6, v3, 1.0
	s_add_u32 s6, s8, s6
	v_mul_f32_e32 v3, v4, v3
	s_addc_u32 s7, s9, s7
	global_store_dword v15, v3, s[6:7]
	s_add_u32 s6, s6, s20
	v_mul_f32_e32 v2, v5, v2
	s_addc_u32 s7, s7, s21
	global_store_dword v15, v2, s[6:7]
	s_branch .LBB0_1391

; __device__ __forceinline__ float bflo(unsigned w) { return __uint_as_float(w << 16); }
; __device__ __forceinline__ float bfhi(unsigned w) { return __uint_as_float(w & 0xffff0000u); }
; template <bool CENTER>
; __device__ __forceinline__ void rot_finish(const u32x4 (&w)[8], signed char* dst, LAS float* red, int tl, int half, int wv4, int lane, float& step_out, float& sum_out) {
;     f32x2 pr[32];
; #pragma unroll
;     for (int j = 0; j < 8; ++j) { pr[4 * j] = (f32x2){bflo(w[j].x), bfhi(w[j].x)}; pr[4 * j + 1] = (f32x2){bflo(w[j].y), bfhi(w[j].y)}; pr[4 * j + 2] = (f32x2){bflo(w[j].z), bfhi(w[j].z)}; pr[4 * j + 3] = (f32x2){bflo(w[j].w), bfhi(w[j].w)}; }
; #pragma unroll
;     for (int i = 0; i < 32; ++i) { const float a = pr[i][0], b = pr[i][1]; pr[i] = (f32x2){a + b, a - b}; }
; #pragma unroll
;     for (int h = 1; h < 32; h <<= 1)
; #pragma unroll
;         for (int i = 0; i < 32; ++i) if (!(i & h)) { const f32x2 a = pr[i], b = pr[i + h]; pr[i] = a + b; pr[i + h] = a - b; }
;     float sm = pr[0][0];
; #pragma unroll
;     for (int o = 1; o < 64; o <<= 1) sm += __shfl_xor(sm, o);
; template <bool CENTER, class Fin>
; __device__ __forceinline__ void rot_rows(const bf16_t* src, size_t src_ld, signed char* dst, int row0, int n, LAS float* red, int tl, int half, int wv4, int lane, Fin fin) {
;     ...
;     rot_load(wa, src + (size_t)(row0 + half) * src_ld, tl);
;     for (int it = 0; it < n; it += 2) {
;         const int ra = row0 + 2 * it + half, rb = ra + 2;
;         rot_load(wb, src + (size_t)rb * src_ld, tl);
;         rot_finish<CENTER>(wa, dst + (size_t)ra * RQ_LD, red, tl, half, wv4, lane, st, sm); if (tl == 0) fin(ra, st, sm);
;         if (it + 2 < n) rot_load(wa, src + (size_t)(rb + 2) * src_ld, tl);
;         rot_finish<CENTER>(wb, dst + (size_t)rb * RQ_LD, red, tl, half, wv4, lane, st, sm); if (tl == 0) fin(rb, st, sm);
.LBB0_1542:
	s_add_i32 s22, s8, 2
	v_mad_i64_i32 v[34:35], s[24:25], s22, v66, v[68:69]
	v_add_co_u32_e32 v36, vcc, s3, v34
	s_waitcnt vmcnt(1)
	v_lshlrev_b32_e32 v73, 16, v16
	v_addc_co_u32_e32 v37, vcc, 0, v35, vcc
	global_load_dwordx4 v[62:65], v[36:37], off offset:-4096 nt
	global_load_dwordx4 v[58:61], v[36:37], off nt
	v_add_co_u32_e32 v36, vcc, s28, v34
	v_and_b32_e32 v74, 0xffff0000, v16
	s_nop 0
	v_addc_co_u32_e32 v37, vcc, 0, v35, vcc
	global_load_dwordx4 v[54:57], v[36:37], off offset:-4096 nt
	global_load_dwordx4 v[50:53], v[36:37], off nt
	v_add_co_u32_e32 v36, vcc, s29, v34
	v_lshlrev_b32_e32 v75, 16, v17
	s_nop 0
	v_addc_co_u32_e32 v37, vcc, 0, v35, vcc
	v_add_co_u32_e32 v38, vcc, s30, v34
	global_load_dwordx4 v[46:49], v[36:37], off offset:-4096 nt
	global_load_dwordx4 v[42:45], v[36:37], off nt
	v_addc_co_u32_e32 v39, vcc, 0, v35, vcc
	global_load_dwordx4 v[34:37], v[34:35], off nt
	s_nop 0
	global_load_dwordx4 v[38:41], v[38:39], off nt
	v_and_b32_e32 v76, 0xffff0000, v17
	v_lshlrev_b32_e32 v77, 16, v2
	v_and_b32_e32 v78, 0xffff0000, v2
	v_lshlrev_b32_e32 v79, 16, v3
	v_and_b32_e32 v80, 0xffff0000, v3
	v_lshlrev_b32_e32 v81, 16, v4
	v_and_b32_e32 v82, 0xffff0000, v4
	v_lshlrev_b32_e32 v83, 16, v5
	v_and_b32_e32 v84, 0xffff0000, v5
	v_lshlrev_b32_e32 v85, 16, v6
	v_and_b32_e32 v86, 0xffff0000, v6
	v_lshlrev_b32_e32 v87, 16, v7
	v_and_b32_e32 v88, 0xffff0000, v7
	v_lshlrev_b32_e32 v89, 16, v8
	v_and_b32_e32 v90, 0xffff0000, v8
	v_lshlrev_b32_e32 v91, 16, v9
	v_and_b32_e32 v92, 0xffff0000, v9
	v_lshlrev_b32_e32 v93, 16, v10
	v_and_b32_e32 v94, 0xffff0000, v10
	v_lshlrev_b32_e32 v95, 16, v11
	v_and_b32_e32 v96, 0xffff0000, v11
	v_lshlrev_b32_e32 v97, 16, v12
	v_and_b32_e32 v98, 0xffff0000, v12
	v_lshlrev_b32_e32 v99, 16, v13
	v_and_b32_e32 v100, 0xffff0000, v13
	v_lshlrev_b32_e32 v101, 16, v18
	v_and_b32_e32 v102, 0xffff0000, v18
	v_lshlrev_b32_e32 v103, 16, v19
	v_and_b32_e32 v104, 0xffff0000, v19
	v_lshlrev_b32_e32 v105, 16, v20
	v_and_b32_e32 v107, 0xffff0000, v20
	v_add_f32_e32 v72, v73, v74
	v_sub_f32_e32 v73, v73, v74
	v_add_f32_e32 v74, v75, v76
	v_sub_f32_e32 v75, v75, v76
	v_add_f32_e32 v76, v77, v78
	v_sub_f32_e32 v77, v77, v78
	v_add_f32_e32 v78, v79, v80
	v_sub_f32_e32 v79, v79, v80
	v_add_f32_e32 v80, v81, v82
	v_sub_f32_e32 v81, v81, v82
	v_add_f32_e32 v82, v83, v84
	v_sub_f32_e32 v83, v83, v84
	v_add_f32_e32 v84, v85, v86
	v_sub_f32_e32 v85, v85, v86
	v_add_f32_e32 v86, v87, v88
	v_sub_f32_e32 v87, v87, v88
	v_add_f32_e32 v88, v89, v90
	v_sub_f32_e32 v89, v89, v90
	v_add_f32_e32 v90, v91, v92
	v_sub_f32_e32 v91, v91, v92
	v_add_f32_e32 v92, v93, v94
	v_sub_f32_e32 v93, v93, v94
	v_add_f32_e32 v94, v95, v96
	v_sub_f32_e32 v95, v95, v96
	v_add_f32_e32 v96, v97, v98
	v_sub_f32_e32 v97, v97, v98
	v_add_f32_e32 v98, v99, v100
	v_sub_f32_e32 v99, v99, v100
	v_add_f32_e32 v100, v101, v102
	v_sub_f32_e32 v101, v101, v102
	v_add_f32_e32 v102, v103, v104
	v_sub_f32_e32 v103, v103, v104
	v_add_f32_e32 v106, v105, v107
	v_sub_f32_e32 v107, v105, v107
	v_lshlrev_b32_e32 v104, 16, v15
	v_and_b32_e32 v105, 0xffff0000, v15
	v_lshlrev_b32_e32 v109, 16, v21
	v_and_b32_e32 v110, 0xffff0000, v21
	v_lshlrev_b32_e32 v111, 16, v22
	v_and_b32_e32 v113, 0xffff0000, v22
	v_lshlrev_b32_e32 v114, 16, v23
	v_and_b32_e32 v115, 0xffff0000, v23
	v_lshlrev_b32_e32 v119, 16, v24
	v_and_b32_e32 v120, 0xffff0000, v24
	v_lshlrev_b32_e32 v121, 16, v25
	v_and_b32_e32 v122, 0xffff0000, v25
	v_lshlrev_b32_e32 v123, 16, v26
	v_and_b32_e32 v124, 0xffff0000, v26
	v_lshlrev_b32_e32 v125, 16, v27
	v_and_b32_e32 v129, 0xffff0000, v27
	v_lshlrev_b32_e32 v131, 16, v28
	v_and_b32_e32 v132, 0xffff0000, v28
	v_lshlrev_b32_e32 v133, 16, v29
	v_and_b32_e32 v134, 0xffff0000, v29
	s_waitcnt vmcnt(8)
	v_lshlrev_b32_e32 v135, 16, v30
	v_and_b32_e32 v136, 0xffff0000, v30
	v_lshlrev_b32_e32 v137, 16, v31
	v_and_b32_e32 v140, 0xffff0000, v31
	v_lshlrev_b32_e32 v141, 16, v32
	v_and_b32_e32 v142, 0xffff0000, v32
	v_lshlrev_b32_e32 v143, 16, v33
	v_and_b32_e32 v148, 0xffff0000, v33
	v_add_f32_e32 v196, v104, v105
	v_sub_f32_e32 v197, v104, v105
	v_lshlrev_b32_e32 v104, 16, v14
	v_and_b32_e32 v105, 0xffff0000, v14
	v_add_f32_e32 v108, v109, v110
	v_sub_f32_e32 v109, v109, v110
	v_add_f32_e32 v112, v111, v113
	v_sub_f32_e32 v113, v111, v113
	v_add_f32_e32 v116, v114, v115
	v_sub_f32_e32 v117, v114, v115
	v_add_f32_e32 v118, v119, v120
	v_sub_f32_e32 v119, v119, v120
	v_add_f32_e32 v120, v121, v122
	v_sub_f32_e32 v121, v121, v122
	v_add_f32_e32 v126, v123, v124
	v_sub_f32_e32 v127, v123, v124
	v_add_f32_e32 v128, v125, v129
	v_sub_f32_e32 v129, v125, v129
	v_add_f32_e32 v130, v131, v132
	v_sub_f32_e32 v131, v131, v132
	v_add_f32_e32 v132, v133, v134
	v_sub_f32_e32 v133, v133, v134
	v_add_f32_e32 v138, v135, v136
	v_sub_f32_e32 v139, v135, v136
	v_add_f32_e32 v144, v137, v140
	v_sub_f32_e32 v145, v137, v140
	v_add_f32_e32 v146, v141, v142
	v_sub_f32_e32 v147, v141, v142
	v_add_f32_e32 v152, v143, v148
	v_sub_f32_e32 v153, v143, v148
	v_add_f32_e32 v198, v104, v105
	v_sub_f32_e32 v199, v104, v105
	v_pk_add_f32 v[190:191], v[198:199], v[196:197]
	v_pk_add_f32 v[194:195], v[72:73], v[74:75]
	v_pk_add_f32 v[186:187], v[76:77], v[78:79]
	v_pk_add_f32 v[192:193], v[80:81], v[82:83]
	v_pk_add_f32 v[180:181], v[84:85], v[86:87]
	v_pk_add_f32 v[188:189], v[88:89], v[90:91]
	v_pk_add_f32 v[176:177], v[92:93], v[94:95]
	v_pk_add_f32 v[184:185], v[96:97], v[98:99]
	v_pk_add_f32 v[172:173], v[100:101], v[102:103]
	v_pk_add_f32 v[178:179], v[106:107], v[108:109]
	v_pk_add_f32 v[168:169], v[112:113], v[116:117]
	v_pk_add_f32 v[174:175], v[118:119], v[120:121]
	v_pk_add_f32 v[164:165], v[126:127], v[128:129]
	v_pk_add_f32 v[170:171], v[130:131], v[132:133]
	v_pk_add_f32 v[160:161], v[138:139], v[144:145]
	v_pk_add_f32 v[166:167], v[146:147], v[152:153]
	v_pk_add_f32 v[158:159], v[190:191], v[194:195]
	v_pk_add_f32 v[162:163], v[186:187], v[192:193]
	v_pk_add_f32 v[154:155], v[180:181], v[188:189]
	v_pk_add_f32 v[156:157], v[176:177], v[184:185]
	v_pk_add_f32 v[148:149], v[172:173], v[178:179]
	v_pk_add_f32 v[150:151], v[168:169], v[174:175]
	v_pk_add_f32 v[140:141], v[164:165], v[170:171]
	v_pk_add_f32 v[142:143], v[160:161], v[166:167]
	v_pk_add_f32 v[134:135], v[158:159], v[162:163]
	v_pk_add_f32 v[136:137], v[154:155], v[156:157]
	v_pk_add_f32 v[122:123], v[148:149], v[150:151]
	v_pk_add_f32 v[124:125], v[140:141], v[142:143]
	v_pk_add_f32 v[110:111], v[134:135], v[136:137]
	v_pk_add_f32 v[114:115], v[122:123], v[124:125]
	s_nop 0
	v_pk_add_f32 v[104:105], v[110:111], v[114:115]
	s_nop 1
	v_mov_b32_dpp v206, v104 quad_perm:[1,0,3,2] row_mask:0xf bank_mask:0xf
	s_waitcnt lgkmcnt(0)
; template <bool CENTER>
; __device__ __forceinline__ void rot_finish(const u32x4 (&w)[8], signed char* dst, LAS float* red, int tl, int half, int wv4, int lane, float& step_out, float& sum_out) {
;     ...
;     for (int i = 0; i < 32; ++i) { const float a = pr[i][0], b = pr[i][1]; pr[i] = (f32x2){a + b, a - b}; }
; #pragma unroll
;     for (int h = 1; h < 32; h <<= 1)
; #pragma unroll
;         for (int i = 0; i < 32; ++i) if (!(i & h)) { const f32x2 a = pr[i], b = pr[i + h]; pr[i] = a + b; pr[i + h] = a - b; }
;     float sm = pr[0][0];
; #pragma unroll
;     for (int o = 1; o < 64; o <<= 1) sm += __shfl_xor(sm, o);
;     float mx = 0.f;
;     if (CENTER) {
;         if (lane == 0) red[half * 4 + wv4] = sm;
	v_add_f32_e32 v206, v104, v206
	s_nop 1
	v_mov_b32_dpp v207, v206 quad_perm:[2,3,0,1] row_mask:0xf bank_mask:0xf
	s_waitcnt lgkmcnt(0)
	v_add_f32_e32 v206, v206, v207
	s_nop 1
	v_mov_b32_dpp v207, v206 row_half_mirror row_mask:0xf bank_mask:0xf
	s_waitcnt lgkmcnt(0)
	v_add_f32_e32 v206, v206, v207
	s_nop 1
	v_mov_b32_dpp v207, v206 row_mirror row_mask:0xf bank_mask:0xf
	s_waitcnt lgkmcnt(0)
	v_add_f32_e32 v206, v206, v207
	ds_bpermute_b32 v207, v203, v206
	s_waitcnt lgkmcnt(0)
	v_add_f32_e32 v206, v206, v207
	ds_bpermute_b32 v207, v204, v206
	s_and_saveexec_b64 s[24:25], s[4:5]
	s_cbranch_execz .LBB0_1544
	s_add_i32 s9, s33, s34
	s_waitcnt lgkmcnt(0)
	v_add_f32_e32 v206, v206, v207
	v_mov_b32_e32 v207, s9
	ds_write_b32 v207, v206
.LBB0_1544:
	s_or_b64 exec, exec, s[24:25]
	v_pk_add_f32 v[196:197], v[198:199], v[196:197] neg_lo:[0,1] neg_hi:[0,1]
	v_pk_add_f32 v[72:73], v[72:73], v[74:75] neg_lo:[0,1] neg_hi:[0,1]
	v_pk_add_f32 v[74:75], v[76:77], v[78:79] neg_lo:[0,1] neg_hi:[0,1]
	v_pk_add_f32 v[76:77], v[80:81], v[82:83] neg_lo:[0,1] neg_hi:[0,1]
	v_pk_add_f32 v[78:79], v[84:85], v[86:87] neg_lo:[0,1] neg_hi:[0,1]
	v_pk_add_f32 v[80:81], v[88:89], v[90:91] neg_lo:[0,1] neg_hi:[0,1]
	v_pk_add_f32 v[82:83], v[92:93], v[94:95] neg_lo:[0,1] neg_hi:[0,1]
	v_pk_add_f32 v[84:85], v[96:97], v[98:99] neg_lo:[0,1] neg_hi:[0,1]
	v_pk_add_f32 v[86:87], v[100:101], v[102:103] neg_lo:[0,1] neg_hi:[0,1]
	v_pk_add_f32 v[88:89], v[106:107], v[108:109] neg_lo:[0,1] neg_hi:[0,1]
	v_pk_add_f32 v[90:91], v[112:113], v[116:117] neg_lo:[0,1] neg_hi:[0,1]
	v_pk_add_f32 v[92:93], v[118:119], v[120:121] neg_lo:[0,1] neg_hi:[0,1]
	v_pk_add_f32 v[94:95], v[126:127], v[128:129] neg_lo:[0,1] neg_hi:[0,1]
	v_pk_add_f32 v[96:97], v[130:131], v[132:133] neg_lo:[0,1] neg_hi:[0,1]
	v_pk_add_f32 v[98:99], v[138:139], v[144:145] neg_lo:[0,1] neg_hi:[0,1]
	v_pk_add_f32 v[100:101], v[146:147], v[152:153] neg_lo:[0,1] neg_hi:[0,1]
	v_pk_add_f32 v[102:103], v[190:191], v[194:195] neg_lo:[0,1] neg_hi:[0,1]
	v_pk_add_f32 v[106:107], v[196:197], v[72:73]
	v_pk_add_f32 v[72:73], v[196:197], v[72:73] neg_lo:[0,1] neg_hi:[0,1]
	v_pk_add_f32 v[108:109], v[186:187], v[192:193] neg_lo:[0,1] neg_hi:[0,1]
	v_pk_add_f32 v[112:113], v[74:75], v[76:77]
	v_pk_add_f32 v[74:75], v[74:75], v[76:77] neg_lo:[0,1] neg_hi:[0,1]
	v_pk_add_f32 v[76:77], v[180:181], v[188:189] neg_lo:[0,1] neg_hi:[0,1]
	v_pk_add_f32 v[116:117], v[78:79], v[80:81]
	v_pk_add_f32 v[78:79], v[78:79], v[80:81] neg_lo:[0,1] neg_hi:[0,1]
	v_pk_add_f32 v[80:81], v[176:177], v[184:185] neg_lo:[0,1] neg_hi:[0,1]
	v_pk_add_f32 v[118:119], v[82:83], v[84:85]
	v_pk_add_f32 v[82:83], v[82:83], v[84:85] neg_lo:[0,1] neg_hi:[0,1]
	v_pk_add_f32 v[84:85], v[172:173], v[178:179] neg_lo:[0,1] neg_hi:[0,1]
	v_pk_add_f32 v[120:121], v[86:87], v[88:89]
	v_pk_add_f32 v[86:87], v[86:87], v[88:89] neg_lo:[0,1] neg_hi:[0,1]
	v_pk_add_f32 v[88:89], v[168:169], v[174:175] neg_lo:[0,1] neg_hi:[0,1]
	v_pk_add_f32 v[126:127], v[90:91], v[92:93]
	v_pk_add_f32 v[90:91], v[90:91], v[92:93] neg_lo:[0,1] neg_hi:[0,1]
	v_pk_add_f32 v[92:93], v[164:165], v[170:171] neg_lo:[0,1] neg_hi:[0,1]
	v_pk_add_f32 v[128:129], v[94:95], v[96:97]
	v_pk_add_f32 v[94:95], v[94:95], v[96:97] neg_lo:[0,1] neg_hi:[0,1]
	v_pk_add_f32 v[96:97], v[160:161], v[166:167] neg_lo:[0,1] neg_hi:[0,1]
	v_pk_add_f32 v[130:131], v[98:99], v[100:101]
	v_pk_add_f32 v[98:99], v[98:99], v[100:101] neg_lo:[0,1] neg_hi:[0,1]
	v_pk_add_f32 v[100:101], v[158:159], v[162:163] neg_lo:[0,1] neg_hi:[0,1]
	v_pk_add_f32 v[132:133], v[106:107], v[112:113]
	v_pk_add_f32 v[106:107], v[106:107], v[112:113] neg_lo:[0,1] neg_hi:[0,1]
	v_pk_add_f32 v[112:113], v[102:103], v[108:109]
	v_pk_add_f32 v[102:103], v[102:103], v[108:109] neg_lo:[0,1] neg_hi:[0,1]
	v_pk_add_f32 v[108:109], v[72:73], v[74:75]
	v_pk_add_f32 v[72:73], v[72:73], v[74:75] neg_lo:[0,1] neg_hi:[0,1]
	v_pk_add_f32 v[74:75], v[154:155], v[156:157] neg_lo:[0,1] neg_hi:[0,1]
	v_pk_add_f32 v[138:139], v[116:117], v[118:119]
	v_pk_add_f32 v[116:117], v[116:117], v[118:119] neg_lo:[0,1] neg_hi:[0,1]
	v_pk_add_f32 v[118:119], v[76:77], v[80:81]
	v_pk_add_f32 v[76:77], v[76:77], v[80:81] neg_lo:[0,1] neg_hi:[0,1]
	v_pk_add_f32 v[80:81], v[78:79], v[82:83]
	v_pk_add_f32 v[78:79], v[78:79], v[82:83] neg_lo:[0,1] neg_hi:[0,1]
	v_pk_add_f32 v[82:83], v[148:149], v[150:151] neg_lo:[0,1] neg_hi:[0,1]
	v_pk_add_f32 v[144:145], v[120:121], v[126:127]
	v_pk_add_f32 v[120:121], v[120:121], v[126:127] neg_lo:[0,1] neg_hi:[0,1]
	v_pk_add_f32 v[126:127], v[84:85], v[88:89]
	v_pk_add_f32 v[84:85], v[84:85], v[88:89] neg_lo:[0,1] neg_hi:[0,1]
	v_pk_add_f32 v[88:89], v[86:87], v[90:91]
	v_pk_add_f32 v[86:87], v[86:87], v[90:91] neg_lo:[0,1] neg_hi:[0,1]
	v_pk_add_f32 v[90:91], v[140:141], v[142:143] neg_lo:[0,1] neg_hi:[0,1]
	v_pk_add_f32 v[140:141], v[128:129], v[130:131]
	v_pk_add_f32 v[128:129], v[128:129], v[130:131] neg_lo:[0,1] neg_hi:[0,1]
	v_pk_add_f32 v[130:131], v[92:93], v[96:97]
	v_pk_add_f32 v[92:93], v[92:93], v[96:97] neg_lo:[0,1] neg_hi:[0,1]
	v_pk_add_f32 v[96:97], v[94:95], v[98:99]
	v_pk_add_f32 v[94:95], v[94:95], v[98:99] neg_lo:[0,1] neg_hi:[0,1]
	v_pk_add_f32 v[136:137], v[134:135], v[136:137] neg_lo:[0,1] neg_hi:[0,1]
	v_pk_add_f32 v[98:99], v[132:133], v[138:139]
	v_pk_add_f32 v[138:139], v[132:133], v[138:139] neg_lo:[0,1] neg_hi:[0,1]
	v_pk_add_f32 v[132:133], v[112:113], v[118:119]
	v_pk_add_f32 v[112:113], v[112:113], v[118:119] neg_lo:[0,1] neg_hi:[0,1]
	v_pk_add_f32 v[118:119], v[108:109], v[80:81]
	v_pk_add_f32 v[108:109], v[108:109], v[80:81] neg_lo:[0,1] neg_hi:[0,1]
	v_pk_add_f32 v[80:81], v[100:101], v[74:75]
; template <bool CENTER>
; __device__ __forceinline__ void rot_finish(const u32x4 (&w)[8], signed char* dst, LAS float* red, int tl, int half, int wv4, int lane, float& step_out, float& sum_out) {
;     ...
;     float mx = 0.f;
;     if (CENTER) {
;         if (lane == 0) red[half * 4 + wv4] = sm;
;         __syncthreads();
;         sm = (red[half * 4] + red[half * 4 + 1]) + (red[half * 4 + 2] + red[half * 4 + 3]);
;         pr[0][0] -= sm * (64.0f / DFF);
;     }
; #pragma unroll
;     for (int i = 0; i < 32; ++i) mx = fmaxf(mx, fmaxf(fabsf(pr[i][0]), fabsf(pr[i][1])));
; #pragma unroll
;     for (int o = 1; o < 64; o <<= 1) mx = fmaxf(mx, __shfl_xor(mx, o));
;     if (lane == 0) { red[16 + half * 4 + wv4] = mx; if (!CENTER) red[half * 4 + wv4] = sm; }
	v_pk_add_f32 v[142:143], v[106:107], v[116:117]
	v_pk_add_f32 v[106:107], v[106:107], v[116:117] neg_lo:[0,1] neg_hi:[0,1]
	v_pk_add_f32 v[116:117], v[102:103], v[76:77]
	v_pk_add_f32 v[146:147], v[72:73], v[78:79]
	v_pk_add_f32 v[148:149], v[72:73], v[78:79] neg_lo:[0,1] neg_hi:[0,1]
	v_pk_add_f32 v[72:73], v[122:123], v[124:125] neg_lo:[0,1] neg_hi:[0,1]
	v_pk_add_f32 v[78:79], v[144:145], v[140:141]
	v_pk_add_f32 v[122:123], v[126:127], v[130:131]
	v_pk_add_f32 v[124:125], v[88:89], v[96:97]
	v_pk_add_f32 v[150:151], v[88:89], v[96:97] neg_lo:[0,1] neg_hi:[0,1]
	v_pk_add_f32 v[88:89], v[82:83], v[90:91]
	v_pk_add_f32 v[152:153], v[82:83], v[90:91] neg_lo:[0,1] neg_hi:[0,1]
	v_pk_add_f32 v[90:91], v[84:85], v[92:93]
	v_pk_add_f32 v[156:157], v[84:85], v[92:93] neg_lo:[0,1] neg_hi:[0,1]
	v_pk_add_f32 v[84:85], v[86:87], v[94:95]
	v_pk_add_f32 v[76:77], v[102:103], v[76:77] neg_lo:[0,1] neg_hi:[0,1]
	v_pk_add_f32 v[140:141], v[144:145], v[140:141] neg_lo:[0,1] neg_hi:[0,1]
	v_pk_add_f32 v[144:145], v[126:127], v[130:131] neg_lo:[0,1] neg_hi:[0,1]
	v_pk_add_f32 v[134:135], v[98:99], v[78:79]
	v_pk_add_f32 v[102:103], v[98:99], v[78:79] neg_lo:[0,1] neg_hi:[0,1]
	v_pk_add_f32 v[130:131], v[132:133], v[122:123]
	v_pk_add_f32 v[96:97], v[132:133], v[122:123] neg_lo:[0,1] neg_hi:[0,1]
	v_pk_add_f32 v[132:133], v[118:119], v[124:125]
	v_pk_add_f32 v[98:99], v[118:119], v[124:125] neg_lo:[0,1] neg_hi:[0,1]
	v_pk_add_f32 v[126:127], v[80:81], v[88:89]
	v_pk_add_f32 v[92:93], v[80:81], v[88:89] neg_lo:[0,1] neg_hi:[0,1]
	v_pk_add_f32 v[122:123], v[116:117], v[90:91]
	v_pk_add_f32 v[88:89], v[116:117], v[90:91] neg_lo:[0,1] neg_hi:[0,1]
	v_pk_add_f32 v[124:125], v[146:147], v[84:85]
	v_pk_add_f32 v[90:91], v[146:147], v[84:85] neg_lo:[0,1] neg_hi:[0,1]
	v_pk_add_f32 v[118:119], v[136:137], v[72:73]
	v_pk_add_f32 v[84:85], v[136:137], v[72:73] neg_lo:[0,1] neg_hi:[0,1]
	v_mov_b32_e32 v72, s35
	v_pk_add_f32 v[82:83], v[120:121], v[128:129]
	v_pk_add_f32 v[154:155], v[120:121], v[128:129] neg_lo:[0,1] neg_hi:[0,1]
	v_pk_add_f32 v[158:159], v[86:87], v[94:95] neg_lo:[0,1] neg_hi:[0,1]
	v_pk_add_f32 v[120:121], v[138:139], v[140:141]
	v_pk_add_f32 v[86:87], v[138:139], v[140:141] neg_lo:[0,1] neg_hi:[0,1]
	s_waitcnt lgkmcnt(0)
	s_barrier
	ds_read_b128 v[136:139], v72
	v_pk_add_f32 v[128:129], v[142:143], v[82:83]
	v_pk_add_f32 v[74:75], v[100:101], v[74:75] neg_lo:[0,1] neg_hi:[0,1]
	v_pk_add_f32 v[100:101], v[110:111], v[114:115] neg_lo:[0,1] neg_hi:[0,1]
	v_pk_add_f32 v[114:115], v[112:113], v[144:145]
	s_waitcnt lgkmcnt(0)
	v_add_f32_e32 v136, v136, v137
	v_add_f32_e32 v137, v138, v139
	v_add_f32_e32 v136, v136, v137
	v_fmamk_f32 v104, v136, 0xbb800000, v104
	v_max_f32_e64 v137, |v105|, |v105|
	v_max_f32_e64 v137, |v104|, v137
	v_max_f32_e64 v138, |v134|, |v135|
	v_max3_f32 v137, v137, 0, v138
	v_max_f32_e64 v138, |v130|, |v131|
	v_max_f32_e64 v139, |v132|, |v133|
	v_max3_f32 v137, v137, v138, v139
	v_max_f32_e64 v138, |v126|, |v127|
	v_max_f32_e64 v139, |v128|, |v129|
	v_max3_f32 v137, v137, v138, v139
	v_max_f32_e64 v138, |v122|, |v123|
	v_max_f32_e64 v139, |v124|, |v125|
	v_pk_add_f32 v[116:117], v[108:109], v[150:151]
	v_max3_f32 v137, v137, v138, v139
	v_max_f32_e64 v138, |v118|, |v119|
	v_max_f32_e64 v139, |v120|, |v121|
	v_pk_add_f32 v[94:95], v[142:143], v[82:83] neg_lo:[0,1] neg_hi:[0,1]
	v_pk_add_f32 v[80:81], v[112:113], v[144:145] neg_lo:[0,1] neg_hi:[0,1]
	v_pk_add_f32 v[82:83], v[108:109], v[150:151] neg_lo:[0,1] neg_hi:[0,1]
	v_pk_add_f32 v[108:109], v[74:75], v[152:153]
	v_pk_add_f32 v[112:113], v[106:107], v[154:155]
	v_max3_f32 v137, v137, v138, v139
	v_max_f32_e64 v138, |v114|, |v115|
	v_max_f32_e64 v139, |v116|, |v117|
	v_pk_add_f32 v[78:79], v[106:107], v[154:155] neg_lo:[0,1] neg_hi:[0,1]
	v_pk_add_f32 v[106:107], v[76:77], v[156:157]
	v_pk_add_f32 v[110:111], v[148:149], v[158:159]
	v_max3_f32 v137, v137, v138, v139
	v_max_f32_e64 v138, |v108|, |v109|
	v_max_f32_e64 v139, |v112|, |v113|
	v_max3_f32 v137, v137, v138, v139
	v_max_f32_e64 v138, |v106|, |v107|
	v_max_f32_e64 v139, |v110|, |v111|
	v_max3_f32 v137, v137, v138, v139
	v_max_f32_e64 v138, |v100|, |v101|
	v_max_f32_e64 v139, |v102|, |v103|
	v_max3_f32 v137, v137, v138, v139
	v_max_f32_e64 v138, |v96|, |v97|
	v_max_f32_e64 v139, |v98|, |v99|
	v_max3_f32 v137, v137, v138, v139
	v_max_f32_e64 v138, |v92|, |v93|
	v_max_f32_e64 v139, |v94|, |v95|
	v_max3_f32 v137, v137, v138, v139
	v_max_f32_e64 v138, |v88|, |v89|
	v_max_f32_e64 v139, |v90|, |v91|
	v_max3_f32 v137, v137, v138, v139
	v_max_f32_e64 v138, |v84|, |v85|
	v_max_f32_e64 v139, |v86|, |v87|
	v_pk_add_f32 v[74:75], v[74:75], v[152:153] neg_lo:[0,1] neg_hi:[0,1]
	v_max3_f32 v137, v137, v138, v139
	v_max_f32_e64 v138, |v80|, |v81|
	v_max_f32_e64 v139, |v82|, |v83|
	v_pk_add_f32 v[72:73], v[76:77], v[156:157] neg_lo:[0,1] neg_hi:[0,1]
	v_pk_add_f32 v[76:77], v[148:149], v[158:159] neg_lo:[0,1] neg_hi:[0,1]
	v_max3_f32 v137, v137, v138, v139
	v_max_f32_e64 v138, |v74|, |v75|
	v_max_f32_e64 v139, |v78|, |v79|
	v_max3_f32 v137, v137, v138, v139
	v_max_f32_e64 v138, |v72|, |v73|
	v_max_f32_e64 v139, |v76|, |v77|
	v_max3_f32 v137, v137, v138, v139
	s_nop 1
	v_mov_b32_dpp v138, v137 quad_perm:[1,0,3,2] row_mask:0xf bank_mask:0xf
	s_waitcnt lgkmcnt(0)
	v_max_f32_e32 v138, v138, v138
	v_max_f32_e32 v137, v137, v138
	s_nop 1
	v_mov_b32_dpp v138, v137 quad_perm:[2,3,0,1] row_mask:0xf bank_mask:0xf
	s_waitcnt lgkmcnt(0)
	v_max_f32_e32 v138, v138, v138
	v_max_f32_e32 v137, v137, v138
	s_nop 1
	v_mov_b32_dpp v138, v137 row_half_mirror row_mask:0xf bank_mask:0xf
	s_waitcnt lgkmcnt(0)
	v_max_f32_e32 v138, v138, v138
	v_max_f32_e32 v137, v137, v138
	s_nop 1
	v_mov_b32_dpp v138, v137 row_mirror row_mask:0xf bank_mask:0xf
	s_waitcnt lgkmcnt(0)
	v_max_f32_e32 v138, v138, v138
	v_max_f32_e32 v137, v137, v138
	ds_bpermute_b32 v138, v203, v137
	s_waitcnt lgkmcnt(0)
	v_max_f32_e32 v138, v138, v138
	v_max_f32_e32 v137, v137, v138
	ds_bpermute_b32 v138, v204, v137
	s_and_saveexec_b64 s[24:25], s[4:5]
	s_cbranch_execz .LBB0_1546
	s_waitcnt lgkmcnt(0)
	v_max_f32_e32 v138, v138, v138
	v_max_f32_e32 v137, v137, v137
	v_max_f32_e32 v137, v137, v138
	v_mov_b32_e32 v138, s36
	ds_write_b32 v138, v137 offset:64

; __device__ __forceinline__ float bflo(unsigned w) { return __uint_as_float(w << 16); }
; __device__ __forceinline__ float bfhi(unsigned w) { return __uint_as_float(w & 0xffff0000u); }
; template <bool CENTER>
; __device__ __forceinline__ void rot_finish(const u32x4 (&w)[8], signed char* dst, LAS float* red, int tl, int half, int wv4, int lane, float& step_out, float& sum_out) {
;     f32x2 pr[32];
; #pragma unroll
;     for (int j = 0; j < 8; ++j) { pr[4 * j] = (f32x2){bflo(w[j].x), bfhi(w[j].x)}; pr[4 * j + 1] = (f32x2){bflo(w[j].y), bfhi(w[j].y)}; pr[4 * j + 2] = (f32x2){bflo(w[j].z), bfhi(w[j].z)}; pr[4 * j + 3] = (f32x2){bflo(w[j].w), bfhi(w[j].w)}; }
; #pragma unroll
;     for (int i = 0; i < 32; ++i) { const float a = pr[i][0], b = pr[i][1]; pr[i] = (f32x2){a + b, a - b}; }
; #pragma unroll
;     for (int h = 1; h < 32; h <<= 1)
; #pragma unroll
;         for (int i = 0; i < 32; ++i) if (!(i & h)) { const f32x2 a = pr[i], b = pr[i + h]; pr[i] = a + b; pr[i + h] = a - b; }
;     float sm = pr[0][0];
; #pragma unroll
;     for (int o = 1; o < 64; o <<= 1) sm += __shfl_xor(sm, o);
;     float mx = 0.f;
;     if (CENTER) {
;         if (lane == 0) red[half * 4 + wv4] = sm;
.LBB0_1550:
	s_waitcnt vmcnt(5)
	v_lshlrev_b32_e32 v72, 16, v36
	v_and_b32_e32 v73, 0xffff0000, v36
	v_lshlrev_b32_e32 v74, 16, v37
	v_and_b32_e32 v75, 0xffff0000, v37
	v_add_f32_e32 v36, v72, v73
	v_sub_f32_e32 v37, v72, v73
	v_lshlrev_b32_e32 v72, 16, v35
	v_and_b32_e32 v35, 0xffff0000, v35
	v_lshlrev_b32_e32 v76, 16, v62
	v_and_b32_e32 v62, 0xffff0000, v62
	v_lshlrev_b32_e32 v77, 16, v63
	v_and_b32_e32 v63, 0xffff0000, v63
	v_lshlrev_b32_e32 v78, 16, v64
	v_and_b32_e32 v64, 0xffff0000, v64
	v_lshlrev_b32_e32 v79, 16, v65
	v_and_b32_e32 v65, 0xffff0000, v65
	v_lshlrev_b32_e32 v80, 16, v58
	v_and_b32_e32 v58, 0xffff0000, v58
	v_lshlrev_b32_e32 v81, 16, v59
	v_and_b32_e32 v59, 0xffff0000, v59
	v_lshlrev_b32_e32 v82, 16, v60
	v_and_b32_e32 v60, 0xffff0000, v60
	v_lshlrev_b32_e32 v83, 16, v61
	v_and_b32_e32 v61, 0xffff0000, v61
	v_lshlrev_b32_e32 v84, 16, v54
	v_and_b32_e32 v85, 0xffff0000, v54
	v_lshlrev_b32_e32 v86, 16, v55
	v_and_b32_e32 v87, 0xffff0000, v55
	v_lshlrev_b32_e32 v88, 16, v56
	v_and_b32_e32 v89, 0xffff0000, v56
	v_lshlrev_b32_e32 v90, 16, v57
	v_and_b32_e32 v91, 0xffff0000, v57
	v_lshlrev_b32_e32 v92, 16, v50
	v_and_b32_e32 v93, 0xffff0000, v50
	v_lshlrev_b32_e32 v94, 16, v51
	v_and_b32_e32 v95, 0xffff0000, v51
	v_lshlrev_b32_e32 v96, 16, v52
	v_and_b32_e32 v97, 0xffff0000, v52
	v_lshlrev_b32_e32 v98, 16, v53
	v_and_b32_e32 v99, 0xffff0000, v53
	v_lshlrev_b32_e32 v100, 16, v46
	v_and_b32_e32 v101, 0xffff0000, v46
	v_lshlrev_b32_e32 v102, 16, v47
	v_and_b32_e32 v103, 0xffff0000, v47
	v_lshlrev_b32_e32 v104, 16, v48
	v_and_b32_e32 v105, 0xffff0000, v48
	v_lshlrev_b32_e32 v106, 16, v49
	v_and_b32_e32 v107, 0xffff0000, v49
	v_lshlrev_b32_e32 v108, 16, v42
	v_and_b32_e32 v109, 0xffff0000, v42
	v_lshlrev_b32_e32 v110, 16, v43
	v_and_b32_e32 v111, 0xffff0000, v43
	v_lshlrev_b32_e32 v112, 16, v44
	v_and_b32_e32 v113, 0xffff0000, v44
	v_lshlrev_b32_e32 v114, 16, v45
	v_and_b32_e32 v115, 0xffff0000, v45
	s_waitcnt vmcnt(4)
	v_lshlrev_b32_e32 v116, 16, v38
	v_and_b32_e32 v117, 0xffff0000, v38
	v_lshlrev_b32_e32 v118, 16, v39
	v_and_b32_e32 v119, 0xffff0000, v39
	v_lshlrev_b32_e32 v120, 16, v40
	v_and_b32_e32 v121, 0xffff0000, v40
	v_lshlrev_b32_e32 v122, 16, v41
	v_and_b32_e32 v123, 0xffff0000, v41
	v_add_f32_e32 v162, v72, v35
	v_sub_f32_e32 v163, v72, v35
	v_lshlrev_b32_e32 v35, 16, v34
	v_and_b32_e32 v34, 0xffff0000, v34
	v_add_f32_e32 v38, v74, v75
	v_sub_f32_e32 v39, v74, v75
	v_add_f32_e32 v40, v76, v62
	v_sub_f32_e32 v41, v76, v62
	v_add_f32_e32 v42, v77, v63
	v_sub_f32_e32 v43, v77, v63
	v_add_f32_e32 v44, v78, v64
	v_sub_f32_e32 v45, v78, v64
	v_add_f32_e32 v46, v79, v65
	v_sub_f32_e32 v47, v79, v65
	v_add_f32_e32 v48, v80, v58
	v_sub_f32_e32 v49, v80, v58
	v_add_f32_e32 v50, v81, v59
	v_sub_f32_e32 v51, v81, v59
	v_add_f32_e32 v52, v82, v60
	v_sub_f32_e32 v53, v82, v60
	v_add_f32_e32 v54, v83, v61
	v_sub_f32_e32 v55, v83, v61
	v_add_f32_e32 v56, v84, v85
	v_sub_f32_e32 v57, v84, v85
	v_add_f32_e32 v58, v86, v87
	v_sub_f32_e32 v59, v86, v87
	v_add_f32_e32 v60, v88, v89
	v_sub_f32_e32 v61, v88, v89
	v_add_f32_e32 v62, v90, v91
	v_sub_f32_e32 v63, v90, v91
	v_add_f32_e32 v64, v92, v93
	v_sub_f32_e32 v65, v92, v93
	v_add_f32_e32 v74, v94, v95
	v_sub_f32_e32 v75, v94, v95
	v_add_f32_e32 v76, v96, v97
	v_sub_f32_e32 v77, v96, v97
	v_add_f32_e32 v78, v98, v99
	v_sub_f32_e32 v79, v98, v99
	v_add_f32_e32 v80, v100, v101
	v_sub_f32_e32 v81, v100, v101
	v_add_f32_e32 v84, v102, v103
	v_sub_f32_e32 v85, v102, v103
	v_add_f32_e32 v86, v104, v105
	v_sub_f32_e32 v87, v104, v105
	v_add_f32_e32 v88, v106, v107
	v_sub_f32_e32 v89, v106, v107
	v_add_f32_e32 v94, v108, v109
	v_sub_f32_e32 v95, v108, v109
	v_add_f32_e32 v96, v110, v111
	v_sub_f32_e32 v97, v110, v111
	v_add_f32_e32 v98, v112, v113
	v_sub_f32_e32 v99, v112, v113
	v_add_f32_e32 v100, v114, v115
	v_sub_f32_e32 v101, v114, v115
	v_add_f32_e32 v106, v116, v117
	v_sub_f32_e32 v107, v116, v117
	v_add_f32_e32 v112, v118, v119
	v_sub_f32_e32 v113, v118, v119
	v_add_f32_e32 v114, v120, v121
	v_sub_f32_e32 v115, v120, v121
	v_add_f32_e32 v120, v122, v123
	v_sub_f32_e32 v121, v122, v123
	v_add_f32_e32 v164, v35, v34
	v_sub_f32_e32 v165, v35, v34
	v_pk_add_f32 v[156:157], v[164:165], v[162:163]
	v_pk_add_f32 v[160:161], v[36:37], v[38:39]
	v_pk_add_f32 v[152:153], v[40:41], v[42:43]
	v_pk_add_f32 v[158:159], v[44:45], v[46:47]
	v_pk_add_f32 v[148:149], v[48:49], v[50:51]
	v_pk_add_f32 v[154:155], v[52:53], v[54:55]
	v_pk_add_f32 v[144:145], v[56:57], v[58:59]
	v_pk_add_f32 v[150:151], v[60:61], v[62:63]
	v_pk_add_f32 v[140:141], v[64:65], v[74:75]
	v_pk_add_f32 v[146:147], v[76:77], v[78:79]
	v_pk_add_f32 v[136:137], v[80:81], v[84:85]
	v_pk_add_f32 v[142:143], v[86:87], v[88:89]
	v_pk_add_f32 v[132:133], v[94:95], v[96:97]
	v_pk_add_f32 v[138:139], v[98:99], v[100:101]
	v_pk_add_f32 v[128:129], v[106:107], v[112:113]
	v_pk_add_f32 v[134:135], v[114:115], v[120:121]
	v_pk_add_f32 v[126:127], v[156:157], v[160:161]
	v_pk_add_f32 v[130:131], v[152:153], v[158:159]
	v_pk_add_f32 v[122:123], v[148:149], v[154:155]
	v_pk_add_f32 v[124:125], v[144:145], v[150:151]
	v_pk_add_f32 v[116:117], v[140:141], v[146:147]
	v_pk_add_f32 v[118:119], v[136:137], v[142:143]
	v_pk_add_f32 v[108:109], v[132:133], v[138:139]
	v_pk_add_f32 v[110:111], v[128:129], v[134:135]
	v_pk_add_f32 v[102:103], v[126:127], v[130:131]
	v_pk_add_f32 v[104:105], v[122:123], v[124:125]
	v_pk_add_f32 v[90:91], v[116:117], v[118:119]
	v_pk_add_f32 v[92:93], v[108:109], v[110:111]
	v_pk_add_f32 v[34:35], v[102:103], v[104:105]
	v_pk_add_f32 v[82:83], v[90:91], v[92:93]
	s_nop 0
	v_pk_add_f32 v[72:73], v[34:35], v[82:83]
	s_nop 1
	v_mov_b32_dpp v166, v72 quad_perm:[1,0,3,2] row_mask:0xf bank_mask:0xf
	s_waitcnt lgkmcnt(0)
	v_add_f32_e32 v166, v72, v166
	s_nop 1
	v_mov_b32_dpp v167, v166 quad_perm:[2,3,0,1] row_mask:0xf bank_mask:0xf
	s_waitcnt lgkmcnt(0)
	v_add_f32_e32 v166, v166, v167
	s_nop 1
	v_mov_b32_dpp v167, v166 row_half_mirror row_mask:0xf bank_mask:0xf
	s_waitcnt lgkmcnt(0)
	v_add_f32_e32 v166, v166, v167
	s_nop 1
	v_mov_b32_dpp v167, v166 row_mirror row_mask:0xf bank_mask:0xf
	s_waitcnt lgkmcnt(0)
	v_add_f32_e32 v166, v166, v167
	ds_bpermute_b32 v167, v203, v166
	s_waitcnt lgkmcnt(0)
	v_add_f32_e32 v166, v166, v167
	ds_bpermute_b32 v167, v204, v166
	s_and_saveexec_b64 s[26:27], s[4:5]
	s_cbranch_execz .LBB0_1552
	s_add_i32 s9, s33, s34
	s_waitcnt lgkmcnt(0)
	v_add_f32_e32 v166, v166, v167
	v_mov_b32_e32 v167, s9
	ds_write_b32 v167, v166
; template <bool CENTER>
; __device__ __forceinline__ void rot_finish(const u32x4 (&w)[8], signed char* dst, LAS float* red, int tl, int half, int wv4, int lane, float& step_out, float& sum_out) {
;     ...
;     for (int i = 0; i < 32; ++i) { const float a = pr[i][0], b = pr[i][1]; pr[i] = (f32x2){a + b, a - b}; }
; #pragma unroll
;     for (int h = 1; h < 32; h <<= 1)
; #pragma unroll
;         for (int i = 0; i < 32; ++i) if (!(i & h)) { const f32x2 a = pr[i], b = pr[i + h]; pr[i] = a + b; pr[i + h] = a - b; }
.LBB0_1552:
	s_or_b64 exec, exec, s[26:27]
	v_pk_add_f32 v[162:163], v[164:165], v[162:163] neg_lo:[0,1] neg_hi:[0,1]
	v_pk_add_f32 v[36:37], v[36:37], v[38:39] neg_lo:[0,1] neg_hi:[0,1]
	v_pk_add_f32 v[38:39], v[40:41], v[42:43] neg_lo:[0,1] neg_hi:[0,1]
	v_pk_add_f32 v[40:41], v[44:45], v[46:47] neg_lo:[0,1] neg_hi:[0,1]
	v_pk_add_f32 v[42:43], v[48:49], v[50:51] neg_lo:[0,1] neg_hi:[0,1]
	v_pk_add_f32 v[44:45], v[52:53], v[54:55] neg_lo:[0,1] neg_hi:[0,1]
	v_pk_add_f32 v[46:47], v[56:57], v[58:59] neg_lo:[0,1] neg_hi:[0,1]
	v_pk_add_f32 v[48:49], v[60:61], v[62:63] neg_lo:[0,1] neg_hi:[0,1]
	v_pk_add_f32 v[50:51], v[64:65], v[74:75] neg_lo:[0,1] neg_hi:[0,1]
	v_pk_add_f32 v[52:53], v[76:77], v[78:79] neg_lo:[0,1] neg_hi:[0,1]
	v_pk_add_f32 v[54:55], v[80:81], v[84:85] neg_lo:[0,1] neg_hi:[0,1]
	v_pk_add_f32 v[56:57], v[86:87], v[88:89] neg_lo:[0,1] neg_hi:[0,1]
	v_pk_add_f32 v[58:59], v[94:95], v[96:97] neg_lo:[0,1] neg_hi:[0,1]
	v_pk_add_f32 v[60:61], v[98:99], v[100:101] neg_lo:[0,1] neg_hi:[0,1]
	v_pk_add_f32 v[62:63], v[106:107], v[112:113] neg_lo:[0,1] neg_hi:[0,1]
	v_pk_add_f32 v[64:65], v[114:115], v[120:121] neg_lo:[0,1] neg_hi:[0,1]
	v_pk_add_f32 v[74:75], v[156:157], v[160:161] neg_lo:[0,1] neg_hi:[0,1]
	v_pk_add_f32 v[76:77], v[162:163], v[36:37]
	v_pk_add_f32 v[36:37], v[162:163], v[36:37] neg_lo:[0,1] neg_hi:[0,1]
	v_pk_add_f32 v[78:79], v[152:153], v[158:159] neg_lo:[0,1] neg_hi:[0,1]
	v_pk_add_f32 v[80:81], v[38:39], v[40:41]
	v_pk_add_f32 v[38:39], v[38:39], v[40:41] neg_lo:[0,1] neg_hi:[0,1]
	v_pk_add_f32 v[40:41], v[148:149], v[154:155] neg_lo:[0,1] neg_hi:[0,1]
	v_pk_add_f32 v[84:85], v[42:43], v[44:45]
	v_pk_add_f32 v[42:43], v[42:43], v[44:45] neg_lo:[0,1] neg_hi:[0,1]
	v_pk_add_f32 v[44:45], v[144:145], v[150:151] neg_lo:[0,1] neg_hi:[0,1]
	v_pk_add_f32 v[86:87], v[46:47], v[48:49]
	v_pk_add_f32 v[46:47], v[46:47], v[48:49] neg_lo:[0,1] neg_hi:[0,1]
	v_pk_add_f32 v[48:49], v[140:141], v[146:147] neg_lo:[0,1] neg_hi:[0,1]
	v_pk_add_f32 v[88:89], v[50:51], v[52:53]
	v_pk_add_f32 v[50:51], v[50:51], v[52:53] neg_lo:[0,1] neg_hi:[0,1]
	v_pk_add_f32 v[52:53], v[136:137], v[142:143] neg_lo:[0,1] neg_hi:[0,1]
	v_pk_add_f32 v[94:95], v[54:55], v[56:57]
	v_pk_add_f32 v[54:55], v[54:55], v[56:57] neg_lo:[0,1] neg_hi:[0,1]
	v_pk_add_f32 v[56:57], v[132:133], v[138:139] neg_lo:[0,1] neg_hi:[0,1]
	v_pk_add_f32 v[96:97], v[58:59], v[60:61]
	v_pk_add_f32 v[58:59], v[58:59], v[60:61] neg_lo:[0,1] neg_hi:[0,1]
	v_pk_add_f32 v[60:61], v[128:129], v[134:135] neg_lo:[0,1] neg_hi:[0,1]
	v_pk_add_f32 v[98:99], v[62:63], v[64:65]
	v_pk_add_f32 v[62:63], v[62:63], v[64:65] neg_lo:[0,1] neg_hi:[0,1]
	v_pk_add_f32 v[64:65], v[126:127], v[130:131] neg_lo:[0,1] neg_hi:[0,1]
	v_pk_add_f32 v[100:101], v[76:77], v[80:81]
	v_pk_add_f32 v[76:77], v[76:77], v[80:81] neg_lo:[0,1] neg_hi:[0,1]
	v_pk_add_f32 v[80:81], v[74:75], v[78:79]
	v_pk_add_f32 v[74:75], v[74:75], v[78:79] neg_lo:[0,1] neg_hi:[0,1]
	v_pk_add_f32 v[78:79], v[36:37], v[38:39]
	v_pk_add_f32 v[36:37], v[36:37], v[38:39] neg_lo:[0,1] neg_hi:[0,1]
	v_pk_add_f32 v[38:39], v[122:123], v[124:125] neg_lo:[0,1] neg_hi:[0,1]
	v_pk_add_f32 v[106:107], v[84:85], v[86:87]
	v_pk_add_f32 v[84:85], v[84:85], v[86:87] neg_lo:[0,1] neg_hi:[0,1]
	v_pk_add_f32 v[86:87], v[40:41], v[44:45]
	v_pk_add_f32 v[40:41], v[40:41], v[44:45] neg_lo:[0,1] neg_hi:[0,1]
	v_pk_add_f32 v[44:45], v[42:43], v[46:47]
	v_pk_add_f32 v[42:43], v[42:43], v[46:47] neg_lo:[0,1] neg_hi:[0,1]
	v_pk_add_f32 v[46:47], v[116:117], v[118:119] neg_lo:[0,1] neg_hi:[0,1]
	v_pk_add_f32 v[112:113], v[88:89], v[94:95]
	v_pk_add_f32 v[88:89], v[88:89], v[94:95] neg_lo:[0,1] neg_hi:[0,1]
	v_pk_add_f32 v[94:95], v[48:49], v[52:53]
	v_pk_add_f32 v[48:49], v[48:49], v[52:53] neg_lo:[0,1] neg_hi:[0,1]
	v_pk_add_f32 v[52:53], v[50:51], v[54:55]
	v_pk_add_f32 v[50:51], v[50:51], v[54:55] neg_lo:[0,1] neg_hi:[0,1]
	v_pk_add_f32 v[54:55], v[108:109], v[110:111] neg_lo:[0,1] neg_hi:[0,1]
	v_pk_add_f32 v[108:109], v[96:97], v[98:99]
	v_pk_add_f32 v[96:97], v[96:97], v[98:99] neg_lo:[0,1] neg_hi:[0,1]
	v_pk_add_f32 v[98:99], v[56:57], v[60:61]
	v_pk_add_f32 v[56:57], v[56:57], v[60:61] neg_lo:[0,1] neg_hi:[0,1]
	v_pk_add_f32 v[60:61], v[58:59], v[62:63]
	v_pk_add_f32 v[58:59], v[58:59], v[62:63] neg_lo:[0,1] neg_hi:[0,1]
	v_pk_add_f32 v[104:105], v[102:103], v[104:105] neg_lo:[0,1] neg_hi:[0,1]
	v_pk_add_f32 v[110:111], v[100:101], v[106:107]
	v_pk_add_f32 v[106:107], v[100:101], v[106:107] neg_lo:[0,1] neg_hi:[0,1]
	v_pk_add_f32 v[100:101], v[80:81], v[86:87]
	v_pk_add_f32 v[80:81], v[80:81], v[86:87] neg_lo:[0,1] neg_hi:[0,1]
	v_pk_add_f32 v[86:87], v[78:79], v[44:45]
	v_pk_add_f32 v[44:45], v[78:79], v[44:45] neg_lo:[0,1] neg_hi:[0,1]
	v_pk_add_f32 v[78:79], v[64:65], v[38:39]
	v_pk_add_f32 v[114:115], v[76:77], v[84:85]
	v_pk_add_f32 v[116:117], v[76:77], v[84:85] neg_lo:[0,1] neg_hi:[0,1]
	v_pk_add_f32 v[76:77], v[74:75], v[40:41]
	v_pk_add_f32 v[118:119], v[74:75], v[40:41] neg_lo:[0,1] neg_hi:[0,1]
	v_pk_add_f32 v[40:41], v[36:37], v[42:43]
	v_pk_add_f32 v[120:121], v[36:37], v[42:43] neg_lo:[0,1] neg_hi:[0,1]
	v_pk_add_f32 v[36:37], v[90:91], v[92:93] neg_lo:[0,1] neg_hi:[0,1]
	v_pk_add_f32 v[42:43], v[112:113], v[108:109]
	v_pk_add_f32 v[74:75], v[112:113], v[108:109] neg_lo:[0,1] neg_hi:[0,1]
	v_pk_add_f32 v[84:85], v[94:95], v[98:99]
	v_pk_add_f32 v[90:91], v[52:53], v[60:61]
	v_pk_add_f32 v[112:113], v[52:53], v[60:61] neg_lo:[0,1] neg_hi:[0,1]
	v_pk_add_f32 v[52:53], v[46:47], v[54:55]
	v_pk_add_f32 v[122:123], v[46:47], v[54:55] neg_lo:[0,1] neg_hi:[0,1]
	v_pk_add_f32 v[46:47], v[88:89], v[96:97]
	v_pk_add_f32 v[124:125], v[88:89], v[96:97] neg_lo:[0,1] neg_hi:[0,1]
	v_pk_add_f32 v[88:89], v[48:49], v[56:57]
	v_pk_add_f32 v[126:127], v[48:49], v[56:57] neg_lo:[0,1] neg_hi:[0,1]
	v_pk_add_f32 v[48:49], v[50:51], v[58:59]
	v_pk_add_f32 v[62:63], v[34:35], v[82:83] neg_lo:[0,1] neg_hi:[0,1]
	v_mov_b32_e32 v34, s35
	v_pk_add_f32 v[108:109], v[94:95], v[98:99] neg_lo:[0,1] neg_hi:[0,1]
	v_pk_add_f32 v[128:129], v[50:51], v[58:59] neg_lo:[0,1] neg_hi:[0,1]
	v_pk_add_f32 v[98:99], v[100:101], v[84:85]
	v_pk_add_f32 v[58:59], v[100:101], v[84:85] neg_lo:[0,1] neg_hi:[0,1]
	v_pk_add_f32 v[100:101], v[86:87], v[90:91]
	v_pk_add_f32 v[60:61], v[86:87], v[90:91] neg_lo:[0,1] neg_hi:[0,1]
	v_pk_add_f32 v[94:95], v[78:79], v[52:53]
	v_pk_add_f32 v[54:55], v[78:79], v[52:53] neg_lo:[0,1] neg_hi:[0,1]
	v_pk_add_f32 v[96:97], v[114:115], v[46:47]
	v_pk_add_f32 v[56:57], v[114:115], v[46:47] neg_lo:[0,1] neg_hi:[0,1]
	v_pk_add_f32 v[90:91], v[76:77], v[88:89]
	v_pk_add_f32 v[50:51], v[76:77], v[88:89] neg_lo:[0,1] neg_hi:[0,1]
	v_pk_add_f32 v[92:93], v[40:41], v[48:49]
	v_pk_add_f32 v[52:53], v[40:41], v[48:49] neg_lo:[0,1] neg_hi:[0,1]
	v_pk_add_f32 v[86:87], v[104:105], v[36:37]
	v_pk_add_f32 v[46:47], v[104:105], v[36:37] neg_lo:[0,1] neg_hi:[0,1]
	v_pk_add_f32 v[88:89], v[106:107], v[74:75]
	v_pk_add_f32 v[48:49], v[106:107], v[74:75] neg_lo:[0,1] neg_hi:[0,1]
	s_waitcnt lgkmcnt(0)
	s_barrier
; template <bool CENTER>
; __device__ __forceinline__ void rot_finish(const u32x4 (&w)[8], signed char* dst, LAS float* red, int tl, int half, int wv4, int lane, float& step_out, float& sum_out) {
;     ...
;         sm = (red[half * 4] + red[half * 4 + 1]) + (red[half * 4 + 2] + red[half * 4 + 3]);
;         pr[0][0] -= sm * (64.0f / DFF);
;     }
; #pragma unroll
;     for (int i = 0; i < 32; ++i) mx = fmaxf(mx, fmaxf(fabsf(pr[i][0]), fabsf(pr[i][1])));
; #pragma unroll
;     for (int o = 1; o < 64; o <<= 1) mx = fmaxf(mx, __shfl_xor(mx, o));
;     if (lane == 0) { red[16 + half * 4 + wv4] = mx; if (!CENTER) red[half * 4 + wv4] = sm; }
	ds_read_b128 v[104:107], v34
	v_pk_add_f32 v[102:103], v[110:111], v[42:43]
	v_pk_add_f32 v[38:39], v[64:65], v[38:39] neg_lo:[0,1] neg_hi:[0,1]
	v_pk_add_f32 v[82:83], v[80:81], v[108:109]
	v_pk_add_f32 v[84:85], v[44:45], v[112:113]
	s_waitcnt lgkmcnt(0)
	v_add_f32_e32 v104, v104, v105
	v_add_f32_e32 v105, v106, v107
	v_add_f32_e32 v104, v104, v105
	v_fmamk_f32 v72, v104, 0xbb800000, v72
	v_max_f32_e64 v105, |v73|, |v73|
	v_max_f32_e64 v105, |v72|, v105
	v_max_f32_e64 v106, |v102|, |v103|
	v_max3_f32 v105, v105, 0, v106
	v_max_f32_e64 v106, |v98|, |v99|
	v_max_f32_e64 v107, |v100|, |v101|
	v_max3_f32 v105, v105, v106, v107
	v_max_f32_e64 v106, |v94|, |v95|
	v_max_f32_e64 v107, |v96|, |v97|
	v_max3_f32 v105, v105, v106, v107
	v_max_f32_e64 v106, |v90|, |v91|
	v_max_f32_e64 v107, |v92|, |v93|
	v_max3_f32 v105, v105, v106, v107
	v_max_f32_e64 v106, |v86|, |v87|
	v_max_f32_e64 v107, |v88|, |v89|
	v_pk_add_f32 v[64:65], v[110:111], v[42:43] neg_lo:[0,1] neg_hi:[0,1]
	v_pk_add_f32 v[42:43], v[80:81], v[108:109] neg_lo:[0,1] neg_hi:[0,1]
	v_pk_add_f32 v[76:77], v[38:39], v[122:123]
	v_pk_add_f32 v[80:81], v[116:117], v[124:125]
	v_max3_f32 v105, v105, v106, v107
	v_max_f32_e64 v106, |v82|, |v83|
	v_max_f32_e64 v107, |v84|, |v85|
	v_pk_add_f32 v[74:75], v[118:119], v[126:127]
	v_pk_add_f32 v[78:79], v[120:121], v[128:129]
	v_max3_f32 v105, v105, v106, v107
	v_max_f32_e64 v106, |v76|, |v77|
	v_max_f32_e64 v107, |v80|, |v81|
	v_max3_f32 v105, v105, v106, v107
	v_max_f32_e64 v106, |v74|, |v75|
	v_max_f32_e64 v107, |v78|, |v79|
	v_max3_f32 v105, v105, v106, v107
	v_max_f32_e64 v106, |v62|, |v63|
	v_max_f32_e64 v107, |v64|, |v65|
	v_max3_f32 v105, v105, v106, v107
	v_max_f32_e64 v106, |v58|, |v59|
	v_max_f32_e64 v107, |v60|, |v61|
	v_max3_f32 v105, v105, v106, v107
	v_max_f32_e64 v106, |v54|, |v55|
	v_max_f32_e64 v107, |v56|, |v57|
	v_max3_f32 v105, v105, v106, v107
	v_max_f32_e64 v106, |v50|, |v51|
	v_max_f32_e64 v107, |v52|, |v53|
	v_pk_add_f32 v[44:45], v[44:45], v[112:113] neg_lo:[0,1] neg_hi:[0,1]
	v_max3_f32 v105, v105, v106, v107
	v_max_f32_e64 v106, |v46|, |v47|
	v_max_f32_e64 v107, |v48|, |v49|
	v_pk_add_f32 v[36:37], v[38:39], v[122:123] neg_lo:[0,1] neg_hi:[0,1]
	v_pk_add_f32 v[40:41], v[116:117], v[124:125] neg_lo:[0,1] neg_hi:[0,1]
	v_max3_f32 v105, v105, v106, v107
	v_max_f32_e64 v106, |v42|, |v43|
	v_max_f32_e64 v107, |v44|, |v45|
	v_pk_add_f32 v[34:35], v[118:119], v[126:127] neg_lo:[0,1] neg_hi:[0,1]
	v_pk_add_f32 v[38:39], v[120:121], v[128:129] neg_lo:[0,1] neg_hi:[0,1]
	v_max3_f32 v105, v105, v106, v107
	v_max_f32_e64 v106, |v36|, |v37|
	v_max_f32_e64 v107, |v40|, |v41|
	v_max3_f32 v105, v105, v106, v107
	v_max_f32_e64 v106, |v34|, |v35|
	v_max_f32_e64 v107, |v38|, |v39|
	v_max3_f32 v105, v105, v106, v107
	s_nop 1
	v_mov_b32_dpp v106, v105 quad_perm:[1,0,3,2] row_mask:0xf bank_mask:0xf
	s_waitcnt lgkmcnt(0)
	v_max_f32_e32 v106, v106, v106
	v_max_f32_e32 v105, v105, v106
	s_nop 1
	v_mov_b32_dpp v106, v105 quad_perm:[2,3,0,1] row_mask:0xf bank_mask:0xf
	s_waitcnt lgkmcnt(0)
	v_max_f32_e32 v106, v106, v106
	v_max_f32_e32 v105, v105, v106
	s_nop 1
	v_mov_b32_dpp v106, v105 row_half_mirror row_mask:0xf bank_mask:0xf
	s_waitcnt lgkmcnt(0)
	v_max_f32_e32 v106, v106, v106
	v_max_f32_e32 v105, v105, v106
	s_nop 1
	v_mov_b32_dpp v106, v105 row_mirror row_mask:0xf bank_mask:0xf
	s_waitcnt lgkmcnt(0)
	v_max_f32_e32 v106, v106, v106
	v_max_f32_e32 v105, v105, v106
	ds_bpermute_b32 v106, v203, v105
	s_waitcnt lgkmcnt(0)
	v_max_f32_e32 v106, v106, v106
	v_max_f32_e32 v105, v105, v106
	ds_bpermute_b32 v106, v204, v105
	s_and_saveexec_b64 s[26:27], s[4:5]
	s_cbranch_execz .LBB0_1554
	s_waitcnt lgkmcnt(0)
	v_max_f32_e32 v106, v106, v106
	v_max_f32_e32 v105, v105, v105
	v_max_f32_e32 v105, v105, v106
	v_mov_b32_e32 v106, s36
	ds_write_b32 v106, v105 offset:64

; __device__ __forceinline__ float bflo(unsigned w) { return __uint_as_float(w << 16); }
; __device__ __forceinline__ float bfhi(unsigned w) { return __uint_as_float(w & 0xffff0000u); }
; __global__ void __launch_bounds__(NWAVES * 64, 2) fwd(Args args) {
;     ...
;         for (int row = gw; row < T; row += 2 * NGW) {
;             const int row2 = row + NGW;
;             const float pa = part[(size_t)row * 64 + F.lane], pb = part[(size_t)row2 * 64 + F.lane];
;             const u32x4* hp = (const u32x4*)(hb + (size_t)row * DM) + F.lane; const u32x4* hq = (const u32x4*)(hb + (size_t)row2 * DM) + F.lane; u32x4 wa[8], wb[8];
; #pragma unroll
;             for (int j = 0; j < 8; ++j) { wa[j] = hp[64 * j]; wb[j] = hq[64 * j]; }
;             const float rsa = 1.0f / sqrtf(wave_sum(pa) * (1.0f / DM) + EPS), rsb = 1.0f / sqrtf(wave_sum(pb) * (1.0f / DM) + EPS);
;             f32x4* oa = (f32x4*)(F.out + (size_t)row * DM) + 2 * F.lane; f32x4* ob = (f32x4*)(F.out + (size_t)row2 * DM) + 2 * F.lane;
; #pragma unroll
;             for (int j = 0; j < 8; ++j) { const f32x4 g0 = gfp[128 * j], g1 = gfp[128 * j + 1]; const u32x4 w = wa[j], w2 = wb[j];
;                 const f32x4 v0 = {bflo(w.x) * g0[0] * rsa, bfhi(w.x) * g0[1] * rsa, bflo(w.y) * g0[2] * rsa, bfhi(w.y) * g0[3] * rsa}, v1 = {bflo(w.z) * g1[0] * rsa, bfhi(w.z) * g1[1] * rsa, bflo(w.w) * g1[2] * rsa, bfhi(w.w) * g1[3] * rsa};
;                 const f32x4 u0 = {bflo(w2.x) * g0[0] * rsb, bfhi(w2.x) * g0[1] * rsb, bflo(w2.y) * g0[2] * rsb, bfhi(w2.y) * g0[3] * rsb}, u1 = {bflo(w2.z) * g1[0] * rsb, bfhi(w2.z) * g1[1] * rsb, bflo(w2.w) * g1[2] * rsb, bfhi(w2.w) * g1[3] * rsb};
.LBB0_1714:
	v_lshl_add_u64 v[4:5], s[78:79], 0, v[72:73]
	v_lshl_add_u64 v[6:7], s[78:79], 0, v[70:71]
	v_lshl_add_u64 v[2:3], s[78:79], 0, v[68:69]
	flat_load_dwordx4 v[28:31], v[42:43]
	flat_load_dwordx4 v[24:27], v[42:43] offset:16
	global_load_dword v163, v[4:5], off
	global_load_dword v164, v[6:7], off
	v_add_co_u32_e32 v4, vcc, 0x26000000, v2
	v_lshl_add_u64 v[0:1], s[78:79], 0, v[74:75]
	s_nop 0
	v_addc_co_u32_e32 v5, vcc, 0, v3, vcc
	global_load_dwordx4 v[98:101], v[4:5], off
	global_load_dwordx4 v[102:105], v[4:5], off offset:1024
	global_load_dwordx4 v[106:109], v[4:5], off offset:2048
	v_add_co_u32_e32 v6, vcc, 0x26000000, v0
	v_lshl_add_u64 v[78:79], s[10:11], 0, v[40:41]
	s_nop 0
	v_addc_co_u32_e32 v7, vcc, 0, v1, vcc
	global_load_dwordx4 v[110:113], v[6:7], off
	global_load_dwordx4 v[114:117], v[6:7], off offset:1024
	global_load_dwordx4 v[118:121], v[6:7], off offset:2048
	global_load_dwordx4 v[122:125], v[4:5], off offset:3072
	global_load_dwordx4 v[126:129], v[6:7], off offset:3072
	v_add_co_u32_e64 v84, s[0:1], s19, v78
	v_lshl_add_u64 v[76:77], s[16:17], 0, v[40:41]
	s_nop 0
	v_addc_co_u32_e64 v85, s[0:1], 0, v79, s[0:1]
	v_add_co_u32_e64 v80, s[0:1], s20, v78
	v_add_co_u32_e32 v2, vcc, s7, v2
	s_nop 0
	v_addc_co_u32_e64 v81, s[0:1], 0, v79, s[0:1]
	v_add_co_u32_e64 v86, s[0:1], s19, v76
	v_addc_co_u32_e32 v3, vcc, 0, v3, vcc
	s_nop 0
	v_addc_co_u32_e64 v87, s[0:1], 0, v77, s[0:1]
	v_add_co_u32_e64 v82, s[0:1], s20, v76
	v_add_co_u32_e32 v0, vcc, s7, v0
	s_nop 0
	v_addc_co_u32_e64 v83, s[0:1], 0, v77, s[0:1]
	v_addc_co_u32_e32 v1, vcc, 0, v1, vcc
	global_load_dwordx4 v[36:39], v[2:3], off
	global_load_dwordx4 v[20:23], v[2:3], off offset:1024
	global_load_dwordx4 v[12:15], v[2:3], off offset:2048
	global_load_dwordx4 v[16:19], v[0:1], off offset:1024
	global_load_dwordx4 v[8:11], v[0:1], off offset:2048
	global_load_dwordx4 v[32:35], v[0:1], off
	global_load_dwordx4 v[4:7], v[2:3], off offset:3072
	s_nop 0
	global_load_dwordx4 v[0:3], v[0:1], off offset:3072
	s_add_i32 s82, s82, s6
	s_add_u32 s10, s10, s12
	s_addc_u32 s11, s11, s13
	s_add_u32 s16, s16, s12
	s_addc_u32 s17, s17, s13
	v_lshl_add_u64 v[68:69], v[68:69], 0, s[8:9]
	v_lshl_add_u64 v[70:71], v[70:71], 0, s[14:15]
	v_lshl_add_u64 v[72:73], v[72:73], 0, s[14:15]
	v_lshl_add_u64 v[74:75], v[74:75], 0, s[8:9]
	s_cmpk_lt_i32 s82, 0x4000
	s_waitcnt vmcnt(0)
	s_nop 1
	v_mov_b32_dpp v165, v163 quad_perm:[1,0,3,2] row_mask:0xf bank_mask:0xf
	s_nop 1
	v_mov_b32_dpp v166, v164 quad_perm:[1,0,3,2] row_mask:0xf bank_mask:0xf
	v_lshlrev_b32_e32 v132, 16, v100
	v_and_b32_e32 v133, 0xffff0000, v100
	v_lshlrev_b32_e32 v88, 16, v106
	v_and_b32_e32 v89, 0xffff0000, v106
	v_lshlrev_b32_e32 v142, 16, v107
	v_and_b32_e32 v143, 0xffff0000, v107
	v_lshlrev_b32_e32 v144, 16, v108
	v_and_b32_e32 v145, 0xffff0000, v108
	v_lshlrev_b32_e32 v146, 16, v109
	v_and_b32_e32 v147, 0xffff0000, v109
	v_lshlrev_b32_e32 v106, 16, v110
	v_and_b32_e32 v107, 0xffff0000, v110
	v_lshlrev_b32_e32 v108, 16, v111
	v_and_b32_e32 v109, 0xffff0000, v111
	v_lshlrev_b32_e32 v110, 16, v112
	v_and_b32_e32 v111, 0xffff0000, v112
	v_lshlrev_b32_e32 v100, 16, v101
	v_and_b32_e32 v101, 0xffff0000, v101
	v_lshlrev_b32_e32 v138, 16, v104
	v_and_b32_e32 v139, 0xffff0000, v104
	v_lshlrev_b32_e32 v140, 16, v105
	v_and_b32_e32 v141, 0xffff0000, v105
	s_waitcnt lgkmcnt(0)
	v_pk_mul_f32 v[104:105], v[24:25], v[132:133]
	v_lshlrev_b32_e32 v112, 16, v113
	v_and_b32_e32 v113, 0xffff0000, v113
	v_pk_mul_f32 v[110:111], v[24:25], v[110:111]
	v_add_f32_e32 v24, v163, v165
	v_pk_mul_f32 v[100:101], v[26:27], v[100:101]
	v_pk_mul_f32 v[112:113], v[26:27], v[112:113]
	v_add_f32_e32 v25, v164, v166
	s_nop 1
	v_mov_b32_dpp v26, v24 quad_perm:[2,3,0,1] row_mask:0xf bank_mask:0xf
	s_nop 1
	v_mov_b32_dpp v27, v25 quad_perm:[2,3,0,1] row_mask:0xf bank_mask:0xf
	v_lshlrev_b32_e32 v130, 16, v98
	v_and_b32_e32 v131, 0xffff0000, v98
	v_lshlrev_b32_e32 v98, 16, v99
	s_waitcnt lgkmcnt(0)
	v_add_f32_e32 v24, v24, v26
	s_waitcnt lgkmcnt(0)
	v_add_f32_e32 v25, v25, v27
	s_nop 1
	v_mov_b32_dpp v26, v24 row_half_mirror row_mask:0xf bank_mask:0xf
	s_nop 1
	v_mov_b32_dpp v27, v25 row_half_mirror row_mask:0xf bank_mask:0xf
	v_and_b32_e32 v99, 0xffff0000, v99
	v_lshlrev_b32_e32 v134, 16, v102
	v_and_b32_e32 v135, 0xffff0000, v102
	s_waitcnt lgkmcnt(0)
	v_add_f32_e32 v24, v24, v26
	s_waitcnt lgkmcnt(0)
	v_add_f32_e32 v25, v25, v27
	s_nop 1
	v_mov_b32_dpp v26, v24 row_mirror row_mask:0xf bank_mask:0xf
	s_nop 1
	v_mov_b32_dpp v27, v25 row_mirror row_mask:0xf bank_mask:0xf
	v_lshlrev_b32_e32 v136, 16, v103
	v_and_b32_e32 v137, 0xffff0000, v103
	v_pk_mul_f32 v[102:103], v[28:29], v[130:131]
	s_waitcnt lgkmcnt(0)
	v_add_f32_e32 v24, v24, v26
	s_waitcnt lgkmcnt(0)
	v_add_f32_e32 v25, v25, v27
	ds_bpermute_b32 v26, v94, v24
	ds_bpermute_b32 v27, v94, v25
	v_pk_mul_f32 v[106:107], v[28:29], v[106:107]
	v_pk_mul_f32 v[98:99], v[30:31], v[98:99]
	v_pk_mul_f32 v[108:109], v[30:31], v[108:109]
	s_waitcnt lgkmcnt(1)
	v_add_f32_e32 v24, v24, v26
	s_waitcnt lgkmcnt(0)
	v_add_f32_e32 v25, v25, v27
	ds_bpermute_b32 v26, v95, v24
	ds_bpermute_b32 v27, v95, v25
	v_lshlrev_b32_e32 v130, 16, v114
	v_and_b32_e32 v131, 0xffff0000, v114
	v_lshlrev_b32_e32 v114, 16, v115
	s_waitcnt lgkmcnt(1)
	v_add_f32_e32 v24, v24, v26
	s_waitcnt lgkmcnt(0)
; __device__ __forceinline__ float bflo(unsigned w) { return __uint_as_float(w << 16); }
; __device__ __forceinline__ float bfhi(unsigned w) { return __uint_as_float(w & 0xffff0000u); }
; __global__ void __launch_bounds__(NWAVES * 64, 2) fwd(Args args) {
;     ...
;             const float rsa = 1.0f / sqrtf(wave_sum(pa) * (1.0f / DM) + EPS), rsb = 1.0f / sqrtf(wave_sum(pb) * (1.0f / DM) + EPS);
;             f32x4* oa = (f32x4*)(F.out + (size_t)row * DM) + 2 * F.lane; f32x4* ob = (f32x4*)(F.out + (size_t)row2 * DM) + 2 * F.lane;
; #pragma unroll
;             for (int j = 0; j < 8; ++j) { const f32x4 g0 = gfp[128 * j], g1 = gfp[128 * j + 1]; const u32x4 w = wa[j], w2 = wb[j];
;                 const f32x4 v0 = {bflo(w.x) * g0[0] * rsa, bfhi(w.x) * g0[1] * rsa, bflo(w.y) * g0[2] * rsa, bfhi(w.y) * g0[3] * rsa}, v1 = {bflo(w.z) * g1[0] * rsa, bfhi(w.z) * g1[1] * rsa, bflo(w.w) * g1[2] * rsa, bfhi(w.w) * g1[3] * rsa};
;                 const f32x4 u0 = {bflo(w2.x) * g0[0] * rsb, bfhi(w2.x) * g0[1] * rsb, bflo(w2.y) * g0[2] * rsb, bfhi(w2.y) * g0[3] * rsb}, u1 = {bflo(w2.z) * g1[0] * rsb, bfhi(w2.z) * g1[1] * rsb, bflo(w2.w) * g1[2] * rsb, bfhi(w2.w) * g1[3] * rsb};
;                 __builtin_nontemporal_store(v0, oa + 128 * j); __builtin_nontemporal_store(v1, oa + 128 * j + 1); __builtin_nontemporal_store(u0, ob + 128 * j); __builtin_nontemporal_store(u1, ob + 128 * j + 1); } }
	v_add_f32_e32 v25, v25, v27
	v_fmamk_f32 v24, v24, 0x39800000, v96
	v_fmamk_f32 v25, v25, 0x39800000, v96
	v_mul_f32_e32 v26, 0x4f800000, v24
	v_cmp_gt_f32_e64 s[0:1], s18, v24
	v_mul_f32_e32 v27, 0x4f800000, v25
	v_cmp_gt_f32_e32 vcc, s18, v25
	v_cndmask_b32_e64 v24, v24, v26, s[0:1]
	v_sqrt_f32_e32 v26, v24
	v_cndmask_b32_e32 v25, v25, v27, vcc
	v_sqrt_f32_e32 v27, v25
	v_and_b32_e32 v115, 0xffff0000, v115
	v_add_u32_e32 v28, -1, v26
	v_add_u32_e32 v29, 1, v26
	v_add_u32_e32 v30, -1, v27
	v_fma_f32 v163, -v28, v26, v24
	v_add_u32_e32 v31, 1, v27
	v_fma_f32 v164, -v29, v26, v24
	v_fma_f32 v165, -v30, v27, v25
	v_cmp_ge_f32_e64 s[2:3], 0, v163
	v_fma_f32 v166, -v31, v27, v25
	v_cmp_lt_f32_e64 s[4:5], 0, v164
	v_cndmask_b32_e64 v26, v26, v28, s[2:3]
	v_cmp_ge_f32_e64 s[2:3], 0, v165
	v_cndmask_b32_e64 v26, v26, v29, s[4:5]
	v_mul_f32_e32 v28, 0x37800000, v26
	v_cndmask_b32_e64 v27, v27, v30, s[2:3]
	v_cmp_lt_f32_e64 s[2:3], 0, v166
	v_cndmask_b32_e64 v26, v26, v28, s[0:1]
	v_cmp_class_f32_e64 s[0:1], v24, v97
	v_cndmask_b32_e64 v27, v27, v31, s[2:3]
	v_mul_f32_e32 v29, 0x37800000, v27
	v_cndmask_b32_e32 v27, v27, v29, vcc
	v_cmp_class_f32_e32 vcc, v25, v97
	v_cndmask_b32_e64 v24, v26, v24, s[0:1]
	v_div_scale_f32 v26, s[0:1], v24, v24, 1.0
	v_cndmask_b32_e32 v25, v27, v25, vcc
	v_div_scale_f32 v28, s[0:1], v25, v25, 1.0
	v_rcp_f32_e32 v30, v26
	v_rcp_f32_e32 v31, v28
	v_div_scale_f32 v27, vcc, 1.0, v24, 1.0
	v_fma_f32 v163, -v26, v30, 1.0
	v_fma_f32 v164, -v28, v31, 1.0
	v_fmac_f32_e32 v30, v163, v30
	v_div_scale_f32 v29, s[0:1], 1.0, v25, 1.0
	v_fmac_f32_e32 v31, v164, v31
	v_mul_f32_e32 v163, v27, v30
	v_mul_f32_e32 v164, v29, v31
	v_fma_f32 v165, -v26, v163, v27
	v_fma_f32 v166, -v28, v164, v29
	v_fmac_f32_e32 v163, v165, v30
	v_fmac_f32_e32 v164, v166, v31
	v_fma_f32 v26, -v26, v163, v27
	v_fma_f32 v27, -v28, v164, v29
	v_div_fmas_f32 v26, v26, v30, v163
	s_mov_b64 vcc, s[0:1]
	v_div_fixup_f32 v26, v26, v24, 1.0
	v_div_fmas_f32 v24, v27, v31, v164
	v_div_fixup_f32 v24, v24, v25, 1.0
	v_pk_mul_f32 v[28:29], v[26:27], v[102:103] op_sel_hi:[0,1]
	v_pk_mul_f32 v[30:31], v[26:27], v[98:99] op_sel_hi:[0,1]
	v_pk_mul_f32 v[98:99], v[26:27], v[104:105] op_sel_hi:[0,1]
	v_pk_mul_f32 v[100:101], v[26:27], v[100:101] op_sel_hi:[0,1]
	v_pk_mul_f32 v[102:103], v[24:25], v[106:107] op_sel_hi:[0,1]
	v_pk_mul_f32 v[104:105], v[24:25], v[108:109] op_sel_hi:[0,1]
	v_pk_mul_f32 v[106:107], v[24:25], v[110:111] op_sel_hi:[0,1]
	v_pk_mul_f32 v[108:109], v[24:25], v[112:113] op_sel_hi:[0,1]
	global_store_dwordx4 v[78:79], v[28:31], off nt
	global_store_dwordx4 v[78:79], v[98:101], off offset:16 nt
	global_store_dwordx4 v[76:77], v[102:105], off nt
	global_store_dwordx4 v[76:77], v[106:109], off offset:16 nt
	flat_load_dwordx4 v[28:31], v[42:43] offset:2048
	s_nop 0
	flat_load_dwordx4 v[98:101], v[42:43] offset:2064
	v_lshlrev_b32_e32 v132, 16, v116
	v_and_b32_e32 v133, 0xffff0000, v116
	v_lshlrev_b32_e32 v116, 16, v117
	v_and_b32_e32 v117, 0xffff0000, v117
	v_lshlrev_b32_e32 v148, 16, v118
	v_and_b32_e32 v149, 0xffff0000, v118
	v_lshlrev_b32_e32 v118, 16, v119
	v_and_b32_e32 v119, 0xffff0000, v119
	v_lshlrev_b32_e32 v150, 16, v120
	v_and_b32_e32 v151, 0xffff0000, v120
	v_lshlrev_b32_e32 v120, 16, v121
	v_and_b32_e32 v121, 0xffff0000, v121
	v_lshlrev_b32_e32 v152, 16, v122
	v_and_b32_e32 v153, 0xffff0000, v122
	v_lshlrev_b32_e32 v122, 16, v123
	v_and_b32_e32 v123, 0xffff0000, v123
	v_lshlrev_b32_e32 v154, 16, v124
	v_and_b32_e32 v155, 0xffff0000, v124
	v_lshlrev_b32_e32 v124, 16, v125
	v_and_b32_e32 v125, 0xffff0000, v125
	v_lshlrev_b32_e32 v156, 16, v126
	v_and_b32_e32 v157, 0xffff0000, v126
	v_lshlrev_b32_e32 v126, 16, v127
	v_and_b32_e32 v127, 0xffff0000, v127
	v_lshlrev_b32_e32 v158, 16, v128
	v_and_b32_e32 v159, 0xffff0000, v128
	v_lshlrev_b32_e32 v128, 16, v129
	v_and_b32_e32 v129, 0xffff0000, v129
	v_lshlrev_b32_e32 v160, 16, v36
	v_and_b32_e32 v161, 0xffff0000, v36
	v_lshlrev_b32_e32 v36, 16, v37
	v_and_b32_e32 v37, 0xffff0000, v37
	v_lshlrev_b32_e32 v162, 16, v38
	v_and_b32_e32 v163, 0xffff0000, v38
	v_lshlrev_b32_e32 v38, 16, v39
	v_and_b32_e32 v39, 0xffff0000, v39
	s_waitcnt vmcnt(0) lgkmcnt(0)
	v_pk_mul_f32 v[102:103], v[28:29], v[134:135]
	v_pk_mul_f32 v[104:105], v[30:31], v[136:137]
	v_pk_mul_f32 v[106:107], v[98:99], v[138:139]
	v_pk_mul_f32 v[108:109], v[100:101], v[140:141]
	v_pk_mul_f32 v[110:111], v[28:29], v[130:131]
	v_pk_mul_f32 v[112:113], v[30:31], v[114:115]
	v_pk_mul_f32 v[114:115], v[98:99], v[132:133]
	v_pk_mul_f32 v[116:117], v[100:101], v[116:117]
	v_pk_mul_f32 v[28:29], v[26:27], v[102:103] op_sel_hi:[0,1]
	v_pk_mul_f32 v[30:31], v[26:27], v[104:105] op_sel_hi:[0,1]
	v_pk_mul_f32 v[98:99], v[26:27], v[106:107] op_sel_hi:[0,1]
	v_pk_mul_f32 v[100:101], v[26:27], v[108:109] op_sel_hi:[0,1]
	v_pk_mul_f32 v[102:103], v[24:25], v[110:111] op_sel_hi:[0,1]
	v_pk_mul_f32 v[104:105], v[24:25], v[112:113] op_sel_hi:[0,1]
	v_pk_mul_f32 v[106:107], v[24:25], v[114:115] op_sel_hi:[0,1]
	v_pk_mul_f32 v[108:109], v[24:25], v[116:117] op_sel_hi:[0,1]
	global_store_dwordx4 v[78:79], v[28:31], off offset:2048 nt
	global_store_dwordx4 v[78:79], v[98:101], off offset:2064 nt
	global_store_dwordx4 v[76:77], v[102:105], off offset:2048 nt
	global_store_dwordx4 v[76:77], v[106:109], off offset:2064 nt
	flat_load_dwordx4 v[28:31], v[44:45]
	s_nop 0
	flat_load_dwordx4 v[98:101], v[46:47]
	s_waitcnt vmcnt(0) lgkmcnt(0)
; __device__ __forceinline__ float bflo(unsigned w) { return __uint_as_float(w << 16); }
; __device__ __forceinline__ float bfhi(unsigned w) { return __uint_as_float(w & 0xffff0000u); }
; __global__ void __launch_bounds__(NWAVES * 64, 2) fwd(Args args) {
;     ...
; #pragma unroll
;             for (int j = 0; j < 8; ++j) { const f32x4 g0 = gfp[128 * j], g1 = gfp[128 * j + 1]; const u32x4 w = wa[j], w2 = wb[j];
;                 const f32x4 v0 = {bflo(w.x) * g0[0] * rsa, bfhi(w.x) * g0[1] * rsa, bflo(w.y) * g0[2] * rsa, bfhi(w.y) * g0[3] * rsa}, v1 = {bflo(w.z) * g1[0] * rsa, bfhi(w.z) * g1[1] * rsa, bflo(w.w) * g1[2] * rsa, bfhi(w.w) * g1[3] * rsa};
;                 const f32x4 u0 = {bflo(w2.x) * g0[0] * rsb, bfhi(w2.x) * g0[1] * rsb, bflo(w2.y) * g0[2] * rsb, bfhi(w2.y) * g0[3] * rsb}, u1 = {bflo(w2.z) * g1[0] * rsb, bfhi(w2.z) * g1[1] * rsb, bflo(w2.w) * g1[2] * rsb, bfhi(w2.w) * g1[3] * rsb};
;                 __builtin_nontemporal_store(v0, oa + 128 * j); __builtin_nontemporal_store(v1, oa + 128 * j + 1); __builtin_nontemporal_store(u0, ob + 128 * j); __builtin_nontemporal_store(u1, ob + 128 * j + 1); } }
	v_pk_mul_f32 v[88:89], v[28:29], v[88:89]
	v_pk_mul_f32 v[102:103], v[30:31], v[142:143]
	v_pk_mul_f32 v[104:105], v[98:99], v[144:145]
	v_pk_mul_f32 v[106:107], v[100:101], v[146:147]
	v_pk_mul_f32 v[108:109], v[28:29], v[148:149]
	v_pk_mul_f32 v[110:111], v[30:31], v[118:119]
	v_pk_mul_f32 v[112:113], v[98:99], v[150:151]
	v_pk_mul_f32 v[114:115], v[100:101], v[120:121]
	v_pk_mul_f32 v[28:29], v[26:27], v[88:89] op_sel_hi:[0,1]
	v_pk_mul_f32 v[30:31], v[26:27], v[102:103] op_sel_hi:[0,1]
	v_pk_mul_f32 v[98:99], v[26:27], v[104:105] op_sel_hi:[0,1]
	v_pk_mul_f32 v[100:101], v[26:27], v[106:107] op_sel_hi:[0,1]
	v_pk_mul_f32 v[102:103], v[24:25], v[108:109] op_sel_hi:[0,1]
	v_pk_mul_f32 v[104:105], v[24:25], v[110:111] op_sel_hi:[0,1]
	v_pk_mul_f32 v[106:107], v[24:25], v[112:113] op_sel_hi:[0,1]
	v_pk_mul_f32 v[108:109], v[24:25], v[114:115] op_sel_hi:[0,1]
	global_store_dwordx4 v[80:81], v[28:31], off offset:-4096 nt
	global_store_dwordx4 v[84:85], v[98:101], off offset:16 nt
	global_store_dwordx4 v[82:83], v[102:105], off offset:-4096 nt
	global_store_dwordx4 v[86:87], v[106:109], off offset:16 nt
	flat_load_dwordx4 v[28:31], v[48:49]
	s_nop 0
	flat_load_dwordx4 v[98:101], v[50:51]
	s_waitcnt vmcnt(0) lgkmcnt(0)
	v_pk_mul_f32 v[88:89], v[28:29], v[152:153]
	v_pk_mul_f32 v[102:103], v[30:31], v[122:123]
	v_pk_mul_f32 v[104:105], v[98:99], v[154:155]
	v_pk_mul_f32 v[106:107], v[100:101], v[124:125]
	v_pk_mul_f32 v[108:109], v[28:29], v[156:157]
	v_pk_mul_f32 v[110:111], v[30:31], v[126:127]
	v_pk_mul_f32 v[112:113], v[98:99], v[158:159]
	v_pk_mul_f32 v[114:115], v[100:101], v[128:129]
	v_pk_mul_f32 v[28:29], v[26:27], v[88:89] op_sel_hi:[0,1]
	v_pk_mul_f32 v[30:31], v[26:27], v[102:103] op_sel_hi:[0,1]
	v_pk_mul_f32 v[98:99], v[26:27], v[104:105] op_sel_hi:[0,1]
	v_pk_mul_f32 v[100:101], v[26:27], v[106:107] op_sel_hi:[0,1]
	v_pk_mul_f32 v[102:103], v[24:25], v[108:109] op_sel_hi:[0,1]
	v_pk_mul_f32 v[104:105], v[24:25], v[110:111] op_sel_hi:[0,1]
	v_pk_mul_f32 v[106:107], v[24:25], v[112:113] op_sel_hi:[0,1]
	v_pk_mul_f32 v[108:109], v[24:25], v[114:115] op_sel_hi:[0,1]
	global_store_dwordx4 v[84:85], v[28:31], off offset:2048 nt
	global_store_dwordx4 v[84:85], v[98:101], off offset:2064 nt
	global_store_dwordx4 v[86:87], v[102:105], off offset:2048 nt
	global_store_dwordx4 v[86:87], v[106:109], off offset:2064 nt
	flat_load_dwordx4 v[28:31], v[52:53]
	s_nop 0
	flat_load_dwordx4 v[84:87], v[54:55]
	v_lshlrev_b32_e32 v88, 16, v32
	v_and_b32_e32 v89, 0xffff0000, v32
	v_lshlrev_b32_e32 v32, 16, v33
	v_and_b32_e32 v33, 0xffff0000, v33
	v_lshlrev_b32_e32 v98, 16, v34
	v_and_b32_e32 v99, 0xffff0000, v34
	v_lshlrev_b32_e32 v34, 16, v35
	v_and_b32_e32 v35, 0xffff0000, v35
	s_waitcnt vmcnt(0) lgkmcnt(0)
	v_pk_mul_f32 v[100:101], v[28:29], v[160:161]
	v_pk_mul_f32 v[36:37], v[30:31], v[36:37]
	v_pk_mul_f32 v[102:103], v[84:85], v[162:163]
	v_pk_mul_f32 v[38:39], v[86:87], v[38:39]
	v_pk_mul_f32 v[88:89], v[28:29], v[88:89]
	v_pk_mul_f32 v[104:105], v[30:31], v[32:33]
	v_pk_mul_f32 v[84:85], v[84:85], v[98:99]
	v_pk_mul_f32 v[86:87], v[86:87], v[34:35]
	v_pk_mul_f32 v[28:29], v[26:27], v[100:101] op_sel_hi:[0,1]
	v_pk_mul_f32 v[30:31], v[26:27], v[36:37] op_sel_hi:[0,1]
	v_pk_mul_f32 v[32:33], v[26:27], v[102:103] op_sel_hi:[0,1]
	v_pk_mul_f32 v[34:35], v[26:27], v[38:39] op_sel_hi:[0,1]
	v_pk_mul_f32 v[36:37], v[24:25], v[88:89] op_sel_hi:[0,1]
	v_pk_mul_f32 v[38:39], v[24:25], v[104:105] op_sel_hi:[0,1]
	v_pk_mul_f32 v[84:85], v[24:25], v[84:85] op_sel_hi:[0,1]
	v_pk_mul_f32 v[86:87], v[24:25], v[86:87] op_sel_hi:[0,1]
	global_store_dwordx4 v[80:81], v[28:31], off nt
	global_store_dwordx4 v[80:81], v[32:35], off offset:16 nt
	global_store_dwordx4 v[82:83], v[36:39], off nt
	global_store_dwordx4 v[82:83], v[84:87], off offset:16 nt
	flat_load_dwordx4 v[28:31], v[56:57]
	s_nop 0
	flat_load_dwordx4 v[32:35], v[58:59]
	v_lshlrev_b32_e32 v36, 16, v20
	v_and_b32_e32 v37, 0xffff0000, v20
	v_lshlrev_b32_e32 v20, 16, v21
	v_and_b32_e32 v21, 0xffff0000, v21
	v_lshlrev_b32_e32 v38, 16, v22
	v_and_b32_e32 v39, 0xffff0000, v22
	v_lshlrev_b32_e32 v22, 16, v23
	v_and_b32_e32 v23, 0xffff0000, v23
	v_lshlrev_b32_e32 v84, 16, v16
	v_and_b32_e32 v85, 0xffff0000, v16
	v_lshlrev_b32_e32 v16, 16, v17
	v_and_b32_e32 v17, 0xffff0000, v17
	v_lshlrev_b32_e32 v86, 16, v18
	v_and_b32_e32 v87, 0xffff0000, v18
	v_lshlrev_b32_e32 v18, 16, v19
	v_and_b32_e32 v19, 0xffff0000, v19
	s_waitcnt vmcnt(0) lgkmcnt(0)
; __device__ __forceinline__ float bflo(unsigned w) { return __uint_as_float(w << 16); }
; __device__ __forceinline__ float bfhi(unsigned w) { return __uint_as_float(w & 0xffff0000u); }
; __global__ void __launch_bounds__(NWAVES * 64, 2) fwd(Args args) {
;     ...
; #pragma unroll
;             for (int j = 0; j < 8; ++j) { const f32x4 g0 = gfp[128 * j], g1 = gfp[128 * j + 1]; const u32x4 w = wa[j], w2 = wb[j];
;                 const f32x4 v0 = {bflo(w.x) * g0[0] * rsa, bfhi(w.x) * g0[1] * rsa, bflo(w.y) * g0[2] * rsa, bfhi(w.y) * g0[3] * rsa}, v1 = {bflo(w.z) * g1[0] * rsa, bfhi(w.z) * g1[1] * rsa, bflo(w.w) * g1[2] * rsa, bfhi(w.w) * g1[3] * rsa};
;                 const f32x4 u0 = {bflo(w2.x) * g0[0] * rsb, bfhi(w2.x) * g0[1] * rsb, bflo(w2.y) * g0[2] * rsb, bfhi(w2.y) * g0[3] * rsb}, u1 = {bflo(w2.z) * g1[0] * rsb, bfhi(w2.z) * g1[1] * rsb, bflo(w2.w) * g1[2] * rsb, bfhi(w2.w) * g1[3] * rsb};
;                 __builtin_nontemporal_store(v0, oa + 128 * j); __builtin_nontemporal_store(v1, oa + 128 * j + 1); __builtin_nontemporal_store(u0, ob + 128 * j); __builtin_nontemporal_store(u1, ob + 128 * j + 1); } }
	v_pk_mul_f32 v[36:37], v[28:29], v[36:37]
	v_pk_mul_f32 v[20:21], v[30:31], v[20:21]
	v_pk_mul_f32 v[38:39], v[32:33], v[38:39]
	v_pk_mul_f32 v[22:23], v[34:35], v[22:23]
	v_pk_mul_f32 v[28:29], v[28:29], v[84:85]
	v_pk_mul_f32 v[30:31], v[30:31], v[16:17]
	v_pk_mul_f32 v[32:33], v[32:33], v[86:87]
	v_pk_mul_f32 v[34:35], v[34:35], v[18:19]
	v_pk_mul_f32 v[16:17], v[26:27], v[36:37] op_sel_hi:[0,1]
	v_pk_mul_f32 v[18:19], v[26:27], v[20:21] op_sel_hi:[0,1]
	v_pk_mul_f32 v[20:21], v[26:27], v[38:39] op_sel_hi:[0,1]
	v_pk_mul_f32 v[22:23], v[26:27], v[22:23] op_sel_hi:[0,1]
	v_pk_mul_f32 v[28:29], v[24:25], v[28:29] op_sel_hi:[0,1]
	v_pk_mul_f32 v[30:31], v[24:25], v[30:31] op_sel_hi:[0,1]
	v_pk_mul_f32 v[32:33], v[24:25], v[32:33] op_sel_hi:[0,1]
	v_pk_mul_f32 v[34:35], v[24:25], v[34:35] op_sel_hi:[0,1]
	global_store_dwordx4 v[80:81], v[16:19], off offset:2048 nt
	global_store_dwordx4 v[80:81], v[20:23], off offset:2064 nt
	global_store_dwordx4 v[82:83], v[28:31], off offset:2048 nt
	global_store_dwordx4 v[82:83], v[32:35], off offset:2064 nt
	flat_load_dwordx4 v[16:19], v[60:61]
	s_nop 0
	flat_load_dwordx4 v[20:23], v[62:63]
	v_add_co_u32_e32 v28, vcc, s21, v78
	v_lshlrev_b32_e32 v32, 16, v12
	v_and_b32_e32 v33, 0xffff0000, v12
	v_lshlrev_b32_e32 v12, 16, v13
	v_and_b32_e32 v13, 0xffff0000, v13
	v_addc_co_u32_e32 v29, vcc, 0, v79, vcc
	v_lshlrev_b32_e32 v34, 16, v14
	v_and_b32_e32 v35, 0xffff0000, v14
	v_lshlrev_b32_e32 v14, 16, v15
	v_and_b32_e32 v15, 0xffff0000, v15
	v_lshlrev_b32_e32 v36, 16, v8
	v_and_b32_e32 v37, 0xffff0000, v8
	v_lshlrev_b32_e32 v8, 16, v9
	v_and_b32_e32 v9, 0xffff0000, v9
	v_lshlrev_b32_e32 v38, 16, v10
	v_and_b32_e32 v39, 0xffff0000, v10
	v_lshlrev_b32_e32 v10, 16, v11
	v_and_b32_e32 v11, 0xffff0000, v11
	v_add_co_u32_e32 v30, vcc, s21, v76
	s_waitcnt vmcnt(0) lgkmcnt(0)
	v_pk_mul_f32 v[32:33], v[16:17], v[32:33]
	v_pk_mul_f32 v[12:13], v[18:19], v[12:13]
	v_pk_mul_f32 v[34:35], v[20:21], v[34:35]
	v_pk_mul_f32 v[14:15], v[22:23], v[14:15]
	v_pk_mul_f32 v[16:17], v[16:17], v[36:37]
	v_pk_mul_f32 v[18:19], v[18:19], v[8:9]
	v_pk_mul_f32 v[20:21], v[20:21], v[38:39]
	v_pk_mul_f32 v[22:23], v[22:23], v[10:11]
	v_pk_mul_f32 v[8:9], v[26:27], v[32:33] op_sel_hi:[0,1]
	v_pk_mul_f32 v[10:11], v[26:27], v[12:13] op_sel_hi:[0,1]
	v_addc_co_u32_e32 v31, vcc, 0, v77, vcc
	v_pk_mul_f32 v[12:13], v[26:27], v[34:35] op_sel_hi:[0,1]
	v_pk_mul_f32 v[14:15], v[26:27], v[14:15] op_sel_hi:[0,1]
	v_pk_mul_f32 v[16:17], v[24:25], v[16:17] op_sel_hi:[0,1]
	v_pk_mul_f32 v[18:19], v[24:25], v[18:19] op_sel_hi:[0,1]
	v_pk_mul_f32 v[20:21], v[24:25], v[20:21] op_sel_hi:[0,1]
	v_pk_mul_f32 v[22:23], v[24:25], v[22:23] op_sel_hi:[0,1]
	global_store_dwordx4 v[28:29], v[8:11], off nt
	global_store_dwordx4 v[28:29], v[12:15], off offset:16 nt
	global_store_dwordx4 v[30:31], v[16:19], off nt
	global_store_dwordx4 v[30:31], v[20:23], off offset:16 nt
	flat_load_dwordx4 v[8:11], v[64:65]
	s_nop 0
	flat_load_dwordx4 v[12:15], v[66:67]
	v_lshlrev_b32_e32 v16, 16, v4
	v_and_b32_e32 v17, 0xffff0000, v4
	v_lshlrev_b32_e32 v4, 16, v5
	v_and_b32_e32 v5, 0xffff0000, v5
	v_lshlrev_b32_e32 v18, 16, v6
	v_and_b32_e32 v19, 0xffff0000, v6
	v_lshlrev_b32_e32 v6, 16, v7
	v_and_b32_e32 v7, 0xffff0000, v7
	v_lshlrev_b32_e32 v20, 16, v0
	v_and_b32_e32 v21, 0xffff0000, v0
	v_lshlrev_b32_e32 v0, 16, v1
	v_and_b32_e32 v1, 0xffff0000, v1
	v_lshlrev_b32_e32 v22, 16, v2
	v_and_b32_e32 v23, 0xffff0000, v2
	v_lshlrev_b32_e32 v2, 16, v3
	v_and_b32_e32 v3, 0xffff0000, v3
	s_waitcnt vmcnt(0) lgkmcnt(0)
	v_pk_mul_f32 v[16:17], v[8:9], v[16:17]
	v_pk_mul_f32 v[4:5], v[10:11], v[4:5]
	v_pk_mul_f32 v[18:19], v[12:13], v[18:19]
	v_pk_mul_f32 v[6:7], v[14:15], v[6:7]
	v_pk_mul_f32 v[8:9], v[8:9], v[20:21]
	v_pk_mul_f32 v[10:11], v[10:11], v[0:1]
	v_pk_mul_f32 v[12:13], v[12:13], v[22:23]
	v_pk_mul_f32 v[14:15], v[14:15], v[2:3]
	v_pk_mul_f32 v[0:1], v[26:27], v[16:17] op_sel_hi:[0,1]
	v_pk_mul_f32 v[2:3], v[26:27], v[4:5] op_sel_hi:[0,1]
	v_pk_mul_f32 v[4:5], v[26:27], v[18:19] op_sel_hi:[0,1]
	v_pk_mul_f32 v[6:7], v[26:27], v[6:7] op_sel_hi:[0,1]
	v_pk_mul_f32 v[8:9], v[24:25], v[8:9] op_sel_hi:[0,1]
	v_pk_mul_f32 v[10:11], v[24:25], v[10:11] op_sel_hi:[0,1]
	v_pk_mul_f32 v[12:13], v[24:25], v[12:13] op_sel_hi:[0,1]
	v_pk_mul_f32 v[14:15], v[24:25], v[14:15] op_sel_hi:[0,1]
	global_store_dwordx4 v[28:29], v[0:3], off offset:2048 nt
	global_store_dwordx4 v[28:29], v[4:7], off offset:2064 nt
	global_store_dwordx4 v[30:31], v[8:11], off offset:2048 nt
	global_store_dwordx4 v[30:31], v[12:15], off offset:2064 nt
	s_cbranch_scc1 .LBB0_1714
